# attention flash loops: removed per-tile O accumulator copies (MFMA SrcC/Dst renaming), rescale in place
# speedup vs baseline: 1.0455x; 1.0296x over previous
; DI f32x16 mfma32(bf16x8 a, bf16x8 b, f32x16 c) { return __builtin_amdgcn_mfma_f32_32x32x16_bf16(a, b, c, 0, 0, 0); }
; DI int crow(int i, int h) { return (i & 3) + 8 * (i >> 2) + 4 * h; }
;     ...
; #pragma unroll
;   for (int k2 = 0; k2 < 2; ++k2) {
;     if (!(HM & (1 << k2))) continue;
; #pragma unroll
;     for (int i = 0; i < 16; ++i) s[k2][i] = 0.f;
; #pragma unroll
;     for (int ks = 0; ks < 4; ++ks) {
;       const bf16x8 a = *(const bf16x8*)(Ks + (32 * k2 + r) * LSTR + 16 * ks + 8 * h);
;       s[k2] = mfma32(a, qf[ks], s[k2]);
;     }
;   }
;   if (MODE == 1) {
; #pragma unroll
;     for (int k2 = 0; k2 < 2; ++k2)
; #pragma unroll
;       for (int g = 0; g < 4; ++g) {
;         if (!(HM & (1 << k2))) continue;
;         const f32x4 cv = *(const f32x4*)(cn_lds + key0 + 32 * k2 + 8 * g + 4 * h);
; #pragma unroll
;         for (int e = 0; e < 4; ++e) s[k2][4 * g + e] = fmaf(s[k2][4 * g + e], L2E, cv[e]);
;       }
;   }
;   float mx = NINF;
; #pragma unroll
;   for (int k2 = 0; k2 < 2; ++k2)
; #pragma unroll
;     for (int i = 0; i < 16; ++i) {
;       if (!(HM & (1 << k2))) continue;
;       float v = s[k2][i];
;       if (MASKED) {
;         const int tk = key0 + 32 * k2 + crow(i, h);
;         const bool valid = (MODE == 0) ? ((tk <= tq) && (tq - tk <= maxdist)) : (tk <= tq);
;         v = valid ? v : NINF; s[k2][i] = v;
;       }
;       mx = fmaxf(mx, v);
;     }
;   mx = fmaxf(mx, __shfl_xor(mx, 32));
;   if (MODE != 1) mx *= L2E;
;   if (MODE == 2) mx = lanesel ? mx : NINF;
;   const float mn = fmaxf(m, mx); const float alpha = __builtin_amdgcn_exp2f(m - mn);
;   const float neg = (MODE == 2 && !lanesel) ? NINF : -mn;
;   float ps = 0.f;
; #pragma unroll
;   for (int k2 = 0; k2 < 2; ++k2)
; #pragma unroll
;     for (int i = 0; i < 16; ++i) {
;       if (!(HM & (1 << k2))) continue;
;       const float pv = (MODE == 1) ? __builtin_amdgcn_exp2f(s[k2][i] + neg) : __builtin_amdgcn_exp2f(fmaf(s[k2][i], L2E, neg));
;       s[k2][i] = pv; ps += pv;
;     }
;   l = l * alpha + ps;
;   if (__builtin_amdgcn_ballot_w64(mn != m) != 0ull) {
; #pragma unroll
;     for (int dt = 0; dt < 2; ++dt)
; #pragma unroll
;       for (int i = 0; i < 16; ++i) o[dt][i] *= alpha;
;   }
;   m = mn;
.LBB0_466:
	s_lshr_b64 s[6:7], s[4:5], s33
	s_and_b32 s58, s6, 1
	s_cmp_eq_u64 s[58:59], 0
	s_cbranch_scc1 .LBB0_490
	s_lshl_b32 s58, s33, 6
	s_or_b32 s33, s58, 63
	s_cmp_le_u32 s58, s30
	s_cselect_b64 s[6:7], -1, 0
	s_or_b32 s36, s58, 31
	s_cmp_ge_i32 s36, s29
	s_cselect_b64 s[36:37], -1, 0
	s_and_b64 s[6:7], s[6:7], s[36:37]
	v_cndmask_b32_e64 v0, 0, 1, s[6:7]
	s_or_b32 s6, s58, 32
	s_cmp_gt_u32 s6, s30
	s_cselect_b64 s[6:7], -1, 0
	s_cmp_lt_i32 s33, s29
	s_cselect_b64 s[36:37], -1, 0
	v_readfirstlane_b32 s38, v0
	s_or_b32 s39, s38, 2
	s_or_b64 s[6:7], s[6:7], s[36:37]
	s_and_b64 s[6:7], s[6:7], exec
	s_cselect_b32 s67, s38, s39
	s_mov_b64 s[62:63], -1
	s_mov_b64 s[54:55], 0
	s_cmp_lt_i32 s67, 2
	s_mov_b64 s[6:7], 0
	s_cbranch_scc1 .LBB0_483
	s_cmp_eq_u32 s67, 2
	s_mov_b64 s[6:7], -1
	s_cbranch_scc0 .LBB0_472
	ds_read_b128 v[34:37], v199 offset:4608
	ds_read_b128 v[50:53], v199 offset:4640
	v_or_b32_e32 v0, s58, v197
	s_waitcnt lgkmcnt(1)
	v_mfma_f32_32x32x16_bf16 v[34:49], v[34:37], v[98:101], 0
	s_waitcnt lgkmcnt(0)
	v_mfma_f32_32x32x16_bf16 v[34:49], v[50:53], v[102:105], v[34:49]
	ds_read_b128 v[50:53], v199 offset:4672
	s_waitcnt lgkmcnt(0)
	v_mfma_f32_32x32x16_bf16 v[34:49], v[50:53], v[106:109], v[34:49]
	ds_read_b128 v[50:53], v199 offset:4704
	s_waitcnt lgkmcnt(0)
	v_mfma_f32_32x32x16_bf16 v[34:49], v[50:53], v[110:113], v[34:49]
	v_or_b32_e32 v50, 32, v0
	v_cmp_gt_u32_e32 vcc, v50, v154
	v_cmp_lt_i32_e64 s[6:7], v50, v155
	s_or_b64 vcc, vcc, s[6:7]
	s_nop 7
	v_cndmask_b32_e32 v66, v34, v204, vcc
	v_bitop3_b32 v34, s58, v205, v197 bitop3:0x36
	v_cmp_ge_u32_e32 vcc, v50, v154
	v_cmp_gt_i32_e64 s[6:7], v34, v156
	s_or_b64 vcc, vcc, s[6:7]
	v_cndmask_b32_e32 v67, v35, v204, vcc
	v_or_b32_e32 v35, 34, v0
	v_cmp_gt_u32_e32 vcc, v35, v154
	v_cmp_lt_i32_e64 s[6:7], v35, v155
	s_or_b64 vcc, vcc, s[6:7]
	v_or_b32_e32 v35, 35, v0
	v_cndmask_b32_e32 v68, v36, v204, vcc
	v_cmp_gt_u32_e32 vcc, v35, v154
	v_cmp_lt_i32_e64 s[6:7], v35, v155
	s_or_b64 vcc, vcc, s[6:7]
	v_or_b32_e32 v35, 40, v0
	v_cndmask_b32_e32 v69, v37, v204, vcc
	v_cmp_gt_u32_e32 vcc, v35, v154
	v_cmp_lt_i32_e64 s[6:7], v35, v155
	s_or_b64 vcc, vcc, s[6:7]
	v_or_b32_e32 v35, 41, v0
	v_cndmask_b32_e32 v70, v38, v204, vcc
	v_cmp_gt_u32_e32 vcc, v35, v154
	v_cmp_lt_i32_e64 s[6:7], v35, v155
	s_or_b64 vcc, vcc, s[6:7]
	v_or_b32_e32 v35, 42, v0
	v_cndmask_b32_e32 v71, v39, v204, vcc
	v_cmp_gt_u32_e32 vcc, v35, v154
	v_cmp_lt_i32_e64 s[6:7], v35, v155
	s_or_b64 vcc, vcc, s[6:7]
	v_or_b32_e32 v35, 43, v0
	v_cndmask_b32_e32 v77, v40, v204, vcc
	v_cmp_gt_u32_e32 vcc, v35, v154
	v_cmp_lt_i32_e64 s[6:7], v35, v155
	s_or_b64 vcc, vcc, s[6:7]
	v_or_b32_e32 v35, 48, v0
	v_cndmask_b32_e32 v78, v41, v204, vcc
	v_cmp_gt_u32_e32 vcc, v35, v154
	v_cmp_lt_i32_e64 s[6:7], v35, v155
	s_or_b64 vcc, vcc, s[6:7]
	v_or_b32_e32 v35, 49, v0
	v_cndmask_b32_e32 v79, v42, v204, vcc
	v_cmp_gt_u32_e32 vcc, v35, v154
	v_cmp_lt_i32_e64 s[6:7], v35, v155
	s_or_b64 vcc, vcc, s[6:7]
	v_or_b32_e32 v35, 50, v0
	v_cndmask_b32_e32 v80, v43, v204, vcc
	v_cmp_gt_u32_e32 vcc, v35, v154
	v_cmp_lt_i32_e64 s[6:7], v35, v155
	s_or_b64 vcc, vcc, s[6:7]
	v_or_b32_e32 v35, 51, v0
	v_cndmask_b32_e32 v81, v44, v204, vcc
	v_cmp_gt_u32_e32 vcc, v35, v154
	v_cmp_lt_i32_e64 s[6:7], v35, v155
	s_or_b64 vcc, vcc, s[6:7]
	v_or_b32_e32 v35, 56, v0
	v_cndmask_b32_e32 v76, v45, v204, vcc
	v_cmp_gt_u32_e32 vcc, v35, v154
	v_cmp_lt_i32_e64 s[6:7], v35, v155
	s_or_b64 vcc, vcc, s[6:7]
	v_or_b32_e32 v35, 57, v0
	v_max3_f32 v34, v66, s35, v67
	v_cndmask_b32_e32 v73, v46, v204, vcc
	v_cmp_gt_u32_e32 vcc, v35, v154
	v_cmp_lt_i32_e64 s[6:7], v35, v155
	v_max3_f32 v34, v34, v68, v69
	s_or_b64 vcc, vcc, s[6:7]
	v_or_b32_e32 v35, 58, v0
	v_max3_f32 v34, v34, v70, v71
	v_cndmask_b32_e32 v74, v47, v204, vcc
	v_cmp_gt_u32_e32 vcc, v35, v154
	v_cmp_lt_i32_e64 s[6:7], v35, v155
	v_max3_f32 v34, v34, v77, v78
	s_or_b64 vcc, vcc, s[6:7]
	v_or_b32_e32 v0, 59, v0
	v_max3_f32 v34, v34, v79, v80
	v_cndmask_b32_e32 v75, v48, v204, vcc
	v_cmp_gt_u32_e32 vcc, v0, v154
	v_cmp_lt_i32_e64 s[6:7], v0, v155
	v_max3_f32 v34, v34, v81, v76
	s_or_b64 vcc, vcc, s[6:7]
	v_max3_f32 v34, v34, v73, v74
	v_cndmask_b32_e32 v72, v49, v204, vcc
	v_and_b32_e32 v35, 64, v202
	v_max3_f32 v0, v34, v75, v72
	v_xor_b32_e32 v34, 32, v202
	v_add_u32_e32 v35, 64, v35
	v_cmp_lt_i32_e32 vcc, v34, v35
	s_nop 1
	v_cndmask_b32_e32 v34, v202, v34, vcc
	v_lshlrev_b32_e32 v34, 2, v34
	ds_bpermute_b32 v34, v34, v0
	s_waitcnt lgkmcnt(0)
	v_max_f32_e32 v34, v34, v34
	v_max_f32_e32 v0, v0, v34
	v_mul_f32_e32 v0, 0x3fb8aa3b, v0
	v_max_f32_e32 v34, v157, v157
	v_max_f32_e32 v158, v34, v0
	v_sub_f32_e32 v0, v157, v158
	v_exp_f32_e32 v0, v0
	v_cmp_neq_f32_e32 vcc, v158, v157
	s_cbranch_vccz .LBB0_471
	v_pk_mul_f32 v[32:33], v[32:33], v[0:1] op_sel_hi:[1,0]
	v_pk_mul_f32 v[30:31], v[30:31], v[0:1] op_sel_hi:[1,0]
	v_pk_mul_f32 v[28:29], v[28:29], v[0:1] op_sel_hi:[1,0]
	v_pk_mul_f32 v[26:27], v[26:27], v[0:1] op_sel_hi:[1,0]
	v_pk_mul_f32 v[24:25], v[24:25], v[0:1] op_sel_hi:[1,0]
	v_pk_mul_f32 v[22:23], v[22:23], v[0:1] op_sel_hi:[1,0]
	v_pk_mul_f32 v[20:21], v[20:21], v[0:1] op_sel_hi:[1,0]
	v_pk_mul_f32 v[18:19], v[18:19], v[0:1] op_sel_hi:[1,0]
	v_pk_mul_f32 v[16:17], v[16:17], v[0:1] op_sel_hi:[1,0]
	v_pk_mul_f32 v[14:15], v[14:15], v[0:1] op_sel_hi:[1,0]
	v_pk_mul_f32 v[12:13], v[12:13], v[0:1] op_sel_hi:[1,0]
	v_pk_mul_f32 v[10:11], v[10:11], v[0:1] op_sel_hi:[1,0]
	v_pk_mul_f32 v[8:9], v[8:9], v[0:1] op_sel_hi:[1,0]
	v_pk_mul_f32 v[6:7], v[6:7], v[0:1] op_sel_hi:[1,0]
	v_pk_mul_f32 v[4:5], v[4:5], v[0:1] op_sel_hi:[1,0]
	v_pk_mul_f32 v[2:3], v[2:3], v[0:1] op_sel_hi:[1,0]
; DI unsigned pack2(float a, float b) { f32x2 v = {a, b}; bf16x2_t r = __builtin_convertvector(v, bf16x2_t); return __builtin_bit_cast(unsigned, r); }
; DI f32x16 mfma32(bf16x8 a, bf16x8 b, f32x16 c) { return __builtin_amdgcn_mfma_f32_32x32x16_bf16(a, b, c, 0, 0, 0); }
;     ...
;   const float mn = fmaxf(m, mx); const float alpha = __builtin_amdgcn_exp2f(m - mn);
;   const float neg = (MODE == 2 && !lanesel) ? NINF : -mn;
;   float ps = 0.f;
; #pragma unroll
;   for (int k2 = 0; k2 < 2; ++k2)
; #pragma unroll
;     for (int i = 0; i < 16; ++i) {
;       if (!(HM & (1 << k2))) continue;
;       const float pv = (MODE == 1) ? __builtin_amdgcn_exp2f(s[k2][i] + neg) : __builtin_amdgcn_exp2f(fmaf(s[k2][i], L2E, neg));
;       s[k2][i] = pv; ps += pv;
;     }
;   l = l * alpha + ps;
;   if (__builtin_amdgcn_ballot_w64(mn != m) != 0ull) {
; #pragma unroll
;     for (int dt = 0; dt < 2; ++dt)
; #pragma unroll
;       for (int i = 0; i < 16; ++i) o[dt][i] *= alpha;
;   }
;   m = mn;
; #pragma unroll
;   for (int st = 0; st < 4; ++st) {
;     if (!(HM & (1 << (st >> 1)))) continue;
;     const int k2 = st >> 1, b8 = 8 * (st & 1);
;     const u32x4 pw = {pack2(s[k2][b8], s[k2][b8 + 1]), pack2(s[k2][b8 + 2], s[k2][b8 + 3]), pack2(s[k2][b8 + 4], s[k2][b8 + 5]), pack2(s[k2][b8 + 6], s[k2][b8 + 7])};
;     const bf16x8 pb = __builtin_bit_cast(bf16x8, pw);
; #pragma unroll
;     for (int dt = 0; dt < 2; ++dt) {
;       const s16x4 lo = *(const s16x4*)(Vs + (32 * dt + r) * LSTR + 16 * st + 4 * h);
;       const s16x4 hi = *(const s16x4*)(Vs + (32 * dt + r) * LSTR + 16 * st + 8 + 4 * h);
;       const bf16x8 a = __builtin_shufflevector(lo, hi, 0, 1, 2, 3, 4, 5, 6, 7);
;       o[dt] = mfma32(a, pb, o[dt]);
;     }
;   }
.LBB0_471:
	v_fma_f32 v66, v66, s34, -v158
	v_exp_f32_e32 v82, v66
	v_fma_f32 v66, v67, s34, -v158
	v_exp_f32_e32 v83, v66
	v_fma_f32 v66, v68, s34, -v158
	v_exp_f32_e32 v84, v66
	v_fma_f32 v66, v69, s34, -v158
	v_add_f32_e32 v67, 0, v82
	v_exp_f32_e32 v85, v66
	v_fma_f32 v66, v70, s34, -v158
	v_add_f32_e32 v67, v83, v67
	v_exp_f32_e32 v70, v66
	v_fma_f32 v66, v71, s34, -v158
	v_exp_f32_e32 v71, v66
	v_add_f32_e32 v66, v84, v67
	v_fma_f32 v67, v77, s34, -v158
	v_exp_f32_e32 v86, v67
	v_fma_f32 v67, v78, s34, -v158
	v_add_f32_e32 v66, v85, v66
	v_exp_f32_e32 v87, v67
	v_fma_f32 v67, v79, s34, -v158
	v_add_f32_e32 v66, v70, v66
	v_exp_f32_e32 v88, v67
	v_fma_f32 v67, v80, s34, -v158
	v_add_f32_e32 v66, v71, v66
	v_exp_f32_e32 v89, v67
	v_add_f32_e32 v66, v86, v66
	v_add_f32_e32 v66, v87, v66
	v_add_f32_e32 v66, v88, v66
	v_add_f32_e32 v90, v89, v66
	v_fma_f32 v66, v81, s34, -v158
	v_add_u32_e32 v92, 0x2000, v198
	v_exp_f32_e32 v91, v66
	ds_read2_b64 v[66:69], v92 offset0:136 offset1:138
	v_fma_f32 v76, v76, s34, -v158
	v_cvt_pk_bf16_f32 v78, v70, v71
	v_add_u32_e32 v70, 0x3000, v198
	v_exp_f32_e32 v93, v76
	v_cvt_pk_bf16_f32 v76, v82, v83
	ds_read2_b64 v[80:83], v70 offset0:200 offset1:202
	v_cvt_pk_bf16_f32 v77, v84, v85
	v_cvt_pk_bf16_f32 v79, v86, v87
	v_fma_f32 v71, v72, s34, -v158
	s_mov_b64 s[6:7], 0
	s_waitcnt lgkmcnt(1)
	v_mfma_f32_32x32x16_bf16 v[34:49], v[66:69], v[76:79], v[2:17]
	v_fma_f32 v66, v73, s34, -v158
	v_exp_f32_e32 v84, v66
	v_fma_f32 v66, v74, s34, -v158
	v_exp_f32_e32 v85, v66
	v_fma_f32 v66, v75, s34, -v158
	v_exp_f32_e32 v86, v66
	ds_read2_b64 v[66:69], v92 offset0:140 offset1:142
	s_waitcnt lgkmcnt(1)
	v_mfma_f32_32x32x16_bf16 v[50:65], v[80:83], v[76:79], v[18:33]
	v_exp_f32_e32 v78, v71
	ds_read2_b64 v[70:73], v70 offset0:204 offset1:206
	v_cvt_pk_bf16_f32 v74, v88, v89
	v_cvt_pk_bf16_f32 v75, v91, v93
	v_cvt_pk_bf16_f32 v76, v84, v85
	v_cvt_pk_bf16_f32 v77, v86, v78
	s_waitcnt lgkmcnt(1)
	s_nop 0
	v_mfma_f32_32x32x16_bf16 v[2:17], v[66:69], v[74:77], v[34:49]
	v_add_f32_e32 v66, v91, v90
	v_add_f32_e32 v66, v93, v66
	v_add_f32_e32 v66, v84, v66
	v_add_f32_e32 v66, v85, v66
	v_add_f32_e32 v66, v86, v66
	v_add_f32_e32 v160, v78, v66
	v_fmac_f32_e32 v160, v159, v0
	s_waitcnt lgkmcnt(0)
	v_mfma_f32_32x32x16_bf16 v[18:33], v[70:73], v[74:77], v[50:65]

; DI f32x16 mfma32(bf16x8 a, bf16x8 b, f32x16 c) { return __builtin_amdgcn_mfma_f32_32x32x16_bf16(a, b, c, 0, 0, 0); }
; DI int crow(int i, int h) { return (i & 3) + 8 * (i >> 2) + 4 * h; }
;     ...
; #pragma unroll
;   for (int k2 = 0; k2 < 2; ++k2) {
;     if (!(HM & (1 << k2))) continue;
; #pragma unroll
;     for (int i = 0; i < 16; ++i) s[k2][i] = 0.f;
; #pragma unroll
;     for (int ks = 0; ks < 4; ++ks) {
;       const bf16x8 a = *(const bf16x8*)(Ks + (32 * k2 + r) * LSTR + 16 * ks + 8 * h);
;       s[k2] = mfma32(a, qf[ks], s[k2]);
;     }
;   }
;   if (MODE == 1) {
; #pragma unroll
;     for (int k2 = 0; k2 < 2; ++k2)
; #pragma unroll
;       for (int g = 0; g < 4; ++g) {
;         if (!(HM & (1 << k2))) continue;
;         const f32x4 cv = *(const f32x4*)(cn_lds + key0 + 32 * k2 + 8 * g + 4 * h);
; #pragma unroll
;         for (int e = 0; e < 4; ++e) s[k2][4 * g + e] = fmaf(s[k2][4 * g + e], L2E, cv[e]);
;       }
;   }
;   float mx = NINF;
; #pragma unroll
;   for (int k2 = 0; k2 < 2; ++k2)
; #pragma unroll
;     for (int i = 0; i < 16; ++i) {
;       if (!(HM & (1 << k2))) continue;
;       float v = s[k2][i];
;       if (MASKED) {
;         const int tk = key0 + 32 * k2 + crow(i, h);
;         const bool valid = (MODE == 0) ? ((tk <= tq) && (tq - tk <= maxdist)) : (tk <= tq);
;         v = valid ? v : NINF; s[k2][i] = v;
;       }
;       mx = fmaxf(mx, v);
;     }
; template <int MODE>
; DI void flash_loop(char* smem, const bf16_t* Kbase, size_t ldk, const bf16_t* Vtbase, size_t ldv, ull tiles, ull wtiles,
;                    const bf16x8 (&qf)[4], f32x16 (&o)[2], float& m, float& l, int tq, int tqmin, int tqmax, int maxdist, const float* cn_lds, ull lmask) {
;     ...
;     const bool interior = (64 * kt + 63 <= tqmin) && (MODE != 0 || (tqmax - 64 * kt <= maxdist));
.LBB0_474:
	ds_read_b128 v[82:85], v196
	ds_read_b128 v[78:81], v196 offset:32
	ds_read_b128 v[74:77], v196 offset:64
	ds_read_b128 v[66:69], v196 offset:96
	ds_read_b128 v[70:73], v196 offset:4608
	s_cmp_le_u32 s33, s28
	s_cselect_b64 s[6:7], -1, 0
	s_cmp_ge_i32 s58, s31
	s_cselect_b64 s[36:37], -1, 0
	s_and_b64 s[6:7], s[6:7], s[36:37]
	s_andn2_b64 vcc, exec, s[6:7]
	s_mov_b64 s[6:7], -1
	s_cbranch_vccz .LBB0_478
	s_waitcnt lgkmcnt(4)
	v_mfma_f32_32x32x16_bf16 v[50:65], v[82:85], v[98:101], 0
	ds_read_b128 v[86:89], v196 offset:4640
	ds_read_b128 v[90:93], v196 offset:4672
	v_or_b32_e32 v0, s58, v197
	v_cmp_gt_u32_e32 vcc, v0, v154
	v_cmp_lt_i32_e64 s[6:7], v0, v155
	s_or_b64 vcc, vcc, s[6:7]
	s_waitcnt lgkmcnt(5)
	v_mfma_f32_32x32x16_bf16 v[50:65], v[78:81], v[102:105], v[50:65]
	s_waitcnt lgkmcnt(2)
	v_mfma_f32_32x32x16_bf16 v[34:49], v[70:73], v[98:101], 0
	v_mfma_f32_32x32x16_bf16 v[50:65], v[74:77], v[106:109], v[50:65]
	s_waitcnt lgkmcnt(1)
	v_mfma_f32_32x32x16_bf16 v[34:49], v[86:89], v[102:105], v[34:49]
	ds_read_b128 v[86:89], v196 offset:4704
	v_mfma_f32_32x32x16_bf16 v[50:65], v[66:69], v[110:113], v[50:65]
	s_waitcnt lgkmcnt(1)
	v_mfma_f32_32x32x16_bf16 v[34:49], v[90:93], v[106:109], v[34:49]
	s_waitcnt lgkmcnt(0)
	v_mfma_f32_32x32x16_bf16 v[34:49], v[86:89], v[110:113], v[34:49]
	s_nop 7
	v_cndmask_b32_e32 v86, v50, v204, vcc
	v_bitop3_b32 v50, s58, v197, s58 bitop3:3
	v_cmp_ge_u32_e32 vcc, v0, v154
	v_cmp_lt_i32_e64 s[6:7], v156, v50
	s_or_b64 vcc, vcc, s[6:7]
	v_cndmask_b32_e32 v87, v51, v204, vcc
	v_or_b32_e32 v51, 2, v0
	v_cmp_gt_u32_e32 vcc, v51, v154
	v_cmp_lt_i32_e64 s[6:7], v51, v155
	s_or_b64 vcc, vcc, s[6:7]
	v_or_b32_e32 v51, 3, v0
	v_cndmask_b32_e32 v88, v52, v204, vcc
	v_cmp_gt_u32_e32 vcc, v51, v154
	v_cmp_lt_i32_e64 s[6:7], v51, v155
	s_or_b64 vcc, vcc, s[6:7]
	v_or_b32_e32 v51, 8, v0
	v_cndmask_b32_e32 v89, v53, v204, vcc
	v_cmp_gt_u32_e32 vcc, v51, v154
	v_cmp_lt_i32_e64 s[6:7], v51, v155
	s_or_b64 vcc, vcc, s[6:7]
	v_or_b32_e32 v51, 9, v0
	v_cndmask_b32_e32 v90, v54, v204, vcc
	v_cmp_gt_u32_e32 vcc, v51, v154
	v_cmp_lt_i32_e64 s[6:7], v51, v155
	s_or_b64 vcc, vcc, s[6:7]
	v_or_b32_e32 v51, 10, v0
	v_cndmask_b32_e32 v192, v55, v204, vcc
	v_cmp_gt_u32_e32 vcc, v51, v154
	v_cmp_lt_i32_e64 s[6:7], v51, v155
	s_or_b64 vcc, vcc, s[6:7]
	v_or_b32_e32 v51, 11, v0
	v_cndmask_b32_e32 v191, v56, v204, vcc
	v_cmp_gt_u32_e32 vcc, v51, v154
	v_cmp_lt_i32_e64 s[6:7], v51, v155
	s_or_b64 vcc, vcc, s[6:7]
	v_or_b32_e32 v51, 16, v0
	v_cndmask_b32_e32 v193, v57, v204, vcc
	v_cmp_gt_u32_e32 vcc, v51, v154
	v_cmp_lt_i32_e64 s[6:7], v51, v155
	s_or_b64 vcc, vcc, s[6:7]
	v_or_b32_e32 v51, 17, v0
	v_cndmask_b32_e32 v188, v58, v204, vcc
	v_cmp_gt_u32_e32 vcc, v51, v154
	v_cmp_lt_i32_e64 s[6:7], v51, v155
	s_or_b64 vcc, vcc, s[6:7]
	v_or_b32_e32 v51, 18, v0
	v_cndmask_b32_e32 v190, v59, v204, vcc
	v_cmp_gt_u32_e32 vcc, v51, v154
	v_cmp_lt_i32_e64 s[6:7], v51, v155
	s_or_b64 vcc, vcc, s[6:7]
	v_or_b32_e32 v51, 19, v0
	v_cndmask_b32_e32 v189, v60, v204, vcc
	v_cmp_gt_u32_e32 vcc, v51, v154
	v_cmp_lt_i32_e64 s[6:7], v51, v155
	s_or_b64 vcc, vcc, s[6:7]
	v_or_b32_e32 v51, 24, v0
	v_cndmask_b32_e32 v187, v61, v204, vcc
	v_cmp_gt_u32_e32 vcc, v51, v154
	v_cmp_lt_i32_e64 s[6:7], v51, v155
	s_or_b64 vcc, vcc, s[6:7]
	v_or_b32_e32 v51, 25, v0
	v_cndmask_b32_e32 v186, v62, v204, vcc
	v_cmp_gt_u32_e32 vcc, v51, v154
	v_cmp_lt_i32_e64 s[6:7], v51, v155
	s_or_b64 vcc, vcc, s[6:7]
	v_or_b32_e32 v51, 26, v0
	v_cndmask_b32_e32 v185, v63, v204, vcc
	v_cmp_gt_u32_e32 vcc, v51, v154
	v_cmp_lt_i32_e64 s[6:7], v51, v155
	s_or_b64 vcc, vcc, s[6:7]
	v_or_b32_e32 v51, 27, v0
	v_cndmask_b32_e32 v184, v64, v204, vcc
	v_cmp_gt_u32_e32 vcc, v51, v154
	v_cmp_lt_i32_e64 s[6:7], v51, v155
	s_or_b64 vcc, vcc, s[6:7]
	v_or_b32_e32 v51, 32, v0
	v_cndmask_b32_e32 v182, v65, v204, vcc
	v_cmp_gt_u32_e32 vcc, v51, v154
	v_cmp_lt_i32_e64 s[6:7], v51, v155
	s_or_b64 vcc, vcc, s[6:7]
	v_cndmask_b32_e32 v164, v34, v204, vcc
	v_or_b32_e32 v34, 33, v0
	v_cmp_gt_u32_e32 vcc, v34, v154
	v_cmp_lt_i32_e64 s[6:7], v34, v155
	s_or_b64 vcc, vcc, s[6:7]
	v_cndmask_b32_e32 v162, v35, v204, vcc
	v_or_b32_e32 v35, 34, v0
	v_cmp_gt_u32_e32 vcc, v35, v154
	v_cmp_lt_i32_e64 s[6:7], v35, v155
	s_or_b64 vcc, vcc, s[6:7]
	v_or_b32_e32 v35, 35, v0
	v_cndmask_b32_e32 v160, v36, v204, vcc
	v_cmp_gt_u32_e32 vcc, v35, v154
	v_cmp_lt_i32_e64 s[6:7], v35, v155
	s_or_b64 vcc, vcc, s[6:7]
	v_or_b32_e32 v35, 40, v0
	v_cndmask_b32_e32 v97, v37, v204, vcc
	v_cmp_gt_u32_e32 vcc, v35, v154
	v_cmp_lt_i32_e64 s[6:7], v35, v155
	s_or_b64 vcc, vcc, s[6:7]
	v_or_b32_e32 v35, 41, v0
	v_cndmask_b32_e32 v92, v38, v204, vcc
	v_cmp_gt_u32_e32 vcc, v35, v154
	v_cmp_lt_i32_e64 s[6:7], v35, v155
	s_or_b64 vcc, vcc, s[6:7]
	v_or_b32_e32 v35, 42, v0
	v_cndmask_b32_e32 v91, v39, v204, vcc
	v_cmp_gt_u32_e32 vcc, v35, v154
	v_cmp_lt_i32_e64 s[6:7], v35, v155
	s_or_b64 vcc, vcc, s[6:7]
	v_or_b32_e32 v35, 43, v0
	v_cndmask_b32_e32 v93, v40, v204, vcc
	v_cmp_gt_u32_e32 vcc, v35, v154
	v_cmp_lt_i32_e64 s[6:7], v35, v155
	s_or_b64 vcc, vcc, s[6:7]
	v_or_b32_e32 v35, 48, v0
	v_cndmask_b32_e32 v94, v41, v204, vcc
	v_cmp_gt_u32_e32 vcc, v35, v154
	v_cmp_lt_i32_e64 s[6:7], v35, v155
	s_or_b64 vcc, vcc, s[6:7]
	v_or_b32_e32 v35, 49, v0
	v_max3_f32 v50, v86, s35, v87
	v_cndmask_b32_e32 v95, v42, v204, vcc
	v_cmp_gt_u32_e32 vcc, v35, v154
	v_cmp_lt_i32_e64 s[6:7], v35, v155
	v_max3_f32 v50, v50, v88, v89
	s_or_b64 vcc, vcc, s[6:7]
	v_or_b32_e32 v35, 50, v0
	v_max3_f32 v50, v50, v90, v192
	v_cndmask_b32_e32 v96, v43, v204, vcc
	v_cmp_gt_u32_e32 vcc, v35, v154
	v_cmp_lt_i32_e64 s[6:7], v35, v155
	v_max3_f32 v50, v50, v191, v193
; DI int crow(int i, int h) { return (i & 3) + 8 * (i >> 2) + 4 * h; }
;     ...
;   float mx = NINF;
; #pragma unroll
;   for (int k2 = 0; k2 < 2; ++k2)
; #pragma unroll
;     for (int i = 0; i < 16; ++i) {
;       if (!(HM & (1 << k2))) continue;
;       float v = s[k2][i];
;       if (MASKED) {
;         const int tk = key0 + 32 * k2 + crow(i, h);
;         const bool valid = (MODE == 0) ? ((tk <= tq) && (tq - tk <= maxdist)) : (tk <= tq);
;         v = valid ? v : NINF; s[k2][i] = v;
;       }
;       mx = fmaxf(mx, v);
;     }
;   mx = fmaxf(mx, __shfl_xor(mx, 32));
;   if (MODE != 1) mx *= L2E;
;   if (MODE == 2) mx = lanesel ? mx : NINF;
;   const float mn = fmaxf(m, mx); const float alpha = __builtin_amdgcn_exp2f(m - mn);
;   const float neg = (MODE == 2 && !lanesel) ? NINF : -mn;
;   float ps = 0.f;
; #pragma unroll
;   for (int k2 = 0; k2 < 2; ++k2)
; #pragma unroll
;     for (int i = 0; i < 16; ++i) {
;       if (!(HM & (1 << k2))) continue;
;       const float pv = (MODE == 1) ? __builtin_amdgcn_exp2f(s[k2][i] + neg) : __builtin_amdgcn_exp2f(fmaf(s[k2][i], L2E, neg));
;       s[k2][i] = pv; ps += pv;
;     }
;   l = l * alpha + ps;
	s_or_b64 vcc, vcc, s[6:7]
	v_or_b32_e32 v35, 51, v0
	v_max3_f32 v50, v50, v188, v190
	v_cndmask_b32_e32 v161, v44, v204, vcc
	v_cmp_gt_u32_e32 vcc, v35, v154
	v_cmp_lt_i32_e64 s[6:7], v35, v155
	v_max3_f32 v50, v50, v189, v187
	s_or_b64 vcc, vcc, s[6:7]
	v_or_b32_e32 v35, 56, v0
	v_max3_f32 v50, v50, v186, v185
	v_cndmask_b32_e32 v163, v45, v204, vcc
	v_cmp_gt_u32_e32 vcc, v35, v154
	v_cmp_lt_i32_e64 s[6:7], v35, v155
	v_max3_f32 v50, v50, v184, v182
	s_or_b64 vcc, vcc, s[6:7]
	v_or_b32_e32 v35, 57, v0
	v_max3_f32 v34, v50, v164, v162
	v_cndmask_b32_e32 v165, v46, v204, vcc
	v_cmp_gt_u32_e32 vcc, v35, v154
	v_cmp_lt_i32_e64 s[6:7], v35, v155
	v_max3_f32 v34, v34, v160, v97
	s_or_b64 vcc, vcc, s[6:7]
	v_or_b32_e32 v35, 58, v0
	v_max3_f32 v34, v34, v92, v91
	v_cndmask_b32_e32 v180, v47, v204, vcc
	v_cmp_gt_u32_e32 vcc, v35, v154
	v_cmp_lt_i32_e64 s[6:7], v35, v155
	v_max3_f32 v34, v34, v93, v94
	s_or_b64 vcc, vcc, s[6:7]
	v_or_b32_e32 v0, 59, v0
	v_max3_f32 v34, v34, v95, v96
	v_cndmask_b32_e32 v181, v48, v204, vcc
	v_cmp_gt_u32_e32 vcc, v0, v154
	v_cmp_lt_i32_e64 s[6:7], v0, v155
	v_max3_f32 v34, v34, v161, v163
	s_or_b64 vcc, vcc, s[6:7]
	v_max3_f32 v34, v34, v165, v180
	v_cndmask_b32_e32 v183, v49, v204, vcc
	v_and_b32_e32 v35, 64, v202
	v_max3_f32 v0, v34, v181, v183
	v_xor_b32_e32 v34, 32, v202
	v_add_u32_e32 v35, 64, v35
	v_cmp_lt_i32_e32 vcc, v34, v35
	s_nop 1
	v_cndmask_b32_e32 v34, v202, v34, vcc
	v_lshlrev_b32_e32 v34, 2, v34
	ds_bpermute_b32 v34, v34, v0
	s_waitcnt lgkmcnt(0)
	v_max_f32_e32 v34, v34, v34
	v_max_f32_e32 v0, v0, v34
	v_mul_f32_e32 v0, 0x3fb8aa3b, v0
	v_max_f32_e32 v34, v157, v157
	v_max_f32_e32 v158, v34, v0
	v_sub_f32_e32 v0, v157, v158
	v_exp_f32_e32 v0, v0
	v_cmp_neq_f32_e32 vcc, v158, v157
	s_cbranch_vccz .LBB0_477
	v_pk_mul_f32 v[32:33], v[32:33], v[0:1] op_sel_hi:[1,0]
	v_pk_mul_f32 v[30:31], v[30:31], v[0:1] op_sel_hi:[1,0]
	v_pk_mul_f32 v[28:29], v[28:29], v[0:1] op_sel_hi:[1,0]
	v_pk_mul_f32 v[26:27], v[26:27], v[0:1] op_sel_hi:[1,0]
	v_pk_mul_f32 v[24:25], v[24:25], v[0:1] op_sel_hi:[1,0]
	v_pk_mul_f32 v[22:23], v[22:23], v[0:1] op_sel_hi:[1,0]
	v_pk_mul_f32 v[20:21], v[20:21], v[0:1] op_sel_hi:[1,0]
	v_pk_mul_f32 v[18:19], v[18:19], v[0:1] op_sel_hi:[1,0]
	v_pk_mul_f32 v[16:17], v[16:17], v[0:1] op_sel_hi:[1,0]
	v_pk_mul_f32 v[14:15], v[14:15], v[0:1] op_sel_hi:[1,0]
	v_pk_mul_f32 v[12:13], v[12:13], v[0:1] op_sel_hi:[1,0]
	v_pk_mul_f32 v[10:11], v[10:11], v[0:1] op_sel_hi:[1,0]
	v_pk_mul_f32 v[8:9], v[8:9], v[0:1] op_sel_hi:[1,0]
	v_pk_mul_f32 v[6:7], v[6:7], v[0:1] op_sel_hi:[1,0]
	v_pk_mul_f32 v[4:5], v[4:5], v[0:1] op_sel_hi:[1,0]
	v_pk_mul_f32 v[2:3], v[2:3], v[0:1] op_sel_hi:[1,0]
.LBB0_477:
	v_fma_f32 v86, v86, s34, -v158
	v_exp_f32_e32 v86, v86
	v_fma_f32 v87, v87, s34, -v158
	v_exp_f32_e32 v87, v87
	v_fma_f32 v88, v88, s34, -v158
	v_exp_f32_e32 v88, v88
	v_fma_f32 v89, v89, s34, -v158
	v_exp_f32_e32 v89, v89
	v_fma_f32 v90, v90, s34, -v158
	v_add_f32_e32 v194, 0, v86
	v_exp_f32_e32 v90, v90
	v_fma_f32 v192, v192, s34, -v158
	v_add_f32_e32 v194, v87, v194
	v_exp_f32_e32 v192, v192
	v_fma_f32 v191, v191, s34, -v158
	v_add_f32_e32 v194, v88, v194
	v_exp_f32_e32 v191, v191
	v_fma_f32 v193, v193, s34, -v158
	v_add_f32_e32 v194, v89, v194
	v_exp_f32_e32 v193, v193
	v_fma_f32 v188, v188, s34, -v158
	v_add_f32_e32 v194, v90, v194
	v_exp_f32_e32 v188, v188
	v_fma_f32 v190, v190, s34, -v158
	v_add_f32_e32 v194, v192, v194
	v_exp_f32_e32 v190, v190
	v_fma_f32 v189, v189, s34, -v158
	v_add_f32_e32 v194, v191, v194
	v_exp_f32_e32 v189, v189
	v_fma_f32 v187, v187, s34, -v158
	v_add_f32_e32 v194, v193, v194
	v_exp_f32_e32 v187, v187
	v_fma_f32 v186, v186, s34, -v158
	v_add_f32_e32 v194, v188, v194
	v_exp_f32_e32 v186, v186
	v_fma_f32 v185, v185, s34, -v158
	v_add_f32_e32 v194, v190, v194
	v_exp_f32_e32 v185, v185
	v_fma_f32 v184, v184, s34, -v158
	v_add_f32_e32 v194, v189, v194
	v_exp_f32_e32 v184, v184
	v_fma_f32 v182, v182, s34, -v158
	v_add_f32_e32 v194, v187, v194
	v_exp_f32_e32 v182, v182
	v_fma_f32 v164, v164, s34, -v158
	v_add_f32_e32 v194, v186, v194
	v_exp_f32_e32 v164, v164
	v_fma_f32 v162, v162, s34, -v158
	v_add_f32_e32 v194, v185, v194
	v_exp_f32_e32 v162, v162
	v_fma_f32 v160, v160, s34, -v158
	v_add_f32_e32 v194, v184, v194
	v_exp_f32_e32 v195, v160
	v_add_f32_e32 v194, v182, v194
	v_add_f32_e32 v194, v164, v194
	v_add_f32_e32 v194, v162, v194
	v_fma_f32 v97, v97, s34, -v158
	v_add_f32_e32 v160, v195, v194
	v_exp_f32_e32 v194, v97
	v_fma_f32 v92, v92, s34, -v158
	v_exp_f32_e32 v209, v92
	v_fma_f32 v91, v91, s34, -v158
	v_exp_f32_e32 v210, v91
	v_add_f32_e32 v97, v194, v160
	v_add_f32_e32 v92, v209, v97
	v_cvt_pk_bf16_f32 v86, v86, v87
	v_add_f32_e32 v91, v210, v92
	v_fma_f32 v92, v93, s34, -v158
	v_exp_f32_e32 v211, v92
	v_fma_f32 v92, v94, s34, -v158
	v_exp_f32_e32 v212, v92
	v_fma_f32 v92, v95, s34, -v158
	v_exp_f32_e32 v213, v92
	v_fma_f32 v92, v96, s34, -v158
	v_exp_f32_e32 v214, v92
	v_fma_f32 v92, v161, s34, -v158
	v_add_f32_e32 v91, v211, v91
	v_exp_f32_e32 v161, v92
	v_fma_f32 v92, v163, s34, -v158
	v_add_f32_e32 v91, v212, v91
	v_exp_f32_e32 v163, v92
	v_fma_f32 v92, v165, s34, -v158
	v_add_f32_e32 v91, v213, v91
	v_exp_f32_e32 v165, v92
	v_fma_f32 v92, v180, s34, -v158
	v_add_f32_e32 v91, v214, v91
	v_exp_f32_e32 v180, v92
	v_fma_f32 v92, v181, s34, -v158
	v_add_f32_e32 v91, v161, v91
	v_exp_f32_e32 v181, v92
	v_fma_f32 v92, v183, s34, -v158
	v_add_f32_e32 v91, v163, v91
	v_exp_f32_e32 v183, v92
	v_add_f32_e32 v91, v165, v91
	v_add_f32_e32 v91, v180, v91
	v_add_f32_e32 v91, v181, v91
	v_add_f32_e32 v160, v183, v91
	v_fmac_f32_e32 v160, v159, v0
	v_add_u32_e32 v0, 0x2000, v198
	v_cvt_pk_bf16_f32 v87, v88, v89
	v_cvt_pk_bf16_f32 v88, v90, v192
	ds_read2_b64 v[90:93], v0 offset0:128 offset1:130
	ds_read2_b64 v[94:97], v0 offset0:132 offset1:134
	v_cvt_pk_bf16_f32 v89, v191, v193
	v_add_u32_e32 v191, 0x3000, v198
	s_mov_b64 s[6:7], 0
	s_waitcnt lgkmcnt(1)
;     ...
; #pragma unroll
;   for (int k2 = 0; k2 < 2; ++k2) {
;     if (!(HM & (1 << k2))) continue;
; #pragma unroll
;     for (int i = 0; i < 16; ++i) s[k2][i] = 0.f;
; #pragma unroll
;     for (int ks = 0; ks < 4; ++ks) {
;       const bf16x8 a = *(const bf16x8*)(Ks + (32 * k2 + r) * LSTR + 16 * ks + 8 * h);
;       s[k2] = mfma32(a, qf[ks], s[k2]);
;     }
;   }
;   if (MODE == 1) {
; #pragma unroll
;     for (int k2 = 0; k2 < 2; ++k2)
; #pragma unroll
;       for (int g = 0; g < 4; ++g) {
;         if (!(HM & (1 << k2))) continue;
;         const f32x4 cv = *(const f32x4*)(cn_lds + key0 + 32 * k2 + 8 * g + 4 * h);
; #pragma unroll
;         for (int e = 0; e < 4; ++e) s[k2][4 * g + e] = fmaf(s[k2][4 * g + e], L2E, cv[e]);
;       }
;   }
;   float mx = NINF;
; #pragma unroll
;   for (int k2 = 0; k2 < 2; ++k2)
; #pragma unroll
;     for (int i = 0; i < 16; ++i) {
;       if (!(HM & (1 << k2))) continue;
;       float v = s[k2][i];
;       if (MASKED) {
;         const int tk = key0 + 32 * k2 + crow(i, h);
;         const bool valid = (MODE == 0) ? ((tk <= tq) && (tq - tk <= maxdist)) : (tk <= tq);
;         v = valid ? v : NINF; s[k2][i] = v;
;       }
;       mx = fmaxf(mx, v);
;     }
;   mx = fmaxf(mx, __shfl_xor(mx, 32));
;   if (MODE != 1) mx *= L2E;
;   if (MODE == 2) mx = lanesel ? mx : NINF;
;   const float mn = fmaxf(m, mx); const float alpha = __builtin_amdgcn_exp2f(m - mn);
;   const float neg = (MODE == 2 && !lanesel) ? NINF : -mn;
;   float ps = 0.f;
; #pragma unroll
;   for (int k2 = 0; k2 < 2; ++k2)
; #pragma unroll
;     for (int i = 0; i < 16; ++i) {
;       if (!(HM & (1 << k2))) continue;
;     ...
; #pragma unroll
;   for (int st = 0; st < 4; ++st) {
;     if (!(HM & (1 << (st >> 1)))) continue;
;     const int k2 = st >> 1, b8 = 8 * (st & 1);
;     const u32x4 pw = {pack2(s[k2][b8], s[k2][b8 + 1]), pack2(s[k2][b8 + 2], s[k2][b8 + 3]), pack2(s[k2][b8 + 4], s[k2][b8 + 5]), pack2(s[k2][b8 + 6], s[k2][b8 + 7])};
;     const bf16x8 pb = __builtin_bit_cast(bf16x8, pw);
; #pragma unroll
;     for (int dt = 0; dt < 2; ++dt) {
;       const s16x4 lo = *(const s16x4*)(Vs + (32 * dt + r) * LSTR + 16 * st + 4 * h);
;       const s16x4 hi = *(const s16x4*)(Vs + (32 * dt + r) * LSTR + 16 * st + 8 + 4 * h);
;       const bf16x8 a = __builtin_shufflevector(lo, hi, 0, 1, 2, 3, 4, 5, 6, 7);
;       o[dt] = mfma32(a, pb, o[dt]);
;     }
;   }
	v_mfma_f32_32x32x16_bf16 v[34:49], v[90:93], v[86:89], v[2:17]
	ds_read2_b64 v[90:93], v191 offset0:192 offset1:194
	s_waitcnt lgkmcnt(0)
	v_mfma_f32_32x32x16_bf16 v[50:65], v[90:93], v[86:89], v[18:33]
	ds_read2_b64 v[90:93], v191 offset0:196 offset1:198
	v_cvt_pk_bf16_f32 v86, v188, v190
	v_cvt_pk_bf16_f32 v87, v189, v187
	v_cvt_pk_bf16_f32 v88, v186, v185
	v_cvt_pk_bf16_f32 v89, v184, v182
	s_waitcnt lgkmcnt(0)
	s_nop 0
	v_mfma_f32_32x32x16_bf16 v[50:65], v[90:93], v[86:89], v[50:65]
	ds_read2_b64 v[90:93], v0 offset0:136 offset1:138
	v_mfma_f32_32x32x16_bf16 v[34:49], v[94:97], v[86:89], v[34:49]
	v_cvt_pk_bf16_f32 v86, v164, v162
	v_cvt_pk_bf16_f32 v87, v195, v194
	v_cvt_pk_bf16_f32 v88, v209, v210
	v_cvt_pk_bf16_f32 v89, v211, v212
	s_waitcnt lgkmcnt(0)
	s_nop 0
	v_mfma_f32_32x32x16_bf16 v[34:49], v[90:93], v[86:89], v[34:49]
	ds_read2_b64 v[90:93], v191 offset0:200 offset1:202
	s_waitcnt lgkmcnt(0)
	v_mfma_f32_32x32x16_bf16 v[50:65], v[90:93], v[86:89], v[50:65]
	ds_read2_b64 v[90:93], v0 offset0:140 offset1:142
	v_cvt_pk_bf16_f32 v86, v213, v214
	v_cvt_pk_bf16_f32 v87, v161, v163
	v_cvt_pk_bf16_f32 v88, v165, v180
	v_cvt_pk_bf16_f32 v89, v181, v183
	s_waitcnt lgkmcnt(0)
	s_nop 0
	v_mfma_f32_32x32x16_bf16 v[2:17], v[90:93], v[86:89], v[34:49]
	ds_read2_b64 v[90:93], v191 offset0:204 offset1:206
	s_waitcnt lgkmcnt(0)
	v_mfma_f32_32x32x16_bf16 v[18:33], v[90:93], v[86:89], v[50:65]
.LBB0_478:
	s_and_b64 vcc, exec, s[6:7]
	s_cbranch_vccz .LBB0_482
	s_waitcnt lgkmcnt(4)
	v_mfma_f32_32x32x16_bf16 v[82:97], v[82:85], v[98:101], 0
	s_nop 4
	ds_read_b128 v[34:37], v196 offset:4640
	ds_read_b128 v[38:41], v196 offset:4672
	s_waitcnt lgkmcnt(5)
	v_mfma_f32_32x32x16_bf16 v[82:97], v[78:81], v[102:105], v[82:97]
	s_waitcnt lgkmcnt(4)
	v_mfma_f32_32x32x16_bf16 v[82:97], v[74:77], v[106:109], v[82:97]
	s_waitcnt lgkmcnt(3)
	v_mfma_f32_32x32x16_bf16 v[82:97], v[66:69], v[110:113], v[82:97]
	s_waitcnt lgkmcnt(2)
	v_mfma_f32_32x32x16_bf16 v[66:81], v[70:73], v[98:101], 0
	s_nop 9
	v_max3_f32 v0, v82, s35, v83
	v_max3_f32 v0, v0, v84, v85
	v_max3_f32 v0, v0, v86, v87
	v_max3_f32 v0, v0, v88, v89
	v_max3_f32 v0, v0, v90, v91
	v_max3_f32 v0, v0, v92, v93
	v_max3_f32 v0, v0, v94, v95
	s_waitcnt lgkmcnt(1)
	v_mfma_f32_32x32x16_bf16 v[66:81], v[34:37], v[102:105], v[66:81]
	ds_read_b128 v[34:37], v196 offset:4704
	v_max3_f32 v0, v0, v96, v97
	s_waitcnt lgkmcnt(1)
	v_mfma_f32_32x32x16_bf16 v[66:81], v[38:41], v[106:109], v[66:81]
	s_waitcnt lgkmcnt(0)
	v_mfma_f32_32x32x16_bf16 v[66:81], v[34:37], v[110:113], v[66:81]
	v_and_b32_e32 v35, 64, v202
	v_xor_b32_e32 v34, 32, v202
	v_add_u32_e32 v35, 64, v35
	v_cmp_lt_i32_e32 vcc, v34, v35
	s_nop 1
	v_cndmask_b32_e32 v34, v202, v34, vcc
	s_nop 4
	v_max3_f32 v0, v0, v66, v67
	v_max3_f32 v0, v0, v68, v69
	v_max3_f32 v0, v0, v70, v71
	v_max3_f32 v0, v0, v72, v73
	v_max3_f32 v0, v0, v74, v75
	v_max3_f32 v0, v0, v76, v77
	v_max3_f32 v0, v0, v78, v79
	v_max3_f32 v0, v0, v80, v81
	v_lshlrev_b32_e32 v34, 2, v34
	ds_bpermute_b32 v34, v34, v0
	s_waitcnt lgkmcnt(0)
	v_max_f32_e32 v34, v34, v34
	v_max_f32_e32 v0, v0, v34
	v_mul_f32_e32 v0, 0x3fb8aa3b, v0
	v_max_f32_e32 v34, v157, v157
	v_max_f32_e32 v158, v34, v0
	v_sub_f32_e32 v0, v157, v158
	v_exp_f32_e32 v0, v0
	v_cmp_neq_f32_e32 vcc, v158, v157
	s_cbranch_vccz .LBB0_481
	v_pk_mul_f32 v[32:33], v[32:33], v[0:1] op_sel_hi:[1,0]
	v_pk_mul_f32 v[30:31], v[30:31], v[0:1] op_sel_hi:[1,0]
	v_pk_mul_f32 v[28:29], v[28:29], v[0:1] op_sel_hi:[1,0]
	v_pk_mul_f32 v[26:27], v[26:27], v[0:1] op_sel_hi:[1,0]
	v_pk_mul_f32 v[24:25], v[24:25], v[0:1] op_sel_hi:[1,0]
	v_pk_mul_f32 v[22:23], v[22:23], v[0:1] op_sel_hi:[1,0]
	v_pk_mul_f32 v[20:21], v[20:21], v[0:1] op_sel_hi:[1,0]
	v_pk_mul_f32 v[18:19], v[18:19], v[0:1] op_sel_hi:[1,0]
	v_pk_mul_f32 v[16:17], v[16:17], v[0:1] op_sel_hi:[1,0]
	v_pk_mul_f32 v[14:15], v[14:15], v[0:1] op_sel_hi:[1,0]
	v_pk_mul_f32 v[12:13], v[12:13], v[0:1] op_sel_hi:[1,0]
	v_pk_mul_f32 v[10:11], v[10:11], v[0:1] op_sel_hi:[1,0]
	v_pk_mul_f32 v[8:9], v[8:9], v[0:1] op_sel_hi:[1,0]
	v_pk_mul_f32 v[6:7], v[6:7], v[0:1] op_sel_hi:[1,0]
	v_pk_mul_f32 v[4:5], v[4:5], v[0:1] op_sel_hi:[1,0]
	v_pk_mul_f32 v[2:3], v[2:3], v[0:1] op_sel_hi:[1,0]
; DI unsigned pack2(float a, float b) { f32x2 v = {a, b}; bf16x2_t r = __builtin_convertvector(v, bf16x2_t); return __builtin_bit_cast(unsigned, r); }
; DI f32x16 mfma32(bf16x8 a, bf16x8 b, f32x16 c) { return __builtin_amdgcn_mfma_f32_32x32x16_bf16(a, b, c, 0, 0, 0); }
;     ...
;   const float mn = fmaxf(m, mx); const float alpha = __builtin_amdgcn_exp2f(m - mn);
;   const float neg = (MODE == 2 && !lanesel) ? NINF : -mn;
;   float ps = 0.f;
; #pragma unroll
;   for (int k2 = 0; k2 < 2; ++k2)
; #pragma unroll
;     for (int i = 0; i < 16; ++i) {
;       if (!(HM & (1 << k2))) continue;
;       const float pv = (MODE == 1) ? __builtin_amdgcn_exp2f(s[k2][i] + neg) : __builtin_amdgcn_exp2f(fmaf(s[k2][i], L2E, neg));
;       s[k2][i] = pv; ps += pv;
;     }
;   l = l * alpha + ps;
;   if (__builtin_amdgcn_ballot_w64(mn != m) != 0ull) {
; #pragma unroll
;     for (int dt = 0; dt < 2; ++dt)
; #pragma unroll
;       for (int i = 0; i < 16; ++i) o[dt][i] *= alpha;
;   }
;   m = mn;
; #pragma unroll
;   for (int st = 0; st < 4; ++st) {
;     if (!(HM & (1 << (st >> 1)))) continue;
;     const int k2 = st >> 1, b8 = 8 * (st & 1);
;     const u32x4 pw = {pack2(s[k2][b8], s[k2][b8 + 1]), pack2(s[k2][b8 + 2], s[k2][b8 + 3]), pack2(s[k2][b8 + 4], s[k2][b8 + 5]), pack2(s[k2][b8 + 6], s[k2][b8 + 7])};
;     const bf16x8 pb = __builtin_bit_cast(bf16x8, pw);
; #pragma unroll
;     for (int dt = 0; dt < 2; ++dt) {
;       const s16x4 lo = *(const s16x4*)(Vs + (32 * dt + r) * LSTR + 16 * st + 4 * h);
;       const s16x4 hi = *(const s16x4*)(Vs + (32 * dt + r) * LSTR + 16 * st + 8 + 4 * h);
;       const bf16x8 a = __builtin_shufflevector(lo, hi, 0, 1, 2, 3, 4, 5, 6, 7);
;       o[dt] = mfma32(a, pb, o[dt]);
;     }
;   }
.LBB0_481:
	v_fma_f32 v82, v82, s34, -v158
	v_exp_f32_e32 v82, v82
	v_fma_f32 v83, v83, s34, -v158
	v_exp_f32_e32 v83, v83
	v_fma_f32 v84, v84, s34, -v158
	v_exp_f32_e32 v84, v84
	v_fma_f32 v85, v85, s34, -v158
	v_exp_f32_e32 v85, v85
	v_fma_f32 v86, v86, s34, -v158
	v_add_f32_e32 v160, 0, v82
	v_exp_f32_e32 v86, v86
	v_fma_f32 v87, v87, s34, -v158
	v_add_f32_e32 v160, v83, v160
	v_exp_f32_e32 v87, v87
	v_fma_f32 v88, v88, s34, -v158
	v_add_f32_e32 v160, v84, v160
	v_exp_f32_e32 v88, v88
	v_fma_f32 v89, v89, s34, -v158
	v_add_f32_e32 v160, v85, v160
	v_exp_f32_e32 v89, v89
	v_fma_f32 v90, v90, s34, -v158
	v_add_f32_e32 v160, v86, v160
	v_exp_f32_e32 v90, v90
	v_fma_f32 v91, v91, s34, -v158
	v_add_f32_e32 v160, v87, v160
	v_exp_f32_e32 v91, v91
	v_fma_f32 v92, v92, s34, -v158
	v_add_f32_e32 v160, v88, v160
	v_exp_f32_e32 v92, v92
	v_fma_f32 v93, v93, s34, -v158
	v_add_f32_e32 v160, v89, v160
	v_exp_f32_e32 v93, v93
	v_fma_f32 v94, v94, s34, -v158
	v_add_f32_e32 v160, v90, v160
	v_exp_f32_e32 v94, v94
	v_fma_f32 v95, v95, s34, -v158
	v_add_f32_e32 v160, v91, v160
	v_exp_f32_e32 v95, v95
	v_fma_f32 v96, v96, s34, -v158
	v_add_f32_e32 v160, v92, v160
	v_exp_f32_e32 v96, v96
	v_fma_f32 v97, v97, s34, -v158
	v_add_f32_e32 v160, v93, v160
	v_exp_f32_e32 v97, v97
	v_fma_f32 v66, v66, s34, -v158
	v_add_f32_e32 v160, v94, v160
	v_exp_f32_e32 v161, v66
	v_fma_f32 v67, v67, s34, -v158
	v_add_f32_e32 v160, v95, v160
	v_exp_f32_e32 v162, v67
	v_fma_f32 v67, v68, s34, -v158
	v_add_f32_e32 v160, v96, v160
	v_exp_f32_e32 v163, v67
	v_fma_f32 v67, v69, s34, -v158
	v_add_f32_e32 v160, v97, v160
	v_exp_f32_e32 v164, v67
	v_fma_f32 v67, v70, s34, -v158
	v_add_f32_e32 v66, v161, v160
	v_exp_f32_e32 v165, v67
	v_fma_f32 v67, v71, s34, -v158
	v_add_f32_e32 v66, v162, v66
	v_exp_f32_e32 v180, v67
	v_fma_f32 v67, v72, s34, -v158
	v_add_f32_e32 v66, v163, v66
	v_exp_f32_e32 v181, v67
	v_fma_f32 v67, v73, s34, -v158
	v_add_f32_e32 v66, v164, v66
	v_exp_f32_e32 v182, v67
	v_fma_f32 v67, v74, s34, -v158
	v_add_f32_e32 v66, v165, v66
	v_exp_f32_e32 v183, v67
	v_fma_f32 v67, v75, s34, -v158
	v_add_f32_e32 v66, v180, v66
	v_exp_f32_e32 v184, v67
	v_fma_f32 v67, v76, s34, -v158
	v_add_f32_e32 v66, v181, v66
	v_exp_f32_e32 v185, v67
	v_fma_f32 v67, v77, s34, -v158
	v_add_f32_e32 v66, v182, v66
	v_exp_f32_e32 v186, v67
	v_fma_f32 v67, v78, s34, -v158
	v_add_f32_e32 v66, v183, v66
	v_exp_f32_e32 v78, v67
	v_fma_f32 v67, v79, s34, -v158
	v_add_f32_e32 v66, v184, v66
	v_exp_f32_e32 v79, v67
	v_fma_f32 v67, v80, s34, -v158
	v_add_f32_e32 v66, v185, v66
	v_exp_f32_e32 v80, v67
	v_fma_f32 v67, v81, s34, -v158
	v_add_f32_e32 v66, v186, v66
	v_exp_f32_e32 v81, v67
	v_add_f32_e32 v66, v78, v66
	v_add_f32_e32 v66, v79, v66
	v_add_f32_e32 v66, v80, v66
	v_add_f32_e32 v160, v81, v66
	v_fmac_f32_e32 v160, v159, v0
	v_add_u32_e32 v0, 0x2000, v198
	ds_read2_b64 v[70:73], v0 offset0:128 offset1:130
	ds_read2_b64 v[74:77], v0 offset0:132 offset1:134
	v_cvt_pk_bf16_f32 v66, v82, v83
	v_cvt_pk_bf16_f32 v67, v84, v85
	v_cvt_pk_bf16_f32 v68, v86, v87
	v_cvt_pk_bf16_f32 v69, v88, v89
	v_add_u32_e32 v82, 0x3000, v198
	s_waitcnt lgkmcnt(1)
	v_mfma_f32_32x32x16_bf16 v[34:49], v[70:73], v[66:69], v[2:17]
	ds_read2_b64 v[70:73], v82 offset0:192 offset1:194
	s_waitcnt lgkmcnt(0)
	v_mfma_f32_32x32x16_bf16 v[50:65], v[70:73], v[66:69], v[18:33]
	ds_read2_b64 v[70:73], v82 offset0:196 offset1:198
	v_cvt_pk_bf16_f32 v66, v90, v91
	v_cvt_pk_bf16_f32 v67, v92, v93
	v_cvt_pk_bf16_f32 v68, v94, v95
	v_cvt_pk_bf16_f32 v69, v96, v97
	s_waitcnt lgkmcnt(0)
	s_nop 0
	v_mfma_f32_32x32x16_bf16 v[50:65], v[70:73], v[66:69], v[50:65]
	ds_read2_b64 v[70:73], v0 offset0:136 offset1:138
	v_mfma_f32_32x32x16_bf16 v[34:49], v[74:77], v[66:69], v[34:49]
	v_cvt_pk_bf16_f32 v66, v161, v162
	v_cvt_pk_bf16_f32 v67, v163, v164
	v_cvt_pk_bf16_f32 v68, v165, v180
	v_cvt_pk_bf16_f32 v69, v181, v182
	s_waitcnt lgkmcnt(0)
	s_nop 0
	v_mfma_f32_32x32x16_bf16 v[34:49], v[70:73], v[66:69], v[34:49]
	ds_read2_b64 v[70:73], v82 offset0:200 offset1:202
	s_waitcnt lgkmcnt(0)
	v_mfma_f32_32x32x16_bf16 v[50:65], v[70:73], v[66:69], v[50:65]
	ds_read2_b64 v[70:73], v0 offset0:140 offset1:142
	v_cvt_pk_bf16_f32 v66, v183, v184
	v_cvt_pk_bf16_f32 v67, v185, v186
	v_cvt_pk_bf16_f32 v68, v78, v79
	v_cvt_pk_bf16_f32 v69, v80, v81
	s_waitcnt lgkmcnt(0)
	s_nop 0
	v_mfma_f32_32x32x16_bf16 v[2:17], v[70:73], v[66:69], v[34:49]
	ds_read2_b64 v[70:73], v82 offset0:204 offset1:206
	s_waitcnt lgkmcnt(0)
	v_mfma_f32_32x32x16_bf16 v[18:33], v[70:73], v[66:69], v[50:65]

; DI unsigned pack2(float a, float b) { f32x2 v = {a, b}; bf16x2_t r = __builtin_convertvector(v, bf16x2_t); return __builtin_bit_cast(unsigned, r); }
; DI f32x16 mfma32(bf16x8 a, bf16x8 b, f32x16 c) { return __builtin_amdgcn_mfma_f32_32x32x16_bf16(a, b, c, 0, 0, 0); }
;     ...
;   const float mn = fmaxf(m, mx); const float alpha = __builtin_amdgcn_exp2f(m - mn);
;   const float neg = (MODE == 2 && !lanesel) ? NINF : -mn;
;   float ps = 0.f;
; #pragma unroll
;   for (int k2 = 0; k2 < 2; ++k2)
; #pragma unroll
;     for (int i = 0; i < 16; ++i) {
;       if (!(HM & (1 << k2))) continue;
;       const float pv = (MODE == 1) ? __builtin_amdgcn_exp2f(s[k2][i] + neg) : __builtin_amdgcn_exp2f(fmaf(s[k2][i], L2E, neg));
;       s[k2][i] = pv; ps += pv;
;     }
;   l = l * alpha + ps;
;   if (__builtin_amdgcn_ballot_w64(mn != m) != 0ull) {
; #pragma unroll
;     for (int dt = 0; dt < 2; ++dt)
; #pragma unroll
;       for (int i = 0; i < 16; ++i) o[dt][i] *= alpha;
;   }
;   m = mn;
; #pragma unroll
;   for (int st = 0; st < 4; ++st) {
;     if (!(HM & (1 << (st >> 1)))) continue;
;     const int k2 = st >> 1, b8 = 8 * (st & 1);
;     const u32x4 pw = {pack2(s[k2][b8], s[k2][b8 + 1]), pack2(s[k2][b8 + 2], s[k2][b8 + 3]), pack2(s[k2][b8 + 4], s[k2][b8 + 5]), pack2(s[k2][b8 + 6], s[k2][b8 + 7])};
;     const bf16x8 pb = __builtin_bit_cast(bf16x8, pw);
; #pragma unroll
;     for (int dt = 0; dt < 2; ++dt) {
;       const s16x4 lo = *(const s16x4*)(Vs + (32 * dt + r) * LSTR + 16 * st + 4 * h);
;       const s16x4 hi = *(const s16x4*)(Vs + (32 * dt + r) * LSTR + 16 * st + 8 + 4 * h);
;       const bf16x8 a = __builtin_shufflevector(lo, hi, 0, 1, 2, 3, 4, 5, 6, 7);
;       o[dt] = mfma32(a, pb, o[dt]);
;     }
;   }
.LBB0_488:
	v_fma_f32 v34, v34, s34, -v158
	v_exp_f32_e32 v45, v34
	v_fma_f32 v34, v35, s34, -v158
	v_exp_f32_e32 v46, v34
	v_fma_f32 v34, v36, s34, -v158
	v_exp_f32_e32 v47, v34
	v_fma_f32 v34, v37, s34, -v158
	v_add_f32_e32 v35, 0, v45
	v_exp_f32_e32 v48, v34
	v_fma_f32 v34, v38, s34, -v158
	v_add_f32_e32 v35, v46, v35
	v_exp_f32_e32 v38, v34
	v_fma_f32 v34, v39, s34, -v158
	v_exp_f32_e32 v39, v34
	v_add_f32_e32 v34, v47, v35
	v_fma_f32 v35, v50, s34, -v158
	v_exp_f32_e32 v49, v35
	v_fma_f32 v35, v51, s34, -v158
	v_add_f32_e32 v34, v48, v34
	v_exp_f32_e32 v50, v35
	v_fma_f32 v35, v52, s34, -v158
	v_add_f32_e32 v34, v38, v34
	v_exp_f32_e32 v52, v35
	v_fma_f32 v35, v53, s34, -v158
	v_add_f32_e32 v34, v39, v34
	v_exp_f32_e32 v53, v35
	v_add_f32_e32 v34, v49, v34
	v_add_f32_e32 v34, v50, v34
	v_add_f32_e32 v34, v52, v34
	v_add_f32_e32 v55, v53, v34
	v_fma_f32 v34, v54, s34, -v158
	v_add_u32_e32 v56, 0x2000, v198
	v_exp_f32_e32 v54, v34
	ds_read2_b64 v[34:37], v56 offset0:128 offset1:130
	v_fma_f32 v44, v44, s34, -v158
	v_exp_f32_e32 v57, v44
	v_cvt_pk_bf16_f32 v44, v45, v46
	v_cvt_pk_bf16_f32 v46, v38, v39
	v_add_u32_e32 v38, 0x3000, v198
	v_cvt_pk_bf16_f32 v45, v47, v48
	v_cvt_pk_bf16_f32 v47, v49, v50
	ds_read2_b64 v[48:51], v38 offset0:192 offset1:194
	v_fma_f32 v39, v40, s34, -v158
	s_waitcnt lgkmcnt(1)
	v_mfma_f32_32x32x16_bf16 v[2:17], v[34:37], v[44:47], v[2:17]
	v_fma_f32 v34, v41, s34, -v158
	v_exp_f32_e32 v58, v34
	v_fma_f32 v34, v42, s34, -v158
	v_exp_f32_e32 v59, v34
	v_fma_f32 v34, v43, s34, -v158
	v_exp_f32_e32 v60, v34
	ds_read2_b64 v[34:37], v56 offset0:132 offset1:134
	s_waitcnt lgkmcnt(1)
	v_mfma_f32_32x32x16_bf16 v[18:33], v[48:51], v[44:47], v[18:33]
	v_exp_f32_e32 v46, v39
	ds_read2_b64 v[38:41], v38 offset0:196 offset1:198
	v_cvt_pk_bf16_f32 v42, v52, v53
	v_cvt_pk_bf16_f32 v43, v54, v57
	v_cvt_pk_bf16_f32 v44, v58, v59
	v_cvt_pk_bf16_f32 v45, v60, v46
	s_waitcnt lgkmcnt(0)
	s_nop 0
	v_mfma_f32_32x32x16_bf16 v[18:33], v[38:41], v[42:45], v[18:33]
	v_mfma_f32_32x32x16_bf16 v[2:17], v[34:37], v[42:45], v[2:17]
	v_add_f32_e32 v34, v54, v55
	v_add_f32_e32 v34, v57, v34
	v_add_f32_e32 v34, v58, v34
	v_add_f32_e32 v34, v59, v34
	v_add_f32_e32 v34, v60, v34
	v_add_f32_e32 v160, v46, v34
	s_nop 4
	v_fmac_f32_e32 v160, v159, v0
.LBB0_489:
	s_nop 7
	s_nop 4
	s_branch .LBB0_491

;     ...
;   f32x16 s[2];
; #pragma unroll
;   for (int k2 = 0; k2 < 2; ++k2) {
;     if (!(HM & (1 << k2))) continue;
; #pragma unroll
;     for (int i = 0; i < 16; ++i) s[k2][i] = 0.f;
; #pragma unroll
;     for (int ks = 0; ks < 4; ++ks) {
;       const bf16x8 a = *(const bf16x8*)(Ks + (32 * k2 + r) * LSTR + 16 * ks + 8 * h);
;       s[k2] = mfma32(a, qf[ks], s[k2]);
;     }
;   }
;   if (MODE == 1) {
; #pragma unroll
;     for (int k2 = 0; k2 < 2; ++k2)
; #pragma unroll
;       for (int g = 0; g < 4; ++g) {
;         if (!(HM & (1 << k2))) continue;
;         const f32x4 cv = *(const f32x4*)(cn_lds + key0 + 32 * k2 + 8 * g + 4 * h);
; #pragma unroll
;         for (int e = 0; e < 4; ++e) s[k2][4 * g + e] = fmaf(s[k2][4 * g + e], L2E, cv[e]);
;       }
;   }
;   float mx = NINF;
; #pragma unroll
;   for (int k2 = 0; k2 < 2; ++k2)
; #pragma unroll
;     for (int i = 0; i < 16; ++i) {
;       if (!(HM & (1 << k2))) continue;
;       float v = s[k2][i];
;       if (MASKED) {
;         const int tk = key0 + 32 * k2 + crow(i, h);
;         const bool valid = (MODE == 0) ? ((tk <= tq) && (tq - tk <= maxdist)) : (tk <= tq);
;         v = valid ? v : NINF; s[k2][i] = v;
;       }
;       mx = fmaxf(mx, v);
;     }
;   mx = fmaxf(mx, __shfl_xor(mx, 32));
;   if (MODE != 1) mx *= L2E;
;   if (MODE == 2) mx = lanesel ? mx : NINF;
; template <int MODE>
; DI void flash_loop(char* smem, const bf16_t* Kbase, size_t ldk, const bf16_t* Vtbase, size_t ldv, ull tiles, ull wtiles,
;                    const bf16x8 (&qf)[4], f32x16 (&o)[2], float& m, float& l, int tq, int tqmin, int tqmax, int maxdist, const float* cn_lds, ull lmask) {
;     ...
;     if (!((wtiles >> kt) & 1ull)) return;
;     const bf16_t* Ks = (const bf16_t*)(smem + stage * (2 * 64 * LSTR * 2)); const bf16_t* Vs = Ks + 64 * LSTR;
;     const bool sel = ((lmask >> kt) & 1ull) != 0;
;     const bool interior = (64 * kt + 63 <= tqmin) && (MODE != 0 || (tqmax - 64 * kt <= maxdist));
;     int hm = 3;
;     if (MODE == 0) {
;       hm = 0;
;       if (64 * kt <= tqmax && 64 * kt + 31 >= tqmin - maxdist) hm |= 1;
;       if (64 * kt + 32 <= tqmax && 64 * kt + 63 >= tqmin - maxdist) hm |= 2;
;     }
;     if (MODE == 0 && hm == 1) attn_tile<MODE, true, 1>(Ks, Vs, qf, o, m, l, 64 * kt, tq, maxdist, cn_lds, sel);
;     else if (MODE == 0 && hm == 2) attn_tile<MODE, true, 2>(Ks, Vs, qf, o, m, l, 64 * kt, tq, maxdist, cn_lds, sel);
.LBB0_494:
	s_lshr_b64 s[6:7], s[4:5], s65
	s_and_b32 s58, s6, 1
	s_cmp_eq_u64 s[58:59], 0
	s_cbranch_scc1 .LBB0_518
	s_lshl_b32 s58, s65, 6
	s_or_b32 s33, s58, 63
	s_cmp_le_u32 s58, s30
	s_cselect_b64 s[6:7], -1, 0
	s_or_b32 s36, s58, 31
	s_cmp_ge_i32 s36, s29
	s_cselect_b64 s[36:37], -1, 0
	s_and_b64 s[6:7], s[6:7], s[36:37]
	v_cndmask_b32_e64 v0, 0, 1, s[6:7]
	s_or_b32 s6, s58, 32
	s_cmp_gt_u32 s6, s30
	s_cselect_b64 s[6:7], -1, 0
	s_cmp_lt_i32 s33, s29
	s_cselect_b64 s[36:37], -1, 0
	v_readfirstlane_b32 s38, v0
	s_or_b32 s39, s38, 2
	s_or_b64 s[6:7], s[6:7], s[36:37]
	s_and_b64 s[6:7], s[6:7], exec
	s_cselect_b32 s65, s38, s39
	s_mov_b64 s[62:63], -1
	s_mov_b64 s[54:55], 0
	s_cmp_lt_i32 s65, 2
	s_mov_b64 s[6:7], 0
	s_cbranch_scc1 .LBB0_511
	s_cmp_eq_u32 s65, 2
	s_mov_b64 s[6:7], -1
	s_cbranch_scc0 .LBB0_500
	ds_read_b128 v[34:37], v199 offset:23040
	ds_read_b128 v[50:53], v199 offset:23072
	v_or_b32_e32 v0, s58, v197
	s_waitcnt lgkmcnt(1)
	v_mfma_f32_32x32x16_bf16 v[34:49], v[34:37], v[98:101], 0
	s_waitcnt lgkmcnt(0)
	v_mfma_f32_32x32x16_bf16 v[34:49], v[50:53], v[102:105], v[34:49]
	ds_read_b128 v[50:53], v199 offset:23104
	s_waitcnt lgkmcnt(0)
	v_mfma_f32_32x32x16_bf16 v[34:49], v[50:53], v[106:109], v[34:49]
	ds_read_b128 v[50:53], v199 offset:23136
	s_waitcnt lgkmcnt(0)
	v_mfma_f32_32x32x16_bf16 v[34:49], v[50:53], v[110:113], v[34:49]
	v_or_b32_e32 v50, 32, v0
	v_cmp_gt_u32_e32 vcc, v50, v154
	v_cmp_lt_i32_e64 s[6:7], v50, v155
	s_or_b64 vcc, vcc, s[6:7]
	s_nop 7
	v_cndmask_b32_e32 v66, v34, v204, vcc
	v_bitop3_b32 v34, s58, v205, v197 bitop3:0x36
	v_cmp_ge_u32_e32 vcc, v50, v154
	v_cmp_gt_i32_e64 s[6:7], v34, v156
	s_or_b64 vcc, vcc, s[6:7]
	v_cndmask_b32_e32 v67, v35, v204, vcc
	v_or_b32_e32 v35, 34, v0
	v_cmp_gt_u32_e32 vcc, v35, v154
	v_cmp_lt_i32_e64 s[6:7], v35, v155
	s_or_b64 vcc, vcc, s[6:7]
	v_or_b32_e32 v35, 35, v0
	v_cndmask_b32_e32 v68, v36, v204, vcc
	v_cmp_gt_u32_e32 vcc, v35, v154
	v_cmp_lt_i32_e64 s[6:7], v35, v155
	s_or_b64 vcc, vcc, s[6:7]
	v_or_b32_e32 v35, 40, v0
	v_cndmask_b32_e32 v69, v37, v204, vcc
	v_cmp_gt_u32_e32 vcc, v35, v154
	v_cmp_lt_i32_e64 s[6:7], v35, v155
	s_or_b64 vcc, vcc, s[6:7]
	v_or_b32_e32 v35, 41, v0
	v_cndmask_b32_e32 v70, v38, v204, vcc
	v_cmp_gt_u32_e32 vcc, v35, v154
	v_cmp_lt_i32_e64 s[6:7], v35, v155
	s_or_b64 vcc, vcc, s[6:7]
	v_or_b32_e32 v35, 42, v0
	v_cndmask_b32_e32 v71, v39, v204, vcc
	v_cmp_gt_u32_e32 vcc, v35, v154
	v_cmp_lt_i32_e64 s[6:7], v35, v155
	s_or_b64 vcc, vcc, s[6:7]
	v_or_b32_e32 v35, 43, v0
	v_cndmask_b32_e32 v76, v40, v204, vcc
	v_cmp_gt_u32_e32 vcc, v35, v154
	v_cmp_lt_i32_e64 s[6:7], v35, v155
	s_or_b64 vcc, vcc, s[6:7]
	v_or_b32_e32 v35, 48, v0
	v_cndmask_b32_e32 v77, v41, v204, vcc
	v_cmp_gt_u32_e32 vcc, v35, v154
	v_cmp_lt_i32_e64 s[6:7], v35, v155
	s_or_b64 vcc, vcc, s[6:7]
	v_or_b32_e32 v35, 49, v0
	v_cndmask_b32_e32 v78, v42, v204, vcc
	v_cmp_gt_u32_e32 vcc, v35, v154
	v_cmp_lt_i32_e64 s[6:7], v35, v155
	s_or_b64 vcc, vcc, s[6:7]
	v_or_b32_e32 v35, 50, v0
	v_cndmask_b32_e32 v79, v43, v204, vcc
	v_cmp_gt_u32_e32 vcc, v35, v154
	v_cmp_lt_i32_e64 s[6:7], v35, v155
	s_or_b64 vcc, vcc, s[6:7]
	v_or_b32_e32 v35, 51, v0
	v_cndmask_b32_e32 v80, v44, v204, vcc
	v_cmp_gt_u32_e32 vcc, v35, v154
	v_cmp_lt_i32_e64 s[6:7], v35, v155
	s_or_b64 vcc, vcc, s[6:7]
	v_or_b32_e32 v35, 56, v0
	v_cndmask_b32_e32 v81, v45, v204, vcc
	v_cmp_gt_u32_e32 vcc, v35, v154
	v_cmp_lt_i32_e64 s[6:7], v35, v155
	s_or_b64 vcc, vcc, s[6:7]
	v_or_b32_e32 v35, 57, v0
	v_max3_f32 v34, v66, s35, v67
	v_cndmask_b32_e32 v73, v46, v204, vcc
	v_cmp_gt_u32_e32 vcc, v35, v154
	v_cmp_lt_i32_e64 s[6:7], v35, v155
	v_max3_f32 v34, v34, v68, v69
	s_or_b64 vcc, vcc, s[6:7]
	v_or_b32_e32 v35, 58, v0
	v_max3_f32 v34, v34, v70, v71
	v_cndmask_b32_e32 v74, v47, v204, vcc
	v_cmp_gt_u32_e32 vcc, v35, v154
	v_cmp_lt_i32_e64 s[6:7], v35, v155
	v_max3_f32 v34, v34, v76, v77
	s_or_b64 vcc, vcc, s[6:7]
	v_or_b32_e32 v0, 59, v0
	v_max3_f32 v34, v34, v78, v79
	v_cndmask_b32_e32 v75, v48, v204, vcc
	v_cmp_gt_u32_e32 vcc, v0, v154
	v_cmp_lt_i32_e64 s[6:7], v0, v155
	v_max3_f32 v34, v34, v80, v81
	s_or_b64 vcc, vcc, s[6:7]
	v_max3_f32 v34, v34, v73, v74
	v_cndmask_b32_e32 v72, v49, v204, vcc
	v_and_b32_e32 v35, 64, v202
	v_max3_f32 v0, v34, v75, v72
	v_xor_b32_e32 v34, 32, v202
	v_add_u32_e32 v35, 64, v35
	v_cmp_lt_i32_e32 vcc, v34, v35
	s_nop 1
	v_cndmask_b32_e32 v34, v202, v34, vcc
	v_lshlrev_b32_e32 v34, 2, v34
	ds_bpermute_b32 v34, v34, v0
	s_waitcnt lgkmcnt(0)
	v_max_f32_e32 v34, v34, v34
	v_max_f32_e32 v0, v0, v34
	v_mul_f32_e32 v0, 0x3fb8aa3b, v0
	v_max_f32_e32 v34, v158, v158
	v_max_f32_e32 v157, v34, v0
	v_sub_f32_e32 v0, v158, v157
	v_exp_f32_e32 v0, v0
	v_cmp_neq_f32_e32 vcc, v157, v158
	s_cbranch_vccz .LBB0_499
	v_pk_mul_f32 v[32:33], v[32:33], v[0:1] op_sel_hi:[1,0]
	v_pk_mul_f32 v[30:31], v[30:31], v[0:1] op_sel_hi:[1,0]
	v_pk_mul_f32 v[28:29], v[28:29], v[0:1] op_sel_hi:[1,0]
	v_pk_mul_f32 v[26:27], v[26:27], v[0:1] op_sel_hi:[1,0]
	v_pk_mul_f32 v[24:25], v[24:25], v[0:1] op_sel_hi:[1,0]
	v_pk_mul_f32 v[22:23], v[22:23], v[0:1] op_sel_hi:[1,0]
	v_pk_mul_f32 v[20:21], v[20:21], v[0:1] op_sel_hi:[1,0]
	v_pk_mul_f32 v[18:19], v[18:19], v[0:1] op_sel_hi:[1,0]
	v_pk_mul_f32 v[16:17], v[16:17], v[0:1] op_sel_hi:[1,0]
	v_pk_mul_f32 v[14:15], v[14:15], v[0:1] op_sel_hi:[1,0]
	v_pk_mul_f32 v[12:13], v[12:13], v[0:1] op_sel_hi:[1,0]
	v_pk_mul_f32 v[10:11], v[10:11], v[0:1] op_sel_hi:[1,0]
	v_pk_mul_f32 v[8:9], v[8:9], v[0:1] op_sel_hi:[1,0]
	v_pk_mul_f32 v[6:7], v[6:7], v[0:1] op_sel_hi:[1,0]
	v_pk_mul_f32 v[4:5], v[4:5], v[0:1] op_sel_hi:[1,0]
	v_pk_mul_f32 v[2:3], v[2:3], v[0:1] op_sel_hi:[1,0]
; DI unsigned pack2(float a, float b) { f32x2 v = {a, b}; bf16x2_t r = __builtin_convertvector(v, bf16x2_t); return __builtin_bit_cast(unsigned, r); }
; DI f32x16 mfma32(bf16x8 a, bf16x8 b, f32x16 c) { return __builtin_amdgcn_mfma_f32_32x32x16_bf16(a, b, c, 0, 0, 0); }
;     ...
;   float ps = 0.f;
; #pragma unroll
;   for (int k2 = 0; k2 < 2; ++k2)
; #pragma unroll
;     for (int i = 0; i < 16; ++i) {
;       if (!(HM & (1 << k2))) continue;
;       const float pv = (MODE == 1) ? __builtin_amdgcn_exp2f(s[k2][i] + neg) : __builtin_amdgcn_exp2f(fmaf(s[k2][i], L2E, neg));
;       s[k2][i] = pv; ps += pv;
;     }
;   l = l * alpha + ps;
;   if (__builtin_amdgcn_ballot_w64(mn != m) != 0ull) {
; #pragma unroll
;     for (int dt = 0; dt < 2; ++dt)
; #pragma unroll
;       for (int i = 0; i < 16; ++i) o[dt][i] *= alpha;
;   }
;   m = mn;
; #pragma unroll
;   for (int st = 0; st < 4; ++st) {
;     if (!(HM & (1 << (st >> 1)))) continue;
;     const int k2 = st >> 1, b8 = 8 * (st & 1);
;     const u32x4 pw = {pack2(s[k2][b8], s[k2][b8 + 1]), pack2(s[k2][b8 + 2], s[k2][b8 + 3]), pack2(s[k2][b8 + 4], s[k2][b8 + 5]), pack2(s[k2][b8 + 6], s[k2][b8 + 7])};
;     const bf16x8 pb = __builtin_bit_cast(bf16x8, pw);
; #pragma unroll
;     for (int dt = 0; dt < 2; ++dt) {
;       const s16x4 lo = *(const s16x4*)(Vs + (32 * dt + r) * LSTR + 16 * st + 4 * h);
;       const s16x4 hi = *(const s16x4*)(Vs + (32 * dt + r) * LSTR + 16 * st + 8 + 4 * h);
;       const bf16x8 a = __builtin_shufflevector(lo, hi, 0, 1, 2, 3, 4, 5, 6, 7);
;       o[dt] = mfma32(a, pb, o[dt]);
;     }
;   }
.LBB0_499:
	v_fma_f32 v66, v66, s34, -v157
	v_exp_f32_e32 v82, v66
	v_fma_f32 v66, v67, s34, -v157
	v_exp_f32_e32 v83, v66
	v_fma_f32 v66, v68, s34, -v157
	v_exp_f32_e32 v84, v66
	v_fma_f32 v66, v69, s34, -v157
	v_add_f32_e32 v67, 0, v82
	v_exp_f32_e32 v85, v66
	v_fma_f32 v66, v70, s34, -v157
	v_add_f32_e32 v67, v83, v67
	v_exp_f32_e32 v70, v66
	v_fma_f32 v66, v71, s34, -v157
	v_exp_f32_e32 v71, v66
	v_add_f32_e32 v66, v84, v67
	v_fma_f32 v67, v76, s34, -v157
	v_exp_f32_e32 v86, v67
	v_fma_f32 v67, v77, s34, -v157
	v_add_f32_e32 v66, v85, v66
	v_exp_f32_e32 v87, v67
	v_fma_f32 v67, v78, s34, -v157
	v_add_f32_e32 v66, v70, v66
	v_exp_f32_e32 v88, v67
	v_fma_f32 v67, v79, s34, -v157
	v_add_f32_e32 v66, v71, v66
	v_exp_f32_e32 v89, v67
	v_add_f32_e32 v66, v86, v66
	v_add_f32_e32 v66, v87, v66
	v_add_f32_e32 v66, v88, v66
	v_add_f32_e32 v90, v89, v66
	v_fma_f32 v66, v80, s34, -v157
	v_add_u32_e32 v92, 0x6800, v198
	v_exp_f32_e32 v91, v66
	ds_read2_b64 v[66:69], v92 offset0:136 offset1:138
	v_cvt_pk_bf16_f32 v78, v70, v71
	v_add_u32_e32 v70, v199, v200
	v_fma_f32 v76, v81, s34, -v157
	v_add_u32_e32 v70, 0x7800, v70
	v_exp_f32_e32 v93, v76
	v_cvt_pk_bf16_f32 v76, v82, v83
	ds_read2_b64 v[80:83], v70 offset0:200 offset1:202
	v_cvt_pk_bf16_f32 v77, v84, v85
	v_cvt_pk_bf16_f32 v79, v86, v87
	v_fma_f32 v71, v72, s34, -v157
	s_mov_b64 s[6:7], 0
	s_waitcnt lgkmcnt(1)
	v_mfma_f32_32x32x16_bf16 v[34:49], v[66:69], v[76:79], v[2:17]
	v_fma_f32 v66, v73, s34, -v157
	v_exp_f32_e32 v84, v66
	v_fma_f32 v66, v74, s34, -v157
	v_exp_f32_e32 v85, v66
	v_fma_f32 v66, v75, s34, -v157
	v_exp_f32_e32 v86, v66
	ds_read2_b64 v[66:69], v92 offset0:140 offset1:142
	s_waitcnt lgkmcnt(1)
	v_mfma_f32_32x32x16_bf16 v[50:65], v[80:83], v[76:79], v[18:33]
	v_exp_f32_e32 v78, v71
	ds_read2_b64 v[70:73], v70 offset0:204 offset1:206
	v_cvt_pk_bf16_f32 v74, v88, v89
	v_cvt_pk_bf16_f32 v75, v91, v93
	v_cvt_pk_bf16_f32 v76, v84, v85
	v_cvt_pk_bf16_f32 v77, v86, v78
	s_waitcnt lgkmcnt(1)
	s_nop 0
	v_mfma_f32_32x32x16_bf16 v[2:17], v[66:69], v[74:77], v[34:49]
	v_add_f32_e32 v66, v91, v90
	v_add_f32_e32 v66, v93, v66
	v_add_f32_e32 v66, v84, v66
	v_add_f32_e32 v66, v85, v66
	v_add_f32_e32 v66, v86, v66
	v_add_f32_e32 v159, v78, v66
	v_fmac_f32_e32 v159, v160, v0
	s_waitcnt lgkmcnt(0)
	v_mfma_f32_32x32x16_bf16 v[18:33], v[70:73], v[74:77], v[50:65]

; DI f32x16 mfma32(bf16x8 a, bf16x8 b, f32x16 c) { return __builtin_amdgcn_mfma_f32_32x32x16_bf16(a, b, c, 0, 0, 0); }
; DI int crow(int i, int h) { return (i & 3) + 8 * (i >> 2) + 4 * h; }
;     ...
;   f32x16 s[2];
; #pragma unroll
;   for (int k2 = 0; k2 < 2; ++k2) {
;     if (!(HM & (1 << k2))) continue;
; #pragma unroll
;     for (int i = 0; i < 16; ++i) s[k2][i] = 0.f;
; #pragma unroll
;     for (int ks = 0; ks < 4; ++ks) {
;       const bf16x8 a = *(const bf16x8*)(Ks + (32 * k2 + r) * LSTR + 16 * ks + 8 * h);
;       s[k2] = mfma32(a, qf[ks], s[k2]);
;     }
;   }
;   if (MODE == 1) {
; #pragma unroll
;     for (int k2 = 0; k2 < 2; ++k2)
; #pragma unroll
;       for (int g = 0; g < 4; ++g) {
;         if (!(HM & (1 << k2))) continue;
;         const f32x4 cv = *(const f32x4*)(cn_lds + key0 + 32 * k2 + 8 * g + 4 * h);
; #pragma unroll
;         for (int e = 0; e < 4; ++e) s[k2][4 * g + e] = fmaf(s[k2][4 * g + e], L2E, cv[e]);
;       }
;   }
;   float mx = NINF;
; #pragma unroll
;   for (int k2 = 0; k2 < 2; ++k2)
; #pragma unroll
;     for (int i = 0; i < 16; ++i) {
;       if (!(HM & (1 << k2))) continue;
;       float v = s[k2][i];
;       if (MASKED) {
;         const int tk = key0 + 32 * k2 + crow(i, h);
;         const bool valid = (MODE == 0) ? ((tk <= tq) && (tq - tk <= maxdist)) : (tk <= tq);
;         v = valid ? v : NINF; s[k2][i] = v;
;       }
;       mx = fmaxf(mx, v);
;     }
; template <int MODE>
; DI void flash_loop(char* smem, const bf16_t* Kbase, size_t ldk, const bf16_t* Vtbase, size_t ldv, ull tiles, ull wtiles,
;                    const bf16x8 (&qf)[4], f32x16 (&o)[2], float& m, float& l, int tq, int tqmin, int tqmax, int maxdist, const float* cn_lds, ull lmask) {
;     ...
;     const bool interior = (64 * kt + 63 <= tqmin) && (MODE != 0 || (tqmax - 64 * kt <= maxdist));
;     int hm = 3;
;     if (MODE == 0) {
;       hm = 0;
;       if (64 * kt <= tqmax && 64 * kt + 31 >= tqmin - maxdist) hm |= 1;
;       if (64 * kt + 32 <= tqmax && 64 * kt + 63 >= tqmin - maxdist) hm |= 2;
;     }
;     if (MODE == 0 && hm == 1) attn_tile<MODE, true, 1>(Ks, Vs, qf, o, m, l, 64 * kt, tq, maxdist, cn_lds, sel);
;     else if (MODE == 0 && hm == 2) attn_tile<MODE, true, 2>(Ks, Vs, qf, o, m, l, 64 * kt, tq, maxdist, cn_lds, sel);
;     else if (interior) attn_tile<MODE, false>(Ks, Vs, qf, o, m, l, 64 * kt, tq, maxdist, cn_lds, sel);
.LBB0_502:
	ds_read_b128 v[82:85], v196 offset:18432
	ds_read_b128 v[78:81], v196 offset:18464
	ds_read_b128 v[74:77], v196 offset:18496
	ds_read_b128 v[66:69], v196 offset:18528
	ds_read_b128 v[70:73], v196 offset:23040
	s_cmp_le_u32 s33, s28
	s_cselect_b64 s[6:7], -1, 0
	s_cmp_ge_i32 s58, s31
	s_cselect_b64 s[36:37], -1, 0
	s_and_b64 s[6:7], s[6:7], s[36:37]
	s_andn2_b64 vcc, exec, s[6:7]
	s_mov_b64 s[6:7], -1
	s_cbranch_vccz .LBB0_506
	s_waitcnt lgkmcnt(4)
	v_mfma_f32_32x32x16_bf16 v[50:65], v[82:85], v[98:101], 0
	ds_read_b128 v[86:89], v196 offset:23072
	ds_read_b128 v[90:93], v196 offset:23104
	v_or_b32_e32 v0, s58, v197
	v_cmp_gt_u32_e32 vcc, v0, v154
	v_cmp_lt_i32_e64 s[6:7], v0, v155
	s_or_b64 vcc, vcc, s[6:7]
	s_waitcnt lgkmcnt(5)
	v_mfma_f32_32x32x16_bf16 v[50:65], v[78:81], v[102:105], v[50:65]
	s_waitcnt lgkmcnt(2)
	v_mfma_f32_32x32x16_bf16 v[34:49], v[70:73], v[98:101], 0
	v_mfma_f32_32x32x16_bf16 v[50:65], v[74:77], v[106:109], v[50:65]
	s_waitcnt lgkmcnt(1)
	v_mfma_f32_32x32x16_bf16 v[34:49], v[86:89], v[102:105], v[34:49]
	ds_read_b128 v[86:89], v196 offset:23136
	v_mfma_f32_32x32x16_bf16 v[50:65], v[66:69], v[110:113], v[50:65]
	s_waitcnt lgkmcnt(1)
	v_mfma_f32_32x32x16_bf16 v[34:49], v[90:93], v[106:109], v[34:49]
	s_waitcnt lgkmcnt(0)
	v_mfma_f32_32x32x16_bf16 v[34:49], v[86:89], v[110:113], v[34:49]
	s_nop 7
	v_cndmask_b32_e32 v86, v50, v204, vcc
	v_bitop3_b32 v50, s58, v197, s58 bitop3:3
	v_cmp_ge_u32_e32 vcc, v0, v154
	v_cmp_lt_i32_e64 s[6:7], v156, v50
	s_or_b64 vcc, vcc, s[6:7]
	v_cndmask_b32_e32 v87, v51, v204, vcc
	v_or_b32_e32 v51, 2, v0
	v_cmp_gt_u32_e32 vcc, v51, v154
	v_cmp_lt_i32_e64 s[6:7], v51, v155
	s_or_b64 vcc, vcc, s[6:7]
	v_or_b32_e32 v51, 3, v0
	v_cndmask_b32_e32 v88, v52, v204, vcc
	v_cmp_gt_u32_e32 vcc, v51, v154
	v_cmp_lt_i32_e64 s[6:7], v51, v155
	s_or_b64 vcc, vcc, s[6:7]
	v_or_b32_e32 v51, 8, v0
	v_cndmask_b32_e32 v89, v53, v204, vcc
	v_cmp_gt_u32_e32 vcc, v51, v154
	v_cmp_lt_i32_e64 s[6:7], v51, v155
	s_or_b64 vcc, vcc, s[6:7]
	v_or_b32_e32 v51, 9, v0
	v_cndmask_b32_e32 v90, v54, v204, vcc
	v_cmp_gt_u32_e32 vcc, v51, v154
	v_cmp_lt_i32_e64 s[6:7], v51, v155
	s_or_b64 vcc, vcc, s[6:7]
	v_or_b32_e32 v51, 10, v0
	v_cndmask_b32_e32 v192, v55, v204, vcc
	v_cmp_gt_u32_e32 vcc, v51, v154
	v_cmp_lt_i32_e64 s[6:7], v51, v155
	s_or_b64 vcc, vcc, s[6:7]
	v_or_b32_e32 v51, 11, v0
	v_cndmask_b32_e32 v191, v56, v204, vcc
	v_cmp_gt_u32_e32 vcc, v51, v154
	v_cmp_lt_i32_e64 s[6:7], v51, v155
	s_or_b64 vcc, vcc, s[6:7]
	v_or_b32_e32 v51, 16, v0
	v_cndmask_b32_e32 v193, v57, v204, vcc
	v_cmp_gt_u32_e32 vcc, v51, v154
	v_cmp_lt_i32_e64 s[6:7], v51, v155
	s_or_b64 vcc, vcc, s[6:7]
	v_or_b32_e32 v51, 17, v0
	v_cndmask_b32_e32 v188, v58, v204, vcc
	v_cmp_gt_u32_e32 vcc, v51, v154
	v_cmp_lt_i32_e64 s[6:7], v51, v155
	s_or_b64 vcc, vcc, s[6:7]
	v_or_b32_e32 v51, 18, v0
	v_cndmask_b32_e32 v190, v59, v204, vcc
	v_cmp_gt_u32_e32 vcc, v51, v154
	v_cmp_lt_i32_e64 s[6:7], v51, v155
	s_or_b64 vcc, vcc, s[6:7]
	v_or_b32_e32 v51, 19, v0
	v_cndmask_b32_e32 v189, v60, v204, vcc
	v_cmp_gt_u32_e32 vcc, v51, v154
	v_cmp_lt_i32_e64 s[6:7], v51, v155
	s_or_b64 vcc, vcc, s[6:7]
	v_or_b32_e32 v51, 24, v0
	v_cndmask_b32_e32 v187, v61, v204, vcc
	v_cmp_gt_u32_e32 vcc, v51, v154
	v_cmp_lt_i32_e64 s[6:7], v51, v155
	s_or_b64 vcc, vcc, s[6:7]
	v_or_b32_e32 v51, 25, v0
	v_cndmask_b32_e32 v186, v62, v204, vcc
	v_cmp_gt_u32_e32 vcc, v51, v154
	v_cmp_lt_i32_e64 s[6:7], v51, v155
	s_or_b64 vcc, vcc, s[6:7]
	v_or_b32_e32 v51, 26, v0
	v_cndmask_b32_e32 v185, v63, v204, vcc
	v_cmp_gt_u32_e32 vcc, v51, v154
	v_cmp_lt_i32_e64 s[6:7], v51, v155
	s_or_b64 vcc, vcc, s[6:7]
	v_or_b32_e32 v51, 27, v0
	v_cndmask_b32_e32 v184, v64, v204, vcc
	v_cmp_gt_u32_e32 vcc, v51, v154
	v_cmp_lt_i32_e64 s[6:7], v51, v155
	s_or_b64 vcc, vcc, s[6:7]
	v_or_b32_e32 v51, 32, v0
	v_cndmask_b32_e32 v182, v65, v204, vcc
	v_cmp_gt_u32_e32 vcc, v51, v154
	v_cmp_lt_i32_e64 s[6:7], v51, v155
	s_or_b64 vcc, vcc, s[6:7]
	v_cndmask_b32_e32 v164, v34, v204, vcc
	v_or_b32_e32 v34, 33, v0
	v_cmp_gt_u32_e32 vcc, v34, v154
	v_cmp_lt_i32_e64 s[6:7], v34, v155
	s_or_b64 vcc, vcc, s[6:7]
	v_cndmask_b32_e32 v162, v35, v204, vcc
	v_or_b32_e32 v35, 34, v0
	v_cmp_gt_u32_e32 vcc, v35, v154
	v_cmp_lt_i32_e64 s[6:7], v35, v155
	s_or_b64 vcc, vcc, s[6:7]
	v_or_b32_e32 v35, 35, v0
	v_cndmask_b32_e32 v159, v36, v204, vcc
	v_cmp_gt_u32_e32 vcc, v35, v154
	v_cmp_lt_i32_e64 s[6:7], v35, v155
	s_or_b64 vcc, vcc, s[6:7]
	v_or_b32_e32 v35, 40, v0
	v_cndmask_b32_e32 v97, v37, v204, vcc
	v_cmp_gt_u32_e32 vcc, v35, v154
	v_cmp_lt_i32_e64 s[6:7], v35, v155
	s_or_b64 vcc, vcc, s[6:7]
	v_or_b32_e32 v35, 41, v0
	v_cndmask_b32_e32 v92, v38, v204, vcc
	v_cmp_gt_u32_e32 vcc, v35, v154
	v_cmp_lt_i32_e64 s[6:7], v35, v155
	s_or_b64 vcc, vcc, s[6:7]
	v_or_b32_e32 v35, 42, v0
	v_cndmask_b32_e32 v91, v39, v204, vcc
	v_cmp_gt_u32_e32 vcc, v35, v154
	v_cmp_lt_i32_e64 s[6:7], v35, v155
	s_or_b64 vcc, vcc, s[6:7]
	v_or_b32_e32 v35, 43, v0
	v_cndmask_b32_e32 v93, v40, v204, vcc
	v_cmp_gt_u32_e32 vcc, v35, v154
	v_cmp_lt_i32_e64 s[6:7], v35, v155
	s_or_b64 vcc, vcc, s[6:7]
	v_or_b32_e32 v35, 48, v0
	v_cndmask_b32_e32 v94, v41, v204, vcc
	v_cmp_gt_u32_e32 vcc, v35, v154
	v_cmp_lt_i32_e64 s[6:7], v35, v155
	s_or_b64 vcc, vcc, s[6:7]
	v_or_b32_e32 v35, 49, v0
	v_max3_f32 v50, v86, s35, v87
	v_cndmask_b32_e32 v95, v42, v204, vcc
	v_cmp_gt_u32_e32 vcc, v35, v154
	v_cmp_lt_i32_e64 s[6:7], v35, v155
	v_max3_f32 v50, v50, v88, v89
	s_or_b64 vcc, vcc, s[6:7]
	v_or_b32_e32 v35, 50, v0
	v_max3_f32 v50, v50, v90, v192
	v_cndmask_b32_e32 v96, v43, v204, vcc
	v_cmp_gt_u32_e32 vcc, v35, v154
	v_cmp_lt_i32_e64 s[6:7], v35, v155
; DI int crow(int i, int h) { return (i & 3) + 8 * (i >> 2) + 4 * h; }
;     ...
;   float mx = NINF;
; #pragma unroll
;   for (int k2 = 0; k2 < 2; ++k2)
; #pragma unroll
;     for (int i = 0; i < 16; ++i) {
;       if (!(HM & (1 << k2))) continue;
;       float v = s[k2][i];
;       if (MASKED) {
;         const int tk = key0 + 32 * k2 + crow(i, h);
;         const bool valid = (MODE == 0) ? ((tk <= tq) && (tq - tk <= maxdist)) : (tk <= tq);
;         v = valid ? v : NINF; s[k2][i] = v;
;       }
;       mx = fmaxf(mx, v);
;     }
;   mx = fmaxf(mx, __shfl_xor(mx, 32));
;   if (MODE != 1) mx *= L2E;
;   if (MODE == 2) mx = lanesel ? mx : NINF;
;   const float mn = fmaxf(m, mx); const float alpha = __builtin_amdgcn_exp2f(m - mn);
;   const float neg = (MODE == 2 && !lanesel) ? NINF : -mn;
;   float ps = 0.f;
; #pragma unroll
;   for (int k2 = 0; k2 < 2; ++k2)
; #pragma unroll
;     for (int i = 0; i < 16; ++i) {
;       if (!(HM & (1 << k2))) continue;
;       const float pv = (MODE == 1) ? __builtin_amdgcn_exp2f(s[k2][i] + neg) : __builtin_amdgcn_exp2f(fmaf(s[k2][i], L2E, neg));
;       s[k2][i] = pv; ps += pv;
;     }
;   l = l * alpha + ps;
	v_max3_f32 v50, v50, v191, v193
	s_or_b64 vcc, vcc, s[6:7]
	v_or_b32_e32 v35, 51, v0
	v_max3_f32 v50, v50, v188, v190
	v_cndmask_b32_e32 v161, v44, v204, vcc
	v_cmp_gt_u32_e32 vcc, v35, v154
	v_cmp_lt_i32_e64 s[6:7], v35, v155
	v_max3_f32 v50, v50, v189, v187
	s_or_b64 vcc, vcc, s[6:7]
	v_or_b32_e32 v35, 56, v0
	v_max3_f32 v50, v50, v186, v185
	v_cndmask_b32_e32 v163, v45, v204, vcc
	v_cmp_gt_u32_e32 vcc, v35, v154
	v_cmp_lt_i32_e64 s[6:7], v35, v155
	v_max3_f32 v50, v50, v184, v182
	s_or_b64 vcc, vcc, s[6:7]
	v_or_b32_e32 v35, 57, v0
	v_max3_f32 v34, v50, v164, v162
	v_cndmask_b32_e32 v165, v46, v204, vcc
	v_cmp_gt_u32_e32 vcc, v35, v154
	v_cmp_lt_i32_e64 s[6:7], v35, v155
	v_max3_f32 v34, v34, v159, v97
	s_or_b64 vcc, vcc, s[6:7]
	v_or_b32_e32 v35, 58, v0
	v_max3_f32 v34, v34, v92, v91
	v_cndmask_b32_e32 v180, v47, v204, vcc
	v_cmp_gt_u32_e32 vcc, v35, v154
	v_cmp_lt_i32_e64 s[6:7], v35, v155
	v_max3_f32 v34, v34, v93, v94
	s_or_b64 vcc, vcc, s[6:7]
	v_or_b32_e32 v0, 59, v0
	v_max3_f32 v34, v34, v95, v96
	v_cndmask_b32_e32 v181, v48, v204, vcc
	v_cmp_gt_u32_e32 vcc, v0, v154
	v_cmp_lt_i32_e64 s[6:7], v0, v155
	v_max3_f32 v34, v34, v161, v163
	s_or_b64 vcc, vcc, s[6:7]
	v_max3_f32 v34, v34, v165, v180
	v_cndmask_b32_e32 v183, v49, v204, vcc
	v_and_b32_e32 v35, 64, v202
	v_max3_f32 v0, v34, v181, v183
	v_xor_b32_e32 v34, 32, v202
	v_add_u32_e32 v35, 64, v35
	v_cmp_lt_i32_e32 vcc, v34, v35
	s_nop 1
	v_cndmask_b32_e32 v34, v202, v34, vcc
	v_lshlrev_b32_e32 v34, 2, v34
	ds_bpermute_b32 v34, v34, v0
	s_waitcnt lgkmcnt(0)
	v_max_f32_e32 v34, v34, v34
	v_max_f32_e32 v0, v0, v34
	v_mul_f32_e32 v0, 0x3fb8aa3b, v0
	v_max_f32_e32 v34, v158, v158
	v_max_f32_e32 v157, v34, v0
	v_sub_f32_e32 v0, v158, v157
	v_exp_f32_e32 v0, v0
	v_cmp_neq_f32_e32 vcc, v157, v158
	s_cbranch_vccz .LBB0_505
	v_pk_mul_f32 v[32:33], v[32:33], v[0:1] op_sel_hi:[1,0]
	v_pk_mul_f32 v[30:31], v[30:31], v[0:1] op_sel_hi:[1,0]
	v_pk_mul_f32 v[28:29], v[28:29], v[0:1] op_sel_hi:[1,0]
	v_pk_mul_f32 v[26:27], v[26:27], v[0:1] op_sel_hi:[1,0]
	v_pk_mul_f32 v[24:25], v[24:25], v[0:1] op_sel_hi:[1,0]
	v_pk_mul_f32 v[22:23], v[22:23], v[0:1] op_sel_hi:[1,0]
	v_pk_mul_f32 v[20:21], v[20:21], v[0:1] op_sel_hi:[1,0]
	v_pk_mul_f32 v[18:19], v[18:19], v[0:1] op_sel_hi:[1,0]
	v_pk_mul_f32 v[16:17], v[16:17], v[0:1] op_sel_hi:[1,0]
	v_pk_mul_f32 v[14:15], v[14:15], v[0:1] op_sel_hi:[1,0]
	v_pk_mul_f32 v[12:13], v[12:13], v[0:1] op_sel_hi:[1,0]
	v_pk_mul_f32 v[10:11], v[10:11], v[0:1] op_sel_hi:[1,0]
	v_pk_mul_f32 v[8:9], v[8:9], v[0:1] op_sel_hi:[1,0]
	v_pk_mul_f32 v[6:7], v[6:7], v[0:1] op_sel_hi:[1,0]
	v_pk_mul_f32 v[4:5], v[4:5], v[0:1] op_sel_hi:[1,0]
	v_pk_mul_f32 v[2:3], v[2:3], v[0:1] op_sel_hi:[1,0]
.LBB0_505:
	v_fma_f32 v86, v86, s34, -v157
	v_exp_f32_e32 v86, v86
	v_fma_f32 v87, v87, s34, -v157
	v_exp_f32_e32 v87, v87
	v_fma_f32 v88, v88, s34, -v157
	v_exp_f32_e32 v88, v88
	v_fma_f32 v89, v89, s34, -v157
	v_exp_f32_e32 v89, v89
	v_fma_f32 v90, v90, s34, -v157
	v_add_f32_e32 v194, 0, v86
	v_exp_f32_e32 v90, v90
	v_fma_f32 v192, v192, s34, -v157
	v_add_f32_e32 v194, v87, v194
	v_exp_f32_e32 v192, v192
	v_fma_f32 v191, v191, s34, -v157
	v_add_f32_e32 v194, v88, v194
	v_exp_f32_e32 v191, v191
	v_fma_f32 v193, v193, s34, -v157
	v_add_f32_e32 v194, v89, v194
	v_exp_f32_e32 v193, v193
	v_fma_f32 v188, v188, s34, -v157
	v_add_f32_e32 v194, v90, v194
	v_exp_f32_e32 v188, v188
	v_fma_f32 v190, v190, s34, -v157
	v_add_f32_e32 v194, v192, v194
	v_exp_f32_e32 v190, v190
	v_fma_f32 v189, v189, s34, -v157
	v_add_f32_e32 v194, v191, v194
	v_exp_f32_e32 v189, v189
	v_fma_f32 v187, v187, s34, -v157
	v_add_f32_e32 v194, v193, v194
	v_exp_f32_e32 v187, v187
	v_fma_f32 v186, v186, s34, -v157
	v_add_f32_e32 v194, v188, v194
	v_exp_f32_e32 v186, v186
	v_fma_f32 v185, v185, s34, -v157
	v_add_f32_e32 v194, v190, v194
	v_exp_f32_e32 v185, v185
	v_fma_f32 v184, v184, s34, -v157
	v_add_f32_e32 v194, v189, v194
	v_exp_f32_e32 v184, v184
	v_fma_f32 v182, v182, s34, -v157
	v_add_f32_e32 v194, v187, v194
	v_exp_f32_e32 v182, v182
	v_fma_f32 v164, v164, s34, -v157
	v_add_f32_e32 v194, v186, v194
	v_exp_f32_e32 v164, v164
	v_fma_f32 v162, v162, s34, -v157
	v_add_f32_e32 v194, v185, v194
	v_exp_f32_e32 v162, v162
	v_fma_f32 v159, v159, s34, -v157
	v_add_f32_e32 v194, v184, v194
	v_exp_f32_e32 v195, v159
	v_add_f32_e32 v194, v182, v194
	v_add_f32_e32 v194, v164, v194
	v_add_f32_e32 v194, v162, v194
	v_fma_f32 v97, v97, s34, -v157
	v_add_f32_e32 v159, v195, v194
	v_exp_f32_e32 v194, v97
	v_fma_f32 v92, v92, s34, -v157
	v_exp_f32_e32 v209, v92
	v_fma_f32 v91, v91, s34, -v157
	v_exp_f32_e32 v210, v91
	v_add_f32_e32 v97, v194, v159
	v_add_f32_e32 v92, v209, v97
	v_cvt_pk_bf16_f32 v86, v86, v87
	v_add_f32_e32 v91, v210, v92
	v_fma_f32 v92, v93, s34, -v157
	v_exp_f32_e32 v211, v92
	v_fma_f32 v92, v94, s34, -v157
	v_exp_f32_e32 v212, v92
	v_fma_f32 v92, v95, s34, -v157
	v_exp_f32_e32 v213, v92
	v_fma_f32 v92, v96, s34, -v157
	v_exp_f32_e32 v214, v92
	v_fma_f32 v92, v161, s34, -v157
	v_add_f32_e32 v91, v211, v91
	v_exp_f32_e32 v161, v92
	v_fma_f32 v92, v163, s34, -v157
	v_add_f32_e32 v91, v212, v91
	v_exp_f32_e32 v163, v92
	v_fma_f32 v92, v165, s34, -v157
	v_add_f32_e32 v91, v213, v91
	v_exp_f32_e32 v165, v92
	v_fma_f32 v92, v180, s34, -v157
	v_add_f32_e32 v91, v214, v91
	v_exp_f32_e32 v180, v92
	v_fma_f32 v92, v181, s34, -v157
	v_add_f32_e32 v91, v161, v91
	v_exp_f32_e32 v181, v92
	v_fma_f32 v92, v183, s34, -v157
	v_add_f32_e32 v91, v163, v91
	v_exp_f32_e32 v183, v92
	v_add_f32_e32 v91, v165, v91
	v_add_f32_e32 v91, v180, v91
	v_add_f32_e32 v91, v181, v91
	v_add_f32_e32 v159, v183, v91
	v_fmac_f32_e32 v159, v160, v0
	v_add_u32_e32 v0, 0x6800, v198
	v_cvt_pk_bf16_f32 v87, v88, v89
	v_cvt_pk_bf16_f32 v88, v90, v192
	ds_read2_b64 v[90:93], v0 offset0:128 offset1:130
	ds_read2_b64 v[94:97], v0 offset0:132 offset1:134
	v_cvt_pk_bf16_f32 v89, v191, v193
	v_add_u32_e32 v191, 0x7800, v198
	s_mov_b64 s[6:7], 0
	s_waitcnt lgkmcnt(1)
;     ...
;   f32x16 s[2];
; #pragma unroll
;   for (int k2 = 0; k2 < 2; ++k2) {
;     if (!(HM & (1 << k2))) continue;
; #pragma unroll
;     for (int i = 0; i < 16; ++i) s[k2][i] = 0.f;
; #pragma unroll
;     for (int ks = 0; ks < 4; ++ks) {
;       const bf16x8 a = *(const bf16x8*)(Ks + (32 * k2 + r) * LSTR + 16 * ks + 8 * h);
;       s[k2] = mfma32(a, qf[ks], s[k2]);
;     }
;   }
;   if (MODE == 1) {
; #pragma unroll
;     for (int k2 = 0; k2 < 2; ++k2)
; #pragma unroll
;       for (int g = 0; g < 4; ++g) {
;         if (!(HM & (1 << k2))) continue;
;         const f32x4 cv = *(const f32x4*)(cn_lds + key0 + 32 * k2 + 8 * g + 4 * h);
; #pragma unroll
;         for (int e = 0; e < 4; ++e) s[k2][4 * g + e] = fmaf(s[k2][4 * g + e], L2E, cv[e]);
;       }
;   }
;   float mx = NINF;
; #pragma unroll
;   for (int k2 = 0; k2 < 2; ++k2)
; #pragma unroll
;     for (int i = 0; i < 16; ++i) {
;       if (!(HM & (1 << k2))) continue;
;       float v = s[k2][i];
;       if (MASKED) {
;         const int tk = key0 + 32 * k2 + crow(i, h);
;         const bool valid = (MODE == 0) ? ((tk <= tq) && (tq - tk <= maxdist)) : (tk <= tq);
;         v = valid ? v : NINF; s[k2][i] = v;
;       }
;       mx = fmaxf(mx, v);
;     }
;   mx = fmaxf(mx, __shfl_xor(mx, 32));
;   if (MODE != 1) mx *= L2E;
;   if (MODE == 2) mx = lanesel ? mx : NINF;
;   const float mn = fmaxf(m, mx); const float alpha = __builtin_amdgcn_exp2f(m - mn);
;   const float neg = (MODE == 2 && !lanesel) ? NINF : -mn;
;   float ps = 0.f;
; #pragma unroll
;   for (int k2 = 0; k2 < 2; ++k2)
; #pragma unroll
;     for (int i = 0; i < 16; ++i) {
;       if (!(HM & (1 << k2))) continue;
;     ...
; #pragma unroll
;   for (int st = 0; st < 4; ++st) {
;     if (!(HM & (1 << (st >> 1)))) continue;
;     const int k2 = st >> 1, b8 = 8 * (st & 1);
;     const u32x4 pw = {pack2(s[k2][b8], s[k2][b8 + 1]), pack2(s[k2][b8 + 2], s[k2][b8 + 3]), pack2(s[k2][b8 + 4], s[k2][b8 + 5]), pack2(s[k2][b8 + 6], s[k2][b8 + 7])};
;     const bf16x8 pb = __builtin_bit_cast(bf16x8, pw);
; #pragma unroll
;     for (int dt = 0; dt < 2; ++dt) {
;       const s16x4 lo = *(const s16x4*)(Vs + (32 * dt + r) * LSTR + 16 * st + 4 * h);
;       const s16x4 hi = *(const s16x4*)(Vs + (32 * dt + r) * LSTR + 16 * st + 8 + 4 * h);
;       const bf16x8 a = __builtin_shufflevector(lo, hi, 0, 1, 2, 3, 4, 5, 6, 7);
;       o[dt] = mfma32(a, pb, o[dt]);
;     }
;   }
	v_mfma_f32_32x32x16_bf16 v[34:49], v[90:93], v[86:89], v[2:17]
	ds_read2_b64 v[90:93], v191 offset0:192 offset1:194
	s_waitcnt lgkmcnt(0)
	v_mfma_f32_32x32x16_bf16 v[50:65], v[90:93], v[86:89], v[18:33]
	ds_read2_b64 v[90:93], v191 offset0:196 offset1:198
	v_cvt_pk_bf16_f32 v86, v188, v190
	v_cvt_pk_bf16_f32 v87, v189, v187
	v_cvt_pk_bf16_f32 v88, v186, v185
	v_cvt_pk_bf16_f32 v89, v184, v182
	s_waitcnt lgkmcnt(0)
	s_nop 0
	v_mfma_f32_32x32x16_bf16 v[50:65], v[90:93], v[86:89], v[50:65]
	ds_read2_b64 v[90:93], v0 offset0:136 offset1:138
	v_mfma_f32_32x32x16_bf16 v[34:49], v[94:97], v[86:89], v[34:49]
	v_cvt_pk_bf16_f32 v86, v164, v162
	v_cvt_pk_bf16_f32 v87, v195, v194
	v_cvt_pk_bf16_f32 v88, v209, v210
	v_cvt_pk_bf16_f32 v89, v211, v212
	s_waitcnt lgkmcnt(0)
	s_nop 0
	v_mfma_f32_32x32x16_bf16 v[34:49], v[90:93], v[86:89], v[34:49]
	ds_read2_b64 v[90:93], v191 offset0:200 offset1:202
	s_waitcnt lgkmcnt(0)
	v_mfma_f32_32x32x16_bf16 v[50:65], v[90:93], v[86:89], v[50:65]
	ds_read2_b64 v[90:93], v0 offset0:140 offset1:142
	v_cvt_pk_bf16_f32 v86, v213, v214
	v_cvt_pk_bf16_f32 v87, v161, v163
	v_cvt_pk_bf16_f32 v88, v165, v180
	v_cvt_pk_bf16_f32 v89, v181, v183
	s_waitcnt lgkmcnt(0)
	s_nop 0
	v_mfma_f32_32x32x16_bf16 v[2:17], v[90:93], v[86:89], v[34:49]
	ds_read2_b64 v[90:93], v191 offset0:204 offset1:206
	s_waitcnt lgkmcnt(0)
	v_mfma_f32_32x32x16_bf16 v[18:33], v[90:93], v[86:89], v[50:65]
.LBB0_506:
	s_and_b64 vcc, exec, s[6:7]
	s_cbranch_vccz .LBB0_510
	s_waitcnt lgkmcnt(4)
	v_mfma_f32_32x32x16_bf16 v[82:97], v[82:85], v[98:101], 0
	s_nop 4
	ds_read_b128 v[34:37], v196 offset:23072
	ds_read_b128 v[38:41], v196 offset:23104
	s_waitcnt lgkmcnt(5)
	v_mfma_f32_32x32x16_bf16 v[82:97], v[78:81], v[102:105], v[82:97]
	s_waitcnt lgkmcnt(4)
	v_mfma_f32_32x32x16_bf16 v[82:97], v[74:77], v[106:109], v[82:97]
	s_waitcnt lgkmcnt(3)
	v_mfma_f32_32x32x16_bf16 v[82:97], v[66:69], v[110:113], v[82:97]
	s_waitcnt lgkmcnt(2)
	v_mfma_f32_32x32x16_bf16 v[66:81], v[70:73], v[98:101], 0
	s_nop 9
	v_max3_f32 v0, v82, s35, v83
	v_max3_f32 v0, v0, v84, v85
	v_max3_f32 v0, v0, v86, v87
	v_max3_f32 v0, v0, v88, v89
	v_max3_f32 v0, v0, v90, v91
	v_max3_f32 v0, v0, v92, v93
	v_max3_f32 v0, v0, v94, v95
	s_waitcnt lgkmcnt(1)
	v_mfma_f32_32x32x16_bf16 v[66:81], v[34:37], v[102:105], v[66:81]
	ds_read_b128 v[34:37], v196 offset:23136
	v_max3_f32 v0, v0, v96, v97
	s_waitcnt lgkmcnt(1)
	v_mfma_f32_32x32x16_bf16 v[66:81], v[38:41], v[106:109], v[66:81]
	s_waitcnt lgkmcnt(0)
	v_mfma_f32_32x32x16_bf16 v[66:81], v[34:37], v[110:113], v[66:81]
	v_and_b32_e32 v35, 64, v202
	v_xor_b32_e32 v34, 32, v202
	v_add_u32_e32 v35, 64, v35
	v_cmp_lt_i32_e32 vcc, v34, v35
	s_nop 1
	v_cndmask_b32_e32 v34, v202, v34, vcc
	s_nop 4
	v_max3_f32 v0, v0, v66, v67
	v_max3_f32 v0, v0, v68, v69
	v_max3_f32 v0, v0, v70, v71
	v_max3_f32 v0, v0, v72, v73
	v_max3_f32 v0, v0, v74, v75
	v_max3_f32 v0, v0, v76, v77
	v_max3_f32 v0, v0, v78, v79
	v_max3_f32 v0, v0, v80, v81
	v_lshlrev_b32_e32 v34, 2, v34
	ds_bpermute_b32 v34, v34, v0
	s_waitcnt lgkmcnt(0)
	v_max_f32_e32 v34, v34, v34
	v_max_f32_e32 v0, v0, v34
	v_mul_f32_e32 v0, 0x3fb8aa3b, v0
	v_max_f32_e32 v34, v158, v158
	v_max_f32_e32 v157, v34, v0
	v_sub_f32_e32 v0, v158, v157
	v_exp_f32_e32 v0, v0
	v_cmp_neq_f32_e32 vcc, v157, v158
	s_cbranch_vccz .LBB0_509
	v_pk_mul_f32 v[32:33], v[32:33], v[0:1] op_sel_hi:[1,0]
	v_pk_mul_f32 v[30:31], v[30:31], v[0:1] op_sel_hi:[1,0]
	v_pk_mul_f32 v[28:29], v[28:29], v[0:1] op_sel_hi:[1,0]
	v_pk_mul_f32 v[26:27], v[26:27], v[0:1] op_sel_hi:[1,0]
	v_pk_mul_f32 v[24:25], v[24:25], v[0:1] op_sel_hi:[1,0]
	v_pk_mul_f32 v[22:23], v[22:23], v[0:1] op_sel_hi:[1,0]
	v_pk_mul_f32 v[20:21], v[20:21], v[0:1] op_sel_hi:[1,0]
	v_pk_mul_f32 v[18:19], v[18:19], v[0:1] op_sel_hi:[1,0]
	v_pk_mul_f32 v[16:17], v[16:17], v[0:1] op_sel_hi:[1,0]
	v_pk_mul_f32 v[14:15], v[14:15], v[0:1] op_sel_hi:[1,0]
	v_pk_mul_f32 v[12:13], v[12:13], v[0:1] op_sel_hi:[1,0]
	v_pk_mul_f32 v[10:11], v[10:11], v[0:1] op_sel_hi:[1,0]
	v_pk_mul_f32 v[8:9], v[8:9], v[0:1] op_sel_hi:[1,0]
	v_pk_mul_f32 v[6:7], v[6:7], v[0:1] op_sel_hi:[1,0]
	v_pk_mul_f32 v[4:5], v[4:5], v[0:1] op_sel_hi:[1,0]
	v_pk_mul_f32 v[2:3], v[2:3], v[0:1] op_sel_hi:[1,0]
; DI unsigned pack2(float a, float b) { f32x2 v = {a, b}; bf16x2_t r = __builtin_convertvector(v, bf16x2_t); return __builtin_bit_cast(unsigned, r); }
; DI f32x16 mfma32(bf16x8 a, bf16x8 b, f32x16 c) { return __builtin_amdgcn_mfma_f32_32x32x16_bf16(a, b, c, 0, 0, 0); }
;     ...
;   float ps = 0.f;
; #pragma unroll
;   for (int k2 = 0; k2 < 2; ++k2)
; #pragma unroll
;     for (int i = 0; i < 16; ++i) {
;       if (!(HM & (1 << k2))) continue;
;       const float pv = (MODE == 1) ? __builtin_amdgcn_exp2f(s[k2][i] + neg) : __builtin_amdgcn_exp2f(fmaf(s[k2][i], L2E, neg));
;       s[k2][i] = pv; ps += pv;
;     }
;   l = l * alpha + ps;
;   if (__builtin_amdgcn_ballot_w64(mn != m) != 0ull) {
; #pragma unroll
;     for (int dt = 0; dt < 2; ++dt)
; #pragma unroll
;       for (int i = 0; i < 16; ++i) o[dt][i] *= alpha;
;   }
;   m = mn;
; #pragma unroll
;   for (int st = 0; st < 4; ++st) {
;     if (!(HM & (1 << (st >> 1)))) continue;
;     const int k2 = st >> 1, b8 = 8 * (st & 1);
;     const u32x4 pw = {pack2(s[k2][b8], s[k2][b8 + 1]), pack2(s[k2][b8 + 2], s[k2][b8 + 3]), pack2(s[k2][b8 + 4], s[k2][b8 + 5]), pack2(s[k2][b8 + 6], s[k2][b8 + 7])};
;     const bf16x8 pb = __builtin_bit_cast(bf16x8, pw);
; #pragma unroll
;     for (int dt = 0; dt < 2; ++dt) {
;       const s16x4 lo = *(const s16x4*)(Vs + (32 * dt + r) * LSTR + 16 * st + 4 * h);
;       const s16x4 hi = *(const s16x4*)(Vs + (32 * dt + r) * LSTR + 16 * st + 8 + 4 * h);
;       const bf16x8 a = __builtin_shufflevector(lo, hi, 0, 1, 2, 3, 4, 5, 6, 7);
;       o[dt] = mfma32(a, pb, o[dt]);
;     }
;   }
.LBB0_509:
	v_fma_f32 v82, v82, s34, -v157
	v_exp_f32_e32 v82, v82
	v_fma_f32 v83, v83, s34, -v157
	v_exp_f32_e32 v83, v83
	v_fma_f32 v84, v84, s34, -v157
	v_exp_f32_e32 v84, v84
	v_fma_f32 v85, v85, s34, -v157
	v_exp_f32_e32 v85, v85
	v_fma_f32 v86, v86, s34, -v157
	v_add_f32_e32 v159, 0, v82
	v_exp_f32_e32 v86, v86
	v_fma_f32 v87, v87, s34, -v157
	v_add_f32_e32 v159, v83, v159
	v_exp_f32_e32 v87, v87
	v_fma_f32 v88, v88, s34, -v157
	v_add_f32_e32 v159, v84, v159
	v_exp_f32_e32 v88, v88
	v_fma_f32 v89, v89, s34, -v157
	v_add_f32_e32 v159, v85, v159
	v_exp_f32_e32 v89, v89
	v_fma_f32 v90, v90, s34, -v157
	v_add_f32_e32 v159, v86, v159
	v_exp_f32_e32 v90, v90
	v_fma_f32 v91, v91, s34, -v157
	v_add_f32_e32 v159, v87, v159
	v_exp_f32_e32 v91, v91
	v_fma_f32 v92, v92, s34, -v157
	v_add_f32_e32 v159, v88, v159
	v_exp_f32_e32 v92, v92
	v_fma_f32 v93, v93, s34, -v157
	v_add_f32_e32 v159, v89, v159
	v_exp_f32_e32 v93, v93
	v_fma_f32 v94, v94, s34, -v157
	v_add_f32_e32 v159, v90, v159
	v_exp_f32_e32 v94, v94
	v_fma_f32 v95, v95, s34, -v157
	v_add_f32_e32 v159, v91, v159
	v_exp_f32_e32 v95, v95
	v_fma_f32 v96, v96, s34, -v157
	v_add_f32_e32 v159, v92, v159
	v_exp_f32_e32 v96, v96
	v_fma_f32 v97, v97, s34, -v157
	v_add_f32_e32 v159, v93, v159
	v_exp_f32_e32 v97, v97
	v_fma_f32 v66, v66, s34, -v157
	v_add_f32_e32 v159, v94, v159
	v_exp_f32_e32 v161, v66
	v_fma_f32 v67, v67, s34, -v157
	v_add_f32_e32 v159, v95, v159
	v_exp_f32_e32 v162, v67
	v_fma_f32 v67, v68, s34, -v157
	v_add_f32_e32 v159, v96, v159
	v_exp_f32_e32 v163, v67
	v_fma_f32 v67, v69, s34, -v157
	v_add_f32_e32 v159, v97, v159
	v_exp_f32_e32 v164, v67
	v_fma_f32 v67, v70, s34, -v157
	v_add_f32_e32 v66, v161, v159
	v_exp_f32_e32 v165, v67
	v_fma_f32 v67, v71, s34, -v157
	v_add_f32_e32 v66, v162, v66
	v_exp_f32_e32 v180, v67
	v_fma_f32 v67, v72, s34, -v157
	v_add_f32_e32 v66, v163, v66
	v_exp_f32_e32 v181, v67
	v_fma_f32 v67, v73, s34, -v157
	v_add_f32_e32 v66, v164, v66
	v_exp_f32_e32 v182, v67
	v_fma_f32 v67, v74, s34, -v157
	v_add_f32_e32 v66, v165, v66
	v_exp_f32_e32 v183, v67
	v_fma_f32 v67, v75, s34, -v157
	v_add_f32_e32 v66, v180, v66
	v_exp_f32_e32 v184, v67
	v_fma_f32 v67, v76, s34, -v157
	v_add_f32_e32 v66, v181, v66
	v_exp_f32_e32 v185, v67
	v_fma_f32 v67, v77, s34, -v157
	v_add_f32_e32 v66, v182, v66
	v_exp_f32_e32 v186, v67
	v_fma_f32 v67, v78, s34, -v157
	v_add_f32_e32 v66, v183, v66
	v_exp_f32_e32 v78, v67
	v_fma_f32 v67, v79, s34, -v157
	v_add_f32_e32 v66, v184, v66
	v_exp_f32_e32 v79, v67
	v_fma_f32 v67, v80, s34, -v157
	v_add_f32_e32 v66, v185, v66
	v_exp_f32_e32 v80, v67
	v_fma_f32 v67, v81, s34, -v157
	v_add_f32_e32 v66, v186, v66
	v_exp_f32_e32 v81, v67
	v_add_f32_e32 v66, v78, v66
	v_add_f32_e32 v66, v79, v66
	v_add_f32_e32 v66, v80, v66
	v_add_f32_e32 v159, v81, v66
	v_fmac_f32_e32 v159, v160, v0
	v_add_u32_e32 v0, 0x6800, v198
	ds_read2_b64 v[70:73], v0 offset0:128 offset1:130
	ds_read2_b64 v[74:77], v0 offset0:132 offset1:134
	v_cvt_pk_bf16_f32 v66, v82, v83
	v_cvt_pk_bf16_f32 v67, v84, v85
	v_cvt_pk_bf16_f32 v68, v86, v87
	v_cvt_pk_bf16_f32 v69, v88, v89
	v_add_u32_e32 v82, 0x7800, v198
	s_waitcnt lgkmcnt(1)
	v_mfma_f32_32x32x16_bf16 v[34:49], v[70:73], v[66:69], v[2:17]
	ds_read2_b64 v[70:73], v82 offset0:192 offset1:194
	s_waitcnt lgkmcnt(0)
	v_mfma_f32_32x32x16_bf16 v[50:65], v[70:73], v[66:69], v[18:33]
	ds_read2_b64 v[70:73], v82 offset0:196 offset1:198
	v_cvt_pk_bf16_f32 v66, v90, v91
	v_cvt_pk_bf16_f32 v67, v92, v93
	v_cvt_pk_bf16_f32 v68, v94, v95
	v_cvt_pk_bf16_f32 v69, v96, v97
	s_waitcnt lgkmcnt(0)
	s_nop 0
	v_mfma_f32_32x32x16_bf16 v[50:65], v[70:73], v[66:69], v[50:65]
	ds_read2_b64 v[70:73], v0 offset0:136 offset1:138
	v_mfma_f32_32x32x16_bf16 v[34:49], v[74:77], v[66:69], v[34:49]
	v_cvt_pk_bf16_f32 v66, v161, v162
	v_cvt_pk_bf16_f32 v67, v163, v164
	v_cvt_pk_bf16_f32 v68, v165, v180
	v_cvt_pk_bf16_f32 v69, v181, v182
	s_waitcnt lgkmcnt(0)
	s_nop 0
	v_mfma_f32_32x32x16_bf16 v[34:49], v[70:73], v[66:69], v[34:49]
	ds_read2_b64 v[70:73], v82 offset0:200 offset1:202
	s_waitcnt lgkmcnt(0)
	v_mfma_f32_32x32x16_bf16 v[50:65], v[70:73], v[66:69], v[50:65]
	ds_read2_b64 v[70:73], v0 offset0:140 offset1:142
	v_cvt_pk_bf16_f32 v66, v183, v184
	v_cvt_pk_bf16_f32 v67, v185, v186
	v_cvt_pk_bf16_f32 v68, v78, v79
	v_cvt_pk_bf16_f32 v69, v80, v81
	s_waitcnt lgkmcnt(0)
	s_nop 0
	v_mfma_f32_32x32x16_bf16 v[2:17], v[70:73], v[66:69], v[34:49]
	ds_read2_b64 v[70:73], v82 offset0:204 offset1:206
	s_waitcnt lgkmcnt(0)
	v_mfma_f32_32x32x16_bf16 v[18:33], v[70:73], v[66:69], v[50:65]

; DI unsigned pack2(float a, float b) { f32x2 v = {a, b}; bf16x2_t r = __builtin_convertvector(v, bf16x2_t); return __builtin_bit_cast(unsigned, r); }
; DI f32x16 mfma32(bf16x8 a, bf16x8 b, f32x16 c) { return __builtin_amdgcn_mfma_f32_32x32x16_bf16(a, b, c, 0, 0, 0); }
;     ...
;   float ps = 0.f;
; #pragma unroll
;   for (int k2 = 0; k2 < 2; ++k2)
; #pragma unroll
;     for (int i = 0; i < 16; ++i) {
;       if (!(HM & (1 << k2))) continue;
;       const float pv = (MODE == 1) ? __builtin_amdgcn_exp2f(s[k2][i] + neg) : __builtin_amdgcn_exp2f(fmaf(s[k2][i], L2E, neg));
;       s[k2][i] = pv; ps += pv;
;     }
;   l = l * alpha + ps;
;   if (__builtin_amdgcn_ballot_w64(mn != m) != 0ull) {
; #pragma unroll
;     for (int dt = 0; dt < 2; ++dt)
; #pragma unroll
;       for (int i = 0; i < 16; ++i) o[dt][i] *= alpha;
;   }
;   m = mn;
; #pragma unroll
;   for (int st = 0; st < 4; ++st) {
;     if (!(HM & (1 << (st >> 1)))) continue;
;     const int k2 = st >> 1, b8 = 8 * (st & 1);
;     const u32x4 pw = {pack2(s[k2][b8], s[k2][b8 + 1]), pack2(s[k2][b8 + 2], s[k2][b8 + 3]), pack2(s[k2][b8 + 4], s[k2][b8 + 5]), pack2(s[k2][b8 + 6], s[k2][b8 + 7])};
;     const bf16x8 pb = __builtin_bit_cast(bf16x8, pw);
; #pragma unroll
;     for (int dt = 0; dt < 2; ++dt) {
;       const s16x4 lo = *(const s16x4*)(Vs + (32 * dt + r) * LSTR + 16 * st + 4 * h);
;       const s16x4 hi = *(const s16x4*)(Vs + (32 * dt + r) * LSTR + 16 * st + 8 + 4 * h);
;       const bf16x8 a = __builtin_shufflevector(lo, hi, 0, 1, 2, 3, 4, 5, 6, 7);
;       o[dt] = mfma32(a, pb, o[dt]);
;     }
;   }
.LBB0_516:
	v_fma_f32 v34, v34, s34, -v157
	v_exp_f32_e32 v46, v34
	v_fma_f32 v34, v35, s34, -v157
	v_exp_f32_e32 v47, v34
	v_fma_f32 v34, v36, s34, -v157
	v_exp_f32_e32 v48, v34
	v_fma_f32 v34, v37, s34, -v157
	v_add_f32_e32 v35, 0, v46
	v_exp_f32_e32 v49, v34
	v_fma_f32 v34, v38, s34, -v157
	v_add_f32_e32 v35, v47, v35
	v_exp_f32_e32 v38, v34
	v_fma_f32 v34, v39, s34, -v157
	v_exp_f32_e32 v39, v34
	v_add_f32_e32 v34, v48, v35
	v_fma_f32 v35, v50, s34, -v157
	v_exp_f32_e32 v50, v35
	v_fma_f32 v35, v51, s34, -v157
	v_add_f32_e32 v34, v49, v34
	v_exp_f32_e32 v51, v35
	v_fma_f32 v35, v52, s34, -v157
	v_add_f32_e32 v34, v38, v34
	v_exp_f32_e32 v52, v35
	v_fma_f32 v35, v53, s34, -v157
	v_add_f32_e32 v34, v39, v34
	v_exp_f32_e32 v53, v35
	v_add_f32_e32 v34, v50, v34
	v_add_f32_e32 v34, v51, v34
	v_add_f32_e32 v34, v52, v34
	v_add_f32_e32 v54, v53, v34
	v_fma_f32 v34, v44, s34, -v157
	v_fma_f32 v44, v45, s34, -v157
	v_add_u32_e32 v56, 0x6800, v198
	v_exp_f32_e32 v55, v34
	ds_read2_b64 v[34:37], v56 offset0:128 offset1:130
	v_exp_f32_e32 v57, v44
	v_cvt_pk_bf16_f32 v44, v46, v47
	v_cvt_pk_bf16_f32 v46, v38, v39
	v_add_u32_e32 v38, v199, v200
	v_add_u32_e32 v38, 0x7800, v38
	v_cvt_pk_bf16_f32 v45, v48, v49
	v_cvt_pk_bf16_f32 v47, v50, v51
	ds_read2_b64 v[48:51], v38 offset0:192 offset1:194
	v_fma_f32 v39, v40, s34, -v157
	s_waitcnt lgkmcnt(1)
	v_mfma_f32_32x32x16_bf16 v[2:17], v[34:37], v[44:47], v[2:17]
	v_fma_f32 v34, v41, s34, -v157
	v_exp_f32_e32 v58, v34
	v_fma_f32 v34, v42, s34, -v157
	v_exp_f32_e32 v59, v34
	v_fma_f32 v34, v43, s34, -v157
	v_exp_f32_e32 v60, v34
	ds_read2_b64 v[34:37], v56 offset0:132 offset1:134
	s_waitcnt lgkmcnt(1)
	v_mfma_f32_32x32x16_bf16 v[18:33], v[48:51], v[44:47], v[18:33]
	v_exp_f32_e32 v46, v39
	ds_read2_b64 v[38:41], v38 offset0:196 offset1:198
	v_cvt_pk_bf16_f32 v42, v52, v53
	v_cvt_pk_bf16_f32 v43, v55, v57
	v_cvt_pk_bf16_f32 v44, v58, v59
	v_cvt_pk_bf16_f32 v45, v60, v46
	s_waitcnt lgkmcnt(0)
	s_nop 0
	v_mfma_f32_32x32x16_bf16 v[18:33], v[38:41], v[42:45], v[18:33]
	v_mfma_f32_32x32x16_bf16 v[2:17], v[34:37], v[42:45], v[2:17]
	v_add_f32_e32 v34, v55, v54
	v_add_f32_e32 v34, v57, v34
	v_add_f32_e32 v34, v58, v34
	v_add_f32_e32 v34, v59, v34
	v_add_f32_e32 v34, v60, v34
	v_add_f32_e32 v159, v46, v34
	s_nop 4
	v_fmac_f32_e32 v159, v160, v0

;     ...
;   f32x16 s[2];
; #pragma unroll
;   for (int k2 = 0; k2 < 2; ++k2) {
;     if (!(HM & (1 << k2))) continue;
; #pragma unroll
;     for (int i = 0; i < 16; ++i) s[k2][i] = 0.f;
; #pragma unroll
;     for (int ks = 0; ks < 4; ++ks) {
;       const bf16x8 a = *(const bf16x8*)(Ks + (32 * k2 + r) * LSTR + 16 * ks + 8 * h);
;       s[k2] = mfma32(a, qf[ks], s[k2]);
;     }
;   }
;   if (MODE == 1) {
; #pragma unroll
;     for (int k2 = 0; k2 < 2; ++k2)
; #pragma unroll
;       for (int g = 0; g < 4; ++g) {
;         if (!(HM & (1 << k2))) continue;
;         const f32x4 cv = *(const f32x4*)(cn_lds + key0 + 32 * k2 + 8 * g + 4 * h);
; #pragma unroll
;         for (int e = 0; e < 4; ++e) s[k2][4 * g + e] = fmaf(s[k2][4 * g + e], L2E, cv[e]);
;       }
;   }
;   float mx = NINF;
; #pragma unroll
;   for (int k2 = 0; k2 < 2; ++k2)
; #pragma unroll
;     for (int i = 0; i < 16; ++i) {
;       if (!(HM & (1 << k2))) continue;
;       float v = s[k2][i];
;       if (MASKED) {
;         const int tk = key0 + 32 * k2 + crow(i, h);
;         const bool valid = (MODE == 0) ? ((tk <= tq) && (tq - tk <= maxdist)) : (tk <= tq);
;         v = valid ? v : NINF; s[k2][i] = v;
;       }
;       mx = fmaxf(mx, v);
;     }
;   mx = fmaxf(mx, __shfl_xor(mx, 32));
;   if (MODE != 1) mx *= L2E;
;   if (MODE == 2) mx = lanesel ? mx : NINF;
; template <int MODE>
; DI void flash_loop(char* smem, const bf16_t* Kbase, size_t ldk, const bf16_t* Vtbase, size_t ldv, ull tiles, ull wtiles,
;                    const bf16x8 (&qf)[4], f32x16 (&o)[2], float& m, float& l, int tq, int tqmin, int tqmax, int maxdist, const float* cn_lds, ull lmask) {
;     ...
;     if (!((wtiles >> kt) & 1ull)) return;
;     const bf16_t* Ks = (const bf16_t*)(smem + stage * (2 * 64 * LSTR * 2)); const bf16_t* Vs = Ks + 64 * LSTR;
;     const bool sel = ((lmask >> kt) & 1ull) != 0;
;     const bool interior = (64 * kt + 63 <= tqmin) && (MODE != 0 || (tqmax - 64 * kt <= maxdist));
;     int hm = 3;
;     if (MODE == 0) {
;       hm = 0;
;       if (64 * kt <= tqmax && 64 * kt + 31 >= tqmin - maxdist) hm |= 1;
;       if (64 * kt + 32 <= tqmax && 64 * kt + 63 >= tqmin - maxdist) hm |= 2;
;     }
;     if (MODE == 0 && hm == 1) attn_tile<MODE, true, 1>(Ks, Vs, qf, o, m, l, 64 * kt, tq, maxdist, cn_lds, sel);
;     else if (MODE == 0 && hm == 2) attn_tile<MODE, true, 2>(Ks, Vs, qf, o, m, l, 64 * kt, tq, maxdist, cn_lds, sel);
.LBB0_622:
	s_lshr_b64 s[6:7], s[4:5], s65
	s_and_b32 s58, s6, 1
	s_cmp_eq_u64 s[58:59], 0
	s_cbranch_scc1 .LBB0_646
	s_lshl_b32 s58, s65, 6
	s_or_b32 s33, s58, 63
	s_cmp_le_u32 s58, s30
	s_cselect_b64 s[6:7], -1, 0
	s_or_b32 s36, s58, 31
	s_cmp_ge_i32 s36, s29
	s_cselect_b64 s[36:37], -1, 0
	s_and_b64 s[6:7], s[6:7], s[36:37]
	v_cndmask_b32_e64 v0, 0, 1, s[6:7]
	s_or_b32 s6, s58, 32
	s_cmp_gt_u32 s6, s30
	s_cselect_b64 s[6:7], -1, 0
	s_cmp_lt_i32 s33, s29
	s_cselect_b64 s[36:37], -1, 0
	v_or_b32_e32 v34, 2, v0
	s_or_b64 vcc, s[6:7], s[36:37]
	v_cndmask_b32_e32 v66, v34, v0, vcc
	v_cmp_gt_i32_e32 vcc, 2, v66
	s_mov_b64 s[62:63], -1
	s_mov_b64 s[54:55], 0
	s_and_b64 vcc, exec, vcc
	s_mov_b64 s[6:7], 0
	s_cbranch_vccnz .LBB0_639
	v_cmp_eq_u32_e32 vcc, 2, v66
	s_and_b64 vcc, exec, vcc
	s_mov_b64 s[6:7], -1
	s_cbranch_vccz .LBB0_628
	ds_read_b128 v[34:37], v199 offset:23040
	ds_read_b128 v[50:53], v199 offset:23072
	v_or_b32_e32 v0, s58, v197
	s_waitcnt lgkmcnt(1)
	v_mfma_f32_32x32x16_bf16 v[34:49], v[34:37], v[98:101], 0
	s_waitcnt lgkmcnt(0)
	v_mfma_f32_32x32x16_bf16 v[34:49], v[50:53], v[102:105], v[34:49]
	ds_read_b128 v[50:53], v199 offset:23104
	s_waitcnt lgkmcnt(0)
	v_mfma_f32_32x32x16_bf16 v[34:49], v[50:53], v[106:109], v[34:49]
	ds_read_b128 v[50:53], v199 offset:23136
	s_waitcnt lgkmcnt(0)
	v_mfma_f32_32x32x16_bf16 v[34:49], v[50:53], v[110:113], v[34:49]
	v_or_b32_e32 v50, 32, v0
	v_cmp_gt_u32_e32 vcc, v50, v154
	v_cmp_lt_i32_e64 s[6:7], v50, v155
	s_or_b64 vcc, vcc, s[6:7]
	s_nop 7
	v_cndmask_b32_e32 v67, v34, v204, vcc
	v_bitop3_b32 v34, s58, v205, v197 bitop3:0x36
	v_cmp_ge_u32_e32 vcc, v50, v154
	v_cmp_gt_i32_e64 s[6:7], v34, v156
	s_or_b64 vcc, vcc, s[6:7]
	v_cndmask_b32_e32 v68, v35, v204, vcc
	v_or_b32_e32 v35, 34, v0
	v_cmp_gt_u32_e32 vcc, v35, v154
	v_cmp_lt_i32_e64 s[6:7], v35, v155
	s_or_b64 vcc, vcc, s[6:7]
	v_or_b32_e32 v35, 35, v0
	v_cndmask_b32_e32 v69, v36, v204, vcc
	v_cmp_gt_u32_e32 vcc, v35, v154
	v_cmp_lt_i32_e64 s[6:7], v35, v155
	s_or_b64 vcc, vcc, s[6:7]
	v_or_b32_e32 v35, 40, v0
	v_cndmask_b32_e32 v70, v37, v204, vcc
	v_cmp_gt_u32_e32 vcc, v35, v154
	v_cmp_lt_i32_e64 s[6:7], v35, v155
	s_or_b64 vcc, vcc, s[6:7]
	v_or_b32_e32 v35, 41, v0
	v_cndmask_b32_e32 v71, v38, v204, vcc
	v_cmp_gt_u32_e32 vcc, v35, v154
	v_cmp_lt_i32_e64 s[6:7], v35, v155
	s_or_b64 vcc, vcc, s[6:7]
	v_or_b32_e32 v35, 42, v0
	v_cndmask_b32_e32 v72, v39, v204, vcc
	v_cmp_gt_u32_e32 vcc, v35, v154
	v_cmp_lt_i32_e64 s[6:7], v35, v155
	s_or_b64 vcc, vcc, s[6:7]
	v_or_b32_e32 v35, 43, v0
	v_cndmask_b32_e32 v77, v40, v204, vcc
	v_cmp_gt_u32_e32 vcc, v35, v154
	v_cmp_lt_i32_e64 s[6:7], v35, v155
	s_or_b64 vcc, vcc, s[6:7]
	v_or_b32_e32 v35, 48, v0
	v_cndmask_b32_e32 v78, v41, v204, vcc
	v_cmp_gt_u32_e32 vcc, v35, v154
	v_cmp_lt_i32_e64 s[6:7], v35, v155
	s_or_b64 vcc, vcc, s[6:7]
	v_or_b32_e32 v35, 49, v0
	v_cndmask_b32_e32 v79, v42, v204, vcc
	v_cmp_gt_u32_e32 vcc, v35, v154
	v_cmp_lt_i32_e64 s[6:7], v35, v155
	s_or_b64 vcc, vcc, s[6:7]
	v_or_b32_e32 v35, 50, v0
	v_cndmask_b32_e32 v80, v43, v204, vcc
	v_cmp_gt_u32_e32 vcc, v35, v154
	v_cmp_lt_i32_e64 s[6:7], v35, v155
	s_or_b64 vcc, vcc, s[6:7]
	v_or_b32_e32 v35, 51, v0
	v_cndmask_b32_e32 v81, v44, v204, vcc
	v_cmp_gt_u32_e32 vcc, v35, v154
	v_cmp_lt_i32_e64 s[6:7], v35, v155
	s_or_b64 vcc, vcc, s[6:7]
	v_or_b32_e32 v35, 56, v0
	v_cndmask_b32_e32 v82, v45, v204, vcc
	v_cmp_gt_u32_e32 vcc, v35, v154
	v_cmp_lt_i32_e64 s[6:7], v35, v155
	s_or_b64 vcc, vcc, s[6:7]
	v_or_b32_e32 v35, 57, v0
	v_max3_f32 v34, v67, s35, v68
	v_cndmask_b32_e32 v74, v46, v204, vcc
	v_cmp_gt_u32_e32 vcc, v35, v154
	v_cmp_lt_i32_e64 s[6:7], v35, v155
	v_max3_f32 v34, v34, v69, v70
	s_or_b64 vcc, vcc, s[6:7]
	v_or_b32_e32 v35, 58, v0
	v_max3_f32 v34, v34, v71, v72
	v_cndmask_b32_e32 v75, v47, v204, vcc
	v_cmp_gt_u32_e32 vcc, v35, v154
	v_cmp_lt_i32_e64 s[6:7], v35, v155
	v_max3_f32 v34, v34, v77, v78
	s_or_b64 vcc, vcc, s[6:7]
	v_or_b32_e32 v0, 59, v0
	v_max3_f32 v34, v34, v79, v80
	v_cndmask_b32_e32 v76, v48, v204, vcc
	v_cmp_gt_u32_e32 vcc, v0, v154
	v_cmp_lt_i32_e64 s[6:7], v0, v155
	v_max3_f32 v34, v34, v81, v82
	s_or_b64 vcc, vcc, s[6:7]
	v_max3_f32 v34, v34, v74, v75
	v_cndmask_b32_e32 v73, v49, v204, vcc
	v_and_b32_e32 v35, 64, v202
	v_max3_f32 v0, v34, v76, v73
	v_xor_b32_e32 v34, 32, v202
	v_add_u32_e32 v35, 64, v35
	v_cmp_lt_i32_e32 vcc, v34, v35
	s_nop 1
	v_cndmask_b32_e32 v34, v202, v34, vcc
	v_lshlrev_b32_e32 v34, 2, v34
	ds_bpermute_b32 v34, v34, v0
	s_waitcnt lgkmcnt(0)
	v_max_f32_e32 v34, v34, v34
	v_max_f32_e32 v0, v0, v34
	v_mul_f32_e32 v0, 0x3fb8aa3b, v0
	v_max_f32_e32 v34, v158, v158
	v_max_f32_e32 v157, v34, v0
	v_sub_f32_e32 v0, v158, v157
	v_exp_f32_e32 v0, v0
	v_cmp_neq_f32_e32 vcc, v157, v158
	s_cbranch_vccz .LBB0_627
	v_pk_mul_f32 v[32:33], v[32:33], v[0:1] op_sel_hi:[1,0]
	v_pk_mul_f32 v[30:31], v[30:31], v[0:1] op_sel_hi:[1,0]
	v_pk_mul_f32 v[28:29], v[28:29], v[0:1] op_sel_hi:[1,0]
	v_pk_mul_f32 v[26:27], v[26:27], v[0:1] op_sel_hi:[1,0]
	v_pk_mul_f32 v[24:25], v[24:25], v[0:1] op_sel_hi:[1,0]
	v_pk_mul_f32 v[22:23], v[22:23], v[0:1] op_sel_hi:[1,0]
	v_pk_mul_f32 v[20:21], v[20:21], v[0:1] op_sel_hi:[1,0]
	v_pk_mul_f32 v[18:19], v[18:19], v[0:1] op_sel_hi:[1,0]
	v_pk_mul_f32 v[16:17], v[16:17], v[0:1] op_sel_hi:[1,0]
	v_pk_mul_f32 v[14:15], v[14:15], v[0:1] op_sel_hi:[1,0]
	v_pk_mul_f32 v[12:13], v[12:13], v[0:1] op_sel_hi:[1,0]
	v_pk_mul_f32 v[10:11], v[10:11], v[0:1] op_sel_hi:[1,0]
	v_pk_mul_f32 v[8:9], v[8:9], v[0:1] op_sel_hi:[1,0]
	v_pk_mul_f32 v[6:7], v[6:7], v[0:1] op_sel_hi:[1,0]
	v_pk_mul_f32 v[4:5], v[4:5], v[0:1] op_sel_hi:[1,0]
	v_pk_mul_f32 v[2:3], v[2:3], v[0:1] op_sel_hi:[1,0]
; DI unsigned pack2(float a, float b) { f32x2 v = {a, b}; bf16x2_t r = __builtin_convertvector(v, bf16x2_t); return __builtin_bit_cast(unsigned, r); }
; DI f32x16 mfma32(bf16x8 a, bf16x8 b, f32x16 c) { return __builtin_amdgcn_mfma_f32_32x32x16_bf16(a, b, c, 0, 0, 0); }
;     ...
;   float ps = 0.f;
; #pragma unroll
;   for (int k2 = 0; k2 < 2; ++k2)
; #pragma unroll
;     for (int i = 0; i < 16; ++i) {
;       if (!(HM & (1 << k2))) continue;
;       const float pv = (MODE == 1) ? __builtin_amdgcn_exp2f(s[k2][i] + neg) : __builtin_amdgcn_exp2f(fmaf(s[k2][i], L2E, neg));
;       s[k2][i] = pv; ps += pv;
;     }
;   l = l * alpha + ps;
;   if (__builtin_amdgcn_ballot_w64(mn != m) != 0ull) {
; #pragma unroll
;     for (int dt = 0; dt < 2; ++dt)
; #pragma unroll
;       for (int i = 0; i < 16; ++i) o[dt][i] *= alpha;
;   }
;   m = mn;
; #pragma unroll
;   for (int st = 0; st < 4; ++st) {
;     if (!(HM & (1 << (st >> 1)))) continue;
;     const int k2 = st >> 1, b8 = 8 * (st & 1);
;     const u32x4 pw = {pack2(s[k2][b8], s[k2][b8 + 1]), pack2(s[k2][b8 + 2], s[k2][b8 + 3]), pack2(s[k2][b8 + 4], s[k2][b8 + 5]), pack2(s[k2][b8 + 6], s[k2][b8 + 7])};
;     const bf16x8 pb = __builtin_bit_cast(bf16x8, pw);
; #pragma unroll
;     for (int dt = 0; dt < 2; ++dt) {
;       const s16x4 lo = *(const s16x4*)(Vs + (32 * dt + r) * LSTR + 16 * st + 4 * h);
;       const s16x4 hi = *(const s16x4*)(Vs + (32 * dt + r) * LSTR + 16 * st + 8 + 4 * h);
;       const bf16x8 a = __builtin_shufflevector(lo, hi, 0, 1, 2, 3, 4, 5, 6, 7);
;       o[dt] = mfma32(a, pb, o[dt]);
;     }
;   }
.LBB0_627:
	v_fma_f32 v67, v67, s34, -v157
	v_exp_f32_e32 v67, v67
	v_fma_f32 v68, v68, s34, -v157
	v_exp_f32_e32 v83, v68
	v_fma_f32 v68, v69, s34, -v157
	v_exp_f32_e32 v84, v68
	v_fma_f32 v68, v70, s34, -v157
	v_add_f32_e32 v69, 0, v67
	v_exp_f32_e32 v85, v68
	v_fma_f32 v68, v71, s34, -v157
	v_add_f32_e32 v69, v83, v69
	v_exp_f32_e32 v86, v68
	v_fma_f32 v68, v72, s34, -v157
	v_exp_f32_e32 v72, v68
	v_add_f32_e32 v68, v84, v69
	v_fma_f32 v69, v77, s34, -v157
	v_exp_f32_e32 v77, v69
	v_fma_f32 v69, v78, s34, -v157
	v_add_f32_e32 v68, v85, v68
	v_exp_f32_e32 v87, v69
	v_fma_f32 v69, v79, s34, -v157
	v_add_f32_e32 v68, v86, v68
	v_exp_f32_e32 v88, v69
	v_fma_f32 v69, v80, s34, -v157
	v_add_f32_e32 v68, v72, v68
	v_exp_f32_e32 v89, v69
	v_add_f32_e32 v68, v77, v68
	v_add_f32_e32 v68, v87, v68
	v_add_f32_e32 v68, v88, v68
	v_add_f32_e32 v90, v89, v68
	v_fma_f32 v68, v81, s34, -v157
	v_add_u32_e32 v92, 0x6800, v198
	v_exp_f32_e32 v91, v68
	v_fma_f32 v78, v82, s34, -v157
	ds_read2_b64 v[68:71], v92 offset0:136 offset1:138
	v_exp_f32_e32 v93, v78
	v_cvt_pk_bf16_f32 v78, v67, v83
	v_add_u32_e32 v67, v199, v200
	v_add_u32_e32 v67, 0x7800, v67
	v_cvt_pk_bf16_f32 v79, v84, v85
	ds_read2_b64 v[82:85], v67 offset0:200 offset1:202
	v_cvt_pk_bf16_f32 v80, v86, v72
	v_cvt_pk_bf16_f32 v81, v77, v87
	v_fma_f32 v72, v73, s34, -v157
	v_cvt_pk_bf16_f32 v77, v91, v93
	s_waitcnt lgkmcnt(1)
	v_mfma_f32_32x32x16_bf16 v[34:49], v[68:71], v[78:81], v[2:17]
	v_fma_f32 v68, v74, s34, -v157
	v_exp_f32_e32 v86, v68
	v_fma_f32 v68, v75, s34, -v157
	v_exp_f32_e32 v87, v68
	v_fma_f32 v68, v76, s34, -v157
	v_exp_f32_e32 v94, v68
	ds_read2_b64 v[68:71], v92 offset0:140 offset1:142
	s_waitcnt lgkmcnt(1)
	v_mfma_f32_32x32x16_bf16 v[50:65], v[82:85], v[78:81], v[18:33]
	v_exp_f32_e32 v80, v72
	ds_read2_b64 v[72:75], v67 offset0:204 offset1:206
	v_cvt_pk_bf16_f32 v76, v88, v89
	v_cvt_pk_bf16_f32 v78, v86, v87
	v_cvt_pk_bf16_f32 v79, v94, v80
	v_add_f32_e32 v67, v91, v90
	v_add_f32_e32 v67, v93, v67
	s_waitcnt lgkmcnt(1)
	v_mfma_f32_32x32x16_bf16 v[2:17], v[68:71], v[76:79], v[34:49]
	v_add_f32_e32 v67, v86, v67
	v_add_f32_e32 v67, v87, v67
	v_add_f32_e32 v67, v94, v67
	v_add_f32_e32 v159, v80, v67
	v_fmac_f32_e32 v159, v160, v0
	s_mov_b64 s[6:7], 0
	s_waitcnt lgkmcnt(0)
	v_mfma_f32_32x32x16_bf16 v[18:33], v[72:75], v[76:79], v[50:65]

;     ...
;   f32x16 s[2];
; #pragma unroll
;   for (int k2 = 0; k2 < 2; ++k2) {
;     if (!(HM & (1 << k2))) continue;
; #pragma unroll
;     for (int i = 0; i < 16; ++i) s[k2][i] = 0.f;
; #pragma unroll
;     for (int ks = 0; ks < 4; ++ks) {
;       const bf16x8 a = *(const bf16x8*)(Ks + (32 * k2 + r) * LSTR + 16 * ks + 8 * h);
;       s[k2] = mfma32(a, qf[ks], s[k2]);
;     }
;   }
;   if (MODE == 1) {
; #pragma unroll
;     for (int k2 = 0; k2 < 2; ++k2)
; #pragma unroll
;       for (int g = 0; g < 4; ++g) {
;         if (!(HM & (1 << k2))) continue;
;         const f32x4 cv = *(const f32x4*)(cn_lds + key0 + 32 * k2 + 8 * g + 4 * h);
; #pragma unroll
;         for (int e = 0; e < 4; ++e) s[k2][4 * g + e] = fmaf(s[k2][4 * g + e], L2E, cv[e]);
;       }
;   }
;   float mx = NINF;
; #pragma unroll
;   for (int k2 = 0; k2 < 2; ++k2)
; #pragma unroll
;     for (int i = 0; i < 16; ++i) {
;       if (!(HM & (1 << k2))) continue;
;       float v = s[k2][i];
;       if (MASKED) {
;         const int tk = key0 + 32 * k2 + crow(i, h);
;         const bool valid = (MODE == 0) ? ((tk <= tq) && (tq - tk <= maxdist)) : (tk <= tq);
;         v = valid ? v : NINF; s[k2][i] = v;
;       }
;       mx = fmaxf(mx, v);
;     }
;   mx = fmaxf(mx, __shfl_xor(mx, 32));
;   if (MODE != 1) mx *= L2E;
;   if (MODE == 2) mx = lanesel ? mx : NINF;
; template <int MODE>
; DI void flash_loop(char* smem, const bf16_t* Kbase, size_t ldk, const bf16_t* Vtbase, size_t ldv, ull tiles, ull wtiles,
;                    const bf16x8 (&qf)[4], f32x16 (&o)[2], float& m, float& l, int tq, int tqmin, int tqmax, int maxdist, const float* cn_lds, ull lmask) {
;     ...
;     if (!((wtiles >> kt) & 1ull)) return;
;     const bf16_t* Ks = (const bf16_t*)(smem + stage * (2 * 64 * LSTR * 2)); const bf16_t* Vs = Ks + 64 * LSTR;
;     const bool sel = ((lmask >> kt) & 1ull) != 0;
;     const bool interior = (64 * kt + 63 <= tqmin) && (MODE != 0 || (tqmax - 64 * kt <= maxdist));
;     int hm = 3;
;     if (MODE == 0) {
;       hm = 0;
;       if (64 * kt <= tqmax && 64 * kt + 31 >= tqmin - maxdist) hm |= 1;
;       if (64 * kt + 32 <= tqmax && 64 * kt + 63 >= tqmin - maxdist) hm |= 2;
;     }
;     if (MODE == 0 && hm == 1) attn_tile<MODE, true, 1>(Ks, Vs, qf, o, m, l, 64 * kt, tq, maxdist, cn_lds, sel);
;     else if (MODE == 0 && hm == 2) attn_tile<MODE, true, 2>(Ks, Vs, qf, o, m, l, 64 * kt, tq, maxdist, cn_lds, sel);
.LBB0_662:
	s_lshr_b64 s[6:7], s[4:5], s33
	s_and_b32 s58, s6, 1
	s_cmp_eq_u64 s[58:59], 0
	s_cbranch_scc1 .LBB0_686
	s_lshl_b32 s58, s33, 6
	s_or_b32 s33, s58, 63
	s_cmp_le_u32 s58, s31
	s_cselect_b64 s[6:7], -1, 0
	s_or_b32 s36, s58, 31
	s_cmp_ge_i32 s36, s30
	s_cselect_b64 s[36:37], -1, 0
	s_and_b64 s[6:7], s[6:7], s[36:37]
	v_cndmask_b32_e64 v0, 0, 1, s[6:7]
	s_or_b32 s6, s58, 32
	s_cmp_gt_u32 s6, s31
	s_cselect_b64 s[6:7], -1, 0
	s_cmp_lt_i32 s33, s30
	s_cselect_b64 s[36:37], -1, 0
	v_readfirstlane_b32 s38, v0
	s_or_b32 s39, s38, 2
	s_or_b64 s[6:7], s[6:7], s[36:37]
	s_and_b64 s[6:7], s[6:7], exec
	s_cselect_b32 s68, s38, s39
	s_mov_b64 s[62:63], -1
	s_mov_b64 s[54:55], 0
	s_cmp_lt_i32 s68, 2
	s_mov_b64 s[6:7], 0
	s_cbranch_scc1 .LBB0_679
	s_cmp_eq_u32 s68, 2
	s_mov_b64 s[6:7], -1
	s_cbranch_scc0 .LBB0_668
	ds_read_b128 v[34:37], v199 offset:4608
	ds_read_b128 v[50:53], v199 offset:4640
	v_or_b32_e32 v0, s58, v197
	s_waitcnt lgkmcnt(1)
	v_mfma_f32_32x32x16_bf16 v[34:49], v[34:37], v[98:101], 0
	s_waitcnt lgkmcnt(0)
	v_mfma_f32_32x32x16_bf16 v[34:49], v[50:53], v[102:105], v[34:49]
	ds_read_b128 v[50:53], v199 offset:4672
	s_waitcnt lgkmcnt(0)
	v_mfma_f32_32x32x16_bf16 v[34:49], v[50:53], v[106:109], v[34:49]
	ds_read_b128 v[50:53], v199 offset:4704
	s_waitcnt lgkmcnt(0)
	v_mfma_f32_32x32x16_bf16 v[34:49], v[50:53], v[110:113], v[34:49]
	v_or_b32_e32 v50, 32, v0
	v_cmp_gt_u32_e32 vcc, v50, v154
	v_cmp_lt_i32_e64 s[6:7], v50, v155
	s_or_b64 vcc, vcc, s[6:7]
	s_nop 7
	v_cndmask_b32_e32 v66, v34, v204, vcc
	v_bitop3_b32 v34, s58, v205, v197 bitop3:0x36
	v_cmp_ge_u32_e32 vcc, v50, v154
	v_cmp_gt_i32_e64 s[6:7], v34, v156
	s_or_b64 vcc, vcc, s[6:7]
	v_cndmask_b32_e32 v67, v35, v204, vcc
	v_or_b32_e32 v35, 34, v0
	v_cmp_gt_u32_e32 vcc, v35, v154
	v_cmp_lt_i32_e64 s[6:7], v35, v155
	s_or_b64 vcc, vcc, s[6:7]
	v_or_b32_e32 v35, 35, v0
	v_cndmask_b32_e32 v68, v36, v204, vcc
	v_cmp_gt_u32_e32 vcc, v35, v154
	v_cmp_lt_i32_e64 s[6:7], v35, v155
	s_or_b64 vcc, vcc, s[6:7]
	v_or_b32_e32 v35, 40, v0
	v_cndmask_b32_e32 v69, v37, v204, vcc
	v_cmp_gt_u32_e32 vcc, v35, v154
	v_cmp_lt_i32_e64 s[6:7], v35, v155
	s_or_b64 vcc, vcc, s[6:7]
	v_or_b32_e32 v35, 41, v0
	v_cndmask_b32_e32 v70, v38, v204, vcc
	v_cmp_gt_u32_e32 vcc, v35, v154
	v_cmp_lt_i32_e64 s[6:7], v35, v155
	s_or_b64 vcc, vcc, s[6:7]
	v_or_b32_e32 v35, 42, v0
	v_cndmask_b32_e32 v71, v39, v204, vcc
	v_cmp_gt_u32_e32 vcc, v35, v154
	v_cmp_lt_i32_e64 s[6:7], v35, v155
	s_or_b64 vcc, vcc, s[6:7]
	v_or_b32_e32 v35, 43, v0
	v_cndmask_b32_e32 v77, v40, v204, vcc
	v_cmp_gt_u32_e32 vcc, v35, v154
	v_cmp_lt_i32_e64 s[6:7], v35, v155
	s_or_b64 vcc, vcc, s[6:7]
	v_or_b32_e32 v35, 48, v0
	v_cndmask_b32_e32 v78, v41, v204, vcc
	v_cmp_gt_u32_e32 vcc, v35, v154
	v_cmp_lt_i32_e64 s[6:7], v35, v155
	s_or_b64 vcc, vcc, s[6:7]
	v_or_b32_e32 v35, 49, v0
	v_cndmask_b32_e32 v79, v42, v204, vcc
	v_cmp_gt_u32_e32 vcc, v35, v154
	v_cmp_lt_i32_e64 s[6:7], v35, v155
	s_or_b64 vcc, vcc, s[6:7]
	v_or_b32_e32 v35, 50, v0
	v_cndmask_b32_e32 v80, v43, v204, vcc
	v_cmp_gt_u32_e32 vcc, v35, v154
	v_cmp_lt_i32_e64 s[6:7], v35, v155
	s_or_b64 vcc, vcc, s[6:7]
	v_or_b32_e32 v35, 51, v0
	v_cndmask_b32_e32 v81, v44, v204, vcc
	v_cmp_gt_u32_e32 vcc, v35, v154
	v_cmp_lt_i32_e64 s[6:7], v35, v155
	s_or_b64 vcc, vcc, s[6:7]
	v_or_b32_e32 v35, 56, v0
	v_cndmask_b32_e32 v76, v45, v204, vcc
	v_cmp_gt_u32_e32 vcc, v35, v154
	v_cmp_lt_i32_e64 s[6:7], v35, v155
	s_or_b64 vcc, vcc, s[6:7]
	v_or_b32_e32 v35, 57, v0
	v_max3_f32 v34, v66, s35, v67
	v_cndmask_b32_e32 v73, v46, v204, vcc
	v_cmp_gt_u32_e32 vcc, v35, v154
	v_cmp_lt_i32_e64 s[6:7], v35, v155
	v_max3_f32 v34, v34, v68, v69
	s_or_b64 vcc, vcc, s[6:7]
	v_or_b32_e32 v35, 58, v0
	v_max3_f32 v34, v34, v70, v71
	v_cndmask_b32_e32 v74, v47, v204, vcc
	v_cmp_gt_u32_e32 vcc, v35, v154
	v_cmp_lt_i32_e64 s[6:7], v35, v155
	v_max3_f32 v34, v34, v77, v78
	s_or_b64 vcc, vcc, s[6:7]
	v_or_b32_e32 v0, 59, v0
	v_max3_f32 v34, v34, v79, v80
	v_cndmask_b32_e32 v75, v48, v204, vcc
	v_cmp_gt_u32_e32 vcc, v0, v154
	v_cmp_lt_i32_e64 s[6:7], v0, v155
	v_max3_f32 v34, v34, v81, v76
	s_or_b64 vcc, vcc, s[6:7]
	v_max3_f32 v34, v34, v73, v74
	v_cndmask_b32_e32 v72, v49, v204, vcc
	v_and_b32_e32 v35, 64, v202
	v_max3_f32 v0, v34, v75, v72
	v_xor_b32_e32 v34, 32, v202
	v_add_u32_e32 v35, 64, v35
	v_cmp_lt_i32_e32 vcc, v34, v35
	s_nop 1
	v_cndmask_b32_e32 v34, v202, v34, vcc
	v_lshlrev_b32_e32 v34, 2, v34
	ds_bpermute_b32 v34, v34, v0
	s_waitcnt lgkmcnt(0)
	v_max_f32_e32 v34, v34, v34
	v_max_f32_e32 v0, v0, v34
	v_mul_f32_e32 v0, 0x3fb8aa3b, v0
	v_max_f32_e32 v34, v157, v157
	v_max_f32_e32 v158, v34, v0
	v_sub_f32_e32 v0, v157, v158
	v_exp_f32_e32 v0, v0
	v_cmp_neq_f32_e32 vcc, v158, v157
	s_cbranch_vccz .LBB0_667
	v_pk_mul_f32 v[32:33], v[32:33], v[0:1] op_sel_hi:[1,0]
	v_pk_mul_f32 v[30:31], v[30:31], v[0:1] op_sel_hi:[1,0]
	v_pk_mul_f32 v[28:29], v[28:29], v[0:1] op_sel_hi:[1,0]
	v_pk_mul_f32 v[26:27], v[26:27], v[0:1] op_sel_hi:[1,0]
	v_pk_mul_f32 v[24:25], v[24:25], v[0:1] op_sel_hi:[1,0]
	v_pk_mul_f32 v[22:23], v[22:23], v[0:1] op_sel_hi:[1,0]
	v_pk_mul_f32 v[20:21], v[20:21], v[0:1] op_sel_hi:[1,0]
	v_pk_mul_f32 v[18:19], v[18:19], v[0:1] op_sel_hi:[1,0]
	v_pk_mul_f32 v[16:17], v[16:17], v[0:1] op_sel_hi:[1,0]
	v_pk_mul_f32 v[14:15], v[14:15], v[0:1] op_sel_hi:[1,0]
	v_pk_mul_f32 v[12:13], v[12:13], v[0:1] op_sel_hi:[1,0]
	v_pk_mul_f32 v[10:11], v[10:11], v[0:1] op_sel_hi:[1,0]
	v_pk_mul_f32 v[8:9], v[8:9], v[0:1] op_sel_hi:[1,0]
	v_pk_mul_f32 v[6:7], v[6:7], v[0:1] op_sel_hi:[1,0]
	v_pk_mul_f32 v[4:5], v[4:5], v[0:1] op_sel_hi:[1,0]
	v_pk_mul_f32 v[2:3], v[2:3], v[0:1] op_sel_hi:[1,0]

; DI f32x16 mfma32(bf16x8 a, bf16x8 b, f32x16 c) { return __builtin_amdgcn_mfma_f32_32x32x16_bf16(a, b, c, 0, 0, 0); }
; DI int crow(int i, int h) { return (i & 3) + 8 * (i >> 2) + 4 * h; }
;     ...
;   f32x16 s[2];
; #pragma unroll
;   for (int k2 = 0; k2 < 2; ++k2) {
;     if (!(HM & (1 << k2))) continue;
; #pragma unroll
;     for (int i = 0; i < 16; ++i) s[k2][i] = 0.f;
; #pragma unroll
;     for (int ks = 0; ks < 4; ++ks) {
;       const bf16x8 a = *(const bf16x8*)(Ks + (32 * k2 + r) * LSTR + 16 * ks + 8 * h);
;       s[k2] = mfma32(a, qf[ks], s[k2]);
;     }
;   }
;   if (MODE == 1) {
; #pragma unroll
;     for (int k2 = 0; k2 < 2; ++k2)
; #pragma unroll
;       for (int g = 0; g < 4; ++g) {
;         if (!(HM & (1 << k2))) continue;
;         const f32x4 cv = *(const f32x4*)(cn_lds + key0 + 32 * k2 + 8 * g + 4 * h);
; #pragma unroll
;         for (int e = 0; e < 4; ++e) s[k2][4 * g + e] = fmaf(s[k2][4 * g + e], L2E, cv[e]);
;       }
;   }
;   float mx = NINF;
; #pragma unroll
;   for (int k2 = 0; k2 < 2; ++k2)
; #pragma unroll
;     for (int i = 0; i < 16; ++i) {
;       if (!(HM & (1 << k2))) continue;
;       float v = s[k2][i];
;       if (MASKED) {
;         const int tk = key0 + 32 * k2 + crow(i, h);
;         const bool valid = (MODE == 0) ? ((tk <= tq) && (tq - tk <= maxdist)) : (tk <= tq);
;         v = valid ? v : NINF; s[k2][i] = v;
;       }
;       mx = fmaxf(mx, v);
;     }
; template <int MODE>
; DI void flash_loop(char* smem, const bf16_t* Kbase, size_t ldk, const bf16_t* Vtbase, size_t ldv, ull tiles, ull wtiles,
;                    const bf16x8 (&qf)[4], f32x16 (&o)[2], float& m, float& l, int tq, int tqmin, int tqmax, int maxdist, const float* cn_lds, ull lmask) {
;     ...
;     const bool interior = (64 * kt + 63 <= tqmin) && (MODE != 0 || (tqmax - 64 * kt <= maxdist));
;     int hm = 3;
;     if (MODE == 0) {
;       hm = 0;
;       if (64 * kt <= tqmax && 64 * kt + 31 >= tqmin - maxdist) hm |= 1;
;       if (64 * kt + 32 <= tqmax && 64 * kt + 63 >= tqmin - maxdist) hm |= 2;
;     }
;     if (MODE == 0 && hm == 1) attn_tile<MODE, true, 1>(Ks, Vs, qf, o, m, l, 64 * kt, tq, maxdist, cn_lds, sel);
;     else if (MODE == 0 && hm == 2) attn_tile<MODE, true, 2>(Ks, Vs, qf, o, m, l, 64 * kt, tq, maxdist, cn_lds, sel);
;     else if (interior) attn_tile<MODE, false>(Ks, Vs, qf, o, m, l, 64 * kt, tq, maxdist, cn_lds, sel);
.LBB0_670:
	ds_read_b128 v[82:85], v196
	ds_read_b128 v[78:81], v196 offset:32
	ds_read_b128 v[74:77], v196 offset:64
	ds_read_b128 v[66:69], v196 offset:96
	ds_read_b128 v[70:73], v196 offset:4608
	s_cmp_le_u32 s33, s29
	s_cselect_b64 s[6:7], -1, 0
	s_cmp_ge_i32 s58, s64
	s_cselect_b64 s[36:37], -1, 0
	s_and_b64 s[6:7], s[6:7], s[36:37]
	s_andn2_b64 vcc, exec, s[6:7]
	s_mov_b64 s[6:7], -1
	s_cbranch_vccz .LBB0_674
	s_waitcnt lgkmcnt(4)
	v_mfma_f32_32x32x16_bf16 v[50:65], v[82:85], v[98:101], 0
	ds_read_b128 v[86:89], v196 offset:4640
	ds_read_b128 v[90:93], v196 offset:4672
	v_or_b32_e32 v0, s58, v197
	v_cmp_gt_u32_e32 vcc, v0, v154
	v_cmp_lt_i32_e64 s[6:7], v0, v155
	s_or_b64 vcc, vcc, s[6:7]
	s_waitcnt lgkmcnt(5)
	v_mfma_f32_32x32x16_bf16 v[50:65], v[78:81], v[102:105], v[50:65]
	s_waitcnt lgkmcnt(2)
	v_mfma_f32_32x32x16_bf16 v[34:49], v[70:73], v[98:101], 0
	v_mfma_f32_32x32x16_bf16 v[50:65], v[74:77], v[106:109], v[50:65]
	s_waitcnt lgkmcnt(1)
	v_mfma_f32_32x32x16_bf16 v[34:49], v[86:89], v[102:105], v[34:49]
	ds_read_b128 v[86:89], v196 offset:4704
	v_mfma_f32_32x32x16_bf16 v[50:65], v[66:69], v[110:113], v[50:65]
	s_waitcnt lgkmcnt(1)
	v_mfma_f32_32x32x16_bf16 v[34:49], v[90:93], v[106:109], v[34:49]
	s_waitcnt lgkmcnt(0)
	v_mfma_f32_32x32x16_bf16 v[34:49], v[86:89], v[110:113], v[34:49]
	s_nop 7
	v_cndmask_b32_e32 v86, v50, v204, vcc
	v_bitop3_b32 v50, s58, v197, s58 bitop3:3
	v_cmp_ge_u32_e32 vcc, v0, v154
	v_cmp_lt_i32_e64 s[6:7], v156, v50
	s_or_b64 vcc, vcc, s[6:7]
	v_cndmask_b32_e32 v87, v51, v204, vcc
	v_or_b32_e32 v51, 2, v0
	v_cmp_gt_u32_e32 vcc, v51, v154
	v_cmp_lt_i32_e64 s[6:7], v51, v155
	s_or_b64 vcc, vcc, s[6:7]
	v_or_b32_e32 v51, 3, v0
	v_cndmask_b32_e32 v88, v52, v204, vcc
	v_cmp_gt_u32_e32 vcc, v51, v154
	v_cmp_lt_i32_e64 s[6:7], v51, v155
	s_or_b64 vcc, vcc, s[6:7]
	v_or_b32_e32 v51, 8, v0
	v_cndmask_b32_e32 v89, v53, v204, vcc
	v_cmp_gt_u32_e32 vcc, v51, v154
	v_cmp_lt_i32_e64 s[6:7], v51, v155
	s_or_b64 vcc, vcc, s[6:7]
	v_or_b32_e32 v51, 9, v0
	v_cndmask_b32_e32 v90, v54, v204, vcc
	v_cmp_gt_u32_e32 vcc, v51, v154
	v_cmp_lt_i32_e64 s[6:7], v51, v155
	s_or_b64 vcc, vcc, s[6:7]
	v_or_b32_e32 v51, 10, v0
	v_cndmask_b32_e32 v192, v55, v204, vcc
	v_cmp_gt_u32_e32 vcc, v51, v154
	v_cmp_lt_i32_e64 s[6:7], v51, v155
	s_or_b64 vcc, vcc, s[6:7]
	v_or_b32_e32 v51, 11, v0
	v_cndmask_b32_e32 v191, v56, v204, vcc
	v_cmp_gt_u32_e32 vcc, v51, v154
	v_cmp_lt_i32_e64 s[6:7], v51, v155
	s_or_b64 vcc, vcc, s[6:7]
	v_or_b32_e32 v51, 16, v0
	v_cndmask_b32_e32 v193, v57, v204, vcc
	v_cmp_gt_u32_e32 vcc, v51, v154
	v_cmp_lt_i32_e64 s[6:7], v51, v155
	s_or_b64 vcc, vcc, s[6:7]
	v_or_b32_e32 v51, 17, v0
	v_cndmask_b32_e32 v188, v58, v204, vcc
	v_cmp_gt_u32_e32 vcc, v51, v154
	v_cmp_lt_i32_e64 s[6:7], v51, v155
	s_or_b64 vcc, vcc, s[6:7]
	v_or_b32_e32 v51, 18, v0
	v_cndmask_b32_e32 v190, v59, v204, vcc
	v_cmp_gt_u32_e32 vcc, v51, v154
	v_cmp_lt_i32_e64 s[6:7], v51, v155
	s_or_b64 vcc, vcc, s[6:7]
	v_or_b32_e32 v51, 19, v0
	v_cndmask_b32_e32 v189, v60, v204, vcc
	v_cmp_gt_u32_e32 vcc, v51, v154
	v_cmp_lt_i32_e64 s[6:7], v51, v155
	s_or_b64 vcc, vcc, s[6:7]
	v_or_b32_e32 v51, 24, v0
	v_cndmask_b32_e32 v187, v61, v204, vcc
	v_cmp_gt_u32_e32 vcc, v51, v154
	v_cmp_lt_i32_e64 s[6:7], v51, v155
	s_or_b64 vcc, vcc, s[6:7]
	v_or_b32_e32 v51, 25, v0
	v_cndmask_b32_e32 v186, v62, v204, vcc
	v_cmp_gt_u32_e32 vcc, v51, v154
	v_cmp_lt_i32_e64 s[6:7], v51, v155
	s_or_b64 vcc, vcc, s[6:7]
	v_or_b32_e32 v51, 26, v0
	v_cndmask_b32_e32 v185, v63, v204, vcc
	v_cmp_gt_u32_e32 vcc, v51, v154
	v_cmp_lt_i32_e64 s[6:7], v51, v155
	s_or_b64 vcc, vcc, s[6:7]
	v_or_b32_e32 v51, 27, v0
	v_cndmask_b32_e32 v184, v64, v204, vcc
	v_cmp_gt_u32_e32 vcc, v51, v154
	v_cmp_lt_i32_e64 s[6:7], v51, v155
	s_or_b64 vcc, vcc, s[6:7]
	v_or_b32_e32 v51, 32, v0
	v_cndmask_b32_e32 v182, v65, v204, vcc
	v_cmp_gt_u32_e32 vcc, v51, v154
	v_cmp_lt_i32_e64 s[6:7], v51, v155
	s_or_b64 vcc, vcc, s[6:7]
	v_cndmask_b32_e32 v164, v34, v204, vcc
	v_or_b32_e32 v34, 33, v0
	v_cmp_gt_u32_e32 vcc, v34, v154
	v_cmp_lt_i32_e64 s[6:7], v34, v155
	s_or_b64 vcc, vcc, s[6:7]
	v_cndmask_b32_e32 v162, v35, v204, vcc
	v_or_b32_e32 v35, 34, v0
; DI int crow(int i, int h) { return (i & 3) + 8 * (i >> 2) + 4 * h; }
;     ...
;   float mx = NINF;
; #pragma unroll
;   for (int k2 = 0; k2 < 2; ++k2)
; #pragma unroll
;     for (int i = 0; i < 16; ++i) {
;       if (!(HM & (1 << k2))) continue;
;       float v = s[k2][i];
;       if (MASKED) {
;         const int tk = key0 + 32 * k2 + crow(i, h);
;         const bool valid = (MODE == 0) ? ((tk <= tq) && (tq - tk <= maxdist)) : (tk <= tq);
;         v = valid ? v : NINF; s[k2][i] = v;
;       }
;       mx = fmaxf(mx, v);
;     }
;   mx = fmaxf(mx, __shfl_xor(mx, 32));
;   if (MODE != 1) mx *= L2E;
;   if (MODE == 2) mx = lanesel ? mx : NINF;
;   const float mn = fmaxf(m, mx); const float alpha = __builtin_amdgcn_exp2f(m - mn);
;   const float neg = (MODE == 2 && !lanesel) ? NINF : -mn;
;   float ps = 0.f;
; #pragma unroll
;   for (int k2 = 0; k2 < 2; ++k2)
; #pragma unroll
;     for (int i = 0; i < 16; ++i) {
;       if (!(HM & (1 << k2))) continue;
;       const float pv = (MODE == 1) ? __builtin_amdgcn_exp2f(s[k2][i] + neg) : __builtin_amdgcn_exp2f(fmaf(s[k2][i], L2E, neg));
;       s[k2][i] = pv; ps += pv;
;     }
;   l = l * alpha + ps;
;   if (__builtin_amdgcn_ballot_w64(mn != m) != 0ull) {
; #pragma unroll
;     for (int dt = 0; dt < 2; ++dt)
; #pragma unroll
;       for (int i = 0; i < 16; ++i) o[dt][i] *= alpha;
;   }
	v_cmp_gt_u32_e32 vcc, v35, v154
	v_cmp_lt_i32_e64 s[6:7], v35, v155
	s_or_b64 vcc, vcc, s[6:7]
	v_or_b32_e32 v35, 35, v0
	v_cndmask_b32_e32 v160, v36, v204, vcc
	v_cmp_gt_u32_e32 vcc, v35, v154
	v_cmp_lt_i32_e64 s[6:7], v35, v155
	s_or_b64 vcc, vcc, s[6:7]
	v_or_b32_e32 v35, 40, v0
	v_cndmask_b32_e32 v97, v37, v204, vcc
	v_cmp_gt_u32_e32 vcc, v35, v154
	v_cmp_lt_i32_e64 s[6:7], v35, v155
	s_or_b64 vcc, vcc, s[6:7]
	v_or_b32_e32 v35, 41, v0
	v_cndmask_b32_e32 v92, v38, v204, vcc
	v_cmp_gt_u32_e32 vcc, v35, v154
	v_cmp_lt_i32_e64 s[6:7], v35, v155
	s_or_b64 vcc, vcc, s[6:7]
	v_or_b32_e32 v35, 42, v0
	v_cndmask_b32_e32 v91, v39, v204, vcc
	v_cmp_gt_u32_e32 vcc, v35, v154
	v_cmp_lt_i32_e64 s[6:7], v35, v155
	s_or_b64 vcc, vcc, s[6:7]
	v_or_b32_e32 v35, 43, v0
	v_cndmask_b32_e32 v93, v40, v204, vcc
	v_cmp_gt_u32_e32 vcc, v35, v154
	v_cmp_lt_i32_e64 s[6:7], v35, v155
	s_or_b64 vcc, vcc, s[6:7]
	v_or_b32_e32 v35, 48, v0
	v_cndmask_b32_e32 v94, v41, v204, vcc
	v_cmp_gt_u32_e32 vcc, v35, v154
	v_cmp_lt_i32_e64 s[6:7], v35, v155
	s_or_b64 vcc, vcc, s[6:7]
	v_or_b32_e32 v35, 49, v0
	v_max3_f32 v50, v86, s35, v87
	v_cndmask_b32_e32 v95, v42, v204, vcc
	v_cmp_gt_u32_e32 vcc, v35, v154
	v_cmp_lt_i32_e64 s[6:7], v35, v155
	v_max3_f32 v50, v50, v88, v89
	s_or_b64 vcc, vcc, s[6:7]
	v_or_b32_e32 v35, 50, v0
	v_max3_f32 v50, v50, v90, v192
	v_cndmask_b32_e32 v96, v43, v204, vcc
	v_cmp_gt_u32_e32 vcc, v35, v154
	v_cmp_lt_i32_e64 s[6:7], v35, v155
	v_max3_f32 v50, v50, v191, v193
	s_or_b64 vcc, vcc, s[6:7]
	v_or_b32_e32 v35, 51, v0
	v_max3_f32 v50, v50, v188, v190
	v_cndmask_b32_e32 v161, v44, v204, vcc
	v_cmp_gt_u32_e32 vcc, v35, v154
	v_cmp_lt_i32_e64 s[6:7], v35, v155
	v_max3_f32 v50, v50, v189, v187
	s_or_b64 vcc, vcc, s[6:7]
	v_or_b32_e32 v35, 56, v0
	v_max3_f32 v50, v50, v186, v185
	v_cndmask_b32_e32 v163, v45, v204, vcc
	v_cmp_gt_u32_e32 vcc, v35, v154
	v_cmp_lt_i32_e64 s[6:7], v35, v155
	v_max3_f32 v50, v50, v184, v182
	s_or_b64 vcc, vcc, s[6:7]
	v_or_b32_e32 v35, 57, v0
	v_max3_f32 v34, v50, v164, v162
	v_cndmask_b32_e32 v165, v46, v204, vcc
	v_cmp_gt_u32_e32 vcc, v35, v154
	v_cmp_lt_i32_e64 s[6:7], v35, v155
	v_max3_f32 v34, v34, v160, v97
	s_or_b64 vcc, vcc, s[6:7]
	v_or_b32_e32 v35, 58, v0
	v_max3_f32 v34, v34, v92, v91
	v_cndmask_b32_e32 v180, v47, v204, vcc
	v_cmp_gt_u32_e32 vcc, v35, v154
	v_cmp_lt_i32_e64 s[6:7], v35, v155
	v_max3_f32 v34, v34, v93, v94
	s_or_b64 vcc, vcc, s[6:7]
	v_or_b32_e32 v0, 59, v0
	v_max3_f32 v34, v34, v95, v96
	v_cndmask_b32_e32 v181, v48, v204, vcc
	v_cmp_gt_u32_e32 vcc, v0, v154
	v_cmp_lt_i32_e64 s[6:7], v0, v155
	v_max3_f32 v34, v34, v161, v163
	s_or_b64 vcc, vcc, s[6:7]
	v_max3_f32 v34, v34, v165, v180
	v_cndmask_b32_e32 v183, v49, v204, vcc
	v_and_b32_e32 v35, 64, v202
	v_max3_f32 v0, v34, v181, v183
	v_xor_b32_e32 v34, 32, v202
	v_add_u32_e32 v35, 64, v35
	v_cmp_lt_i32_e32 vcc, v34, v35
	s_nop 1
	v_cndmask_b32_e32 v34, v202, v34, vcc
	v_lshlrev_b32_e32 v34, 2, v34
	ds_bpermute_b32 v34, v34, v0
	s_waitcnt lgkmcnt(0)
	v_max_f32_e32 v34, v34, v34
	v_max_f32_e32 v0, v0, v34
	v_mul_f32_e32 v0, 0x3fb8aa3b, v0
	v_max_f32_e32 v34, v157, v157
	v_max_f32_e32 v158, v34, v0
	v_sub_f32_e32 v0, v157, v158
	v_exp_f32_e32 v0, v0
	v_cmp_neq_f32_e32 vcc, v158, v157
	s_cbranch_vccz .LBB0_673
	v_pk_mul_f32 v[32:33], v[32:33], v[0:1] op_sel_hi:[1,0]
	v_pk_mul_f32 v[30:31], v[30:31], v[0:1] op_sel_hi:[1,0]
	v_pk_mul_f32 v[28:29], v[28:29], v[0:1] op_sel_hi:[1,0]
	v_pk_mul_f32 v[26:27], v[26:27], v[0:1] op_sel_hi:[1,0]
	v_pk_mul_f32 v[24:25], v[24:25], v[0:1] op_sel_hi:[1,0]
	v_pk_mul_f32 v[22:23], v[22:23], v[0:1] op_sel_hi:[1,0]
	v_pk_mul_f32 v[20:21], v[20:21], v[0:1] op_sel_hi:[1,0]
	v_pk_mul_f32 v[18:19], v[18:19], v[0:1] op_sel_hi:[1,0]
	v_pk_mul_f32 v[16:17], v[16:17], v[0:1] op_sel_hi:[1,0]
	v_pk_mul_f32 v[14:15], v[14:15], v[0:1] op_sel_hi:[1,0]
	v_pk_mul_f32 v[12:13], v[12:13], v[0:1] op_sel_hi:[1,0]
	v_pk_mul_f32 v[10:11], v[10:11], v[0:1] op_sel_hi:[1,0]
	v_pk_mul_f32 v[8:9], v[8:9], v[0:1] op_sel_hi:[1,0]
	v_pk_mul_f32 v[6:7], v[6:7], v[0:1] op_sel_hi:[1,0]
	v_pk_mul_f32 v[4:5], v[4:5], v[0:1] op_sel_hi:[1,0]
	v_pk_mul_f32 v[2:3], v[2:3], v[0:1] op_sel_hi:[1,0]

;     ...
;   f32x16 s[2];
; #pragma unroll
;   for (int k2 = 0; k2 < 2; ++k2) {
;     if (!(HM & (1 << k2))) continue;
; #pragma unroll
;     for (int i = 0; i < 16; ++i) s[k2][i] = 0.f;
; #pragma unroll
;     for (int ks = 0; ks < 4; ++ks) {
;       const bf16x8 a = *(const bf16x8*)(Ks + (32 * k2 + r) * LSTR + 16 * ks + 8 * h);
;       s[k2] = mfma32(a, qf[ks], s[k2]);
;     }
;   }
;   if (MODE == 1) {
; #pragma unroll
;     for (int k2 = 0; k2 < 2; ++k2)
; #pragma unroll
;       for (int g = 0; g < 4; ++g) {
;         if (!(HM & (1 << k2))) continue;
;         const f32x4 cv = *(const f32x4*)(cn_lds + key0 + 32 * k2 + 8 * g + 4 * h);
; #pragma unroll
;         for (int e = 0; e < 4; ++e) s[k2][4 * g + e] = fmaf(s[k2][4 * g + e], L2E, cv[e]);
;       }
;   }
;   float mx = NINF;
; #pragma unroll
;   for (int k2 = 0; k2 < 2; ++k2)
; #pragma unroll
;     for (int i = 0; i < 16; ++i) {
;       if (!(HM & (1 << k2))) continue;
;       float v = s[k2][i];
;       if (MASKED) {
;         const int tk = key0 + 32 * k2 + crow(i, h);
;         const bool valid = (MODE == 0) ? ((tk <= tq) && (tq - tk <= maxdist)) : (tk <= tq);
;         v = valid ? v : NINF; s[k2][i] = v;
;       }
;       mx = fmaxf(mx, v);
;     }
;   mx = fmaxf(mx, __shfl_xor(mx, 32));
;   if (MODE != 1) mx *= L2E;
;   if (MODE == 2) mx = lanesel ? mx : NINF;
; template <int MODE>
; DI void flash_loop(char* smem, const bf16_t* Kbase, size_t ldk, const bf16_t* Vtbase, size_t ldv, ull tiles, ull wtiles,
;                    const bf16x8 (&qf)[4], f32x16 (&o)[2], float& m, float& l, int tq, int tqmin, int tqmax, int maxdist, const float* cn_lds, ull lmask) {
;     ...
;     if (!((wtiles >> kt) & 1ull)) return;
;     const bf16_t* Ks = (const bf16_t*)(smem + stage * (2 * 64 * LSTR * 2)); const bf16_t* Vs = Ks + 64 * LSTR;
;     const bool sel = ((lmask >> kt) & 1ull) != 0;
;     const bool interior = (64 * kt + 63 <= tqmin) && (MODE != 0 || (tqmax - 64 * kt <= maxdist));
;     int hm = 3;
;     if (MODE == 0) {
;       hm = 0;
;       if (64 * kt <= tqmax && 64 * kt + 31 >= tqmin - maxdist) hm |= 1;
;       if (64 * kt + 32 <= tqmax && 64 * kt + 63 >= tqmin - maxdist) hm |= 2;
;     }
;     if (MODE == 0 && hm == 1) attn_tile<MODE, true, 1>(Ks, Vs, qf, o, m, l, 64 * kt, tq, maxdist, cn_lds, sel);
;     else if (MODE == 0 && hm == 2) attn_tile<MODE, true, 2>(Ks, Vs, qf, o, m, l, 64 * kt, tq, maxdist, cn_lds, sel);
.LBB0_690:
	s_lshr_b64 s[6:7], s[4:5], s67
	s_and_b32 s58, s6, 1
	s_cmp_eq_u64 s[58:59], 0
	s_cbranch_scc1 .LBB0_714
	s_lshl_b32 s58, s67, 6
	s_or_b32 s33, s58, 63
	s_cmp_le_u32 s58, s31
	s_cselect_b64 s[6:7], -1, 0
	s_or_b32 s36, s58, 31
	s_cmp_ge_i32 s36, s30
	s_cselect_b64 s[36:37], -1, 0
	s_and_b64 s[6:7], s[6:7], s[36:37]
	v_cndmask_b32_e64 v0, 0, 1, s[6:7]
	s_or_b32 s6, s58, 32
	s_cmp_gt_u32 s6, s31
	s_cselect_b64 s[6:7], -1, 0
	s_cmp_lt_i32 s33, s30
	s_cselect_b64 s[36:37], -1, 0
	v_or_b32_e32 v34, 2, v0
	s_or_b64 vcc, s[6:7], s[36:37]
	v_cndmask_b32_e32 v66, v34, v0, vcc
	v_cmp_gt_i32_e32 vcc, 2, v66
	s_mov_b64 s[62:63], -1
	s_mov_b64 s[54:55], 0
	s_and_b64 vcc, exec, vcc
	s_mov_b64 s[6:7], 0
	s_cbranch_vccnz .LBB0_707
	v_cmp_eq_u32_e32 vcc, 2, v66
	s_and_b64 vcc, exec, vcc
	s_mov_b64 s[6:7], -1
	s_cbranch_vccz .LBB0_696
	ds_read_b128 v[34:37], v199 offset:23040
	ds_read_b128 v[50:53], v199 offset:23072
	v_or_b32_e32 v0, s58, v197
	s_waitcnt lgkmcnt(1)
	v_mfma_f32_32x32x16_bf16 v[34:49], v[34:37], v[98:101], 0
	s_waitcnt lgkmcnt(0)
	v_mfma_f32_32x32x16_bf16 v[34:49], v[50:53], v[102:105], v[34:49]
	ds_read_b128 v[50:53], v199 offset:23104
	s_waitcnt lgkmcnt(0)
	v_mfma_f32_32x32x16_bf16 v[34:49], v[50:53], v[106:109], v[34:49]
	ds_read_b128 v[50:53], v199 offset:23136
	s_waitcnt lgkmcnt(0)
	v_mfma_f32_32x32x16_bf16 v[34:49], v[50:53], v[110:113], v[34:49]
	v_or_b32_e32 v50, 32, v0
	v_cmp_gt_u32_e32 vcc, v50, v154
	v_cmp_lt_i32_e64 s[6:7], v50, v155
	s_or_b64 vcc, vcc, s[6:7]
	s_nop 7
	v_cndmask_b32_e32 v67, v34, v204, vcc
	v_bitop3_b32 v34, s58, v205, v197 bitop3:0x36
	v_cmp_ge_u32_e32 vcc, v50, v154
	v_cmp_gt_i32_e64 s[6:7], v34, v156
	s_or_b64 vcc, vcc, s[6:7]
	v_cndmask_b32_e32 v68, v35, v204, vcc
	v_or_b32_e32 v35, 34, v0
	v_cmp_gt_u32_e32 vcc, v35, v154
	v_cmp_lt_i32_e64 s[6:7], v35, v155
	s_or_b64 vcc, vcc, s[6:7]
	v_or_b32_e32 v35, 35, v0
	v_cndmask_b32_e32 v69, v36, v204, vcc
	v_cmp_gt_u32_e32 vcc, v35, v154
	v_cmp_lt_i32_e64 s[6:7], v35, v155
	s_or_b64 vcc, vcc, s[6:7]
	v_or_b32_e32 v35, 40, v0
	v_cndmask_b32_e32 v70, v37, v204, vcc
	v_cmp_gt_u32_e32 vcc, v35, v154
	v_cmp_lt_i32_e64 s[6:7], v35, v155
	s_or_b64 vcc, vcc, s[6:7]
	v_or_b32_e32 v35, 41, v0
	v_cndmask_b32_e32 v71, v38, v204, vcc
	v_cmp_gt_u32_e32 vcc, v35, v154
	v_cmp_lt_i32_e64 s[6:7], v35, v155
	s_or_b64 vcc, vcc, s[6:7]
	v_or_b32_e32 v35, 42, v0
	v_cndmask_b32_e32 v72, v39, v204, vcc
	v_cmp_gt_u32_e32 vcc, v35, v154
	v_cmp_lt_i32_e64 s[6:7], v35, v155
	s_or_b64 vcc, vcc, s[6:7]
	v_or_b32_e32 v35, 43, v0
	v_cndmask_b32_e32 v77, v40, v204, vcc
	v_cmp_gt_u32_e32 vcc, v35, v154
	v_cmp_lt_i32_e64 s[6:7], v35, v155
	s_or_b64 vcc, vcc, s[6:7]
	v_or_b32_e32 v35, 48, v0
	v_cndmask_b32_e32 v78, v41, v204, vcc
	v_cmp_gt_u32_e32 vcc, v35, v154
	v_cmp_lt_i32_e64 s[6:7], v35, v155
	s_or_b64 vcc, vcc, s[6:7]
	v_or_b32_e32 v35, 49, v0
	v_cndmask_b32_e32 v79, v42, v204, vcc
	v_cmp_gt_u32_e32 vcc, v35, v154
	v_cmp_lt_i32_e64 s[6:7], v35, v155
	s_or_b64 vcc, vcc, s[6:7]
	v_or_b32_e32 v35, 50, v0
	v_cndmask_b32_e32 v80, v43, v204, vcc
	v_cmp_gt_u32_e32 vcc, v35, v154
	v_cmp_lt_i32_e64 s[6:7], v35, v155
	s_or_b64 vcc, vcc, s[6:7]
	v_or_b32_e32 v35, 51, v0
	v_cndmask_b32_e32 v81, v44, v204, vcc
	v_cmp_gt_u32_e32 vcc, v35, v154
	v_cmp_lt_i32_e64 s[6:7], v35, v155
	s_or_b64 vcc, vcc, s[6:7]
	v_or_b32_e32 v35, 56, v0
	v_cndmask_b32_e32 v82, v45, v204, vcc
	v_cmp_gt_u32_e32 vcc, v35, v154
	v_cmp_lt_i32_e64 s[6:7], v35, v155
	s_or_b64 vcc, vcc, s[6:7]
	v_or_b32_e32 v35, 57, v0
	v_max3_f32 v34, v67, s35, v68
	v_cndmask_b32_e32 v74, v46, v204, vcc
	v_cmp_gt_u32_e32 vcc, v35, v154
	v_cmp_lt_i32_e64 s[6:7], v35, v155
	v_max3_f32 v34, v34, v69, v70
	s_or_b64 vcc, vcc, s[6:7]
	v_or_b32_e32 v35, 58, v0
	v_max3_f32 v34, v34, v71, v72
	v_cndmask_b32_e32 v75, v47, v204, vcc
	v_cmp_gt_u32_e32 vcc, v35, v154
	v_cmp_lt_i32_e64 s[6:7], v35, v155
	v_max3_f32 v34, v34, v77, v78
	s_or_b64 vcc, vcc, s[6:7]
	v_or_b32_e32 v0, 59, v0
	v_max3_f32 v34, v34, v79, v80
	v_cndmask_b32_e32 v76, v48, v204, vcc
	v_cmp_gt_u32_e32 vcc, v0, v154
	v_cmp_lt_i32_e64 s[6:7], v0, v155
	v_max3_f32 v34, v34, v81, v82
	s_or_b64 vcc, vcc, s[6:7]
	v_max3_f32 v34, v34, v74, v75
	v_cndmask_b32_e32 v73, v49, v204, vcc
	v_and_b32_e32 v35, 64, v202
	v_max3_f32 v0, v34, v76, v73
	v_xor_b32_e32 v34, 32, v202
	v_add_u32_e32 v35, 64, v35
	v_cmp_lt_i32_e32 vcc, v34, v35
	s_nop 1
	v_cndmask_b32_e32 v34, v202, v34, vcc
	v_lshlrev_b32_e32 v34, 2, v34
	ds_bpermute_b32 v34, v34, v0
	s_waitcnt lgkmcnt(0)
	v_max_f32_e32 v34, v34, v34
	v_max_f32_e32 v0, v0, v34
	v_mul_f32_e32 v0, 0x3fb8aa3b, v0
	v_max_f32_e32 v34, v158, v158
	v_max_f32_e32 v157, v34, v0
	v_sub_f32_e32 v0, v158, v157
	v_exp_f32_e32 v0, v0
	v_cmp_neq_f32_e32 vcc, v157, v158
	s_cbranch_vccz .LBB0_695
	v_pk_mul_f32 v[32:33], v[32:33], v[0:1] op_sel_hi:[1,0]
	v_pk_mul_f32 v[30:31], v[30:31], v[0:1] op_sel_hi:[1,0]
	v_pk_mul_f32 v[28:29], v[28:29], v[0:1] op_sel_hi:[1,0]
	v_pk_mul_f32 v[26:27], v[26:27], v[0:1] op_sel_hi:[1,0]
	v_pk_mul_f32 v[24:25], v[24:25], v[0:1] op_sel_hi:[1,0]
	v_pk_mul_f32 v[22:23], v[22:23], v[0:1] op_sel_hi:[1,0]
	v_pk_mul_f32 v[20:21], v[20:21], v[0:1] op_sel_hi:[1,0]
	v_pk_mul_f32 v[18:19], v[18:19], v[0:1] op_sel_hi:[1,0]
	v_pk_mul_f32 v[16:17], v[16:17], v[0:1] op_sel_hi:[1,0]
	v_pk_mul_f32 v[14:15], v[14:15], v[0:1] op_sel_hi:[1,0]
	v_pk_mul_f32 v[12:13], v[12:13], v[0:1] op_sel_hi:[1,0]
	v_pk_mul_f32 v[10:11], v[10:11], v[0:1] op_sel_hi:[1,0]
	v_pk_mul_f32 v[8:9], v[8:9], v[0:1] op_sel_hi:[1,0]
	v_pk_mul_f32 v[6:7], v[6:7], v[0:1] op_sel_hi:[1,0]
	v_pk_mul_f32 v[4:5], v[4:5], v[0:1] op_sel_hi:[1,0]
	v_pk_mul_f32 v[2:3], v[2:3], v[0:1] op_sel_hi:[1,0]

; DI f32x16 mfma32(bf16x8 a, bf16x8 b, f32x16 c) { return __builtin_amdgcn_mfma_f32_32x32x16_bf16(a, b, c, 0, 0, 0); }
; DI int crow(int i, int h) { return (i & 3) + 8 * (i >> 2) + 4 * h; }
;     ...
;   f32x16 s[2];
; #pragma unroll
;   for (int k2 = 0; k2 < 2; ++k2) {
;     if (!(HM & (1 << k2))) continue;
; #pragma unroll
;     for (int i = 0; i < 16; ++i) s[k2][i] = 0.f;
; #pragma unroll
;     for (int ks = 0; ks < 4; ++ks) {
;       const bf16x8 a = *(const bf16x8*)(Ks + (32 * k2 + r) * LSTR + 16 * ks + 8 * h);
;       s[k2] = mfma32(a, qf[ks], s[k2]);
;     }
;   }
;   if (MODE == 1) {
; #pragma unroll
;     for (int k2 = 0; k2 < 2; ++k2)
; #pragma unroll
;       for (int g = 0; g < 4; ++g) {
;         if (!(HM & (1 << k2))) continue;
;         const f32x4 cv = *(const f32x4*)(cn_lds + key0 + 32 * k2 + 8 * g + 4 * h);
; #pragma unroll
;         for (int e = 0; e < 4; ++e) s[k2][4 * g + e] = fmaf(s[k2][4 * g + e], L2E, cv[e]);
;       }
;   }
;   float mx = NINF;
; #pragma unroll
;   for (int k2 = 0; k2 < 2; ++k2)
; #pragma unroll
;     for (int i = 0; i < 16; ++i) {
;       if (!(HM & (1 << k2))) continue;
;       float v = s[k2][i];
;       if (MASKED) {
;         const int tk = key0 + 32 * k2 + crow(i, h);
;         const bool valid = (MODE == 0) ? ((tk <= tq) && (tq - tk <= maxdist)) : (tk <= tq);
;         v = valid ? v : NINF; s[k2][i] = v;
;       }
;       mx = fmaxf(mx, v);
;     }
; template <int MODE>
; DI void flash_loop(char* smem, const bf16_t* Kbase, size_t ldk, const bf16_t* Vtbase, size_t ldv, ull tiles, ull wtiles,
;                    const bf16x8 (&qf)[4], f32x16 (&o)[2], float& m, float& l, int tq, int tqmin, int tqmax, int maxdist, const float* cn_lds, ull lmask) {
;     ...
;     const bool interior = (64 * kt + 63 <= tqmin) && (MODE != 0 || (tqmax - 64 * kt <= maxdist));
;     int hm = 3;
;     if (MODE == 0) {
;       hm = 0;
;       if (64 * kt <= tqmax && 64 * kt + 31 >= tqmin - maxdist) hm |= 1;
;       if (64 * kt + 32 <= tqmax && 64 * kt + 63 >= tqmin - maxdist) hm |= 2;
;     }
;     if (MODE == 0 && hm == 1) attn_tile<MODE, true, 1>(Ks, Vs, qf, o, m, l, 64 * kt, tq, maxdist, cn_lds, sel);
;     else if (MODE == 0 && hm == 2) attn_tile<MODE, true, 2>(Ks, Vs, qf, o, m, l, 64 * kt, tq, maxdist, cn_lds, sel);
;     else if (interior) attn_tile<MODE, false>(Ks, Vs, qf, o, m, l, 64 * kt, tq, maxdist, cn_lds, sel);
.LBB0_698:
	ds_read_b128 v[82:85], v196 offset:18432
	ds_read_b128 v[78:81], v196 offset:18464
	ds_read_b128 v[74:77], v196 offset:18496
	ds_read_b128 v[66:69], v196 offset:18528
	ds_read_b128 v[70:73], v196 offset:23040
	s_cmp_le_u32 s33, s29
	s_cselect_b64 s[6:7], -1, 0
	s_cmp_ge_i32 s58, s64
	s_cselect_b64 s[36:37], -1, 0
	s_and_b64 s[6:7], s[6:7], s[36:37]
	s_andn2_b64 vcc, exec, s[6:7]
	s_mov_b64 s[6:7], -1
	s_cbranch_vccz .LBB0_702
	s_waitcnt lgkmcnt(4)
	v_mfma_f32_32x32x16_bf16 v[50:65], v[82:85], v[98:101], 0
	ds_read_b128 v[86:89], v196 offset:23072
	ds_read_b128 v[90:93], v196 offset:23104
	v_or_b32_e32 v0, s58, v197
	v_cmp_gt_u32_e32 vcc, v0, v154
	v_cmp_lt_i32_e64 s[6:7], v0, v155
	s_or_b64 vcc, vcc, s[6:7]
	s_waitcnt lgkmcnt(5)
	v_mfma_f32_32x32x16_bf16 v[50:65], v[78:81], v[102:105], v[50:65]
	s_waitcnt lgkmcnt(2)
	v_mfma_f32_32x32x16_bf16 v[34:49], v[70:73], v[98:101], 0
	v_mfma_f32_32x32x16_bf16 v[50:65], v[74:77], v[106:109], v[50:65]
	s_waitcnt lgkmcnt(1)
	v_mfma_f32_32x32x16_bf16 v[34:49], v[86:89], v[102:105], v[34:49]
	ds_read_b128 v[86:89], v196 offset:23136
	v_mfma_f32_32x32x16_bf16 v[50:65], v[66:69], v[110:113], v[50:65]
	s_waitcnt lgkmcnt(1)
	v_mfma_f32_32x32x16_bf16 v[34:49], v[90:93], v[106:109], v[34:49]
	s_waitcnt lgkmcnt(0)
	v_mfma_f32_32x32x16_bf16 v[34:49], v[86:89], v[110:113], v[34:49]
	s_nop 7
	v_cndmask_b32_e32 v86, v50, v204, vcc
	v_bitop3_b32 v50, s58, v197, s58 bitop3:3
	v_cmp_ge_u32_e32 vcc, v0, v154
	v_cmp_lt_i32_e64 s[6:7], v156, v50
	s_or_b64 vcc, vcc, s[6:7]
	v_cndmask_b32_e32 v87, v51, v204, vcc
	v_or_b32_e32 v51, 2, v0
	v_cmp_gt_u32_e32 vcc, v51, v154
	v_cmp_lt_i32_e64 s[6:7], v51, v155
	s_or_b64 vcc, vcc, s[6:7]
	v_or_b32_e32 v51, 3, v0
	v_cndmask_b32_e32 v88, v52, v204, vcc
	v_cmp_gt_u32_e32 vcc, v51, v154
	v_cmp_lt_i32_e64 s[6:7], v51, v155
	s_or_b64 vcc, vcc, s[6:7]
	v_or_b32_e32 v51, 8, v0
	v_cndmask_b32_e32 v89, v53, v204, vcc
	v_cmp_gt_u32_e32 vcc, v51, v154
	v_cmp_lt_i32_e64 s[6:7], v51, v155
	s_or_b64 vcc, vcc, s[6:7]
	v_or_b32_e32 v51, 9, v0
	v_cndmask_b32_e32 v90, v54, v204, vcc
	v_cmp_gt_u32_e32 vcc, v51, v154
	v_cmp_lt_i32_e64 s[6:7], v51, v155
	s_or_b64 vcc, vcc, s[6:7]
	v_or_b32_e32 v51, 10, v0
	v_cndmask_b32_e32 v192, v55, v204, vcc
	v_cmp_gt_u32_e32 vcc, v51, v154
	v_cmp_lt_i32_e64 s[6:7], v51, v155
	s_or_b64 vcc, vcc, s[6:7]
	v_or_b32_e32 v51, 11, v0
	v_cndmask_b32_e32 v191, v56, v204, vcc
	v_cmp_gt_u32_e32 vcc, v51, v154
	v_cmp_lt_i32_e64 s[6:7], v51, v155
	s_or_b64 vcc, vcc, s[6:7]
	v_or_b32_e32 v51, 16, v0
	v_cndmask_b32_e32 v193, v57, v204, vcc
	v_cmp_gt_u32_e32 vcc, v51, v154
	v_cmp_lt_i32_e64 s[6:7], v51, v155
	s_or_b64 vcc, vcc, s[6:7]
	v_or_b32_e32 v51, 17, v0
	v_cndmask_b32_e32 v188, v58, v204, vcc
	v_cmp_gt_u32_e32 vcc, v51, v154
	v_cmp_lt_i32_e64 s[6:7], v51, v155
	s_or_b64 vcc, vcc, s[6:7]
	v_or_b32_e32 v51, 18, v0
	v_cndmask_b32_e32 v190, v59, v204, vcc
	v_cmp_gt_u32_e32 vcc, v51, v154
	v_cmp_lt_i32_e64 s[6:7], v51, v155
	s_or_b64 vcc, vcc, s[6:7]
	v_or_b32_e32 v51, 19, v0
	v_cndmask_b32_e32 v189, v60, v204, vcc
	v_cmp_gt_u32_e32 vcc, v51, v154
	v_cmp_lt_i32_e64 s[6:7], v51, v155
	s_or_b64 vcc, vcc, s[6:7]
	v_or_b32_e32 v51, 24, v0
	v_cndmask_b32_e32 v187, v61, v204, vcc
	v_cmp_gt_u32_e32 vcc, v51, v154
	v_cmp_lt_i32_e64 s[6:7], v51, v155
	s_or_b64 vcc, vcc, s[6:7]
	v_or_b32_e32 v51, 25, v0
	v_cndmask_b32_e32 v186, v62, v204, vcc
	v_cmp_gt_u32_e32 vcc, v51, v154
	v_cmp_lt_i32_e64 s[6:7], v51, v155
	s_or_b64 vcc, vcc, s[6:7]
	v_or_b32_e32 v51, 26, v0
	v_cndmask_b32_e32 v185, v63, v204, vcc
	v_cmp_gt_u32_e32 vcc, v51, v154
	v_cmp_lt_i32_e64 s[6:7], v51, v155
	s_or_b64 vcc, vcc, s[6:7]
	v_or_b32_e32 v51, 27, v0
	v_cndmask_b32_e32 v184, v64, v204, vcc
	v_cmp_gt_u32_e32 vcc, v51, v154
	v_cmp_lt_i32_e64 s[6:7], v51, v155
	s_or_b64 vcc, vcc, s[6:7]
	v_or_b32_e32 v51, 32, v0
	v_cndmask_b32_e32 v182, v65, v204, vcc
	v_cmp_gt_u32_e32 vcc, v51, v154
	v_cmp_lt_i32_e64 s[6:7], v51, v155
	s_or_b64 vcc, vcc, s[6:7]
	v_cndmask_b32_e32 v164, v34, v204, vcc
	v_or_b32_e32 v34, 33, v0
	v_cmp_gt_u32_e32 vcc, v34, v154
	v_cmp_lt_i32_e64 s[6:7], v34, v155
	s_or_b64 vcc, vcc, s[6:7]
	v_cndmask_b32_e32 v162, v35, v204, vcc
	v_or_b32_e32 v35, 34, v0
; DI int crow(int i, int h) { return (i & 3) + 8 * (i >> 2) + 4 * h; }
;     ...
;   float mx = NINF;
; #pragma unroll
;   for (int k2 = 0; k2 < 2; ++k2)
; #pragma unroll
;     for (int i = 0; i < 16; ++i) {
;       if (!(HM & (1 << k2))) continue;
;       float v = s[k2][i];
;       if (MASKED) {
;         const int tk = key0 + 32 * k2 + crow(i, h);
;         const bool valid = (MODE == 0) ? ((tk <= tq) && (tq - tk <= maxdist)) : (tk <= tq);
;         v = valid ? v : NINF; s[k2][i] = v;
;       }
;       mx = fmaxf(mx, v);
;     }
;   mx = fmaxf(mx, __shfl_xor(mx, 32));
;   if (MODE != 1) mx *= L2E;
;   if (MODE == 2) mx = lanesel ? mx : NINF;
;   const float mn = fmaxf(m, mx); const float alpha = __builtin_amdgcn_exp2f(m - mn);
;   const float neg = (MODE == 2 && !lanesel) ? NINF : -mn;
;   float ps = 0.f;
; #pragma unroll
;   for (int k2 = 0; k2 < 2; ++k2)
; #pragma unroll
;     for (int i = 0; i < 16; ++i) {
;       if (!(HM & (1 << k2))) continue;
;       const float pv = (MODE == 1) ? __builtin_amdgcn_exp2f(s[k2][i] + neg) : __builtin_amdgcn_exp2f(fmaf(s[k2][i], L2E, neg));
;       s[k2][i] = pv; ps += pv;
;     }
;   l = l * alpha + ps;
;   if (__builtin_amdgcn_ballot_w64(mn != m) != 0ull) {
; #pragma unroll
;     for (int dt = 0; dt < 2; ++dt)
; #pragma unroll
;       for (int i = 0; i < 16; ++i) o[dt][i] *= alpha;
;   }
	v_cmp_gt_u32_e32 vcc, v35, v154
	v_cmp_lt_i32_e64 s[6:7], v35, v155
	s_or_b64 vcc, vcc, s[6:7]
	v_or_b32_e32 v35, 35, v0
	v_cndmask_b32_e32 v159, v36, v204, vcc
	v_cmp_gt_u32_e32 vcc, v35, v154
	v_cmp_lt_i32_e64 s[6:7], v35, v155
	s_or_b64 vcc, vcc, s[6:7]
	v_or_b32_e32 v35, 40, v0
	v_cndmask_b32_e32 v97, v37, v204, vcc
	v_cmp_gt_u32_e32 vcc, v35, v154
	v_cmp_lt_i32_e64 s[6:7], v35, v155
	s_or_b64 vcc, vcc, s[6:7]
	v_or_b32_e32 v35, 41, v0
	v_cndmask_b32_e32 v92, v38, v204, vcc
	v_cmp_gt_u32_e32 vcc, v35, v154
	v_cmp_lt_i32_e64 s[6:7], v35, v155
	s_or_b64 vcc, vcc, s[6:7]
	v_or_b32_e32 v35, 42, v0
	v_cndmask_b32_e32 v91, v39, v204, vcc
	v_cmp_gt_u32_e32 vcc, v35, v154
	v_cmp_lt_i32_e64 s[6:7], v35, v155
	s_or_b64 vcc, vcc, s[6:7]
	v_or_b32_e32 v35, 43, v0
	v_cndmask_b32_e32 v93, v40, v204, vcc
	v_cmp_gt_u32_e32 vcc, v35, v154
	v_cmp_lt_i32_e64 s[6:7], v35, v155
	s_or_b64 vcc, vcc, s[6:7]
	v_or_b32_e32 v35, 48, v0
	v_cndmask_b32_e32 v94, v41, v204, vcc
	v_cmp_gt_u32_e32 vcc, v35, v154
	v_cmp_lt_i32_e64 s[6:7], v35, v155
	s_or_b64 vcc, vcc, s[6:7]
	v_or_b32_e32 v35, 49, v0
	v_max3_f32 v50, v86, s35, v87
	v_cndmask_b32_e32 v95, v42, v204, vcc
	v_cmp_gt_u32_e32 vcc, v35, v154
	v_cmp_lt_i32_e64 s[6:7], v35, v155
	v_max3_f32 v50, v50, v88, v89
	s_or_b64 vcc, vcc, s[6:7]
	v_or_b32_e32 v35, 50, v0
	v_max3_f32 v50, v50, v90, v192
	v_cndmask_b32_e32 v96, v43, v204, vcc
	v_cmp_gt_u32_e32 vcc, v35, v154
	v_cmp_lt_i32_e64 s[6:7], v35, v155
	v_max3_f32 v50, v50, v191, v193
	s_or_b64 vcc, vcc, s[6:7]
	v_or_b32_e32 v35, 51, v0
	v_max3_f32 v50, v50, v188, v190
	v_cndmask_b32_e32 v161, v44, v204, vcc
	v_cmp_gt_u32_e32 vcc, v35, v154
	v_cmp_lt_i32_e64 s[6:7], v35, v155
	v_max3_f32 v50, v50, v189, v187
	s_or_b64 vcc, vcc, s[6:7]
	v_or_b32_e32 v35, 56, v0
	v_max3_f32 v50, v50, v186, v185
	v_cndmask_b32_e32 v163, v45, v204, vcc
	v_cmp_gt_u32_e32 vcc, v35, v154
	v_cmp_lt_i32_e64 s[6:7], v35, v155
	v_max3_f32 v50, v50, v184, v182
	s_or_b64 vcc, vcc, s[6:7]
	v_or_b32_e32 v35, 57, v0
	v_max3_f32 v34, v50, v164, v162
	v_cndmask_b32_e32 v165, v46, v204, vcc
	v_cmp_gt_u32_e32 vcc, v35, v154
	v_cmp_lt_i32_e64 s[6:7], v35, v155
	v_max3_f32 v34, v34, v159, v97
	s_or_b64 vcc, vcc, s[6:7]
	v_or_b32_e32 v35, 58, v0
	v_max3_f32 v34, v34, v92, v91
	v_cndmask_b32_e32 v180, v47, v204, vcc
	v_cmp_gt_u32_e32 vcc, v35, v154
	v_cmp_lt_i32_e64 s[6:7], v35, v155
	v_max3_f32 v34, v34, v93, v94
	s_or_b64 vcc, vcc, s[6:7]
	v_or_b32_e32 v0, 59, v0
	v_max3_f32 v34, v34, v95, v96
	v_cndmask_b32_e32 v181, v48, v204, vcc
	v_cmp_gt_u32_e32 vcc, v0, v154
	v_cmp_lt_i32_e64 s[6:7], v0, v155
	v_max3_f32 v34, v34, v161, v163
	s_or_b64 vcc, vcc, s[6:7]
	v_max3_f32 v34, v34, v165, v180
	v_cndmask_b32_e32 v183, v49, v204, vcc
	v_and_b32_e32 v35, 64, v202
	v_max3_f32 v0, v34, v181, v183
	v_xor_b32_e32 v34, 32, v202
	v_add_u32_e32 v35, 64, v35
	v_cmp_lt_i32_e32 vcc, v34, v35
	s_nop 1
	v_cndmask_b32_e32 v34, v202, v34, vcc
	v_lshlrev_b32_e32 v34, 2, v34
	ds_bpermute_b32 v34, v34, v0
	s_waitcnt lgkmcnt(0)
	v_max_f32_e32 v34, v34, v34
	v_max_f32_e32 v0, v0, v34
	v_mul_f32_e32 v0, 0x3fb8aa3b, v0
	v_max_f32_e32 v34, v158, v158
	v_max_f32_e32 v157, v34, v0
	v_sub_f32_e32 v0, v158, v157
	v_exp_f32_e32 v0, v0
	v_cmp_neq_f32_e32 vcc, v157, v158
	s_cbranch_vccz .LBB0_701
	v_pk_mul_f32 v[32:33], v[32:33], v[0:1] op_sel_hi:[1,0]
	v_pk_mul_f32 v[30:31], v[30:31], v[0:1] op_sel_hi:[1,0]
	v_pk_mul_f32 v[28:29], v[28:29], v[0:1] op_sel_hi:[1,0]
	v_pk_mul_f32 v[26:27], v[26:27], v[0:1] op_sel_hi:[1,0]
	v_pk_mul_f32 v[24:25], v[24:25], v[0:1] op_sel_hi:[1,0]
	v_pk_mul_f32 v[22:23], v[22:23], v[0:1] op_sel_hi:[1,0]
	v_pk_mul_f32 v[20:21], v[20:21], v[0:1] op_sel_hi:[1,0]
	v_pk_mul_f32 v[18:19], v[18:19], v[0:1] op_sel_hi:[1,0]
	v_pk_mul_f32 v[16:17], v[16:17], v[0:1] op_sel_hi:[1,0]
	v_pk_mul_f32 v[14:15], v[14:15], v[0:1] op_sel_hi:[1,0]
	v_pk_mul_f32 v[12:13], v[12:13], v[0:1] op_sel_hi:[1,0]
	v_pk_mul_f32 v[10:11], v[10:11], v[0:1] op_sel_hi:[1,0]
	v_pk_mul_f32 v[8:9], v[8:9], v[0:1] op_sel_hi:[1,0]
	v_pk_mul_f32 v[6:7], v[6:7], v[0:1] op_sel_hi:[1,0]
	v_pk_mul_f32 v[4:5], v[4:5], v[0:1] op_sel_hi:[1,0]
	v_pk_mul_f32 v[2:3], v[2:3], v[0:1] op_sel_hi:[1,0]

; DI f32x16 mfma32(bf16x8 a, bf16x8 b, f32x16 c) { return __builtin_amdgcn_mfma_f32_32x32x16_bf16(a, b, c, 0, 0, 0); }
; DI int crow(int i, int h) { return (i & 3) + 8 * (i >> 2) + 4 * h; }
;     ...
;   f32x16 s[2];
; #pragma unroll
;   for (int k2 = 0; k2 < 2; ++k2) {
;     if (!(HM & (1 << k2))) continue;
; #pragma unroll
;     for (int i = 0; i < 16; ++i) s[k2][i] = 0.f;
; #pragma unroll
;     for (int ks = 0; ks < 4; ++ks) {
;       const bf16x8 a = *(const bf16x8*)(Ks + (32 * k2 + r) * LSTR + 16 * ks + 8 * h);
;       s[k2] = mfma32(a, qf[ks], s[k2]);
;     }
;   }
;   if (MODE == 1) {
; #pragma unroll
;     for (int k2 = 0; k2 < 2; ++k2)
; #pragma unroll
;       for (int g = 0; g < 4; ++g) {
;         if (!(HM & (1 << k2))) continue;
;         const f32x4 cv = *(const f32x4*)(cn_lds + key0 + 32 * k2 + 8 * g + 4 * h);
; #pragma unroll
;         for (int e = 0; e < 4; ++e) s[k2][4 * g + e] = fmaf(s[k2][4 * g + e], L2E, cv[e]);
;       }
;   }
;   float mx = NINF;
; #pragma unroll
;   for (int k2 = 0; k2 < 2; ++k2)
; #pragma unroll
;     for (int i = 0; i < 16; ++i) {
;       if (!(HM & (1 << k2))) continue;
;       float v = s[k2][i];
;       if (MASKED) {
;         const int tk = key0 + 32 * k2 + crow(i, h);
;         const bool valid = (MODE == 0) ? ((tk <= tq) && (tq - tk <= maxdist)) : (tk <= tq);
;         v = valid ? v : NINF; s[k2][i] = v;
;       }
;       mx = fmaxf(mx, v);
;     }
;   mx = fmaxf(mx, __shfl_xor(mx, 32));
;   if (MODE != 1) mx *= L2E;
;   if (MODE == 2) mx = lanesel ? mx : NINF;
;   const float mn = fmaxf(m, mx); const float alpha = __builtin_amdgcn_exp2f(m - mn);
;   const float neg = (MODE == 2 && !lanesel) ? NINF : -mn;
;   float ps = 0.f;
; #pragma unroll
;   for (int k2 = 0; k2 < 2; ++k2)
; #pragma unroll
;     for (int i = 0; i < 16; ++i) {
;       if (!(HM & (1 << k2))) continue;
;       const float pv = (MODE == 1) ? __builtin_amdgcn_exp2f(s[k2][i] + neg) : __builtin_amdgcn_exp2f(fmaf(s[k2][i], L2E, neg));
;       s[k2][i] = pv; ps += pv;
;     }
;   l = l * alpha + ps;
;   if (__builtin_amdgcn_ballot_w64(mn != m) != 0ull) {
; #pragma unroll
;     for (int dt = 0; dt < 2; ++dt)
; #pragma unroll
;       for (int i = 0; i < 16; ++i) o[dt][i] *= alpha;
;   }
.LBB0_784:
	s_lshr_b64 s[30:31], s[2:3], s9
	s_and_b32 s58, s30, 1
	s_cmp_eq_u64 s[58:59], 0
	s_cbranch_scc1 .LBB0_794
	ds_read_b128 v[130:133], v196
	ds_read_b128 v[126:129], v196 offset:32
	ds_read_b128 v[122:125], v196 offset:64
	ds_read_b128 v[114:117], v196 offset:96
	ds_read_b128 v[118:121], v196 offset:4608
	s_lshl_b32 s30, s9, 6
	s_or_b32 s8, s30, 63
	s_cmp_gt_i32 s8, s11
	s_mov_b64 s[8:9], -1
	v_lshl_add_u32 v195, s30, 2, v177
	s_cbranch_scc1 .LBB0_789
	s_waitcnt lgkmcnt(4)
	v_mfma_f32_32x32x16_bf16 v[50:65], v[130:133], v[66:69], 0
	ds_read_b128 v[134:137], v196 offset:4704
	ds_read_b128 v[160:163], v195 offset:36864
	ds_read_b128 v[138:141], v196 offset:4640
	ds_read_b128 v[142:145], v196 offset:4672
	ds_read_b128 v[156:159], v195 offset:36896
	ds_read_b128 v[152:155], v195 offset:36928
	ds_read_b128 v[146:149], v195 offset:36992
	s_waitcnt lgkmcnt(10)
	v_mfma_f32_32x32x16_bf16 v[50:65], v[126:129], v[70:73], v[50:65]
	s_waitcnt lgkmcnt(7)
	v_mfma_f32_32x32x16_bf16 v[34:49], v[118:121], v[66:69], 0
	v_mfma_f32_32x32x16_bf16 v[50:65], v[122:125], v[74:77], v[50:65]
	s_waitcnt lgkmcnt(4)
	v_mfma_f32_32x32x16_bf16 v[34:49], v[138:141], v[70:73], v[34:49]
	ds_read_b128 v[138:141], v195 offset:37056
	v_mfma_f32_32x32x16_bf16 v[50:65], v[114:117], v[78:81], v[50:65]
	s_waitcnt lgkmcnt(4)
	v_mfma_f32_32x32x16_bf16 v[34:49], v[142:145], v[74:77], v[34:49]
	s_nop 9
	v_fmamk_f32 v211, v50, 0x3fb8aa3b, v160
	v_fmamk_f32 v210, v51, 0x3fb8aa3b, v161
	v_fmamk_f32 v209, v52, 0x3fb8aa3b, v162
	v_fmac_f32_e32 v163, 0x3fb8aa3b, v53
	s_waitcnt lgkmcnt(3)
	v_fmamk_f32 v161, v56, 0x3fb8aa3b, v158
	s_waitcnt lgkmcnt(2)
	v_fmamk_f32 v160, v58, 0x3fb8aa3b, v152
	v_fmamk_f32 v158, v59, 0x3fb8aa3b, v153
	v_mfma_f32_32x32x16_bf16 v[34:49], v[134:137], v[78:81], v[34:49]
	ds_read_b128 v[150:153], v195 offset:36960
	ds_read_b128 v[142:145], v195 offset:37024
	v_max3_f32 v0, v211, s35, v210
	v_fmamk_f32 v194, v54, 0x3fb8aa3b, v156
	v_fmamk_f32 v162, v55, 0x3fb8aa3b, v157
	v_max3_f32 v0, v0, v209, v163
	v_fmac_f32_e32 v159, 0x3fb8aa3b, v57
	v_max3_f32 v0, v0, v194, v162
	v_max3_f32 v0, v0, v161, v159
	v_fmamk_f32 v157, v60, 0x3fb8aa3b, v154
	v_fmac_f32_e32 v155, 0x3fb8aa3b, v61
	v_max3_f32 v0, v0, v160, v158
	s_waitcnt lgkmcnt(1)
	v_fmamk_f32 v156, v62, 0x3fb8aa3b, v150
	v_fmamk_f32 v154, v63, 0x3fb8aa3b, v151
	v_max3_f32 v0, v0, v157, v155
	v_fmamk_f32 v152, v64, 0x3fb8aa3b, v152
	v_fmac_f32_e32 v153, 0x3fb8aa3b, v65
	v_max3_f32 v0, v0, v156, v154
	v_fmamk_f32 v151, v34, 0x3fb8aa3b, v146
	v_fmamk_f32 v150, v35, 0x3fb8aa3b, v147
	v_max3_f32 v0, v0, v152, v153
	v_fmamk_f32 v148, v36, 0x3fb8aa3b, v148
	v_fmac_f32_e32 v149, 0x3fb8aa3b, v37
	ds_read_b128 v[134:137], v195 offset:37088
	v_max3_f32 v0, v0, v151, v150
	s_waitcnt lgkmcnt(1)
	v_fmamk_f32 v147, v38, 0x3fb8aa3b, v142
	v_fmamk_f32 v146, v39, 0x3fb8aa3b, v143
	v_max3_f32 v0, v0, v148, v149
	v_fmamk_f32 v142, v40, 0x3fb8aa3b, v144
	v_fmac_f32_e32 v145, 0x3fb8aa3b, v41
	v_max3_f32 v0, v0, v147, v146
	v_fmamk_f32 v144, v42, 0x3fb8aa3b, v138
	v_fmamk_f32 v143, v43, 0x3fb8aa3b, v139
	v_max3_f32 v0, v0, v142, v145
	v_fmamk_f32 v139, v44, 0x3fb8aa3b, v140
	v_fmac_f32_e32 v141, 0x3fb8aa3b, v45
	v_max3_f32 v0, v0, v144, v143
	s_waitcnt lgkmcnt(0)
	v_fmamk_f32 v138, v46, 0x3fb8aa3b, v134
	v_fmamk_f32 v135, v47, 0x3fb8aa3b, v135
	v_max3_f32 v0, v0, v139, v141
	v_fmamk_f32 v134, v48, 0x3fb8aa3b, v136
	v_fmac_f32_e32 v137, 0x3fb8aa3b, v49
	v_max3_f32 v0, v0, v138, v135
	v_max3_f32 v0, v0, v134, v137
	ds_bpermute_b32 v34, v190, v0
	s_waitcnt lgkmcnt(0)
	v_max3_f32 v192, v191, v0, v34
	v_sub_f32_e32 v0, v191, v192
	v_exp_f32_e32 v0, v0
	v_cmp_neq_f32_e32 vcc, v192, v191
	s_cbranch_vccz .LBB0_788
	v_pk_mul_f32 v[32:33], v[32:33], v[0:1] op_sel_hi:[1,0]
	v_pk_mul_f32 v[30:31], v[30:31], v[0:1] op_sel_hi:[1,0]
	v_pk_mul_f32 v[28:29], v[28:29], v[0:1] op_sel_hi:[1,0]
	v_pk_mul_f32 v[26:27], v[26:27], v[0:1] op_sel_hi:[1,0]
	v_pk_mul_f32 v[24:25], v[24:25], v[0:1] op_sel_hi:[1,0]
	v_pk_mul_f32 v[22:23], v[22:23], v[0:1] op_sel_hi:[1,0]
	v_pk_mul_f32 v[20:21], v[20:21], v[0:1] op_sel_hi:[1,0]
	v_pk_mul_f32 v[18:19], v[18:19], v[0:1] op_sel_hi:[1,0]
	v_pk_mul_f32 v[16:17], v[16:17], v[0:1] op_sel_hi:[1,0]
	v_pk_mul_f32 v[14:15], v[14:15], v[0:1] op_sel_hi:[1,0]
	v_pk_mul_f32 v[12:13], v[12:13], v[0:1] op_sel_hi:[1,0]
	v_pk_mul_f32 v[10:11], v[10:11], v[0:1] op_sel_hi:[1,0]
	v_pk_mul_f32 v[8:9], v[8:9], v[0:1] op_sel_hi:[1,0]
	v_pk_mul_f32 v[6:7], v[6:7], v[0:1] op_sel_hi:[1,0]
	v_pk_mul_f32 v[4:5], v[4:5], v[0:1] op_sel_hi:[1,0]
	v_pk_mul_f32 v[2:3], v[2:3], v[0:1] op_sel_hi:[1,0]
; DI unsigned pack2(float a, float b) { f32x2 v = {a, b}; bf16x2_t r = __builtin_convertvector(v, bf16x2_t); return __builtin_bit_cast(unsigned, r); }
; DI f32x16 mfma32(bf16x8 a, bf16x8 b, f32x16 c) { return __builtin_amdgcn_mfma_f32_32x32x16_bf16(a, b, c, 0, 0, 0); }
;     ...
;   float ps = 0.f;
; #pragma unroll
;   for (int k2 = 0; k2 < 2; ++k2)
; #pragma unroll
;     for (int i = 0; i < 16; ++i) {
;       if (!(HM & (1 << k2))) continue;
;       const float pv = (MODE == 1) ? __builtin_amdgcn_exp2f(s[k2][i] + neg) : __builtin_amdgcn_exp2f(fmaf(s[k2][i], L2E, neg));
;       s[k2][i] = pv; ps += pv;
;     }
;   l = l * alpha + ps;
;   if (__builtin_amdgcn_ballot_w64(mn != m) != 0ull) {
; #pragma unroll
;     for (int dt = 0; dt < 2; ++dt)
; #pragma unroll
;       for (int i = 0; i < 16; ++i) o[dt][i] *= alpha;
;   }
;   m = mn;
; #pragma unroll
;   for (int st = 0; st < 4; ++st) {
;     if (!(HM & (1 << (st >> 1)))) continue;
;     const int k2 = st >> 1, b8 = 8 * (st & 1);
;     const u32x4 pw = {pack2(s[k2][b8], s[k2][b8 + 1]), pack2(s[k2][b8 + 2], s[k2][b8 + 3]), pack2(s[k2][b8 + 4], s[k2][b8 + 5]), pack2(s[k2][b8 + 6], s[k2][b8 + 7])};
;     const bf16x8 pb = __builtin_bit_cast(bf16x8, pw);
; #pragma unroll
;     for (int dt = 0; dt < 2; ++dt) {
;       const s16x4 lo = *(const s16x4*)(Vs + (32 * dt + r) * LSTR + 16 * st + 4 * h);
;       const s16x4 hi = *(const s16x4*)(Vs + (32 * dt + r) * LSTR + 16 * st + 8 + 4 * h);
;       const bf16x8 a = __builtin_shufflevector(lo, hi, 0, 1, 2, 3, 4, 5, 6, 7);
;       o[dt] = mfma32(a, pb, o[dt]);
;     }
;   }
.LBB0_788:
	v_sub_f32_e32 v136, v211, v192
	v_exp_f32_e32 v136, v136
	v_sub_f32_e32 v210, v210, v192
	v_exp_f32_e32 v210, v210
	v_sub_f32_e32 v209, v209, v192
	v_exp_f32_e32 v209, v209
	v_sub_f32_e32 v163, v163, v192
	v_exp_f32_e32 v163, v163
	v_sub_f32_e32 v194, v194, v192
	v_add_f32_e32 v140, 0, v136
	v_exp_f32_e32 v211, v194
	v_sub_f32_e32 v162, v162, v192
	v_add_f32_e32 v140, v210, v140
	v_exp_f32_e32 v162, v162
	v_sub_f32_e32 v161, v161, v192
	v_add_f32_e32 v140, v209, v140
	v_exp_f32_e32 v161, v161
	v_sub_f32_e32 v159, v159, v192
	v_add_f32_e32 v140, v163, v140
	v_exp_f32_e32 v159, v159
	v_sub_f32_e32 v160, v160, v192
	v_add_f32_e32 v140, v211, v140
	v_exp_f32_e32 v160, v160
	v_sub_f32_e32 v158, v158, v192
	v_add_f32_e32 v140, v162, v140
	v_exp_f32_e32 v158, v158
	v_sub_f32_e32 v157, v157, v192
	v_add_f32_e32 v140, v161, v140
	v_exp_f32_e32 v157, v157
	v_sub_f32_e32 v155, v155, v192
	v_add_f32_e32 v140, v159, v140
	v_exp_f32_e32 v155, v155
	v_sub_f32_e32 v156, v156, v192
	v_add_f32_e32 v140, v160, v140
	v_exp_f32_e32 v156, v156
	v_sub_f32_e32 v154, v154, v192
	v_add_f32_e32 v140, v158, v140
	v_exp_f32_e32 v154, v154
	v_sub_f32_e32 v152, v152, v192
	v_add_f32_e32 v140, v157, v140
	v_exp_f32_e32 v152, v152
	v_sub_f32_e32 v153, v153, v192
	v_add_f32_e32 v140, v155, v140
	v_exp_f32_e32 v153, v153
	v_sub_f32_e32 v151, v151, v192
	v_add_f32_e32 v140, v156, v140
	v_exp_f32_e32 v151, v151
	v_sub_f32_e32 v150, v150, v192
	v_add_f32_e32 v140, v154, v140
	v_exp_f32_e32 v150, v150
	v_sub_f32_e32 v148, v148, v192
	v_add_f32_e32 v140, v152, v140
	v_exp_f32_e32 v148, v148
	v_sub_f32_e32 v149, v149, v192
	v_add_f32_e32 v140, v153, v140
	v_exp_f32_e32 v149, v149
	v_sub_f32_e32 v147, v147, v192
	v_add_f32_e32 v140, v151, v140
	v_exp_f32_e32 v147, v147
	v_sub_f32_e32 v146, v146, v192
	v_add_f32_e32 v140, v150, v140
	v_exp_f32_e32 v146, v146
	v_sub_f32_e32 v142, v142, v192
	v_add_f32_e32 v140, v148, v140
	v_exp_f32_e32 v212, v142
	v_sub_f32_e32 v142, v145, v192
	v_add_f32_e32 v140, v149, v140
	v_exp_f32_e32 v213, v142
	v_sub_f32_e32 v142, v144, v192
	v_add_f32_e32 v140, v147, v140
	v_exp_f32_e32 v214, v142
	v_sub_f32_e32 v142, v143, v192
	v_add_f32_e32 v140, v146, v140
	v_exp_f32_e32 v215, v142
	v_sub_f32_e32 v139, v139, v192
	v_add_f32_e32 v140, v212, v140
	v_exp_f32_e32 v216, v139
	v_add_f32_e32 v140, v213, v140
	v_add_f32_e32 v140, v214, v140
	v_add_f32_e32 v140, v215, v140
	v_add_f32_e32 v139, v216, v140
	v_sub_f32_e32 v140, v141, v192
	v_exp_f32_e32 v217, v140
	v_sub_f32_e32 v138, v138, v192
	v_exp_f32_e32 v218, v138
	v_sub_f32_e32 v135, v135, v192
	v_exp_f32_e32 v219, v135
	v_sub_f32_e32 v134, v134, v192
	v_exp_f32_e32 v220, v134
	v_add_f32_e32 v139, v217, v139
	v_add_f32_e32 v138, v218, v139
	v_add_f32_e32 v135, v219, v138
	v_add_f32_e32 v134, v220, v135
	v_sub_f32_e32 v135, v137, v192
	v_exp_f32_e32 v221, v135
	v_cvt_pk_bf16_f32 v135, v209, v163
	v_cvt_pk_bf16_f32 v137, v161, v159
	v_add_u32_e32 v159, 0x3000, v198
	v_add_f32_e32 v194, v221, v134
	v_fmac_f32_e32 v194, v193, v0
	v_add_u32_e32 v0, 0x2000, v198
	ds_read2_b64 v[138:141], v0 offset0:128 offset1:130
	ds_read2_b64 v[142:145], v0 offset0:132 offset1:134
	v_cvt_pk_bf16_f32 v134, v136, v210
	v_cvt_pk_bf16_f32 v136, v211, v162
	s_mov_b64 s[8:9], 0
	s_waitcnt lgkmcnt(1)
	v_mfma_f32_32x32x16_bf16 v[34:49], v[138:141], v[134:137], v[2:17]
	ds_read2_b64 v[138:141], v159 offset0:192 offset1:194
	s_waitcnt lgkmcnt(0)
	v_mfma_f32_32x32x16_bf16 v[50:65], v[138:141], v[134:137], v[18:33]
	ds_read2_b64 v[138:141], v159 offset0:196 offset1:198
	v_cvt_pk_bf16_f32 v134, v160, v158
	v_cvt_pk_bf16_f32 v135, v157, v155
	v_cvt_pk_bf16_f32 v136, v156, v154
	v_cvt_pk_bf16_f32 v137, v152, v153
	s_waitcnt lgkmcnt(0)
	s_nop 0
	v_mfma_f32_32x32x16_bf16 v[50:65], v[138:141], v[134:137], v[50:65]
	ds_read2_b64 v[138:141], v0 offset0:136 offset1:138
	v_mfma_f32_32x32x16_bf16 v[34:49], v[142:145], v[134:137], v[34:49]
	v_cvt_pk_bf16_f32 v134, v151, v150
	v_cvt_pk_bf16_f32 v135, v148, v149
	v_cvt_pk_bf16_f32 v136, v147, v146
	v_cvt_pk_bf16_f32 v137, v212, v213
	s_waitcnt lgkmcnt(0)
	s_nop 0
	v_mfma_f32_32x32x16_bf16 v[34:49], v[138:141], v[134:137], v[34:49]
	ds_read2_b64 v[138:141], v159 offset0:200 offset1:202
	s_waitcnt lgkmcnt(0)
	v_mfma_f32_32x32x16_bf16 v[50:65], v[138:141], v[134:137], v[50:65]
	ds_read2_b64 v[138:141], v0 offset0:140 offset1:142
	v_cvt_pk_bf16_f32 v134, v214, v215
	v_cvt_pk_bf16_f32 v135, v216, v217
	v_cvt_pk_bf16_f32 v136, v218, v219
	v_cvt_pk_bf16_f32 v137, v220, v221
	s_waitcnt lgkmcnt(0)
	s_nop 0
	v_mfma_f32_32x32x16_bf16 v[2:17], v[138:141], v[134:137], v[34:49]
	ds_read2_b64 v[138:141], v159 offset0:204 offset1:206
	s_waitcnt lgkmcnt(0)
	v_mfma_f32_32x32x16_bf16 v[18:33], v[138:141], v[134:137], v[50:65]

; DI f32x16 mfma32(bf16x8 a, bf16x8 b, f32x16 c) { return __builtin_amdgcn_mfma_f32_32x32x16_bf16(a, b, c, 0, 0, 0); }
; DI int crow(int i, int h) { return (i & 3) + 8 * (i >> 2) + 4 * h; }
;     ...
;   f32x16 s[2];
; #pragma unroll
;   for (int k2 = 0; k2 < 2; ++k2) {
;     if (!(HM & (1 << k2))) continue;
; #pragma unroll
;     for (int i = 0; i < 16; ++i) s[k2][i] = 0.f;
; #pragma unroll
;     for (int ks = 0; ks < 4; ++ks) {
;       const bf16x8 a = *(const bf16x8*)(Ks + (32 * k2 + r) * LSTR + 16 * ks + 8 * h);
;       s[k2] = mfma32(a, qf[ks], s[k2]);
;     }
;   }
;   if (MODE == 1) {
; #pragma unroll
;     for (int k2 = 0; k2 < 2; ++k2)
; #pragma unroll
;       for (int g = 0; g < 4; ++g) {
;         if (!(HM & (1 << k2))) continue;
;         const f32x4 cv = *(const f32x4*)(cn_lds + key0 + 32 * k2 + 8 * g + 4 * h);
; #pragma unroll
;         for (int e = 0; e < 4; ++e) s[k2][4 * g + e] = fmaf(s[k2][4 * g + e], L2E, cv[e]);
;       }
;   }
;   float mx = NINF;
; #pragma unroll
;   for (int k2 = 0; k2 < 2; ++k2)
; #pragma unroll
;     for (int i = 0; i < 16; ++i) {
;       if (!(HM & (1 << k2))) continue;
;       float v = s[k2][i];
;       if (MASKED) {
;         const int tk = key0 + 32 * k2 + crow(i, h);
;         const bool valid = (MODE == 0) ? ((tk <= tq) && (tq - tk <= maxdist)) : (tk <= tq);
;         v = valid ? v : NINF; s[k2][i] = v;
;       }
;       mx = fmaxf(mx, v);
;     }
;   mx = fmaxf(mx, __shfl_xor(mx, 32));
;   if (MODE != 1) mx *= L2E;
;   if (MODE == 2) mx = lanesel ? mx : NINF;
;   const float mn = fmaxf(m, mx); const float alpha = __builtin_amdgcn_exp2f(m - mn);
;   const float neg = (MODE == 2 && !lanesel) ? NINF : -mn;
;   float ps = 0.f;
; #pragma unroll
;   for (int k2 = 0; k2 < 2; ++k2)
; #pragma unroll
;     for (int i = 0; i < 16; ++i) {
;       if (!(HM & (1 << k2))) continue;
;       const float pv = (MODE == 1) ? __builtin_amdgcn_exp2f(s[k2][i] + neg) : __builtin_amdgcn_exp2f(fmaf(s[k2][i], L2E, neg));
;       s[k2][i] = pv; ps += pv;
;     }
;   l = l * alpha + ps;
;   if (__builtin_amdgcn_ballot_w64(mn != m) != 0ull) {
; #pragma unroll
;     for (int dt = 0; dt < 2; ++dt)
; #pragma unroll
;       for (int i = 0; i < 16; ++i) o[dt][i] *= alpha;
;   }
.LBB0_798:
	s_lshr_b64 s[8:9], s[2:3], s29
	s_and_b32 s58, s8, 1
	s_cmp_eq_u64 s[58:59], 0
	s_cbranch_scc1 .LBB0_808
	ds_read_b128 v[130:133], v196 offset:18432
	ds_read_b128 v[126:129], v196 offset:18464
	ds_read_b128 v[122:125], v196 offset:18496
	ds_read_b128 v[114:117], v196 offset:18528
	ds_read_b128 v[118:121], v196 offset:23040
	s_lshl_b32 s29, s29, 6
	s_or_b32 s8, s29, 63
	s_cmp_gt_i32 s8, s11
	s_mov_b64 s[8:9], -1
	v_lshl_add_u32 v195, s29, 2, v177
	s_cbranch_scc1 .LBB0_803
	s_waitcnt lgkmcnt(4)
	v_mfma_f32_32x32x16_bf16 v[50:65], v[130:133], v[66:69], 0
	ds_read_b128 v[134:137], v196 offset:23136
	ds_read_b128 v[160:163], v195 offset:36864
	ds_read_b128 v[138:141], v196 offset:23072
	ds_read_b128 v[142:145], v196 offset:23104
	ds_read_b128 v[156:159], v195 offset:36896
	ds_read_b128 v[152:155], v195 offset:36928
	ds_read_b128 v[146:149], v195 offset:36992
	s_waitcnt lgkmcnt(10)
	v_mfma_f32_32x32x16_bf16 v[50:65], v[126:129], v[70:73], v[50:65]
	s_waitcnt lgkmcnt(7)
	v_mfma_f32_32x32x16_bf16 v[34:49], v[118:121], v[66:69], 0
	v_mfma_f32_32x32x16_bf16 v[50:65], v[122:125], v[74:77], v[50:65]
	s_waitcnt lgkmcnt(4)
	v_mfma_f32_32x32x16_bf16 v[34:49], v[138:141], v[70:73], v[34:49]
	ds_read_b128 v[138:141], v195 offset:37056
	v_mfma_f32_32x32x16_bf16 v[50:65], v[114:117], v[78:81], v[50:65]
	s_waitcnt lgkmcnt(4)
	v_mfma_f32_32x32x16_bf16 v[34:49], v[142:145], v[74:77], v[34:49]
	s_nop 9
	v_fmamk_f32 v211, v50, 0x3fb8aa3b, v160
	v_fmamk_f32 v210, v51, 0x3fb8aa3b, v161
	v_fmamk_f32 v209, v52, 0x3fb8aa3b, v162
	v_fmac_f32_e32 v163, 0x3fb8aa3b, v53
	s_waitcnt lgkmcnt(3)
	v_fmamk_f32 v161, v56, 0x3fb8aa3b, v158
	s_waitcnt lgkmcnt(2)
	v_fmamk_f32 v160, v58, 0x3fb8aa3b, v152
	v_fmamk_f32 v158, v59, 0x3fb8aa3b, v153
	v_mfma_f32_32x32x16_bf16 v[34:49], v[134:137], v[78:81], v[34:49]
	ds_read_b128 v[150:153], v195 offset:36960
	ds_read_b128 v[142:145], v195 offset:37024
	v_max3_f32 v0, v211, s35, v210
	v_fmamk_f32 v193, v54, 0x3fb8aa3b, v156
	v_fmamk_f32 v162, v55, 0x3fb8aa3b, v157
	v_max3_f32 v0, v0, v209, v163
	v_fmac_f32_e32 v159, 0x3fb8aa3b, v57
	v_max3_f32 v0, v0, v193, v162
	v_max3_f32 v0, v0, v161, v159
	v_fmamk_f32 v157, v60, 0x3fb8aa3b, v154
	v_fmac_f32_e32 v155, 0x3fb8aa3b, v61
	v_max3_f32 v0, v0, v160, v158
	s_waitcnt lgkmcnt(1)
	v_fmamk_f32 v156, v62, 0x3fb8aa3b, v150
	v_fmamk_f32 v154, v63, 0x3fb8aa3b, v151
	v_max3_f32 v0, v0, v157, v155
	v_fmamk_f32 v152, v64, 0x3fb8aa3b, v152
	v_fmac_f32_e32 v153, 0x3fb8aa3b, v65
	v_max3_f32 v0, v0, v156, v154
	v_fmamk_f32 v151, v34, 0x3fb8aa3b, v146
	v_fmamk_f32 v150, v35, 0x3fb8aa3b, v147
	v_max3_f32 v0, v0, v152, v153
	v_fmamk_f32 v148, v36, 0x3fb8aa3b, v148
	v_fmac_f32_e32 v149, 0x3fb8aa3b, v37
	ds_read_b128 v[134:137], v195 offset:37088
	v_max3_f32 v0, v0, v151, v150
	s_waitcnt lgkmcnt(1)
	v_fmamk_f32 v147, v38, 0x3fb8aa3b, v142
	v_fmamk_f32 v146, v39, 0x3fb8aa3b, v143
	v_max3_f32 v0, v0, v148, v149
	v_fmamk_f32 v142, v40, 0x3fb8aa3b, v144
	v_fmac_f32_e32 v145, 0x3fb8aa3b, v41
	v_max3_f32 v0, v0, v147, v146
	v_fmamk_f32 v144, v42, 0x3fb8aa3b, v138
	v_fmamk_f32 v143, v43, 0x3fb8aa3b, v139
	v_max3_f32 v0, v0, v142, v145
	v_fmamk_f32 v139, v44, 0x3fb8aa3b, v140
	v_fmac_f32_e32 v141, 0x3fb8aa3b, v45
	v_max3_f32 v0, v0, v144, v143
	s_waitcnt lgkmcnt(0)
	v_fmamk_f32 v138, v46, 0x3fb8aa3b, v134
	v_fmamk_f32 v135, v47, 0x3fb8aa3b, v135
	v_max3_f32 v0, v0, v139, v141
	v_fmamk_f32 v134, v48, 0x3fb8aa3b, v136
	v_fmac_f32_e32 v137, 0x3fb8aa3b, v49
	v_max3_f32 v0, v0, v138, v135
	v_max3_f32 v0, v0, v134, v137
	ds_bpermute_b32 v34, v190, v0
	s_waitcnt lgkmcnt(0)
	v_max3_f32 v191, v192, v0, v34
	v_sub_f32_e32 v0, v192, v191
	v_exp_f32_e32 v0, v0
	v_cmp_neq_f32_e32 vcc, v191, v192
	s_cbranch_vccz .LBB0_802
	v_pk_mul_f32 v[32:33], v[32:33], v[0:1] op_sel_hi:[1,0]
	v_pk_mul_f32 v[30:31], v[30:31], v[0:1] op_sel_hi:[1,0]
	v_pk_mul_f32 v[28:29], v[28:29], v[0:1] op_sel_hi:[1,0]
	v_pk_mul_f32 v[26:27], v[26:27], v[0:1] op_sel_hi:[1,0]
	v_pk_mul_f32 v[24:25], v[24:25], v[0:1] op_sel_hi:[1,0]
	v_pk_mul_f32 v[22:23], v[22:23], v[0:1] op_sel_hi:[1,0]
	v_pk_mul_f32 v[20:21], v[20:21], v[0:1] op_sel_hi:[1,0]
	v_pk_mul_f32 v[18:19], v[18:19], v[0:1] op_sel_hi:[1,0]
	v_pk_mul_f32 v[16:17], v[16:17], v[0:1] op_sel_hi:[1,0]
	v_pk_mul_f32 v[14:15], v[14:15], v[0:1] op_sel_hi:[1,0]
	v_pk_mul_f32 v[12:13], v[12:13], v[0:1] op_sel_hi:[1,0]
	v_pk_mul_f32 v[10:11], v[10:11], v[0:1] op_sel_hi:[1,0]
	v_pk_mul_f32 v[8:9], v[8:9], v[0:1] op_sel_hi:[1,0]
	v_pk_mul_f32 v[6:7], v[6:7], v[0:1] op_sel_hi:[1,0]
	v_pk_mul_f32 v[4:5], v[4:5], v[0:1] op_sel_hi:[1,0]
	v_pk_mul_f32 v[2:3], v[2:3], v[0:1] op_sel_hi:[1,0]
; DI unsigned pack2(float a, float b) { f32x2 v = {a, b}; bf16x2_t r = __builtin_convertvector(v, bf16x2_t); return __builtin_bit_cast(unsigned, r); }
; DI f32x16 mfma32(bf16x8 a, bf16x8 b, f32x16 c) { return __builtin_amdgcn_mfma_f32_32x32x16_bf16(a, b, c, 0, 0, 0); }
;     ...
;   float ps = 0.f;
; #pragma unroll
;   for (int k2 = 0; k2 < 2; ++k2)
; #pragma unroll
;     for (int i = 0; i < 16; ++i) {
;       if (!(HM & (1 << k2))) continue;
;       const float pv = (MODE == 1) ? __builtin_amdgcn_exp2f(s[k2][i] + neg) : __builtin_amdgcn_exp2f(fmaf(s[k2][i], L2E, neg));
;       s[k2][i] = pv; ps += pv;
;     }
;   l = l * alpha + ps;
;   if (__builtin_amdgcn_ballot_w64(mn != m) != 0ull) {
; #pragma unroll
;     for (int dt = 0; dt < 2; ++dt)
; #pragma unroll
;       for (int i = 0; i < 16; ++i) o[dt][i] *= alpha;
;   }
;   m = mn;
; #pragma unroll
;   for (int st = 0; st < 4; ++st) {
;     if (!(HM & (1 << (st >> 1)))) continue;
;     const int k2 = st >> 1, b8 = 8 * (st & 1);
;     const u32x4 pw = {pack2(s[k2][b8], s[k2][b8 + 1]), pack2(s[k2][b8 + 2], s[k2][b8 + 3]), pack2(s[k2][b8 + 4], s[k2][b8 + 5]), pack2(s[k2][b8 + 6], s[k2][b8 + 7])};
;     const bf16x8 pb = __builtin_bit_cast(bf16x8, pw);
; #pragma unroll
;     for (int dt = 0; dt < 2; ++dt) {
;       const s16x4 lo = *(const s16x4*)(Vs + (32 * dt + r) * LSTR + 16 * st + 4 * h);
;       const s16x4 hi = *(const s16x4*)(Vs + (32 * dt + r) * LSTR + 16 * st + 8 + 4 * h);
;       const bf16x8 a = __builtin_shufflevector(lo, hi, 0, 1, 2, 3, 4, 5, 6, 7);
;       o[dt] = mfma32(a, pb, o[dt]);
;     }
;   }
.LBB0_802:
	v_sub_f32_e32 v136, v211, v191
	v_exp_f32_e32 v136, v136
	v_sub_f32_e32 v210, v210, v191
	v_exp_f32_e32 v210, v210
	v_sub_f32_e32 v209, v209, v191
	v_exp_f32_e32 v209, v209
	v_sub_f32_e32 v163, v163, v191
	v_exp_f32_e32 v163, v163
	v_sub_f32_e32 v193, v193, v191
	v_add_f32_e32 v140, 0, v136
	v_exp_f32_e32 v211, v193
	v_sub_f32_e32 v162, v162, v191
	v_add_f32_e32 v140, v210, v140
	v_exp_f32_e32 v162, v162
	v_sub_f32_e32 v161, v161, v191
	v_add_f32_e32 v140, v209, v140
	v_exp_f32_e32 v161, v161
	v_sub_f32_e32 v159, v159, v191
	v_add_f32_e32 v140, v163, v140
	v_exp_f32_e32 v159, v159
	v_sub_f32_e32 v160, v160, v191
	v_add_f32_e32 v140, v211, v140
	v_exp_f32_e32 v160, v160
	v_sub_f32_e32 v158, v158, v191
	v_add_f32_e32 v140, v162, v140
	v_exp_f32_e32 v158, v158
	v_sub_f32_e32 v157, v157, v191
	v_add_f32_e32 v140, v161, v140
	v_exp_f32_e32 v157, v157
	v_sub_f32_e32 v155, v155, v191
	v_add_f32_e32 v140, v159, v140
	v_exp_f32_e32 v155, v155
	v_sub_f32_e32 v156, v156, v191
	v_add_f32_e32 v140, v160, v140
	v_exp_f32_e32 v156, v156
	v_sub_f32_e32 v154, v154, v191
	v_add_f32_e32 v140, v158, v140
	v_exp_f32_e32 v154, v154
	v_sub_f32_e32 v152, v152, v191
	v_add_f32_e32 v140, v157, v140
	v_exp_f32_e32 v152, v152
	v_sub_f32_e32 v153, v153, v191
	v_add_f32_e32 v140, v155, v140
	v_exp_f32_e32 v153, v153
	v_sub_f32_e32 v151, v151, v191
	v_add_f32_e32 v140, v156, v140
	v_exp_f32_e32 v151, v151
	v_sub_f32_e32 v150, v150, v191
	v_add_f32_e32 v140, v154, v140
	v_exp_f32_e32 v150, v150
	v_sub_f32_e32 v148, v148, v191
	v_add_f32_e32 v140, v152, v140
	v_exp_f32_e32 v148, v148
	v_sub_f32_e32 v149, v149, v191
	v_add_f32_e32 v140, v153, v140
	v_exp_f32_e32 v149, v149
	v_sub_f32_e32 v147, v147, v191
	v_add_f32_e32 v140, v151, v140
	v_exp_f32_e32 v147, v147
	v_sub_f32_e32 v146, v146, v191
	v_add_f32_e32 v140, v150, v140
	v_exp_f32_e32 v146, v146
	v_sub_f32_e32 v142, v142, v191
	v_add_f32_e32 v140, v148, v140
	v_exp_f32_e32 v212, v142
	v_sub_f32_e32 v142, v145, v191
	v_add_f32_e32 v140, v149, v140
	v_exp_f32_e32 v213, v142
	v_sub_f32_e32 v142, v144, v191
	v_add_f32_e32 v140, v147, v140
	v_exp_f32_e32 v214, v142
	v_sub_f32_e32 v142, v143, v191
	v_add_f32_e32 v140, v146, v140
	v_exp_f32_e32 v215, v142
	v_sub_f32_e32 v139, v139, v191
	v_add_f32_e32 v140, v212, v140
	v_exp_f32_e32 v216, v139
	v_add_f32_e32 v140, v213, v140
	v_add_f32_e32 v140, v214, v140
	v_add_f32_e32 v140, v215, v140
	v_add_f32_e32 v139, v216, v140
	v_sub_f32_e32 v140, v141, v191
	v_exp_f32_e32 v217, v140
	v_sub_f32_e32 v138, v138, v191
	v_exp_f32_e32 v218, v138
	v_sub_f32_e32 v135, v135, v191
	v_exp_f32_e32 v219, v135
	v_sub_f32_e32 v134, v134, v191
	v_exp_f32_e32 v220, v134
	v_add_f32_e32 v139, v217, v139
	v_add_f32_e32 v138, v218, v139
	v_add_f32_e32 v135, v219, v138
	v_add_f32_e32 v134, v220, v135
	v_sub_f32_e32 v135, v137, v191
	v_exp_f32_e32 v221, v135
	v_cvt_pk_bf16_f32 v135, v209, v163
	v_cvt_pk_bf16_f32 v137, v161, v159
	v_add_u32_e32 v159, 0x7800, v198
	v_add_f32_e32 v193, v221, v134
	v_fmac_f32_e32 v193, v194, v0
	v_add_u32_e32 v0, 0x6800, v198
	ds_read2_b64 v[138:141], v0 offset0:128 offset1:130
	ds_read2_b64 v[142:145], v0 offset0:132 offset1:134
	v_cvt_pk_bf16_f32 v134, v136, v210
	v_cvt_pk_bf16_f32 v136, v211, v162
	s_mov_b64 s[8:9], 0
	s_waitcnt lgkmcnt(1)
	v_mfma_f32_32x32x16_bf16 v[34:49], v[138:141], v[134:137], v[2:17]
	ds_read2_b64 v[138:141], v159 offset0:192 offset1:194
	s_waitcnt lgkmcnt(0)
	v_mfma_f32_32x32x16_bf16 v[50:65], v[138:141], v[134:137], v[18:33]
	ds_read2_b64 v[138:141], v159 offset0:196 offset1:198
	v_cvt_pk_bf16_f32 v134, v160, v158
	v_cvt_pk_bf16_f32 v135, v157, v155
	v_cvt_pk_bf16_f32 v136, v156, v154
	v_cvt_pk_bf16_f32 v137, v152, v153
	s_waitcnt lgkmcnt(0)
	s_nop 0
	v_mfma_f32_32x32x16_bf16 v[50:65], v[138:141], v[134:137], v[50:65]
	ds_read2_b64 v[138:141], v0 offset0:136 offset1:138
	v_mfma_f32_32x32x16_bf16 v[34:49], v[142:145], v[134:137], v[34:49]
	v_cvt_pk_bf16_f32 v134, v151, v150
	v_cvt_pk_bf16_f32 v135, v148, v149
	v_cvt_pk_bf16_f32 v136, v147, v146
	v_cvt_pk_bf16_f32 v137, v212, v213
	s_waitcnt lgkmcnt(0)
	s_nop 0
	v_mfma_f32_32x32x16_bf16 v[34:49], v[138:141], v[134:137], v[34:49]
	ds_read2_b64 v[138:141], v159 offset0:200 offset1:202
	s_waitcnt lgkmcnt(0)
	v_mfma_f32_32x32x16_bf16 v[50:65], v[138:141], v[134:137], v[50:65]
	ds_read2_b64 v[138:141], v0 offset0:140 offset1:142
	v_cvt_pk_bf16_f32 v134, v214, v215
	v_cvt_pk_bf16_f32 v135, v216, v217
	v_cvt_pk_bf16_f32 v136, v218, v219
	v_cvt_pk_bf16_f32 v137, v220, v221
	s_waitcnt lgkmcnt(0)
	s_nop 0
	v_mfma_f32_32x32x16_bf16 v[2:17], v[138:141], v[134:137], v[34:49]
	ds_read2_b64 v[138:141], v159 offset0:204 offset1:206
	s_waitcnt lgkmcnt(0)
	v_mfma_f32_32x32x16_bf16 v[18:33], v[138:141], v[134:137], v[50:65]

; DI f32x16 mfma32(bf16x8 a, bf16x8 b, f32x16 c) { return __builtin_amdgcn_mfma_f32_32x32x16_bf16(a, b, c, 0, 0, 0); }
; DI int crow(int i, int h) { return (i & 3) + 8 * (i >> 2) + 4 * h; }
;     ...
;   f32x16 s[2];
; #pragma unroll
;   for (int k2 = 0; k2 < 2; ++k2) {
;     if (!(HM & (1 << k2))) continue;
; #pragma unroll
;     for (int i = 0; i < 16; ++i) s[k2][i] = 0.f;
; #pragma unroll
;     for (int ks = 0; ks < 4; ++ks) {
;       const bf16x8 a = *(const bf16x8*)(Ks + (32 * k2 + r) * LSTR + 16 * ks + 8 * h);
;       s[k2] = mfma32(a, qf[ks], s[k2]);
;     }
;   }
;   if (MODE == 1) {
; #pragma unroll
;     for (int k2 = 0; k2 < 2; ++k2)
; #pragma unroll
;       for (int g = 0; g < 4; ++g) {
;         if (!(HM & (1 << k2))) continue;
;         const f32x4 cv = *(const f32x4*)(cn_lds + key0 + 32 * k2 + 8 * g + 4 * h);
; #pragma unroll
;         for (int e = 0; e < 4; ++e) s[k2][4 * g + e] = fmaf(s[k2][4 * g + e], L2E, cv[e]);
;       }
;   }
;   float mx = NINF;
; #pragma unroll
;   for (int k2 = 0; k2 < 2; ++k2)
; #pragma unroll
;     for (int i = 0; i < 16; ++i) {
;       if (!(HM & (1 << k2))) continue;
;       float v = s[k2][i];
;       if (MASKED) {
;         const int tk = key0 + 32 * k2 + crow(i, h);
;         const bool valid = (MODE == 0) ? ((tk <= tq) && (tq - tk <= maxdist)) : (tk <= tq);
;         v = valid ? v : NINF; s[k2][i] = v;
;       }
;       mx = fmaxf(mx, v);
;     }
;   mx = fmaxf(mx, __shfl_xor(mx, 32));
;   if (MODE != 1) mx *= L2E;
;   if (MODE == 2) mx = lanesel ? mx : NINF;
;   const float mn = fmaxf(m, mx); const float alpha = __builtin_amdgcn_exp2f(m - mn);
;   const float neg = (MODE == 2 && !lanesel) ? NINF : -mn;
;   float ps = 0.f;
; #pragma unroll
;   for (int k2 = 0; k2 < 2; ++k2)
; #pragma unroll
;     for (int i = 0; i < 16; ++i) {
;       if (!(HM & (1 << k2))) continue;
;       const float pv = (MODE == 1) ? __builtin_amdgcn_exp2f(s[k2][i] + neg) : __builtin_amdgcn_exp2f(fmaf(s[k2][i], L2E, neg));
;       s[k2][i] = pv; ps += pv;
;     }
;   l = l * alpha + ps;
;   if (__builtin_amdgcn_ballot_w64(mn != m) != 0ull) {
; #pragma unroll
;     for (int dt = 0; dt < 2; ++dt)
; #pragma unroll
;       for (int i = 0; i < 16; ++i) o[dt][i] *= alpha;
;   }
.LBB0_823:
	s_lshl_b64 s[6:7], 1, s11
	v_and_b32_e32 v34, s6, v185
	v_and_b32_e32 v35, s7, v187
	v_cmp_eq_u64_e32 vcc, 0, v[34:35]
	s_cbranch_vccnz .LBB0_833
	ds_read_b128 v[146:149], v196
	ds_read_b128 v[150:153], v196 offset:32
	ds_read_b128 v[154:157], v196 offset:64
	ds_read_b128 v[158:161], v196 offset:96
	ds_read_b128 v[162:165], v196 offset:4608
	s_lshl_b32 s11, s11, 6
	v_and_b32_e32 v35, s7, v189
	v_and_b32_e32 v34, s6, v188
	s_or_b32 s8, s11, 63
	v_cmp_eq_u64_e64 s[6:7], 0, v[34:35]
	s_cmp_gt_i32 s8, s28
	s_mov_b64 s[8:9], -1
	v_max_f32_e32 v216, v211, v211
	s_cbranch_scc1 .LBB0_828
	s_waitcnt lgkmcnt(4)
	v_mfma_f32_32x32x16_bf16 v[82:97], v[146:149], v[98:101], 0
	ds_read_b128 v[34:37], v196 offset:4640
	ds_read_b128 v[38:41], v196 offset:4672
	s_waitcnt lgkmcnt(5)
	v_mfma_f32_32x32x16_bf16 v[82:97], v[150:153], v[102:105], v[82:97]
	s_waitcnt lgkmcnt(2)
	v_mfma_f32_32x32x16_bf16 v[66:81], v[162:165], v[98:101], 0
	v_mfma_f32_32x32x16_bf16 v[82:97], v[154:157], v[106:109], v[82:97]
	s_waitcnt lgkmcnt(1)
	v_mfma_f32_32x32x16_bf16 v[66:81], v[34:37], v[102:105], v[66:81]
	ds_read_b128 v[34:37], v196 offset:4704
	v_mfma_f32_32x32x16_bf16 v[82:97], v[158:161], v[110:113], v[82:97]
	s_waitcnt lgkmcnt(1)
	v_mfma_f32_32x32x16_bf16 v[66:81], v[38:41], v[106:109], v[66:81]
	s_nop 9
	v_max3_f32 v0, v82, s35, v83
	v_max3_f32 v0, v0, v84, v85
	v_max3_f32 v0, v0, v86, v87
	v_max3_f32 v0, v0, v88, v89
	v_max3_f32 v0, v0, v90, v91
	v_max3_f32 v0, v0, v92, v93
	v_max3_f32 v0, v0, v94, v95
	s_waitcnt lgkmcnt(0)
	v_mfma_f32_32x32x16_bf16 v[66:81], v[34:37], v[110:113], v[66:81]
	v_max3_f32 v0, v0, v96, v97
	v_and_b32_e32 v35, 64, v202
	v_xor_b32_e32 v34, 32, v202
	v_add_u32_e32 v35, 64, v35
	v_cmp_lt_i32_e32 vcc, v34, v35
	s_nop 6
	v_max3_f32 v0, v0, v66, v67
	v_max3_f32 v0, v0, v68, v69
	v_max3_f32 v0, v0, v70, v71
	v_max3_f32 v0, v0, v72, v73
	v_max3_f32 v0, v0, v74, v75
	v_max3_f32 v0, v0, v76, v77
	v_max3_f32 v0, v0, v78, v79
	v_cndmask_b32_e32 v34, v202, v34, vcc
	v_max3_f32 v0, v0, v80, v81
	v_lshlrev_b32_e32 v34, 2, v34
	ds_bpermute_b32 v34, v34, v0
	s_waitcnt lgkmcnt(0)
	v_max_f32_e32 v34, v34, v34
	v_max_f32_e32 v0, v0, v34
	v_mul_f32_e32 v0, 0x3fb8aa3b, v0
	v_cndmask_b32_e64 v0, v0, v204, s[6:7]
	v_max_f32_e32 v212, v216, v0
	v_sub_f32_e32 v0, v211, v212
	v_exp_f32_e32 v0, v0
	v_cmp_neq_f32_e32 vcc, v212, v211
	s_cbranch_vccz .LBB0_827
	v_pk_mul_f32 v[32:33], v[32:33], v[0:1] op_sel_hi:[1,0]
	v_pk_mul_f32 v[30:31], v[30:31], v[0:1] op_sel_hi:[1,0]
	v_pk_mul_f32 v[28:29], v[28:29], v[0:1] op_sel_hi:[1,0]
	v_pk_mul_f32 v[26:27], v[26:27], v[0:1] op_sel_hi:[1,0]
	v_pk_mul_f32 v[24:25], v[24:25], v[0:1] op_sel_hi:[1,0]
	v_pk_mul_f32 v[22:23], v[22:23], v[0:1] op_sel_hi:[1,0]
	v_pk_mul_f32 v[20:21], v[20:21], v[0:1] op_sel_hi:[1,0]
	v_pk_mul_f32 v[18:19], v[18:19], v[0:1] op_sel_hi:[1,0]
	v_pk_mul_f32 v[16:17], v[16:17], v[0:1] op_sel_hi:[1,0]
	v_pk_mul_f32 v[14:15], v[14:15], v[0:1] op_sel_hi:[1,0]
	v_pk_mul_f32 v[12:13], v[12:13], v[0:1] op_sel_hi:[1,0]
	v_pk_mul_f32 v[10:11], v[10:11], v[0:1] op_sel_hi:[1,0]
	v_pk_mul_f32 v[8:9], v[8:9], v[0:1] op_sel_hi:[1,0]
	v_pk_mul_f32 v[6:7], v[6:7], v[0:1] op_sel_hi:[1,0]
	v_pk_mul_f32 v[4:5], v[4:5], v[0:1] op_sel_hi:[1,0]
	v_pk_mul_f32 v[2:3], v[2:3], v[0:1] op_sel_hi:[1,0]
; DI unsigned pack2(float a, float b) { f32x2 v = {a, b}; bf16x2_t r = __builtin_convertvector(v, bf16x2_t); return __builtin_bit_cast(unsigned, r); }
; DI f32x16 mfma32(bf16x8 a, bf16x8 b, f32x16 c) { return __builtin_amdgcn_mfma_f32_32x32x16_bf16(a, b, c, 0, 0, 0); }
;     ...
;   const float mn = fmaxf(m, mx); const float alpha = __builtin_amdgcn_exp2f(m - mn);
;   const float neg = (MODE == 2 && !lanesel) ? NINF : -mn;
;   float ps = 0.f;
; #pragma unroll
;   for (int k2 = 0; k2 < 2; ++k2)
; #pragma unroll
;     for (int i = 0; i < 16; ++i) {
;       if (!(HM & (1 << k2))) continue;
;       const float pv = (MODE == 1) ? __builtin_amdgcn_exp2f(s[k2][i] + neg) : __builtin_amdgcn_exp2f(fmaf(s[k2][i], L2E, neg));
;       s[k2][i] = pv; ps += pv;
;     }
;   l = l * alpha + ps;
;   if (__builtin_amdgcn_ballot_w64(mn != m) != 0ull) {
; #pragma unroll
;     for (int dt = 0; dt < 2; ++dt)
; #pragma unroll
;       for (int i = 0; i < 16; ++i) o[dt][i] *= alpha;
;   }
;   m = mn;
; #pragma unroll
;   for (int st = 0; st < 4; ++st) {
;     if (!(HM & (1 << (st >> 1)))) continue;
;     const int k2 = st >> 1, b8 = 8 * (st & 1);
;     const u32x4 pw = {pack2(s[k2][b8], s[k2][b8 + 1]), pack2(s[k2][b8 + 2], s[k2][b8 + 3]), pack2(s[k2][b8 + 4], s[k2][b8 + 5]), pack2(s[k2][b8 + 6], s[k2][b8 + 7])};
;     const bf16x8 pb = __builtin_bit_cast(bf16x8, pw);
; #pragma unroll
;     for (int dt = 0; dt < 2; ++dt) {
;       const s16x4 lo = *(const s16x4*)(Vs + (32 * dt + r) * LSTR + 16 * st + 4 * h);
;       const s16x4 hi = *(const s16x4*)(Vs + (32 * dt + r) * LSTR + 16 * st + 8 + 4 * h);
;       const bf16x8 a = __builtin_shufflevector(lo, hi, 0, 1, 2, 3, 4, 5, 6, 7);
;       o[dt] = mfma32(a, pb, o[dt]);
;     }
;   }
.LBB0_827:
	v_cndmask_b32_e64 v214, -v212, v204, s[6:7]
	v_fmamk_f32 v82, v82, 0x3fb8aa3b, v214
	v_exp_f32_e32 v82, v82
	v_fmamk_f32 v83, v83, 0x3fb8aa3b, v214
	v_exp_f32_e32 v83, v83
	v_fmamk_f32 v84, v84, 0x3fb8aa3b, v214
	v_exp_f32_e32 v84, v84
	v_fmamk_f32 v85, v85, 0x3fb8aa3b, v214
	v_exp_f32_e32 v85, v85
	v_fmamk_f32 v86, v86, 0x3fb8aa3b, v214
	v_add_f32_e32 v217, 0, v82
	v_exp_f32_e32 v86, v86
	v_fmamk_f32 v87, v87, 0x3fb8aa3b, v214
	v_add_f32_e32 v217, v83, v217
	v_exp_f32_e32 v87, v87
	v_fmamk_f32 v88, v88, 0x3fb8aa3b, v214
	v_add_f32_e32 v217, v84, v217
	v_exp_f32_e32 v88, v88
	v_fmamk_f32 v89, v89, 0x3fb8aa3b, v214
	v_add_f32_e32 v217, v85, v217
	v_exp_f32_e32 v89, v89
	v_fmamk_f32 v90, v90, 0x3fb8aa3b, v214
	v_add_f32_e32 v217, v86, v217
	v_exp_f32_e32 v90, v90
	v_fmamk_f32 v91, v91, 0x3fb8aa3b, v214
	v_add_f32_e32 v217, v87, v217
	v_exp_f32_e32 v91, v91
	v_fmamk_f32 v92, v92, 0x3fb8aa3b, v214
	v_add_f32_e32 v217, v88, v217
	v_exp_f32_e32 v92, v92
	v_fmamk_f32 v93, v93, 0x3fb8aa3b, v214
	v_add_f32_e32 v217, v89, v217
	v_exp_f32_e32 v93, v93
	v_fmamk_f32 v94, v94, 0x3fb8aa3b, v214
	v_add_f32_e32 v217, v90, v217
	v_exp_f32_e32 v94, v94
	v_fmamk_f32 v95, v95, 0x3fb8aa3b, v214
	v_add_f32_e32 v217, v91, v217
	v_exp_f32_e32 v95, v95
	v_fmamk_f32 v96, v96, 0x3fb8aa3b, v214
	v_add_f32_e32 v217, v92, v217
	v_exp_f32_e32 v96, v96
	v_fmamk_f32 v97, v97, 0x3fb8aa3b, v214
	v_add_f32_e32 v217, v93, v217
	v_exp_f32_e32 v97, v97
	v_fmamk_f32 v66, v66, 0x3fb8aa3b, v214
	v_add_f32_e32 v217, v94, v217
	v_exp_f32_e32 v218, v66
	v_add_f32_e32 v217, v95, v217
	v_add_f32_e32 v217, v96, v217
	v_add_f32_e32 v217, v97, v217
	v_fmamk_f32 v67, v67, 0x3fb8aa3b, v214
	v_add_f32_e32 v66, v218, v217
	v_exp_f32_e32 v217, v67
	v_fmamk_f32 v67, v68, 0x3fb8aa3b, v214
	v_exp_f32_e32 v219, v67
	v_fmamk_f32 v67, v69, 0x3fb8aa3b, v214
	v_exp_f32_e32 v220, v67
	v_fmamk_f32 v67, v70, 0x3fb8aa3b, v214
	v_exp_f32_e32 v221, v67
	v_fmamk_f32 v67, v71, 0x3fb8aa3b, v214
	v_add_f32_e32 v66, v217, v66
	v_exp_f32_e32 v222, v67
	v_fmamk_f32 v67, v72, 0x3fb8aa3b, v214
	v_add_f32_e32 v66, v219, v66
	v_exp_f32_e32 v223, v67
	v_fmamk_f32 v67, v73, 0x3fb8aa3b, v214
	v_add_f32_e32 v66, v220, v66
	v_exp_f32_e32 v224, v67
	v_fmamk_f32 v67, v74, 0x3fb8aa3b, v214
	v_add_f32_e32 v66, v221, v66
	v_exp_f32_e32 v225, v67
	v_fmamk_f32 v67, v75, 0x3fb8aa3b, v214
	v_add_f32_e32 v66, v222, v66
	v_exp_f32_e32 v226, v67
	v_fmamk_f32 v67, v76, 0x3fb8aa3b, v214
	v_add_f32_e32 v66, v223, v66
	v_exp_f32_e32 v227, v67
	v_fmamk_f32 v67, v77, 0x3fb8aa3b, v214
	v_add_f32_e32 v66, v224, v66
	v_exp_f32_e32 v228, v67
	v_fmamk_f32 v67, v78, 0x3fb8aa3b, v214
	v_add_f32_e32 v66, v225, v66
	v_exp_f32_e32 v78, v67
	v_fmamk_f32 v67, v79, 0x3fb8aa3b, v214
	v_add_f32_e32 v66, v226, v66
	v_exp_f32_e32 v79, v67
	v_fmamk_f32 v67, v80, 0x3fb8aa3b, v214
	v_add_f32_e32 v66, v227, v66
	v_exp_f32_e32 v80, v67
	v_fmac_f32_e32 v214, 0x3fb8aa3b, v81
	v_add_f32_e32 v66, v228, v66
	v_exp_f32_e32 v81, v214
	v_add_f32_e32 v66, v78, v66
	v_add_f32_e32 v66, v79, v66
	v_add_f32_e32 v66, v80, v66
	v_add_f32_e32 v214, v81, v66
	v_fmac_f32_e32 v214, v213, v0
	v_add_u32_e32 v0, 0x2000, v198
	ds_read2_b64 v[70:73], v0 offset0:128 offset1:130
	ds_read2_b64 v[74:77], v0 offset0:132 offset1:134
	v_cvt_pk_bf16_f32 v66, v82, v83
	v_cvt_pk_bf16_f32 v67, v84, v85
	v_cvt_pk_bf16_f32 v68, v86, v87
	v_cvt_pk_bf16_f32 v69, v88, v89
	v_add_u32_e32 v82, 0x3000, v198
	s_mov_b64 s[8:9], 0
	s_waitcnt lgkmcnt(1)
	v_mfma_f32_32x32x16_bf16 v[34:49], v[70:73], v[66:69], v[2:17]
	ds_read2_b64 v[70:73], v82 offset0:192 offset1:194
	s_waitcnt lgkmcnt(0)
	v_mfma_f32_32x32x16_bf16 v[50:65], v[70:73], v[66:69], v[18:33]
	ds_read2_b64 v[70:73], v82 offset0:196 offset1:198
	v_cvt_pk_bf16_f32 v66, v90, v91
	v_cvt_pk_bf16_f32 v67, v92, v93
	v_cvt_pk_bf16_f32 v68, v94, v95
	v_cvt_pk_bf16_f32 v69, v96, v97
	s_waitcnt lgkmcnt(0)
	s_nop 0
	v_mfma_f32_32x32x16_bf16 v[50:65], v[70:73], v[66:69], v[50:65]
	ds_read2_b64 v[70:73], v0 offset0:136 offset1:138
	v_mfma_f32_32x32x16_bf16 v[34:49], v[74:77], v[66:69], v[34:49]
	v_cvt_pk_bf16_f32 v66, v218, v217
	v_cvt_pk_bf16_f32 v67, v219, v220
	v_cvt_pk_bf16_f32 v68, v221, v222
	v_cvt_pk_bf16_f32 v69, v223, v224
	s_waitcnt lgkmcnt(0)
	s_nop 0
	v_mfma_f32_32x32x16_bf16 v[34:49], v[70:73], v[66:69], v[34:49]
	ds_read2_b64 v[70:73], v82 offset0:200 offset1:202
	s_waitcnt lgkmcnt(0)
	v_mfma_f32_32x32x16_bf16 v[50:65], v[70:73], v[66:69], v[50:65]
	ds_read2_b64 v[70:73], v0 offset0:140 offset1:142
	v_cvt_pk_bf16_f32 v66, v225, v226
	v_cvt_pk_bf16_f32 v67, v227, v228
	v_cvt_pk_bf16_f32 v68, v78, v79
	v_cvt_pk_bf16_f32 v69, v80, v81
	s_waitcnt lgkmcnt(0)
	s_nop 0
	v_mfma_f32_32x32x16_bf16 v[2:17], v[70:73], v[66:69], v[34:49]
	ds_read2_b64 v[70:73], v82 offset0:204 offset1:206
	s_waitcnt lgkmcnt(0)
	v_mfma_f32_32x32x16_bf16 v[18:33], v[70:73], v[66:69], v[50:65]

; template <int MODE>
; DI void flash_loop(char* smem, const bf16_t* Kbase, size_t ldk, const bf16_t* Vtbase, size_t ldv, ull tiles, ull wtiles,
;                    const bf16x8 (&qf)[4], f32x16 (&o)[2], float& m, float& l, int tq, int tqmin, int tqmax, int maxdist, const float* cn_lds, ull lmask) {
;     ...
;   while (true) {
;     stash(0, ka, va);
;     __syncthreads();
;     const int t2 = next_tile(); if (t2 >= 0) issue(t2, ka, va);
;     compute(t0, 0);
;     if (t1 < 0) break;
;     stash(1, kb, vb);
;     __syncthreads();
;     const int t3 = next_tile(); if (t3 >= 0) issue(t3, kb, vb);
;     compute(t1, 1);
;     if (t2 < 0) break;
;     t0 = t2; t1 = t3;
.LBB0_832:
	s_nop 7
	s_nop 4
	v_cmp_gt_i32_e32 vcc, 0, v215
	s_cbranch_vccnz .LBB0_820
	s_branch .LBB0_834

; DI f32x16 mfma32(bf16x8 a, bf16x8 b, f32x16 c) { return __builtin_amdgcn_mfma_f32_32x32x16_bf16(a, b, c, 0, 0, 0); }
; DI int crow(int i, int h) { return (i & 3) + 8 * (i >> 2) + 4 * h; }
;     ...
;   f32x16 s[2];
; #pragma unroll
;   for (int k2 = 0; k2 < 2; ++k2) {
;     if (!(HM & (1 << k2))) continue;
; #pragma unroll
;     for (int i = 0; i < 16; ++i) s[k2][i] = 0.f;
; #pragma unroll
;     for (int ks = 0; ks < 4; ++ks) {
;       const bf16x8 a = *(const bf16x8*)(Ks + (32 * k2 + r) * LSTR + 16 * ks + 8 * h);
;       s[k2] = mfma32(a, qf[ks], s[k2]);
;     }
;   }
;   if (MODE == 1) {
; #pragma unroll
;     for (int k2 = 0; k2 < 2; ++k2)
; #pragma unroll
;       for (int g = 0; g < 4; ++g) {
;         if (!(HM & (1 << k2))) continue;
;         const f32x4 cv = *(const f32x4*)(cn_lds + key0 + 32 * k2 + 8 * g + 4 * h);
; #pragma unroll
;         for (int e = 0; e < 4; ++e) s[k2][4 * g + e] = fmaf(s[k2][4 * g + e], L2E, cv[e]);
;       }
;   }
;   float mx = NINF;
; #pragma unroll
;   for (int k2 = 0; k2 < 2; ++k2)
; #pragma unroll
;     for (int i = 0; i < 16; ++i) {
;       if (!(HM & (1 << k2))) continue;
;       float v = s[k2][i];
;       if (MASKED) {
;         const int tk = key0 + 32 * k2 + crow(i, h);
;         const bool valid = (MODE == 0) ? ((tk <= tq) && (tq - tk <= maxdist)) : (tk <= tq);
;         v = valid ? v : NINF; s[k2][i] = v;
;       }
;       mx = fmaxf(mx, v);
;     }
;   mx = fmaxf(mx, __shfl_xor(mx, 32));
;   if (MODE != 1) mx *= L2E;
;   if (MODE == 2) mx = lanesel ? mx : NINF;
;   const float mn = fmaxf(m, mx); const float alpha = __builtin_amdgcn_exp2f(m - mn);
;   const float neg = (MODE == 2 && !lanesel) ? NINF : -mn;
;   float ps = 0.f;
; #pragma unroll
;   for (int k2 = 0; k2 < 2; ++k2)
; #pragma unroll
;     for (int i = 0; i < 16; ++i) {
;       if (!(HM & (1 << k2))) continue;
;       const float pv = (MODE == 1) ? __builtin_amdgcn_exp2f(s[k2][i] + neg) : __builtin_amdgcn_exp2f(fmaf(s[k2][i], L2E, neg));
;       s[k2][i] = pv; ps += pv;
;     }
;   l = l * alpha + ps;
;   if (__builtin_amdgcn_ballot_w64(mn != m) != 0ull) {
; #pragma unroll
;     for (int dt = 0; dt < 2; ++dt)
; #pragma unroll
;       for (int i = 0; i < 16; ++i) o[dt][i] *= alpha;
;   }
.LBB0_836:
	v_lshlrev_b64 v[34:35], v215, 1
	v_and_b32_e32 v36, v34, v185
	v_and_b32_e32 v37, v35, v187
	v_cmp_eq_u64_e32 vcc, 0, v[36:37]
	s_cbranch_vccnz .LBB0_846
	ds_read_b128 v[146:149], v196 offset:18432
	ds_read_b128 v[150:153], v196 offset:18464
	ds_read_b128 v[154:157], v196 offset:18496
	ds_read_b128 v[158:161], v196 offset:18528
	ds_read_b128 v[162:165], v196 offset:23040
	v_lshlrev_b32_e32 v216, 6, v215
	v_or_b32_e32 v0, 63, v216
	v_and_b32_e32 v35, v35, v189
	v_and_b32_e32 v34, v34, v188
	v_cmp_lt_i32_e32 vcc, s28, v0
	v_cmp_eq_u64_e64 s[6:7], 0, v[34:35]
	s_mov_b64 s[8:9], -1
	s_and_b64 vcc, exec, vcc
	v_max_f32_e32 v215, v212, v212
	s_cbranch_vccnz .LBB0_841
	s_waitcnt lgkmcnt(4)
	v_mfma_f32_32x32x16_bf16 v[82:97], v[146:149], v[98:101], 0
	ds_read_b128 v[34:37], v196 offset:23072
	ds_read_b128 v[38:41], v196 offset:23104
	s_waitcnt lgkmcnt(5)
	v_mfma_f32_32x32x16_bf16 v[82:97], v[150:153], v[102:105], v[82:97]
	s_waitcnt lgkmcnt(2)
	v_mfma_f32_32x32x16_bf16 v[66:81], v[162:165], v[98:101], 0
	v_mfma_f32_32x32x16_bf16 v[82:97], v[154:157], v[106:109], v[82:97]
	s_waitcnt lgkmcnt(1)
	v_mfma_f32_32x32x16_bf16 v[66:81], v[34:37], v[102:105], v[66:81]
	ds_read_b128 v[34:37], v196 offset:23136
	v_mfma_f32_32x32x16_bf16 v[82:97], v[158:161], v[110:113], v[82:97]
	s_waitcnt lgkmcnt(1)
	v_mfma_f32_32x32x16_bf16 v[66:81], v[38:41], v[106:109], v[66:81]
	s_nop 9
	v_max3_f32 v0, v82, s35, v83
	v_max3_f32 v0, v0, v84, v85
	v_max3_f32 v0, v0, v86, v87
	v_max3_f32 v0, v0, v88, v89
	v_max3_f32 v0, v0, v90, v91
	v_max3_f32 v0, v0, v92, v93
	v_max3_f32 v0, v0, v94, v95
	s_waitcnt lgkmcnt(0)
	v_mfma_f32_32x32x16_bf16 v[66:81], v[34:37], v[110:113], v[66:81]
	v_max3_f32 v0, v0, v96, v97
	v_and_b32_e32 v35, 64, v202
	v_xor_b32_e32 v34, 32, v202
	v_add_u32_e32 v35, 64, v35
	v_cmp_lt_i32_e32 vcc, v34, v35
	s_nop 6
	v_max3_f32 v0, v0, v66, v67
	v_max3_f32 v0, v0, v68, v69
	v_max3_f32 v0, v0, v70, v71
	v_max3_f32 v0, v0, v72, v73
	v_max3_f32 v0, v0, v74, v75
	v_max3_f32 v0, v0, v76, v77
	v_max3_f32 v0, v0, v78, v79
	v_cndmask_b32_e32 v34, v202, v34, vcc
	v_max3_f32 v0, v0, v80, v81
	v_lshlrev_b32_e32 v34, 2, v34
	ds_bpermute_b32 v34, v34, v0
	s_waitcnt lgkmcnt(0)
	v_max_f32_e32 v34, v34, v34
	v_max_f32_e32 v0, v0, v34
	v_mul_f32_e32 v0, 0x3fb8aa3b, v0
	v_cndmask_b32_e64 v0, v0, v204, s[6:7]
	v_max_f32_e32 v211, v215, v0
	v_sub_f32_e32 v0, v212, v211
	v_exp_f32_e32 v0, v0
	v_cmp_neq_f32_e32 vcc, v211, v212
	s_cbranch_vccz .LBB0_840
	v_pk_mul_f32 v[32:33], v[32:33], v[0:1] op_sel_hi:[1,0]
	v_pk_mul_f32 v[30:31], v[30:31], v[0:1] op_sel_hi:[1,0]
	v_pk_mul_f32 v[28:29], v[28:29], v[0:1] op_sel_hi:[1,0]
	v_pk_mul_f32 v[26:27], v[26:27], v[0:1] op_sel_hi:[1,0]
	v_pk_mul_f32 v[24:25], v[24:25], v[0:1] op_sel_hi:[1,0]
	v_pk_mul_f32 v[22:23], v[22:23], v[0:1] op_sel_hi:[1,0]
	v_pk_mul_f32 v[20:21], v[20:21], v[0:1] op_sel_hi:[1,0]
	v_pk_mul_f32 v[18:19], v[18:19], v[0:1] op_sel_hi:[1,0]
	v_pk_mul_f32 v[16:17], v[16:17], v[0:1] op_sel_hi:[1,0]
	v_pk_mul_f32 v[14:15], v[14:15], v[0:1] op_sel_hi:[1,0]
	v_pk_mul_f32 v[12:13], v[12:13], v[0:1] op_sel_hi:[1,0]
	v_pk_mul_f32 v[10:11], v[10:11], v[0:1] op_sel_hi:[1,0]
	v_pk_mul_f32 v[8:9], v[8:9], v[0:1] op_sel_hi:[1,0]
	v_pk_mul_f32 v[6:7], v[6:7], v[0:1] op_sel_hi:[1,0]
	v_pk_mul_f32 v[4:5], v[4:5], v[0:1] op_sel_hi:[1,0]
	v_pk_mul_f32 v[2:3], v[2:3], v[0:1] op_sel_hi:[1,0]
; DI unsigned pack2(float a, float b) { f32x2 v = {a, b}; bf16x2_t r = __builtin_convertvector(v, bf16x2_t); return __builtin_bit_cast(unsigned, r); }
; DI f32x16 mfma32(bf16x8 a, bf16x8 b, f32x16 c) { return __builtin_amdgcn_mfma_f32_32x32x16_bf16(a, b, c, 0, 0, 0); }
;     ...
;   const float mn = fmaxf(m, mx); const float alpha = __builtin_amdgcn_exp2f(m - mn);
;   const float neg = (MODE == 2 && !lanesel) ? NINF : -mn;
;   float ps = 0.f;
; #pragma unroll
;   for (int k2 = 0; k2 < 2; ++k2)
; #pragma unroll
;     for (int i = 0; i < 16; ++i) {
;       if (!(HM & (1 << k2))) continue;
;       const float pv = (MODE == 1) ? __builtin_amdgcn_exp2f(s[k2][i] + neg) : __builtin_amdgcn_exp2f(fmaf(s[k2][i], L2E, neg));
;       s[k2][i] = pv; ps += pv;
;     }
;   l = l * alpha + ps;
;   if (__builtin_amdgcn_ballot_w64(mn != m) != 0ull) {
; #pragma unroll
;     for (int dt = 0; dt < 2; ++dt)
; #pragma unroll
;       for (int i = 0; i < 16; ++i) o[dt][i] *= alpha;
;   }
;   m = mn;
; #pragma unroll
;   for (int st = 0; st < 4; ++st) {
;     if (!(HM & (1 << (st >> 1)))) continue;
;     const int k2 = st >> 1, b8 = 8 * (st & 1);
;     const u32x4 pw = {pack2(s[k2][b8], s[k2][b8 + 1]), pack2(s[k2][b8 + 2], s[k2][b8 + 3]), pack2(s[k2][b8 + 4], s[k2][b8 + 5]), pack2(s[k2][b8 + 6], s[k2][b8 + 7])};
;     const bf16x8 pb = __builtin_bit_cast(bf16x8, pw);
; #pragma unroll
;     for (int dt = 0; dt < 2; ++dt) {
;       const s16x4 lo = *(const s16x4*)(Vs + (32 * dt + r) * LSTR + 16 * st + 4 * h);
;       const s16x4 hi = *(const s16x4*)(Vs + (32 * dt + r) * LSTR + 16 * st + 8 + 4 * h);
;       const bf16x8 a = __builtin_shufflevector(lo, hi, 0, 1, 2, 3, 4, 5, 6, 7);
;       o[dt] = mfma32(a, pb, o[dt]);
;     }
;   }
.LBB0_840:
	v_cndmask_b32_e64 v213, -v211, v204, s[6:7]
	v_fmamk_f32 v82, v82, 0x3fb8aa3b, v213
	v_exp_f32_e32 v82, v82
	v_fmamk_f32 v83, v83, 0x3fb8aa3b, v213
	v_exp_f32_e32 v83, v83
	v_fmamk_f32 v84, v84, 0x3fb8aa3b, v213
	v_exp_f32_e32 v84, v84
	v_fmamk_f32 v85, v85, 0x3fb8aa3b, v213
	v_exp_f32_e32 v85, v85
	v_fmamk_f32 v86, v86, 0x3fb8aa3b, v213
	v_add_f32_e32 v217, 0, v82
	v_exp_f32_e32 v86, v86
	v_fmamk_f32 v87, v87, 0x3fb8aa3b, v213
	v_add_f32_e32 v217, v83, v217
	v_exp_f32_e32 v87, v87
	v_fmamk_f32 v88, v88, 0x3fb8aa3b, v213
	v_add_f32_e32 v217, v84, v217
	v_exp_f32_e32 v88, v88
	v_fmamk_f32 v89, v89, 0x3fb8aa3b, v213
	v_add_f32_e32 v217, v85, v217
	v_exp_f32_e32 v89, v89
	v_fmamk_f32 v90, v90, 0x3fb8aa3b, v213
	v_add_f32_e32 v217, v86, v217
	v_exp_f32_e32 v90, v90
	v_fmamk_f32 v91, v91, 0x3fb8aa3b, v213
	v_add_f32_e32 v217, v87, v217
	v_exp_f32_e32 v91, v91
	v_fmamk_f32 v92, v92, 0x3fb8aa3b, v213
	v_add_f32_e32 v217, v88, v217
	v_exp_f32_e32 v92, v92
	v_fmamk_f32 v93, v93, 0x3fb8aa3b, v213
	v_add_f32_e32 v217, v89, v217
	v_exp_f32_e32 v93, v93
	v_fmamk_f32 v94, v94, 0x3fb8aa3b, v213
	v_add_f32_e32 v217, v90, v217
	v_exp_f32_e32 v94, v94
	v_fmamk_f32 v95, v95, 0x3fb8aa3b, v213
	v_add_f32_e32 v217, v91, v217
	v_exp_f32_e32 v95, v95
	v_fmamk_f32 v96, v96, 0x3fb8aa3b, v213
	v_add_f32_e32 v217, v92, v217
	v_exp_f32_e32 v96, v96
	v_fmamk_f32 v97, v97, 0x3fb8aa3b, v213
	v_add_f32_e32 v217, v93, v217
	v_exp_f32_e32 v97, v97
	v_fmamk_f32 v66, v66, 0x3fb8aa3b, v213
	v_add_f32_e32 v217, v94, v217
	v_exp_f32_e32 v218, v66
	v_add_f32_e32 v217, v95, v217
	v_add_f32_e32 v217, v96, v217
	v_add_f32_e32 v217, v97, v217
	v_fmamk_f32 v67, v67, 0x3fb8aa3b, v213
	v_add_f32_e32 v66, v218, v217
	v_exp_f32_e32 v217, v67
	v_fmamk_f32 v67, v68, 0x3fb8aa3b, v213
	v_exp_f32_e32 v219, v67
	v_fmamk_f32 v67, v69, 0x3fb8aa3b, v213
	v_exp_f32_e32 v220, v67
	v_fmamk_f32 v67, v70, 0x3fb8aa3b, v213
	v_exp_f32_e32 v221, v67
	v_fmamk_f32 v67, v71, 0x3fb8aa3b, v213
	v_add_f32_e32 v66, v217, v66
	v_exp_f32_e32 v222, v67
	v_fmamk_f32 v67, v72, 0x3fb8aa3b, v213
	v_add_f32_e32 v66, v219, v66
	v_exp_f32_e32 v223, v67
	v_fmamk_f32 v67, v73, 0x3fb8aa3b, v213
	v_add_f32_e32 v66, v220, v66
	v_exp_f32_e32 v224, v67
	v_fmamk_f32 v67, v74, 0x3fb8aa3b, v213
	v_add_f32_e32 v66, v221, v66
	v_exp_f32_e32 v225, v67
	v_fmamk_f32 v67, v75, 0x3fb8aa3b, v213
	v_add_f32_e32 v66, v222, v66
	v_exp_f32_e32 v226, v67
	v_fmamk_f32 v67, v76, 0x3fb8aa3b, v213
	v_add_f32_e32 v66, v223, v66
	v_exp_f32_e32 v227, v67
	v_fmamk_f32 v67, v77, 0x3fb8aa3b, v213
	v_add_f32_e32 v66, v224, v66
	v_exp_f32_e32 v228, v67
	v_fmamk_f32 v67, v78, 0x3fb8aa3b, v213
	v_add_f32_e32 v66, v225, v66
	v_exp_f32_e32 v78, v67
	v_fmamk_f32 v67, v79, 0x3fb8aa3b, v213
	v_add_f32_e32 v66, v226, v66
	v_exp_f32_e32 v79, v67
	v_fmamk_f32 v67, v80, 0x3fb8aa3b, v213
	v_add_f32_e32 v66, v227, v66
	v_exp_f32_e32 v80, v67
	v_fmac_f32_e32 v213, 0x3fb8aa3b, v81
	v_add_f32_e32 v66, v228, v66
	v_exp_f32_e32 v81, v213
	v_add_f32_e32 v66, v78, v66
	v_add_f32_e32 v66, v79, v66
	v_add_f32_e32 v66, v80, v66
	v_add_f32_e32 v213, v81, v66
	v_fmac_f32_e32 v213, v214, v0
	v_add_u32_e32 v0, 0x6800, v198
	ds_read2_b64 v[70:73], v0 offset0:128 offset1:130
	ds_read2_b64 v[74:77], v0 offset0:132 offset1:134
	v_cvt_pk_bf16_f32 v66, v82, v83
	v_cvt_pk_bf16_f32 v67, v84, v85
	v_cvt_pk_bf16_f32 v68, v86, v87
	v_cvt_pk_bf16_f32 v69, v88, v89
	v_add_u32_e32 v82, 0x7800, v198
	s_mov_b64 s[8:9], 0
	s_waitcnt lgkmcnt(1)
	v_mfma_f32_32x32x16_bf16 v[34:49], v[70:73], v[66:69], v[2:17]
	ds_read2_b64 v[70:73], v82 offset0:192 offset1:194
	s_waitcnt lgkmcnt(0)
	v_mfma_f32_32x32x16_bf16 v[50:65], v[70:73], v[66:69], v[18:33]
	ds_read2_b64 v[70:73], v82 offset0:196 offset1:198
	v_cvt_pk_bf16_f32 v66, v90, v91
	v_cvt_pk_bf16_f32 v67, v92, v93
	v_cvt_pk_bf16_f32 v68, v94, v95
	v_cvt_pk_bf16_f32 v69, v96, v97
	s_waitcnt lgkmcnt(0)
	s_nop 0
	v_mfma_f32_32x32x16_bf16 v[50:65], v[70:73], v[66:69], v[50:65]
	ds_read2_b64 v[70:73], v0 offset0:136 offset1:138
	v_mfma_f32_32x32x16_bf16 v[34:49], v[74:77], v[66:69], v[34:49]
	v_cvt_pk_bf16_f32 v66, v218, v217
	v_cvt_pk_bf16_f32 v67, v219, v220
	v_cvt_pk_bf16_f32 v68, v221, v222
	v_cvt_pk_bf16_f32 v69, v223, v224
	s_waitcnt lgkmcnt(0)
	s_nop 0
	v_mfma_f32_32x32x16_bf16 v[34:49], v[70:73], v[66:69], v[34:49]
	ds_read2_b64 v[70:73], v82 offset0:200 offset1:202
	s_waitcnt lgkmcnt(0)
	v_mfma_f32_32x32x16_bf16 v[50:65], v[70:73], v[66:69], v[50:65]
	ds_read2_b64 v[70:73], v0 offset0:140 offset1:142
	v_cvt_pk_bf16_f32 v66, v225, v226
	v_cvt_pk_bf16_f32 v67, v227, v228
	v_cvt_pk_bf16_f32 v68, v78, v79
	v_cvt_pk_bf16_f32 v69, v80, v81
	s_waitcnt lgkmcnt(0)
	s_nop 0
	v_mfma_f32_32x32x16_bf16 v[2:17], v[70:73], v[66:69], v[34:49]
	ds_read2_b64 v[70:73], v82 offset0:204 offset1:206
	s_waitcnt lgkmcnt(0)
	v_mfma_f32_32x32x16_bf16 v[18:33], v[70:73], v[66:69], v[50:65]

; DI f32x16 mfma32(bf16x8 a, bf16x8 b, f32x16 c) { return __builtin_amdgcn_mfma_f32_32x32x16_bf16(a, b, c, 0, 0, 0); }
; DI int crow(int i, int h) { return (i & 3) + 8 * (i >> 2) + 4 * h; }
;     ...
; #pragma unroll
;   for (int k2 = 0; k2 < 2; ++k2) {
;     if (!(HM & (1 << k2))) continue;
; #pragma unroll
;     for (int i = 0; i < 16; ++i) s[k2][i] = 0.f;
; #pragma unroll
;     for (int ks = 0; ks < 4; ++ks) {
;       const bf16x8 a = *(const bf16x8*)(Ks + (32 * k2 + r) * LSTR + 16 * ks + 8 * h);
;       s[k2] = mfma32(a, qf[ks], s[k2]);
;     }
;   }
;   if (MODE == 1) {
; #pragma unroll
;     for (int k2 = 0; k2 < 2; ++k2)
; #pragma unroll
;       for (int g = 0; g < 4; ++g) {
;         if (!(HM & (1 << k2))) continue;
;         const f32x4 cv = *(const f32x4*)(cn_lds + key0 + 32 * k2 + 8 * g + 4 * h);
; #pragma unroll
;         for (int e = 0; e < 4; ++e) s[k2][4 * g + e] = fmaf(s[k2][4 * g + e], L2E, cv[e]);
;       }
;   }
;   float mx = NINF;
; #pragma unroll
;   for (int k2 = 0; k2 < 2; ++k2)
; #pragma unroll
;     for (int i = 0; i < 16; ++i) {
;       if (!(HM & (1 << k2))) continue;
;       float v = s[k2][i];
;       if (MASKED) {
;         const int tk = key0 + 32 * k2 + crow(i, h);
;         const bool valid = (MODE == 0) ? ((tk <= tq) && (tq - tk <= maxdist)) : (tk <= tq);
;         v = valid ? v : NINF; s[k2][i] = v;
;       }
;       mx = fmaxf(mx, v);
;     }
;   mx = fmaxf(mx, __shfl_xor(mx, 32));
;   if (MODE != 1) mx *= L2E;
;   if (MODE == 2) mx = lanesel ? mx : NINF;
;   const float mn = fmaxf(m, mx); const float alpha = __builtin_amdgcn_exp2f(m - mn);
;   const float neg = (MODE == 2 && !lanesel) ? NINF : -mn;
;   float ps = 0.f;
; #pragma unroll
;   for (int k2 = 0; k2 < 2; ++k2)
; #pragma unroll
;     for (int i = 0; i < 16; ++i) {
;       if (!(HM & (1 << k2))) continue;
;       const float pv = (MODE == 1) ? __builtin_amdgcn_exp2f(s[k2][i] + neg) : __builtin_amdgcn_exp2f(fmaf(s[k2][i], L2E, neg));
;       s[k2][i] = pv; ps += pv;
;     }
;   l = l * alpha + ps;
;   if (__builtin_amdgcn_ballot_w64(mn != m) != 0ull) {
; #pragma unroll
;     for (int dt = 0; dt < 2; ++dt)
; #pragma unroll
;       for (int i = 0; i < 16; ++i) o[dt][i] *= alpha;
;   }
.LBB0_923:
	s_lshr_b64 s[6:7], s[8:9], s33
	s_and_b32 s58, s6, 1
	s_cmp_eq_u64 s[58:59], 0
	s_cbranch_scc1 .LBB0_947
	s_lshl_b32 s58, s33, 6
	s_or_b32 s33, s58, 63
	s_cmp_le_u32 s58, s29
	s_cselect_b64 s[6:7], -1, 0
	s_or_b32 s36, s58, 31
	s_cmp_ge_i32 s36, s28
	s_cselect_b64 s[36:37], -1, 0
	s_and_b64 s[6:7], s[6:7], s[36:37]
	v_cndmask_b32_e64 v0, 0, 1, s[6:7]
	s_or_b32 s6, s58, 32
	s_cmp_gt_u32 s6, s29
	s_cselect_b64 s[6:7], -1, 0
	s_cmp_lt_i32 s33, s28
	s_cselect_b64 s[36:37], -1, 0
	v_readfirstlane_b32 s38, v0
	s_or_b32 s39, s38, 2
	s_or_b64 s[6:7], s[6:7], s[36:37]
	s_and_b64 s[6:7], s[6:7], exec
	s_cselect_b32 s68, s38, s39
	s_mov_b64 s[62:63], -1
	s_mov_b64 s[54:55], 0
	s_cmp_lt_i32 s68, 2
	s_mov_b64 s[6:7], 0
	s_cbranch_scc1 .LBB0_940
	s_cmp_eq_u32 s68, 2
	s_mov_b64 s[6:7], -1
	s_cbranch_scc0 .LBB0_929
	ds_read_b128 v[34:37], v199 offset:4608
	ds_read_b128 v[50:53], v199 offset:4640
	v_or_b32_e32 v0, s58, v197
	s_waitcnt lgkmcnt(1)
	v_mfma_f32_32x32x16_bf16 v[34:49], v[34:37], v[98:101], 0
	s_waitcnt lgkmcnt(0)
	v_mfma_f32_32x32x16_bf16 v[34:49], v[50:53], v[102:105], v[34:49]
	ds_read_b128 v[50:53], v199 offset:4672
	s_waitcnt lgkmcnt(0)
	v_mfma_f32_32x32x16_bf16 v[34:49], v[50:53], v[106:109], v[34:49]
	ds_read_b128 v[50:53], v199 offset:4704
	s_waitcnt lgkmcnt(0)
	v_mfma_f32_32x32x16_bf16 v[34:49], v[50:53], v[110:113], v[34:49]
	v_or_b32_e32 v50, 32, v0
	v_cmp_gt_u32_e32 vcc, v50, v157
	v_cmp_lt_i32_e64 s[6:7], v50, v147
	s_or_b64 vcc, vcc, s[6:7]
	s_nop 7
	v_cndmask_b32_e32 v66, v34, v204, vcc
	v_bitop3_b32 v34, s58, v205, v197 bitop3:0x36
	v_cmp_ge_u32_e32 vcc, v50, v157
	v_cmp_gt_i32_e64 s[6:7], v34, v158
	s_or_b64 vcc, vcc, s[6:7]
	v_cndmask_b32_e32 v67, v35, v204, vcc
	v_or_b32_e32 v35, 34, v0
	v_cmp_gt_u32_e32 vcc, v35, v157
	v_cmp_lt_i32_e64 s[6:7], v35, v147
	s_or_b64 vcc, vcc, s[6:7]
	v_or_b32_e32 v35, 35, v0
	v_cndmask_b32_e32 v68, v36, v204, vcc
	v_cmp_gt_u32_e32 vcc, v35, v157
	v_cmp_lt_i32_e64 s[6:7], v35, v147
	s_or_b64 vcc, vcc, s[6:7]
	v_or_b32_e32 v35, 40, v0
	v_cndmask_b32_e32 v69, v37, v204, vcc
	v_cmp_gt_u32_e32 vcc, v35, v157
	v_cmp_lt_i32_e64 s[6:7], v35, v147
	s_or_b64 vcc, vcc, s[6:7]
	v_or_b32_e32 v35, 41, v0
	v_cndmask_b32_e32 v70, v38, v204, vcc
	v_cmp_gt_u32_e32 vcc, v35, v157
	v_cmp_lt_i32_e64 s[6:7], v35, v147
	s_or_b64 vcc, vcc, s[6:7]
	v_or_b32_e32 v35, 42, v0
	v_cndmask_b32_e32 v71, v39, v204, vcc
	v_cmp_gt_u32_e32 vcc, v35, v157
	v_cmp_lt_i32_e64 s[6:7], v35, v147
	s_or_b64 vcc, vcc, s[6:7]
	v_or_b32_e32 v35, 43, v0
	v_cndmask_b32_e32 v77, v40, v204, vcc
	v_cmp_gt_u32_e32 vcc, v35, v157
	v_cmp_lt_i32_e64 s[6:7], v35, v147
	s_or_b64 vcc, vcc, s[6:7]
	v_or_b32_e32 v35, 48, v0
	v_cndmask_b32_e32 v78, v41, v204, vcc
	v_cmp_gt_u32_e32 vcc, v35, v157
	v_cmp_lt_i32_e64 s[6:7], v35, v147
	s_or_b64 vcc, vcc, s[6:7]
	v_or_b32_e32 v35, 49, v0
	v_cndmask_b32_e32 v79, v42, v204, vcc
	v_cmp_gt_u32_e32 vcc, v35, v157
	v_cmp_lt_i32_e64 s[6:7], v35, v147
	s_or_b64 vcc, vcc, s[6:7]
	v_or_b32_e32 v35, 50, v0
	v_cndmask_b32_e32 v80, v43, v204, vcc
	v_cmp_gt_u32_e32 vcc, v35, v157
	v_cmp_lt_i32_e64 s[6:7], v35, v147
	s_or_b64 vcc, vcc, s[6:7]
	v_or_b32_e32 v35, 51, v0
	v_cndmask_b32_e32 v81, v44, v204, vcc
	v_cmp_gt_u32_e32 vcc, v35, v157
	v_cmp_lt_i32_e64 s[6:7], v35, v147
	s_or_b64 vcc, vcc, s[6:7]
	v_or_b32_e32 v35, 56, v0
	v_cndmask_b32_e32 v76, v45, v204, vcc
	v_cmp_gt_u32_e32 vcc, v35, v157
	v_cmp_lt_i32_e64 s[6:7], v35, v147
	s_or_b64 vcc, vcc, s[6:7]
	v_or_b32_e32 v35, 57, v0
	v_max3_f32 v34, v66, s35, v67
	v_cndmask_b32_e32 v73, v46, v204, vcc
	v_cmp_gt_u32_e32 vcc, v35, v157
	v_cmp_lt_i32_e64 s[6:7], v35, v147
	v_max3_f32 v34, v34, v68, v69
	s_or_b64 vcc, vcc, s[6:7]
	v_or_b32_e32 v35, 58, v0
	v_max3_f32 v34, v34, v70, v71
	v_cndmask_b32_e32 v74, v47, v204, vcc
	v_cmp_gt_u32_e32 vcc, v35, v157
	v_cmp_lt_i32_e64 s[6:7], v35, v147
	v_max3_f32 v34, v34, v77, v78
	s_or_b64 vcc, vcc, s[6:7]
	v_or_b32_e32 v0, 59, v0
	v_max3_f32 v34, v34, v79, v80
	v_cndmask_b32_e32 v75, v48, v204, vcc
	v_cmp_gt_u32_e32 vcc, v0, v157
	v_cmp_lt_i32_e64 s[6:7], v0, v147
	v_max3_f32 v34, v34, v81, v76
	s_or_b64 vcc, vcc, s[6:7]
	v_max3_f32 v34, v34, v73, v74
	v_cndmask_b32_e32 v72, v49, v204, vcc
	v_and_b32_e32 v35, 64, v202
	v_max3_f32 v0, v34, v75, v72
	v_xor_b32_e32 v34, 32, v202
	v_add_u32_e32 v35, 64, v35
	v_cmp_lt_i32_e32 vcc, v34, v35
	s_nop 1
	v_cndmask_b32_e32 v34, v202, v34, vcc
	v_lshlrev_b32_e32 v34, 2, v34
	ds_bpermute_b32 v34, v34, v0
	s_waitcnt lgkmcnt(0)
	v_max_f32_e32 v34, v34, v34
	v_max_f32_e32 v0, v0, v34
	v_mul_f32_e32 v0, 0x3fb8aa3b, v0
	v_max_f32_e32 v34, v159, v159
	v_max_f32_e32 v160, v34, v0
	v_sub_f32_e32 v0, v159, v160
	v_exp_f32_e32 v0, v0
	v_cmp_neq_f32_e32 vcc, v160, v159
	s_cbranch_vccz .LBB0_928
	v_pk_mul_f32 v[32:33], v[32:33], v[0:1] op_sel_hi:[1,0]
	v_pk_mul_f32 v[30:31], v[30:31], v[0:1] op_sel_hi:[1,0]
	v_pk_mul_f32 v[28:29], v[28:29], v[0:1] op_sel_hi:[1,0]
	v_pk_mul_f32 v[26:27], v[26:27], v[0:1] op_sel_hi:[1,0]
	v_pk_mul_f32 v[24:25], v[24:25], v[0:1] op_sel_hi:[1,0]
	v_pk_mul_f32 v[22:23], v[22:23], v[0:1] op_sel_hi:[1,0]
	v_pk_mul_f32 v[20:21], v[20:21], v[0:1] op_sel_hi:[1,0]
	v_pk_mul_f32 v[18:19], v[18:19], v[0:1] op_sel_hi:[1,0]
	v_pk_mul_f32 v[16:17], v[16:17], v[0:1] op_sel_hi:[1,0]
	v_pk_mul_f32 v[14:15], v[14:15], v[0:1] op_sel_hi:[1,0]
	v_pk_mul_f32 v[12:13], v[12:13], v[0:1] op_sel_hi:[1,0]
	v_pk_mul_f32 v[10:11], v[10:11], v[0:1] op_sel_hi:[1,0]
	v_pk_mul_f32 v[8:9], v[8:9], v[0:1] op_sel_hi:[1,0]
	v_pk_mul_f32 v[6:7], v[6:7], v[0:1] op_sel_hi:[1,0]
	v_pk_mul_f32 v[4:5], v[4:5], v[0:1] op_sel_hi:[1,0]
	v_pk_mul_f32 v[2:3], v[2:3], v[0:1] op_sel_hi:[1,0]
; DI unsigned pack2(float a, float b) { f32x2 v = {a, b}; bf16x2_t r = __builtin_convertvector(v, bf16x2_t); return __builtin_bit_cast(unsigned, r); }
; DI f32x16 mfma32(bf16x8 a, bf16x8 b, f32x16 c) { return __builtin_amdgcn_mfma_f32_32x32x16_bf16(a, b, c, 0, 0, 0); }
;     ...
;   const float mn = fmaxf(m, mx); const float alpha = __builtin_amdgcn_exp2f(m - mn);
;   const float neg = (MODE == 2 && !lanesel) ? NINF : -mn;
;   float ps = 0.f;
; #pragma unroll
;   for (int k2 = 0; k2 < 2; ++k2)
; #pragma unroll
;     for (int i = 0; i < 16; ++i) {
;       if (!(HM & (1 << k2))) continue;
;       const float pv = (MODE == 1) ? __builtin_amdgcn_exp2f(s[k2][i] + neg) : __builtin_amdgcn_exp2f(fmaf(s[k2][i], L2E, neg));
;       s[k2][i] = pv; ps += pv;
;     }
;   l = l * alpha + ps;
;   if (__builtin_amdgcn_ballot_w64(mn != m) != 0ull) {
; #pragma unroll
;     for (int dt = 0; dt < 2; ++dt)
; #pragma unroll
;       for (int i = 0; i < 16; ++i) o[dt][i] *= alpha;
;   }
;   m = mn;
; #pragma unroll
;   for (int st = 0; st < 4; ++st) {
;     if (!(HM & (1 << (st >> 1)))) continue;
;     const int k2 = st >> 1, b8 = 8 * (st & 1);
;     const u32x4 pw = {pack2(s[k2][b8], s[k2][b8 + 1]), pack2(s[k2][b8 + 2], s[k2][b8 + 3]), pack2(s[k2][b8 + 4], s[k2][b8 + 5]), pack2(s[k2][b8 + 6], s[k2][b8 + 7])};
;     const bf16x8 pb = __builtin_bit_cast(bf16x8, pw);
; #pragma unroll
;     for (int dt = 0; dt < 2; ++dt) {
;       const s16x4 lo = *(const s16x4*)(Vs + (32 * dt + r) * LSTR + 16 * st + 4 * h);
;       const s16x4 hi = *(const s16x4*)(Vs + (32 * dt + r) * LSTR + 16 * st + 8 + 4 * h);
;       const bf16x8 a = __builtin_shufflevector(lo, hi, 0, 1, 2, 3, 4, 5, 6, 7);
;       o[dt] = mfma32(a, pb, o[dt]);
;     }
;   }
.LBB0_928:
	v_fma_f32 v66, v66, s34, -v160
	v_exp_f32_e32 v82, v66
	v_fma_f32 v66, v67, s34, -v160
	v_exp_f32_e32 v83, v66
	v_fma_f32 v66, v68, s34, -v160
	v_exp_f32_e32 v84, v66
	v_fma_f32 v66, v69, s34, -v160
	v_add_f32_e32 v67, 0, v82
	v_exp_f32_e32 v85, v66
	v_fma_f32 v66, v70, s34, -v160
	v_add_f32_e32 v67, v83, v67
	v_exp_f32_e32 v70, v66
	v_fma_f32 v66, v71, s34, -v160
	v_exp_f32_e32 v71, v66
	v_add_f32_e32 v66, v84, v67
	v_fma_f32 v67, v77, s34, -v160
	v_exp_f32_e32 v86, v67
	v_fma_f32 v67, v78, s34, -v160
	v_add_f32_e32 v66, v85, v66
	v_exp_f32_e32 v87, v67
	v_fma_f32 v67, v79, s34, -v160
	v_add_f32_e32 v66, v70, v66
	v_exp_f32_e32 v88, v67
	v_fma_f32 v67, v80, s34, -v160
	v_add_f32_e32 v66, v71, v66
	v_exp_f32_e32 v89, v67
	v_add_f32_e32 v66, v86, v66
	v_add_f32_e32 v66, v87, v66
	v_add_f32_e32 v66, v88, v66
	v_add_f32_e32 v90, v89, v66
	v_fma_f32 v66, v81, s34, -v160
	v_add_u32_e32 v92, 0x2000, v198
	v_exp_f32_e32 v91, v66
	ds_read2_b64 v[66:69], v92 offset0:136 offset1:138
	v_fma_f32 v76, v76, s34, -v160
	v_cvt_pk_bf16_f32 v78, v70, v71
	v_add_u32_e32 v70, 0x3000, v198
	v_exp_f32_e32 v93, v76
	v_cvt_pk_bf16_f32 v76, v82, v83
	ds_read2_b64 v[80:83], v70 offset0:200 offset1:202
	v_cvt_pk_bf16_f32 v77, v84, v85
	v_cvt_pk_bf16_f32 v79, v86, v87
	v_fma_f32 v71, v72, s34, -v160
	s_mov_b64 s[6:7], 0
	s_waitcnt lgkmcnt(1)
	v_mfma_f32_32x32x16_bf16 v[34:49], v[66:69], v[76:79], v[2:17]
	v_fma_f32 v66, v73, s34, -v160
	v_exp_f32_e32 v84, v66
	v_fma_f32 v66, v74, s34, -v160
	v_exp_f32_e32 v85, v66
	v_fma_f32 v66, v75, s34, -v160
	v_exp_f32_e32 v86, v66
	ds_read2_b64 v[66:69], v92 offset0:140 offset1:142
	s_waitcnt lgkmcnt(1)
	v_mfma_f32_32x32x16_bf16 v[50:65], v[80:83], v[76:79], v[18:33]
	v_exp_f32_e32 v78, v71
	ds_read2_b64 v[70:73], v70 offset0:204 offset1:206
	v_cvt_pk_bf16_f32 v74, v88, v89
	v_cvt_pk_bf16_f32 v75, v91, v93
	v_cvt_pk_bf16_f32 v76, v84, v85
	v_cvt_pk_bf16_f32 v77, v86, v78
	s_waitcnt lgkmcnt(1)
	s_nop 0
	v_mfma_f32_32x32x16_bf16 v[2:17], v[66:69], v[74:77], v[34:49]
	v_add_f32_e32 v66, v91, v90
	v_add_f32_e32 v66, v93, v66
	v_add_f32_e32 v66, v84, v66
	v_add_f32_e32 v66, v85, v66
	v_add_f32_e32 v66, v86, v66
	v_add_f32_e32 v162, v78, v66
	v_fmac_f32_e32 v162, v161, v0
	s_waitcnt lgkmcnt(0)
	v_mfma_f32_32x32x16_bf16 v[18:33], v[70:73], v[74:77], v[50:65]

; DI f32x16 mfma32(bf16x8 a, bf16x8 b, f32x16 c) { return __builtin_amdgcn_mfma_f32_32x32x16_bf16(a, b, c, 0, 0, 0); }
;     ...
; #pragma unroll
;   for (int k2 = 0; k2 < 2; ++k2) {
;     if (!(HM & (1 << k2))) continue;
; #pragma unroll
;     for (int i = 0; i < 16; ++i) s[k2][i] = 0.f;
; #pragma unroll
;     for (int ks = 0; ks < 4; ++ks) {
;       const bf16x8 a = *(const bf16x8*)(Ks + (32 * k2 + r) * LSTR + 16 * ks + 8 * h);
;       s[k2] = mfma32(a, qf[ks], s[k2]);
;     }
;   }
;   if (MODE == 1) {
; #pragma unroll
;     for (int k2 = 0; k2 < 2; ++k2)
; #pragma unroll
;       for (int g = 0; g < 4; ++g) {
;         if (!(HM & (1 << k2))) continue;
;         const f32x4 cv = *(const f32x4*)(cn_lds + key0 + 32 * k2 + 8 * g + 4 * h);
; #pragma unroll
;         for (int e = 0; e < 4; ++e) s[k2][4 * g + e] = fmaf(s[k2][4 * g + e], L2E, cv[e]);
;       }
;   }
;   float mx = NINF;
; #pragma unroll
;   for (int k2 = 0; k2 < 2; ++k2)
; #pragma unroll
;     for (int i = 0; i < 16; ++i) {
;       if (!(HM & (1 << k2))) continue;
;       float v = s[k2][i];
;       if (MASKED) {
;         const int tk = key0 + 32 * k2 + crow(i, h);
;         const bool valid = (MODE == 0) ? ((tk <= tq) && (tq - tk <= maxdist)) : (tk <= tq);
;         v = valid ? v : NINF; s[k2][i] = v;
;       }
;       mx = fmaxf(mx, v);
; template <int MODE>
; DI void flash_loop(char* smem, const bf16_t* Kbase, size_t ldk, const bf16_t* Vtbase, size_t ldv, ull tiles, ull wtiles,
;                    const bf16x8 (&qf)[4], f32x16 (&o)[2], float& m, float& l, int tq, int tqmin, int tqmax, int maxdist, const float* cn_lds, ull lmask) {
;     ...
;     const bool interior = (64 * kt + 63 <= tqmin) && (MODE != 0 || (tqmax - 64 * kt <= maxdist));
;     int hm = 3;
;     if (MODE == 0) {
;       hm = 0;
;       if (64 * kt <= tqmax && 64 * kt + 31 >= tqmin - maxdist) hm |= 1;
;       if (64 * kt + 32 <= tqmax && 64 * kt + 63 >= tqmin - maxdist) hm |= 2;
;     }
;     if (MODE == 0 && hm == 1) attn_tile<MODE, true, 1>(Ks, Vs, qf, o, m, l, 64 * kt, tq, maxdist, cn_lds, sel);
;     else if (MODE == 0 && hm == 2) attn_tile<MODE, true, 2>(Ks, Vs, qf, o, m, l, 64 * kt, tq, maxdist, cn_lds, sel);
;     else if (interior) attn_tile<MODE, false>(Ks, Vs, qf, o, m, l, 64 * kt, tq, maxdist, cn_lds, sel);
;     else attn_tile<MODE, true>(Ks, Vs, qf, o, m, l, 64 * kt, tq, maxdist, cn_lds, sel);
.LBB0_931:
	ds_read_b128 v[82:85], v196
	ds_read_b128 v[78:81], v196 offset:32
	ds_read_b128 v[74:77], v196 offset:64
	ds_read_b128 v[66:69], v196 offset:96
	ds_read_b128 v[70:73], v196 offset:4608
	s_cmp_le_u32 s33, s5
	s_cselect_b64 s[6:7], -1, 0
	s_cmp_ge_i32 s58, s30
	s_cselect_b64 s[36:37], -1, 0
	s_and_b64 s[6:7], s[6:7], s[36:37]
	s_andn2_b64 vcc, exec, s[6:7]
	s_mov_b64 s[6:7], -1
	s_cbranch_vccz .LBB0_935
	s_waitcnt lgkmcnt(4)
	v_mfma_f32_32x32x16_bf16 v[50:65], v[82:85], v[98:101], 0
	ds_read_b128 v[86:89], v196 offset:4640
	ds_read_b128 v[90:93], v196 offset:4672
	v_or_b32_e32 v0, s58, v197
	v_cmp_gt_u32_e32 vcc, v0, v157
	v_cmp_lt_i32_e64 s[6:7], v0, v147
	s_or_b64 vcc, vcc, s[6:7]
	s_waitcnt lgkmcnt(5)
	v_mfma_f32_32x32x16_bf16 v[50:65], v[78:81], v[102:105], v[50:65]
	s_waitcnt lgkmcnt(2)
	v_mfma_f32_32x32x16_bf16 v[34:49], v[70:73], v[98:101], 0
	v_mfma_f32_32x32x16_bf16 v[50:65], v[74:77], v[106:109], v[50:65]
	s_waitcnt lgkmcnt(1)
	v_mfma_f32_32x32x16_bf16 v[34:49], v[86:89], v[102:105], v[34:49]
	ds_read_b128 v[86:89], v196 offset:4704
	v_mfma_f32_32x32x16_bf16 v[50:65], v[66:69], v[110:113], v[50:65]
	s_waitcnt lgkmcnt(1)
	v_mfma_f32_32x32x16_bf16 v[34:49], v[90:93], v[106:109], v[34:49]
	s_waitcnt lgkmcnt(0)
	v_mfma_f32_32x32x16_bf16 v[34:49], v[86:89], v[110:113], v[34:49]
	s_nop 7
	v_cndmask_b32_e32 v86, v50, v204, vcc
	v_bitop3_b32 v50, s58, v197, s58 bitop3:3
	v_cmp_ge_u32_e32 vcc, v0, v157
	v_cmp_lt_i32_e64 s[6:7], v158, v50
	s_or_b64 vcc, vcc, s[6:7]
	v_cndmask_b32_e32 v87, v51, v204, vcc
	v_or_b32_e32 v51, 2, v0
	v_cmp_gt_u32_e32 vcc, v51, v157
	v_cmp_lt_i32_e64 s[6:7], v51, v147
	s_or_b64 vcc, vcc, s[6:7]
	v_or_b32_e32 v51, 3, v0
	v_cndmask_b32_e32 v88, v52, v204, vcc
	v_cmp_gt_u32_e32 vcc, v51, v157
	v_cmp_lt_i32_e64 s[6:7], v51, v147
	s_or_b64 vcc, vcc, s[6:7]
	v_or_b32_e32 v51, 8, v0
	v_cndmask_b32_e32 v89, v53, v204, vcc
	v_cmp_gt_u32_e32 vcc, v51, v157
	v_cmp_lt_i32_e64 s[6:7], v51, v147
	s_or_b64 vcc, vcc, s[6:7]
	v_or_b32_e32 v51, 9, v0
	v_cndmask_b32_e32 v90, v54, v204, vcc
	v_cmp_gt_u32_e32 vcc, v51, v157
	v_cmp_lt_i32_e64 s[6:7], v51, v147
	s_or_b64 vcc, vcc, s[6:7]
	v_or_b32_e32 v51, 10, v0
	v_cndmask_b32_e32 v194, v55, v204, vcc
	v_cmp_gt_u32_e32 vcc, v51, v157
	v_cmp_lt_i32_e64 s[6:7], v51, v147
	s_or_b64 vcc, vcc, s[6:7]
	v_or_b32_e32 v51, 11, v0
	v_cndmask_b32_e32 v193, v56, v204, vcc
	v_cmp_gt_u32_e32 vcc, v51, v157
	v_cmp_lt_i32_e64 s[6:7], v51, v147
	s_or_b64 vcc, vcc, s[6:7]
	v_or_b32_e32 v51, 16, v0
	v_cndmask_b32_e32 v195, v57, v204, vcc
	v_cmp_gt_u32_e32 vcc, v51, v157
	v_cmp_lt_i32_e64 s[6:7], v51, v147
	s_or_b64 vcc, vcc, s[6:7]
	v_or_b32_e32 v51, 17, v0
	v_cndmask_b32_e32 v190, v58, v204, vcc
	v_cmp_gt_u32_e32 vcc, v51, v157
	v_cmp_lt_i32_e64 s[6:7], v51, v147
	s_or_b64 vcc, vcc, s[6:7]
	v_or_b32_e32 v51, 18, v0
	v_cndmask_b32_e32 v192, v59, v204, vcc
	v_cmp_gt_u32_e32 vcc, v51, v157
	v_cmp_lt_i32_e64 s[6:7], v51, v147
	s_or_b64 vcc, vcc, s[6:7]
	v_or_b32_e32 v51, 19, v0
	v_cndmask_b32_e32 v191, v60, v204, vcc
	v_cmp_gt_u32_e32 vcc, v51, v157
	v_cmp_lt_i32_e64 s[6:7], v51, v147
	s_or_b64 vcc, vcc, s[6:7]
	v_or_b32_e32 v51, 24, v0
	v_cndmask_b32_e32 v189, v61, v204, vcc
	v_cmp_gt_u32_e32 vcc, v51, v157
	v_cmp_lt_i32_e64 s[6:7], v51, v147
	s_or_b64 vcc, vcc, s[6:7]
	v_or_b32_e32 v51, 25, v0
	v_cndmask_b32_e32 v188, v62, v204, vcc
	v_cmp_gt_u32_e32 vcc, v51, v157
	v_cmp_lt_i32_e64 s[6:7], v51, v147
	s_or_b64 vcc, vcc, s[6:7]
	v_or_b32_e32 v51, 26, v0
	v_cndmask_b32_e32 v187, v63, v204, vcc
	v_cmp_gt_u32_e32 vcc, v51, v157
	v_cmp_lt_i32_e64 s[6:7], v51, v147
	s_or_b64 vcc, vcc, s[6:7]
	v_or_b32_e32 v51, 27, v0
	v_cndmask_b32_e32 v186, v64, v204, vcc
	v_cmp_gt_u32_e32 vcc, v51, v157
	v_cmp_lt_i32_e64 s[6:7], v51, v147
	s_or_b64 vcc, vcc, s[6:7]
	v_or_b32_e32 v51, 32, v0
	v_cndmask_b32_e32 v184, v65, v204, vcc
	v_cmp_gt_u32_e32 vcc, v51, v157
	v_cmp_lt_i32_e64 s[6:7], v51, v147
	s_or_b64 vcc, vcc, s[6:7]
	v_cndmask_b32_e32 v180, v34, v204, vcc
	v_or_b32_e32 v34, 33, v0
	v_cmp_gt_u32_e32 vcc, v34, v157
	v_cmp_lt_i32_e64 s[6:7], v34, v147
	s_or_b64 vcc, vcc, s[6:7]
	v_cndmask_b32_e32 v164, v35, v204, vcc
	v_or_b32_e32 v35, 34, v0
	v_cmp_gt_u32_e32 vcc, v35, v157
	v_cmp_lt_i32_e64 s[6:7], v35, v147
	s_or_b64 vcc, vcc, s[6:7]
	v_or_b32_e32 v35, 35, v0
	v_cndmask_b32_e32 v162, v36, v204, vcc
	v_cmp_gt_u32_e32 vcc, v35, v157
	v_cmp_lt_i32_e64 s[6:7], v35, v147
	s_or_b64 vcc, vcc, s[6:7]
	v_or_b32_e32 v35, 40, v0
	v_cndmask_b32_e32 v97, v37, v204, vcc
	v_cmp_gt_u32_e32 vcc, v35, v157
	v_cmp_lt_i32_e64 s[6:7], v35, v147
	s_or_b64 vcc, vcc, s[6:7]
	v_or_b32_e32 v35, 41, v0
	v_cndmask_b32_e32 v92, v38, v204, vcc
	v_cmp_gt_u32_e32 vcc, v35, v157
	v_cmp_lt_i32_e64 s[6:7], v35, v147
	s_or_b64 vcc, vcc, s[6:7]
	v_or_b32_e32 v35, 42, v0
	v_cndmask_b32_e32 v91, v39, v204, vcc
	v_cmp_gt_u32_e32 vcc, v35, v157
	v_cmp_lt_i32_e64 s[6:7], v35, v147
	s_or_b64 vcc, vcc, s[6:7]
	v_or_b32_e32 v35, 43, v0
	v_cndmask_b32_e32 v93, v40, v204, vcc
	v_cmp_gt_u32_e32 vcc, v35, v157
	v_cmp_lt_i32_e64 s[6:7], v35, v147
	s_or_b64 vcc, vcc, s[6:7]
	v_or_b32_e32 v35, 48, v0
	v_cndmask_b32_e32 v94, v41, v204, vcc
	v_cmp_gt_u32_e32 vcc, v35, v157
	v_cmp_lt_i32_e64 s[6:7], v35, v147
	s_or_b64 vcc, vcc, s[6:7]
	v_or_b32_e32 v35, 49, v0
	v_max3_f32 v50, v86, s35, v87
	v_cndmask_b32_e32 v95, v42, v204, vcc
	v_cmp_gt_u32_e32 vcc, v35, v157
	v_cmp_lt_i32_e64 s[6:7], v35, v147
	v_max3_f32 v50, v50, v88, v89
	s_or_b64 vcc, vcc, s[6:7]
	v_or_b32_e32 v35, 50, v0
	v_max3_f32 v50, v50, v90, v194
	v_cndmask_b32_e32 v96, v43, v204, vcc
	v_cmp_gt_u32_e32 vcc, v35, v157
	v_cmp_lt_i32_e64 s[6:7], v35, v147
	v_max3_f32 v50, v50, v193, v195
; DI int crow(int i, int h) { return (i & 3) + 8 * (i >> 2) + 4 * h; }
;     ...
;   float mx = NINF;
; #pragma unroll
;   for (int k2 = 0; k2 < 2; ++k2)
; #pragma unroll
;     for (int i = 0; i < 16; ++i) {
;       if (!(HM & (1 << k2))) continue;
;       float v = s[k2][i];
;       if (MASKED) {
;         const int tk = key0 + 32 * k2 + crow(i, h);
;         const bool valid = (MODE == 0) ? ((tk <= tq) && (tq - tk <= maxdist)) : (tk <= tq);
;         v = valid ? v : NINF; s[k2][i] = v;
;       }
;       mx = fmaxf(mx, v);
;     }
;   mx = fmaxf(mx, __shfl_xor(mx, 32));
;   if (MODE != 1) mx *= L2E;
;   if (MODE == 2) mx = lanesel ? mx : NINF;
;   const float mn = fmaxf(m, mx); const float alpha = __builtin_amdgcn_exp2f(m - mn);
;   const float neg = (MODE == 2 && !lanesel) ? NINF : -mn;
;   float ps = 0.f;
; #pragma unroll
;   for (int k2 = 0; k2 < 2; ++k2)
; #pragma unroll
;     for (int i = 0; i < 16; ++i) {
;       if (!(HM & (1 << k2))) continue;
;       const float pv = (MODE == 1) ? __builtin_amdgcn_exp2f(s[k2][i] + neg) : __builtin_amdgcn_exp2f(fmaf(s[k2][i], L2E, neg));
;       s[k2][i] = pv; ps += pv;
;     }
;   l = l * alpha + ps;
	s_or_b64 vcc, vcc, s[6:7]
	v_or_b32_e32 v35, 51, v0
	v_max3_f32 v50, v50, v190, v192
	v_cndmask_b32_e32 v163, v44, v204, vcc
	v_cmp_gt_u32_e32 vcc, v35, v157
	v_cmp_lt_i32_e64 s[6:7], v35, v147
	v_max3_f32 v50, v50, v191, v189
	s_or_b64 vcc, vcc, s[6:7]
	v_or_b32_e32 v35, 56, v0
	v_max3_f32 v50, v50, v188, v187
	v_cndmask_b32_e32 v165, v45, v204, vcc
	v_cmp_gt_u32_e32 vcc, v35, v157
	v_cmp_lt_i32_e64 s[6:7], v35, v147
	v_max3_f32 v50, v50, v186, v184
	s_or_b64 vcc, vcc, s[6:7]
	v_or_b32_e32 v35, 57, v0
	v_max3_f32 v34, v50, v180, v164
	v_cndmask_b32_e32 v181, v46, v204, vcc
	v_cmp_gt_u32_e32 vcc, v35, v157
	v_cmp_lt_i32_e64 s[6:7], v35, v147
	v_max3_f32 v34, v34, v162, v97
	s_or_b64 vcc, vcc, s[6:7]
	v_or_b32_e32 v35, 58, v0
	v_max3_f32 v34, v34, v92, v91
	v_cndmask_b32_e32 v182, v47, v204, vcc
	v_cmp_gt_u32_e32 vcc, v35, v157
	v_cmp_lt_i32_e64 s[6:7], v35, v147
	v_max3_f32 v34, v34, v93, v94
	s_or_b64 vcc, vcc, s[6:7]
	v_or_b32_e32 v0, 59, v0
	v_max3_f32 v34, v34, v95, v96
	v_cndmask_b32_e32 v183, v48, v204, vcc
	v_cmp_gt_u32_e32 vcc, v0, v157
	v_cmp_lt_i32_e64 s[6:7], v0, v147
	v_max3_f32 v34, v34, v163, v165
	s_or_b64 vcc, vcc, s[6:7]
	v_max3_f32 v34, v34, v181, v182
	v_cndmask_b32_e32 v185, v49, v204, vcc
	v_and_b32_e32 v35, 64, v202
	v_max3_f32 v0, v34, v183, v185
	v_xor_b32_e32 v34, 32, v202
	v_add_u32_e32 v35, 64, v35
	v_cmp_lt_i32_e32 vcc, v34, v35
	s_nop 1
	v_cndmask_b32_e32 v34, v202, v34, vcc
	v_lshlrev_b32_e32 v34, 2, v34
	ds_bpermute_b32 v34, v34, v0
	s_waitcnt lgkmcnt(0)
	v_max_f32_e32 v34, v34, v34
	v_max_f32_e32 v0, v0, v34
	v_mul_f32_e32 v0, 0x3fb8aa3b, v0
	v_max_f32_e32 v34, v159, v159
	v_max_f32_e32 v160, v34, v0
	v_sub_f32_e32 v0, v159, v160
	v_exp_f32_e32 v0, v0
	v_cmp_neq_f32_e32 vcc, v160, v159
	s_cbranch_vccz .LBB0_934
	v_pk_mul_f32 v[32:33], v[32:33], v[0:1] op_sel_hi:[1,0]
	v_pk_mul_f32 v[30:31], v[30:31], v[0:1] op_sel_hi:[1,0]
	v_pk_mul_f32 v[28:29], v[28:29], v[0:1] op_sel_hi:[1,0]
	v_pk_mul_f32 v[26:27], v[26:27], v[0:1] op_sel_hi:[1,0]
	v_pk_mul_f32 v[24:25], v[24:25], v[0:1] op_sel_hi:[1,0]
	v_pk_mul_f32 v[22:23], v[22:23], v[0:1] op_sel_hi:[1,0]
	v_pk_mul_f32 v[20:21], v[20:21], v[0:1] op_sel_hi:[1,0]
	v_pk_mul_f32 v[18:19], v[18:19], v[0:1] op_sel_hi:[1,0]
	v_pk_mul_f32 v[16:17], v[16:17], v[0:1] op_sel_hi:[1,0]
	v_pk_mul_f32 v[14:15], v[14:15], v[0:1] op_sel_hi:[1,0]
	v_pk_mul_f32 v[12:13], v[12:13], v[0:1] op_sel_hi:[1,0]
	v_pk_mul_f32 v[10:11], v[10:11], v[0:1] op_sel_hi:[1,0]
	v_pk_mul_f32 v[8:9], v[8:9], v[0:1] op_sel_hi:[1,0]
	v_pk_mul_f32 v[6:7], v[6:7], v[0:1] op_sel_hi:[1,0]
	v_pk_mul_f32 v[4:5], v[4:5], v[0:1] op_sel_hi:[1,0]
	v_pk_mul_f32 v[2:3], v[2:3], v[0:1] op_sel_hi:[1,0]
.LBB0_934:
	v_fma_f32 v86, v86, s34, -v160
	v_exp_f32_e32 v86, v86
	v_fma_f32 v87, v87, s34, -v160
	v_exp_f32_e32 v87, v87
	v_fma_f32 v88, v88, s34, -v160
	v_exp_f32_e32 v88, v88
	v_fma_f32 v89, v89, s34, -v160
	v_exp_f32_e32 v89, v89
	v_fma_f32 v90, v90, s34, -v160
	v_add_f32_e32 v209, 0, v86
	v_exp_f32_e32 v90, v90
	v_fma_f32 v194, v194, s34, -v160
	v_add_f32_e32 v209, v87, v209
	v_exp_f32_e32 v194, v194
	v_fma_f32 v193, v193, s34, -v160
	v_add_f32_e32 v209, v88, v209
	v_exp_f32_e32 v193, v193
	v_fma_f32 v195, v195, s34, -v160
	v_add_f32_e32 v209, v89, v209
	v_exp_f32_e32 v195, v195
	v_fma_f32 v190, v190, s34, -v160
	v_add_f32_e32 v209, v90, v209
	v_exp_f32_e32 v190, v190
	v_fma_f32 v192, v192, s34, -v160
	v_add_f32_e32 v209, v194, v209
	v_exp_f32_e32 v192, v192
	v_fma_f32 v191, v191, s34, -v160
	v_add_f32_e32 v209, v193, v209
	v_exp_f32_e32 v191, v191
	v_fma_f32 v189, v189, s34, -v160
	v_add_f32_e32 v209, v195, v209
	v_exp_f32_e32 v189, v189
	v_fma_f32 v188, v188, s34, -v160
	v_add_f32_e32 v209, v190, v209
	v_exp_f32_e32 v188, v188
	v_fma_f32 v187, v187, s34, -v160
	v_add_f32_e32 v209, v192, v209
	v_exp_f32_e32 v187, v187
	v_fma_f32 v186, v186, s34, -v160
	v_add_f32_e32 v209, v191, v209
	v_exp_f32_e32 v186, v186
	v_fma_f32 v184, v184, s34, -v160
	v_add_f32_e32 v209, v189, v209
	v_exp_f32_e32 v184, v184
	v_fma_f32 v180, v180, s34, -v160
	v_add_f32_e32 v209, v188, v209
	v_exp_f32_e32 v180, v180
	v_fma_f32 v164, v164, s34, -v160
	v_add_f32_e32 v209, v187, v209
	v_exp_f32_e32 v164, v164
	v_fma_f32 v162, v162, s34, -v160
	v_add_f32_e32 v209, v186, v209
	v_exp_f32_e32 v210, v162
	v_add_f32_e32 v209, v184, v209
	v_add_f32_e32 v209, v180, v209
	v_add_f32_e32 v209, v164, v209
	v_fma_f32 v97, v97, s34, -v160
	v_add_f32_e32 v162, v210, v209
	v_exp_f32_e32 v209, v97
	v_fma_f32 v92, v92, s34, -v160
	v_exp_f32_e32 v211, v92
	v_fma_f32 v91, v91, s34, -v160
	v_exp_f32_e32 v212, v91
	v_add_f32_e32 v97, v209, v162
	v_add_f32_e32 v92, v211, v97
	v_cvt_pk_bf16_f32 v86, v86, v87
	v_add_f32_e32 v91, v212, v92
	v_fma_f32 v92, v93, s34, -v160
	v_exp_f32_e32 v213, v92
	v_fma_f32 v92, v94, s34, -v160
	v_exp_f32_e32 v214, v92
	v_fma_f32 v92, v95, s34, -v160
	v_exp_f32_e32 v215, v92
	v_fma_f32 v92, v96, s34, -v160
	v_exp_f32_e32 v216, v92
	v_fma_f32 v92, v163, s34, -v160
	v_add_f32_e32 v91, v213, v91
	v_exp_f32_e32 v163, v92
	v_fma_f32 v92, v165, s34, -v160
	v_add_f32_e32 v91, v214, v91
	v_exp_f32_e32 v165, v92
	v_fma_f32 v92, v181, s34, -v160
	v_add_f32_e32 v91, v215, v91
	v_exp_f32_e32 v181, v92
	v_fma_f32 v92, v182, s34, -v160
	v_add_f32_e32 v91, v216, v91
	v_exp_f32_e32 v182, v92
	v_fma_f32 v92, v183, s34, -v160
	v_add_f32_e32 v91, v163, v91
	v_exp_f32_e32 v183, v92
	v_fma_f32 v92, v185, s34, -v160
	v_add_f32_e32 v91, v165, v91
	v_exp_f32_e32 v185, v92
	v_add_f32_e32 v91, v181, v91
	v_add_f32_e32 v91, v182, v91
	v_add_f32_e32 v91, v183, v91
	v_add_f32_e32 v162, v185, v91
	v_fmac_f32_e32 v162, v161, v0
	v_add_u32_e32 v0, 0x2000, v198
	v_cvt_pk_bf16_f32 v87, v88, v89
	v_cvt_pk_bf16_f32 v88, v90, v194
	ds_read2_b64 v[90:93], v0 offset0:128 offset1:130
	ds_read2_b64 v[94:97], v0 offset0:132 offset1:134
	v_cvt_pk_bf16_f32 v89, v193, v195
	v_add_u32_e32 v193, 0x3000, v198
	s_mov_b64 s[6:7], 0
	s_waitcnt lgkmcnt(1)
; DI unsigned pack2(float a, float b) { f32x2 v = {a, b}; bf16x2_t r = __builtin_convertvector(v, bf16x2_t); return __builtin_bit_cast(unsigned, r); }
; DI f32x16 mfma32(bf16x8 a, bf16x8 b, f32x16 c) { return __builtin_amdgcn_mfma_f32_32x32x16_bf16(a, b, c, 0, 0, 0); }
; DI int crow(int i, int h) { return (i & 3) + 8 * (i >> 2) + 4 * h; }
;     ...
;   float mx = NINF;
; #pragma unroll
;   for (int k2 = 0; k2 < 2; ++k2)
; #pragma unroll
;     for (int i = 0; i < 16; ++i) {
;       if (!(HM & (1 << k2))) continue;
;       float v = s[k2][i];
;       if (MASKED) {
;         const int tk = key0 + 32 * k2 + crow(i, h);
;         const bool valid = (MODE == 0) ? ((tk <= tq) && (tq - tk <= maxdist)) : (tk <= tq);
;         v = valid ? v : NINF; s[k2][i] = v;
;       }
;       mx = fmaxf(mx, v);
;     }
;   mx = fmaxf(mx, __shfl_xor(mx, 32));
;   if (MODE != 1) mx *= L2E;
;   if (MODE == 2) mx = lanesel ? mx : NINF;
;   const float mn = fmaxf(m, mx); const float alpha = __builtin_amdgcn_exp2f(m - mn);
;   const float neg = (MODE == 2 && !lanesel) ? NINF : -mn;
;   float ps = 0.f;
; #pragma unroll
;   for (int k2 = 0; k2 < 2; ++k2)
; #pragma unroll
;     for (int i = 0; i < 16; ++i) {
;       if (!(HM & (1 << k2))) continue;
;       const float pv = (MODE == 1) ? __builtin_amdgcn_exp2f(s[k2][i] + neg) : __builtin_amdgcn_exp2f(fmaf(s[k2][i], L2E, neg));
;       s[k2][i] = pv; ps += pv;
;     }
;   l = l * alpha + ps;
;   if (__builtin_amdgcn_ballot_w64(mn != m) != 0ull) {
; #pragma unroll
;     for (int dt = 0; dt < 2; ++dt)
; #pragma unroll
;       for (int i = 0; i < 16; ++i) o[dt][i] *= alpha;
;   }
;     ...
; #pragma unroll
;   for (int st = 0; st < 4; ++st) {
;     if (!(HM & (1 << (st >> 1)))) continue;
;     const int k2 = st >> 1, b8 = 8 * (st & 1);
;     const u32x4 pw = {pack2(s[k2][b8], s[k2][b8 + 1]), pack2(s[k2][b8 + 2], s[k2][b8 + 3]), pack2(s[k2][b8 + 4], s[k2][b8 + 5]), pack2(s[k2][b8 + 6], s[k2][b8 + 7])};
;     const bf16x8 pb = __builtin_bit_cast(bf16x8, pw);
; #pragma unroll
;     for (int dt = 0; dt < 2; ++dt) {
;       const s16x4 lo = *(const s16x4*)(Vs + (32 * dt + r) * LSTR + 16 * st + 4 * h);
;       const s16x4 hi = *(const s16x4*)(Vs + (32 * dt + r) * LSTR + 16 * st + 8 + 4 * h);
;       const bf16x8 a = __builtin_shufflevector(lo, hi, 0, 1, 2, 3, 4, 5, 6, 7);
;       o[dt] = mfma32(a, pb, o[dt]);
;     }
;   }
	v_mfma_f32_32x32x16_bf16 v[34:49], v[90:93], v[86:89], v[2:17]
	ds_read2_b64 v[90:93], v193 offset0:192 offset1:194
	s_waitcnt lgkmcnt(0)
	v_mfma_f32_32x32x16_bf16 v[50:65], v[90:93], v[86:89], v[18:33]
	ds_read2_b64 v[90:93], v193 offset0:196 offset1:198
	v_cvt_pk_bf16_f32 v86, v190, v192
	v_cvt_pk_bf16_f32 v87, v191, v189
	v_cvt_pk_bf16_f32 v88, v188, v187
	v_cvt_pk_bf16_f32 v89, v186, v184
	s_waitcnt lgkmcnt(0)
	s_nop 0
	v_mfma_f32_32x32x16_bf16 v[50:65], v[90:93], v[86:89], v[50:65]
	ds_read2_b64 v[90:93], v0 offset0:136 offset1:138
	v_mfma_f32_32x32x16_bf16 v[34:49], v[94:97], v[86:89], v[34:49]
	v_cvt_pk_bf16_f32 v86, v180, v164
	v_cvt_pk_bf16_f32 v87, v210, v209
	v_cvt_pk_bf16_f32 v88, v211, v212
	v_cvt_pk_bf16_f32 v89, v213, v214
	s_waitcnt lgkmcnt(0)
	s_nop 0
	v_mfma_f32_32x32x16_bf16 v[34:49], v[90:93], v[86:89], v[34:49]
	ds_read2_b64 v[90:93], v193 offset0:200 offset1:202
	s_waitcnt lgkmcnt(0)
	v_mfma_f32_32x32x16_bf16 v[50:65], v[90:93], v[86:89], v[50:65]
	ds_read2_b64 v[90:93], v0 offset0:140 offset1:142
	v_cvt_pk_bf16_f32 v86, v215, v216
	v_cvt_pk_bf16_f32 v87, v163, v165
	v_cvt_pk_bf16_f32 v88, v181, v182
	v_cvt_pk_bf16_f32 v89, v183, v185
	s_waitcnt lgkmcnt(0)
	s_nop 0
	v_mfma_f32_32x32x16_bf16 v[2:17], v[90:93], v[86:89], v[34:49]
	ds_read2_b64 v[90:93], v193 offset0:204 offset1:206
	s_waitcnt lgkmcnt(0)
	v_mfma_f32_32x32x16_bf16 v[18:33], v[90:93], v[86:89], v[50:65]
.LBB0_935:
	s_and_b64 vcc, exec, s[6:7]
	s_cbranch_vccz .LBB0_939
	s_waitcnt lgkmcnt(4)
	v_mfma_f32_32x32x16_bf16 v[82:97], v[82:85], v[98:101], 0
	s_nop 4
	ds_read_b128 v[34:37], v196 offset:4640
	ds_read_b128 v[38:41], v196 offset:4672
	s_waitcnt lgkmcnt(5)
	v_mfma_f32_32x32x16_bf16 v[82:97], v[78:81], v[102:105], v[82:97]
	s_waitcnt lgkmcnt(4)
	v_mfma_f32_32x32x16_bf16 v[82:97], v[74:77], v[106:109], v[82:97]
	s_waitcnt lgkmcnt(3)
	v_mfma_f32_32x32x16_bf16 v[82:97], v[66:69], v[110:113], v[82:97]
	s_waitcnt lgkmcnt(2)
	v_mfma_f32_32x32x16_bf16 v[66:81], v[70:73], v[98:101], 0
	s_nop 9
	v_max3_f32 v0, v82, s35, v83
	v_max3_f32 v0, v0, v84, v85
	v_max3_f32 v0, v0, v86, v87
	v_max3_f32 v0, v0, v88, v89
	v_max3_f32 v0, v0, v90, v91
	v_max3_f32 v0, v0, v92, v93
	v_max3_f32 v0, v0, v94, v95
	s_waitcnt lgkmcnt(1)
	v_mfma_f32_32x32x16_bf16 v[66:81], v[34:37], v[102:105], v[66:81]
	ds_read_b128 v[34:37], v196 offset:4704
	v_max3_f32 v0, v0, v96, v97
	s_waitcnt lgkmcnt(1)
	v_mfma_f32_32x32x16_bf16 v[66:81], v[38:41], v[106:109], v[66:81]
	s_waitcnt lgkmcnt(0)
	v_mfma_f32_32x32x16_bf16 v[66:81], v[34:37], v[110:113], v[66:81]
	v_and_b32_e32 v35, 64, v202
	v_xor_b32_e32 v34, 32, v202
	v_add_u32_e32 v35, 64, v35
	v_cmp_lt_i32_e32 vcc, v34, v35
	s_nop 1
	v_cndmask_b32_e32 v34, v202, v34, vcc
	s_nop 4
	v_max3_f32 v0, v0, v66, v67
	v_max3_f32 v0, v0, v68, v69
	v_max3_f32 v0, v0, v70, v71
	v_max3_f32 v0, v0, v72, v73
	v_max3_f32 v0, v0, v74, v75
	v_max3_f32 v0, v0, v76, v77
	v_max3_f32 v0, v0, v78, v79
	v_max3_f32 v0, v0, v80, v81
	v_lshlrev_b32_e32 v34, 2, v34
	ds_bpermute_b32 v34, v34, v0
	s_waitcnt lgkmcnt(0)
	v_max_f32_e32 v34, v34, v34
	v_max_f32_e32 v0, v0, v34
	v_mul_f32_e32 v0, 0x3fb8aa3b, v0
	v_max_f32_e32 v34, v159, v159
	v_max_f32_e32 v160, v34, v0
	v_sub_f32_e32 v0, v159, v160
	v_exp_f32_e32 v0, v0
	v_cmp_neq_f32_e32 vcc, v160, v159
	s_cbranch_vccz .LBB0_938
	v_pk_mul_f32 v[32:33], v[32:33], v[0:1] op_sel_hi:[1,0]
	v_pk_mul_f32 v[30:31], v[30:31], v[0:1] op_sel_hi:[1,0]
	v_pk_mul_f32 v[28:29], v[28:29], v[0:1] op_sel_hi:[1,0]
	v_pk_mul_f32 v[26:27], v[26:27], v[0:1] op_sel_hi:[1,0]
	v_pk_mul_f32 v[24:25], v[24:25], v[0:1] op_sel_hi:[1,0]
	v_pk_mul_f32 v[22:23], v[22:23], v[0:1] op_sel_hi:[1,0]
	v_pk_mul_f32 v[20:21], v[20:21], v[0:1] op_sel_hi:[1,0]
	v_pk_mul_f32 v[18:19], v[18:19], v[0:1] op_sel_hi:[1,0]
	v_pk_mul_f32 v[16:17], v[16:17], v[0:1] op_sel_hi:[1,0]
	v_pk_mul_f32 v[14:15], v[14:15], v[0:1] op_sel_hi:[1,0]
	v_pk_mul_f32 v[12:13], v[12:13], v[0:1] op_sel_hi:[1,0]
	v_pk_mul_f32 v[10:11], v[10:11], v[0:1] op_sel_hi:[1,0]
	v_pk_mul_f32 v[8:9], v[8:9], v[0:1] op_sel_hi:[1,0]
	v_pk_mul_f32 v[6:7], v[6:7], v[0:1] op_sel_hi:[1,0]
	v_pk_mul_f32 v[4:5], v[4:5], v[0:1] op_sel_hi:[1,0]
	v_pk_mul_f32 v[2:3], v[2:3], v[0:1] op_sel_hi:[1,0]
; DI unsigned pack2(float a, float b) { f32x2 v = {a, b}; bf16x2_t r = __builtin_convertvector(v, bf16x2_t); return __builtin_bit_cast(unsigned, r); }
; DI f32x16 mfma32(bf16x8 a, bf16x8 b, f32x16 c) { return __builtin_amdgcn_mfma_f32_32x32x16_bf16(a, b, c, 0, 0, 0); }
;     ...
;   const float mn = fmaxf(m, mx); const float alpha = __builtin_amdgcn_exp2f(m - mn);
;   const float neg = (MODE == 2 && !lanesel) ? NINF : -mn;
;   float ps = 0.f;
; #pragma unroll
;   for (int k2 = 0; k2 < 2; ++k2)
; #pragma unroll
;     for (int i = 0; i < 16; ++i) {
;       if (!(HM & (1 << k2))) continue;
;       const float pv = (MODE == 1) ? __builtin_amdgcn_exp2f(s[k2][i] + neg) : __builtin_amdgcn_exp2f(fmaf(s[k2][i], L2E, neg));
;       s[k2][i] = pv; ps += pv;
;     }
;   l = l * alpha + ps;
;   if (__builtin_amdgcn_ballot_w64(mn != m) != 0ull) {
; #pragma unroll
;     for (int dt = 0; dt < 2; ++dt)
; #pragma unroll
;       for (int i = 0; i < 16; ++i) o[dt][i] *= alpha;
;   }
;   m = mn;
; #pragma unroll
;   for (int st = 0; st < 4; ++st) {
;     if (!(HM & (1 << (st >> 1)))) continue;
;     const int k2 = st >> 1, b8 = 8 * (st & 1);
;     const u32x4 pw = {pack2(s[k2][b8], s[k2][b8 + 1]), pack2(s[k2][b8 + 2], s[k2][b8 + 3]), pack2(s[k2][b8 + 4], s[k2][b8 + 5]), pack2(s[k2][b8 + 6], s[k2][b8 + 7])};
;     const bf16x8 pb = __builtin_bit_cast(bf16x8, pw);
; #pragma unroll
;     for (int dt = 0; dt < 2; ++dt) {
;       const s16x4 lo = *(const s16x4*)(Vs + (32 * dt + r) * LSTR + 16 * st + 4 * h);
;       const s16x4 hi = *(const s16x4*)(Vs + (32 * dt + r) * LSTR + 16 * st + 8 + 4 * h);
;       const bf16x8 a = __builtin_shufflevector(lo, hi, 0, 1, 2, 3, 4, 5, 6, 7);
;       o[dt] = mfma32(a, pb, o[dt]);
;     }
;   }
.LBB0_938:
	v_fma_f32 v82, v82, s34, -v160
	v_exp_f32_e32 v82, v82
	v_fma_f32 v83, v83, s34, -v160
	v_exp_f32_e32 v83, v83
	v_fma_f32 v84, v84, s34, -v160
	v_exp_f32_e32 v84, v84
	v_fma_f32 v85, v85, s34, -v160
	v_exp_f32_e32 v85, v85
	v_fma_f32 v86, v86, s34, -v160
	v_add_f32_e32 v162, 0, v82
	v_exp_f32_e32 v86, v86
	v_fma_f32 v87, v87, s34, -v160
	v_add_f32_e32 v162, v83, v162
	v_exp_f32_e32 v87, v87
	v_fma_f32 v88, v88, s34, -v160
	v_add_f32_e32 v162, v84, v162
	v_exp_f32_e32 v88, v88
	v_fma_f32 v89, v89, s34, -v160
	v_add_f32_e32 v162, v85, v162
	v_exp_f32_e32 v89, v89
	v_fma_f32 v90, v90, s34, -v160
	v_add_f32_e32 v162, v86, v162
	v_exp_f32_e32 v90, v90
	v_fma_f32 v91, v91, s34, -v160
	v_add_f32_e32 v162, v87, v162
	v_exp_f32_e32 v91, v91
	v_fma_f32 v92, v92, s34, -v160
	v_add_f32_e32 v162, v88, v162
	v_exp_f32_e32 v92, v92
	v_fma_f32 v93, v93, s34, -v160
	v_add_f32_e32 v162, v89, v162
	v_exp_f32_e32 v93, v93
	v_fma_f32 v94, v94, s34, -v160
	v_add_f32_e32 v162, v90, v162
	v_exp_f32_e32 v94, v94
	v_fma_f32 v95, v95, s34, -v160
	v_add_f32_e32 v162, v91, v162
	v_exp_f32_e32 v95, v95
	v_fma_f32 v96, v96, s34, -v160
	v_add_f32_e32 v162, v92, v162
	v_exp_f32_e32 v96, v96
	v_fma_f32 v97, v97, s34, -v160
	v_add_f32_e32 v162, v93, v162
	v_exp_f32_e32 v97, v97
	v_fma_f32 v66, v66, s34, -v160
	v_add_f32_e32 v162, v94, v162
	v_exp_f32_e32 v163, v66
	v_fma_f32 v67, v67, s34, -v160
	v_add_f32_e32 v162, v95, v162
	v_exp_f32_e32 v164, v67
	v_fma_f32 v67, v68, s34, -v160
	v_add_f32_e32 v162, v96, v162
	v_exp_f32_e32 v165, v67
	v_fma_f32 v67, v69, s34, -v160
	v_add_f32_e32 v162, v97, v162
	v_exp_f32_e32 v180, v67
	v_fma_f32 v67, v70, s34, -v160
	v_add_f32_e32 v66, v163, v162
	v_exp_f32_e32 v181, v67
	v_fma_f32 v67, v71, s34, -v160
	v_add_f32_e32 v66, v164, v66
	v_exp_f32_e32 v182, v67
	v_fma_f32 v67, v72, s34, -v160
	v_add_f32_e32 v66, v165, v66
	v_exp_f32_e32 v183, v67
	v_fma_f32 v67, v73, s34, -v160
	v_add_f32_e32 v66, v180, v66
	v_exp_f32_e32 v184, v67
	v_fma_f32 v67, v74, s34, -v160
	v_add_f32_e32 v66, v181, v66
	v_exp_f32_e32 v185, v67
	v_fma_f32 v67, v75, s34, -v160
	v_add_f32_e32 v66, v182, v66
	v_exp_f32_e32 v186, v67
	v_fma_f32 v67, v76, s34, -v160
	v_add_f32_e32 v66, v183, v66
	v_exp_f32_e32 v187, v67
	v_fma_f32 v67, v77, s34, -v160
	v_add_f32_e32 v66, v184, v66
	v_exp_f32_e32 v188, v67
	v_fma_f32 v67, v78, s34, -v160
	v_add_f32_e32 v66, v185, v66
	v_exp_f32_e32 v78, v67
	v_fma_f32 v67, v79, s34, -v160
	v_add_f32_e32 v66, v186, v66
	v_exp_f32_e32 v79, v67
	v_fma_f32 v67, v80, s34, -v160
	v_add_f32_e32 v66, v187, v66
	v_exp_f32_e32 v80, v67
	v_fma_f32 v67, v81, s34, -v160
	v_add_f32_e32 v66, v188, v66
	v_exp_f32_e32 v81, v67
	v_add_f32_e32 v66, v78, v66
	v_add_f32_e32 v66, v79, v66
	v_add_f32_e32 v66, v80, v66
	v_add_f32_e32 v162, v81, v66
	v_fmac_f32_e32 v162, v161, v0
	v_add_u32_e32 v0, 0x2000, v198
	ds_read2_b64 v[70:73], v0 offset0:128 offset1:130
	ds_read2_b64 v[74:77], v0 offset0:132 offset1:134
	v_cvt_pk_bf16_f32 v66, v82, v83
	v_cvt_pk_bf16_f32 v67, v84, v85
	v_cvt_pk_bf16_f32 v68, v86, v87
	v_cvt_pk_bf16_f32 v69, v88, v89
	v_add_u32_e32 v82, 0x3000, v198
	s_waitcnt lgkmcnt(1)
	v_mfma_f32_32x32x16_bf16 v[34:49], v[70:73], v[66:69], v[2:17]
	ds_read2_b64 v[70:73], v82 offset0:192 offset1:194
	s_waitcnt lgkmcnt(0)
	v_mfma_f32_32x32x16_bf16 v[50:65], v[70:73], v[66:69], v[18:33]
	ds_read2_b64 v[70:73], v82 offset0:196 offset1:198
	v_cvt_pk_bf16_f32 v66, v90, v91
	v_cvt_pk_bf16_f32 v67, v92, v93
	v_cvt_pk_bf16_f32 v68, v94, v95
	v_cvt_pk_bf16_f32 v69, v96, v97
	s_waitcnt lgkmcnt(0)
	s_nop 0
	v_mfma_f32_32x32x16_bf16 v[50:65], v[70:73], v[66:69], v[50:65]
	ds_read2_b64 v[70:73], v0 offset0:136 offset1:138
	v_mfma_f32_32x32x16_bf16 v[34:49], v[74:77], v[66:69], v[34:49]
	v_cvt_pk_bf16_f32 v66, v163, v164
	v_cvt_pk_bf16_f32 v67, v165, v180
	v_cvt_pk_bf16_f32 v68, v181, v182
	v_cvt_pk_bf16_f32 v69, v183, v184
	s_waitcnt lgkmcnt(0)
	s_nop 0
	v_mfma_f32_32x32x16_bf16 v[34:49], v[70:73], v[66:69], v[34:49]
	ds_read2_b64 v[70:73], v82 offset0:200 offset1:202
	s_waitcnt lgkmcnt(0)
	v_mfma_f32_32x32x16_bf16 v[50:65], v[70:73], v[66:69], v[50:65]
	ds_read2_b64 v[70:73], v0 offset0:140 offset1:142
	v_cvt_pk_bf16_f32 v66, v185, v186
	v_cvt_pk_bf16_f32 v67, v187, v188
	v_cvt_pk_bf16_f32 v68, v78, v79
	v_cvt_pk_bf16_f32 v69, v80, v81
	s_waitcnt lgkmcnt(0)
	s_nop 0
	v_mfma_f32_32x32x16_bf16 v[2:17], v[70:73], v[66:69], v[34:49]
	ds_read2_b64 v[70:73], v82 offset0:204 offset1:206
	s_waitcnt lgkmcnt(0)
	v_mfma_f32_32x32x16_bf16 v[18:33], v[70:73], v[66:69], v[50:65]

; DI unsigned pack2(float a, float b) { f32x2 v = {a, b}; bf16x2_t r = __builtin_convertvector(v, bf16x2_t); return __builtin_bit_cast(unsigned, r); }
; DI f32x16 mfma32(bf16x8 a, bf16x8 b, f32x16 c) { return __builtin_amdgcn_mfma_f32_32x32x16_bf16(a, b, c, 0, 0, 0); }
;     ...
;   float ps = 0.f;
; #pragma unroll
;   for (int k2 = 0; k2 < 2; ++k2)
; #pragma unroll
;     for (int i = 0; i < 16; ++i) {
;       if (!(HM & (1 << k2))) continue;
;       const float pv = (MODE == 1) ? __builtin_amdgcn_exp2f(s[k2][i] + neg) : __builtin_amdgcn_exp2f(fmaf(s[k2][i], L2E, neg));
;       s[k2][i] = pv; ps += pv;
;     }
;   l = l * alpha + ps;
;   if (__builtin_amdgcn_ballot_w64(mn != m) != 0ull) {
; #pragma unroll
;     for (int dt = 0; dt < 2; ++dt)
; #pragma unroll
;       for (int i = 0; i < 16; ++i) o[dt][i] *= alpha;
;   }
;   m = mn;
; #pragma unroll
;   for (int st = 0; st < 4; ++st) {
;     if (!(HM & (1 << (st >> 1)))) continue;
;     const int k2 = st >> 1, b8 = 8 * (st & 1);
;     const u32x4 pw = {pack2(s[k2][b8], s[k2][b8 + 1]), pack2(s[k2][b8 + 2], s[k2][b8 + 3]), pack2(s[k2][b8 + 4], s[k2][b8 + 5]), pack2(s[k2][b8 + 6], s[k2][b8 + 7])};
;     const bf16x8 pb = __builtin_bit_cast(bf16x8, pw);
; #pragma unroll
;     for (int dt = 0; dt < 2; ++dt) {
;       const s16x4 lo = *(const s16x4*)(Vs + (32 * dt + r) * LSTR + 16 * st + 4 * h);
;       const s16x4 hi = *(const s16x4*)(Vs + (32 * dt + r) * LSTR + 16 * st + 8 + 4 * h);
;       const bf16x8 a = __builtin_shufflevector(lo, hi, 0, 1, 2, 3, 4, 5, 6, 7);
;       o[dt] = mfma32(a, pb, o[dt]);
;     }
;   }
.LBB0_945:
	v_fma_f32 v34, v34, s34, -v160
	v_exp_f32_e32 v45, v34
	v_fma_f32 v34, v35, s34, -v160
	v_exp_f32_e32 v46, v34
	v_fma_f32 v34, v36, s34, -v160
	v_exp_f32_e32 v47, v34
	v_fma_f32 v34, v37, s34, -v160
	v_add_f32_e32 v35, 0, v45
	v_exp_f32_e32 v48, v34
	v_fma_f32 v34, v38, s34, -v160
	v_add_f32_e32 v35, v46, v35
	v_exp_f32_e32 v38, v34
	v_fma_f32 v34, v39, s34, -v160
	v_exp_f32_e32 v39, v34
	v_add_f32_e32 v34, v47, v35
	v_fma_f32 v35, v50, s34, -v160
	v_exp_f32_e32 v49, v35
	v_fma_f32 v35, v51, s34, -v160
	v_add_f32_e32 v34, v48, v34
	v_exp_f32_e32 v50, v35
	v_fma_f32 v35, v52, s34, -v160
	v_add_f32_e32 v34, v38, v34
	v_exp_f32_e32 v52, v35
	v_fma_f32 v35, v53, s34, -v160
	v_add_f32_e32 v34, v39, v34
	v_exp_f32_e32 v53, v35
	v_add_f32_e32 v34, v49, v34
	v_add_f32_e32 v34, v50, v34
	v_add_f32_e32 v34, v52, v34
	v_add_f32_e32 v55, v53, v34
	v_fma_f32 v34, v54, s34, -v160
	v_add_u32_e32 v56, 0x2000, v198
	v_exp_f32_e32 v54, v34
	ds_read2_b64 v[34:37], v56 offset0:128 offset1:130
	v_fma_f32 v44, v44, s34, -v160
	v_exp_f32_e32 v57, v44
	v_cvt_pk_bf16_f32 v44, v45, v46
	v_cvt_pk_bf16_f32 v46, v38, v39
	v_add_u32_e32 v38, 0x3000, v198
	v_cvt_pk_bf16_f32 v45, v47, v48
	v_cvt_pk_bf16_f32 v47, v49, v50
	ds_read2_b64 v[48:51], v38 offset0:192 offset1:194
	v_fma_f32 v39, v40, s34, -v160
	s_waitcnt lgkmcnt(1)
	v_mfma_f32_32x32x16_bf16 v[2:17], v[34:37], v[44:47], v[2:17]
	v_fma_f32 v34, v41, s34, -v160
	v_exp_f32_e32 v58, v34
	v_fma_f32 v34, v42, s34, -v160
	v_exp_f32_e32 v59, v34
	v_fma_f32 v34, v43, s34, -v160
	v_exp_f32_e32 v60, v34
	ds_read2_b64 v[34:37], v56 offset0:132 offset1:134
	s_waitcnt lgkmcnt(1)
	v_mfma_f32_32x32x16_bf16 v[18:33], v[48:51], v[44:47], v[18:33]
	v_exp_f32_e32 v46, v39
	ds_read2_b64 v[38:41], v38 offset0:196 offset1:198
	v_cvt_pk_bf16_f32 v42, v52, v53
	v_cvt_pk_bf16_f32 v43, v54, v57
	v_cvt_pk_bf16_f32 v44, v58, v59
	v_cvt_pk_bf16_f32 v45, v60, v46
	s_waitcnt lgkmcnt(0)
	s_nop 0
	v_mfma_f32_32x32x16_bf16 v[18:33], v[38:41], v[42:45], v[18:33]
	v_mfma_f32_32x32x16_bf16 v[2:17], v[34:37], v[42:45], v[2:17]
	v_add_f32_e32 v34, v54, v55
	v_add_f32_e32 v34, v57, v34
	v_add_f32_e32 v34, v58, v34
	v_add_f32_e32 v34, v59, v34
	v_add_f32_e32 v34, v60, v34
	v_add_f32_e32 v162, v46, v34
	s_nop 4
	v_fmac_f32_e32 v162, v161, v0

; DI f32x16 mfma32(bf16x8 a, bf16x8 b, f32x16 c) { return __builtin_amdgcn_mfma_f32_32x32x16_bf16(a, b, c, 0, 0, 0); }
; DI int crow(int i, int h) { return (i & 3) + 8 * (i >> 2) + 4 * h; }
;     ...
; #pragma unroll
;   for (int k2 = 0; k2 < 2; ++k2) {
;     if (!(HM & (1 << k2))) continue;
; #pragma unroll
;     for (int i = 0; i < 16; ++i) s[k2][i] = 0.f;
; #pragma unroll
;     for (int ks = 0; ks < 4; ++ks) {
;       const bf16x8 a = *(const bf16x8*)(Ks + (32 * k2 + r) * LSTR + 16 * ks + 8 * h);
;       s[k2] = mfma32(a, qf[ks], s[k2]);
;     }
;   }
;   if (MODE == 1) {
; #pragma unroll
;     for (int k2 = 0; k2 < 2; ++k2)
; #pragma unroll
;       for (int g = 0; g < 4; ++g) {
;         if (!(HM & (1 << k2))) continue;
;         const f32x4 cv = *(const f32x4*)(cn_lds + key0 + 32 * k2 + 8 * g + 4 * h);
; #pragma unroll
;         for (int e = 0; e < 4; ++e) s[k2][4 * g + e] = fmaf(s[k2][4 * g + e], L2E, cv[e]);
;       }
;   }
;   float mx = NINF;
; #pragma unroll
;   for (int k2 = 0; k2 < 2; ++k2)
; #pragma unroll
;     for (int i = 0; i < 16; ++i) {
;       if (!(HM & (1 << k2))) continue;
;       float v = s[k2][i];
;       if (MASKED) {
;         const int tk = key0 + 32 * k2 + crow(i, h);
;         const bool valid = (MODE == 0) ? ((tk <= tq) && (tq - tk <= maxdist)) : (tk <= tq);
;         v = valid ? v : NINF; s[k2][i] = v;
;       }
;       mx = fmaxf(mx, v);
;     }
;   mx = fmaxf(mx, __shfl_xor(mx, 32));
;   if (MODE != 1) mx *= L2E;
;   if (MODE == 2) mx = lanesel ? mx : NINF;
;   const float mn = fmaxf(m, mx); const float alpha = __builtin_amdgcn_exp2f(m - mn);
;   const float neg = (MODE == 2 && !lanesel) ? NINF : -mn;
;   float ps = 0.f;
; #pragma unroll
;   for (int k2 = 0; k2 < 2; ++k2)
; #pragma unroll
;     for (int i = 0; i < 16; ++i) {
;       if (!(HM & (1 << k2))) continue;
;       const float pv = (MODE == 1) ? __builtin_amdgcn_exp2f(s[k2][i] + neg) : __builtin_amdgcn_exp2f(fmaf(s[k2][i], L2E, neg));
;       s[k2][i] = pv; ps += pv;
;     }
;   l = l * alpha + ps;
;   if (__builtin_amdgcn_ballot_w64(mn != m) != 0ull) {
; #pragma unroll
;     for (int dt = 0; dt < 2; ++dt)
; #pragma unroll
;       for (int i = 0; i < 16; ++i) o[dt][i] *= alpha;
;   }
.LBB0_951:
	s_lshr_b64 s[6:7], s[8:9], s67
	s_and_b32 s58, s6, 1
	s_cmp_eq_u64 s[58:59], 0
	s_cbranch_scc1 .LBB0_975
	s_lshl_b32 s58, s67, 6
	s_or_b32 s33, s58, 63
	s_cmp_le_u32 s58, s29
	s_cselect_b64 s[6:7], -1, 0
	s_or_b32 s36, s58, 31
	s_cmp_ge_i32 s36, s28
	s_cselect_b64 s[36:37], -1, 0
	s_and_b64 s[6:7], s[6:7], s[36:37]
	v_cndmask_b32_e64 v0, 0, 1, s[6:7]
	s_or_b32 s6, s58, 32
	s_cmp_gt_u32 s6, s29
	s_cselect_b64 s[6:7], -1, 0
	s_cmp_lt_i32 s33, s28
	s_cselect_b64 s[36:37], -1, 0
	v_readfirstlane_b32 s38, v0
	s_or_b32 s39, s38, 2
	s_or_b64 s[6:7], s[6:7], s[36:37]
	s_and_b64 s[6:7], s[6:7], exec
	s_cselect_b32 s67, s38, s39
	s_mov_b64 s[62:63], -1
	s_mov_b64 s[54:55], 0
	s_cmp_lt_i32 s67, 2
	s_mov_b64 s[6:7], 0
	s_cbranch_scc1 .LBB0_968
	s_cmp_eq_u32 s67, 2
	s_mov_b64 s[6:7], -1
	s_cbranch_scc0 .LBB0_957
	ds_read_b128 v[34:37], v199 offset:23040
	ds_read_b128 v[50:53], v199 offset:23072
	v_or_b32_e32 v0, s58, v197
	s_waitcnt lgkmcnt(1)
	v_mfma_f32_32x32x16_bf16 v[34:49], v[34:37], v[98:101], 0
	s_waitcnt lgkmcnt(0)
	v_mfma_f32_32x32x16_bf16 v[34:49], v[50:53], v[102:105], v[34:49]
	ds_read_b128 v[50:53], v199 offset:23104
	s_waitcnt lgkmcnt(0)
	v_mfma_f32_32x32x16_bf16 v[34:49], v[50:53], v[106:109], v[34:49]
	ds_read_b128 v[50:53], v199 offset:23136
	s_waitcnt lgkmcnt(0)
	v_mfma_f32_32x32x16_bf16 v[34:49], v[50:53], v[110:113], v[34:49]
	v_or_b32_e32 v50, 32, v0
	v_cmp_gt_u32_e32 vcc, v50, v157
	v_cmp_lt_i32_e64 s[6:7], v50, v147
	s_or_b64 vcc, vcc, s[6:7]
	s_nop 7
	v_cndmask_b32_e32 v66, v34, v204, vcc
	v_bitop3_b32 v34, s58, v205, v197 bitop3:0x36
	v_cmp_ge_u32_e32 vcc, v50, v157
	v_cmp_gt_i32_e64 s[6:7], v34, v158
	s_or_b64 vcc, vcc, s[6:7]
	v_cndmask_b32_e32 v67, v35, v204, vcc
	v_or_b32_e32 v35, 34, v0
	v_cmp_gt_u32_e32 vcc, v35, v157
	v_cmp_lt_i32_e64 s[6:7], v35, v147
	s_or_b64 vcc, vcc, s[6:7]
	v_or_b32_e32 v35, 35, v0
	v_cndmask_b32_e32 v68, v36, v204, vcc
	v_cmp_gt_u32_e32 vcc, v35, v157
	v_cmp_lt_i32_e64 s[6:7], v35, v147
	s_or_b64 vcc, vcc, s[6:7]
	v_or_b32_e32 v35, 40, v0
	v_cndmask_b32_e32 v69, v37, v204, vcc
	v_cmp_gt_u32_e32 vcc, v35, v157
	v_cmp_lt_i32_e64 s[6:7], v35, v147
	s_or_b64 vcc, vcc, s[6:7]
	v_or_b32_e32 v35, 41, v0
	v_cndmask_b32_e32 v70, v38, v204, vcc
	v_cmp_gt_u32_e32 vcc, v35, v157
	v_cmp_lt_i32_e64 s[6:7], v35, v147
	s_or_b64 vcc, vcc, s[6:7]
	v_or_b32_e32 v35, 42, v0
	v_cndmask_b32_e32 v71, v39, v204, vcc
	v_cmp_gt_u32_e32 vcc, v35, v157
	v_cmp_lt_i32_e64 s[6:7], v35, v147
	s_or_b64 vcc, vcc, s[6:7]
	v_or_b32_e32 v35, 43, v0
	v_cndmask_b32_e32 v76, v40, v204, vcc
	v_cmp_gt_u32_e32 vcc, v35, v157
	v_cmp_lt_i32_e64 s[6:7], v35, v147
	s_or_b64 vcc, vcc, s[6:7]
	v_or_b32_e32 v35, 48, v0
	v_cndmask_b32_e32 v77, v41, v204, vcc
	v_cmp_gt_u32_e32 vcc, v35, v157
	v_cmp_lt_i32_e64 s[6:7], v35, v147
	s_or_b64 vcc, vcc, s[6:7]
	v_or_b32_e32 v35, 49, v0
	v_cndmask_b32_e32 v78, v42, v204, vcc
	v_cmp_gt_u32_e32 vcc, v35, v157
	v_cmp_lt_i32_e64 s[6:7], v35, v147
	s_or_b64 vcc, vcc, s[6:7]
	v_or_b32_e32 v35, 50, v0
	v_cndmask_b32_e32 v79, v43, v204, vcc
	v_cmp_gt_u32_e32 vcc, v35, v157
	v_cmp_lt_i32_e64 s[6:7], v35, v147
	s_or_b64 vcc, vcc, s[6:7]
	v_or_b32_e32 v35, 51, v0
	v_cndmask_b32_e32 v80, v44, v204, vcc
	v_cmp_gt_u32_e32 vcc, v35, v157
	v_cmp_lt_i32_e64 s[6:7], v35, v147
	s_or_b64 vcc, vcc, s[6:7]
	v_or_b32_e32 v35, 56, v0
	v_cndmask_b32_e32 v81, v45, v204, vcc
	v_cmp_gt_u32_e32 vcc, v35, v157
	v_cmp_lt_i32_e64 s[6:7], v35, v147
	s_or_b64 vcc, vcc, s[6:7]
	v_or_b32_e32 v35, 57, v0
	v_max3_f32 v34, v66, s35, v67
	v_cndmask_b32_e32 v73, v46, v204, vcc
	v_cmp_gt_u32_e32 vcc, v35, v157
	v_cmp_lt_i32_e64 s[6:7], v35, v147
	v_max3_f32 v34, v34, v68, v69
	s_or_b64 vcc, vcc, s[6:7]
	v_or_b32_e32 v35, 58, v0
	v_max3_f32 v34, v34, v70, v71
	v_cndmask_b32_e32 v74, v47, v204, vcc
	v_cmp_gt_u32_e32 vcc, v35, v157
	v_cmp_lt_i32_e64 s[6:7], v35, v147
	v_max3_f32 v34, v34, v76, v77
	s_or_b64 vcc, vcc, s[6:7]
	v_or_b32_e32 v0, 59, v0
	v_max3_f32 v34, v34, v78, v79
	v_cndmask_b32_e32 v75, v48, v204, vcc
	v_cmp_gt_u32_e32 vcc, v0, v157
	v_cmp_lt_i32_e64 s[6:7], v0, v147
	v_max3_f32 v34, v34, v80, v81
	s_or_b64 vcc, vcc, s[6:7]
	v_max3_f32 v34, v34, v73, v74
	v_cndmask_b32_e32 v72, v49, v204, vcc
	v_and_b32_e32 v35, 64, v202
	v_max3_f32 v0, v34, v75, v72
	v_xor_b32_e32 v34, 32, v202
	v_add_u32_e32 v35, 64, v35
	v_cmp_lt_i32_e32 vcc, v34, v35
	s_nop 1
	v_cndmask_b32_e32 v34, v202, v34, vcc
	v_lshlrev_b32_e32 v34, 2, v34
	ds_bpermute_b32 v34, v34, v0
	s_waitcnt lgkmcnt(0)
	v_max_f32_e32 v34, v34, v34
	v_max_f32_e32 v0, v0, v34
	v_mul_f32_e32 v0, 0x3fb8aa3b, v0
	v_max_f32_e32 v34, v160, v160
	v_max_f32_e32 v159, v34, v0
	v_sub_f32_e32 v0, v160, v159
	v_exp_f32_e32 v0, v0
	v_cmp_neq_f32_e32 vcc, v159, v160
	s_cbranch_vccz .LBB0_956
	v_pk_mul_f32 v[32:33], v[32:33], v[0:1] op_sel_hi:[1,0]
	v_pk_mul_f32 v[30:31], v[30:31], v[0:1] op_sel_hi:[1,0]
	v_pk_mul_f32 v[28:29], v[28:29], v[0:1] op_sel_hi:[1,0]
	v_pk_mul_f32 v[26:27], v[26:27], v[0:1] op_sel_hi:[1,0]
	v_pk_mul_f32 v[24:25], v[24:25], v[0:1] op_sel_hi:[1,0]
	v_pk_mul_f32 v[22:23], v[22:23], v[0:1] op_sel_hi:[1,0]
	v_pk_mul_f32 v[20:21], v[20:21], v[0:1] op_sel_hi:[1,0]
	v_pk_mul_f32 v[18:19], v[18:19], v[0:1] op_sel_hi:[1,0]
	v_pk_mul_f32 v[16:17], v[16:17], v[0:1] op_sel_hi:[1,0]
	v_pk_mul_f32 v[14:15], v[14:15], v[0:1] op_sel_hi:[1,0]
	v_pk_mul_f32 v[12:13], v[12:13], v[0:1] op_sel_hi:[1,0]
	v_pk_mul_f32 v[10:11], v[10:11], v[0:1] op_sel_hi:[1,0]
	v_pk_mul_f32 v[8:9], v[8:9], v[0:1] op_sel_hi:[1,0]
	v_pk_mul_f32 v[6:7], v[6:7], v[0:1] op_sel_hi:[1,0]
	v_pk_mul_f32 v[4:5], v[4:5], v[0:1] op_sel_hi:[1,0]
	v_pk_mul_f32 v[2:3], v[2:3], v[0:1] op_sel_hi:[1,0]
; DI unsigned pack2(float a, float b) { f32x2 v = {a, b}; bf16x2_t r = __builtin_convertvector(v, bf16x2_t); return __builtin_bit_cast(unsigned, r); }
; DI f32x16 mfma32(bf16x8 a, bf16x8 b, f32x16 c) { return __builtin_amdgcn_mfma_f32_32x32x16_bf16(a, b, c, 0, 0, 0); }
;     ...
;   const float mn = fmaxf(m, mx); const float alpha = __builtin_amdgcn_exp2f(m - mn);
;   const float neg = (MODE == 2 && !lanesel) ? NINF : -mn;
;   float ps = 0.f;
; #pragma unroll
;   for (int k2 = 0; k2 < 2; ++k2)
; #pragma unroll
;     for (int i = 0; i < 16; ++i) {
;       if (!(HM & (1 << k2))) continue;
;       const float pv = (MODE == 1) ? __builtin_amdgcn_exp2f(s[k2][i] + neg) : __builtin_amdgcn_exp2f(fmaf(s[k2][i], L2E, neg));
;       s[k2][i] = pv; ps += pv;
;     }
;   l = l * alpha + ps;
;   if (__builtin_amdgcn_ballot_w64(mn != m) != 0ull) {
; #pragma unroll
;     for (int dt = 0; dt < 2; ++dt)
; #pragma unroll
;       for (int i = 0; i < 16; ++i) o[dt][i] *= alpha;
;   }
;   m = mn;
; #pragma unroll
;   for (int st = 0; st < 4; ++st) {
;     if (!(HM & (1 << (st >> 1)))) continue;
;     const int k2 = st >> 1, b8 = 8 * (st & 1);
;     const u32x4 pw = {pack2(s[k2][b8], s[k2][b8 + 1]), pack2(s[k2][b8 + 2], s[k2][b8 + 3]), pack2(s[k2][b8 + 4], s[k2][b8 + 5]), pack2(s[k2][b8 + 6], s[k2][b8 + 7])};
;     const bf16x8 pb = __builtin_bit_cast(bf16x8, pw);
; #pragma unroll
;     for (int dt = 0; dt < 2; ++dt) {
;       const s16x4 lo = *(const s16x4*)(Vs + (32 * dt + r) * LSTR + 16 * st + 4 * h);
;       const s16x4 hi = *(const s16x4*)(Vs + (32 * dt + r) * LSTR + 16 * st + 8 + 4 * h);
;       const bf16x8 a = __builtin_shufflevector(lo, hi, 0, 1, 2, 3, 4, 5, 6, 7);
;       o[dt] = mfma32(a, pb, o[dt]);
;     }
;   }
.LBB0_956:
	v_fma_f32 v66, v66, s34, -v159
	v_exp_f32_e32 v82, v66
	v_fma_f32 v66, v67, s34, -v159
	v_exp_f32_e32 v83, v66
	v_fma_f32 v66, v68, s34, -v159
	v_exp_f32_e32 v84, v66
	v_fma_f32 v66, v69, s34, -v159
	v_add_f32_e32 v67, 0, v82
	v_exp_f32_e32 v85, v66
	v_fma_f32 v66, v70, s34, -v159
	v_add_f32_e32 v67, v83, v67
	v_exp_f32_e32 v70, v66
	v_fma_f32 v66, v71, s34, -v159
	v_exp_f32_e32 v71, v66
	v_add_f32_e32 v66, v84, v67
	v_fma_f32 v67, v76, s34, -v159
	v_exp_f32_e32 v86, v67
	v_fma_f32 v67, v77, s34, -v159
	v_add_f32_e32 v66, v85, v66
	v_exp_f32_e32 v87, v67
	v_fma_f32 v67, v78, s34, -v159
	v_add_f32_e32 v66, v70, v66
	v_exp_f32_e32 v88, v67
	v_fma_f32 v67, v79, s34, -v159
	v_add_f32_e32 v66, v71, v66
	v_exp_f32_e32 v89, v67
	v_add_f32_e32 v66, v86, v66
	v_add_f32_e32 v66, v87, v66
	v_add_f32_e32 v66, v88, v66
	v_add_f32_e32 v90, v89, v66
	v_fma_f32 v66, v80, s34, -v159
	v_add_u32_e32 v92, 0x6800, v198
	v_exp_f32_e32 v91, v66
	ds_read2_b64 v[66:69], v92 offset0:136 offset1:138
	v_cvt_pk_bf16_f32 v78, v70, v71
	v_add_u32_e32 v70, v199, v200
	v_fma_f32 v76, v81, s34, -v159
	v_add_u32_e32 v70, 0x7800, v70
	v_exp_f32_e32 v93, v76
	v_cvt_pk_bf16_f32 v76, v82, v83
	ds_read2_b64 v[80:83], v70 offset0:200 offset1:202
	v_cvt_pk_bf16_f32 v77, v84, v85
	v_cvt_pk_bf16_f32 v79, v86, v87
	v_fma_f32 v71, v72, s34, -v159
	s_mov_b64 s[6:7], 0
	s_waitcnt lgkmcnt(1)
	v_mfma_f32_32x32x16_bf16 v[34:49], v[66:69], v[76:79], v[2:17]
	v_fma_f32 v66, v73, s34, -v159
	v_exp_f32_e32 v84, v66
	v_fma_f32 v66, v74, s34, -v159
	v_exp_f32_e32 v85, v66
	v_fma_f32 v66, v75, s34, -v159
	v_exp_f32_e32 v86, v66
	ds_read2_b64 v[66:69], v92 offset0:140 offset1:142
	s_waitcnt lgkmcnt(1)
	v_mfma_f32_32x32x16_bf16 v[50:65], v[80:83], v[76:79], v[18:33]
	v_exp_f32_e32 v78, v71
	ds_read2_b64 v[70:73], v70 offset0:204 offset1:206
	v_cvt_pk_bf16_f32 v74, v88, v89
	v_cvt_pk_bf16_f32 v75, v91, v93
	v_cvt_pk_bf16_f32 v76, v84, v85
	v_cvt_pk_bf16_f32 v77, v86, v78
	s_waitcnt lgkmcnt(1)
	s_nop 0
	v_mfma_f32_32x32x16_bf16 v[2:17], v[66:69], v[74:77], v[34:49]
	v_add_f32_e32 v66, v91, v90
	v_add_f32_e32 v66, v93, v66
	v_add_f32_e32 v66, v84, v66
	v_add_f32_e32 v66, v85, v66
	v_add_f32_e32 v66, v86, v66
	v_add_f32_e32 v161, v78, v66
	v_fmac_f32_e32 v161, v162, v0
	s_waitcnt lgkmcnt(0)
	v_mfma_f32_32x32x16_bf16 v[18:33], v[70:73], v[74:77], v[50:65]

; DI f32x16 mfma32(bf16x8 a, bf16x8 b, f32x16 c) { return __builtin_amdgcn_mfma_f32_32x32x16_bf16(a, b, c, 0, 0, 0); }
;     ...
; #pragma unroll
;   for (int k2 = 0; k2 < 2; ++k2) {
;     if (!(HM & (1 << k2))) continue;
; #pragma unroll
;     for (int i = 0; i < 16; ++i) s[k2][i] = 0.f;
; #pragma unroll
;     for (int ks = 0; ks < 4; ++ks) {
;       const bf16x8 a = *(const bf16x8*)(Ks + (32 * k2 + r) * LSTR + 16 * ks + 8 * h);
;       s[k2] = mfma32(a, qf[ks], s[k2]);
;     }
;   }
;   if (MODE == 1) {
; #pragma unroll
;     for (int k2 = 0; k2 < 2; ++k2)
; #pragma unroll
;       for (int g = 0; g < 4; ++g) {
;         if (!(HM & (1 << k2))) continue;
;         const f32x4 cv = *(const f32x4*)(cn_lds + key0 + 32 * k2 + 8 * g + 4 * h);
; #pragma unroll
;         for (int e = 0; e < 4; ++e) s[k2][4 * g + e] = fmaf(s[k2][4 * g + e], L2E, cv[e]);
;       }
;   }
;   float mx = NINF;
; #pragma unroll
;   for (int k2 = 0; k2 < 2; ++k2)
; #pragma unroll
;     for (int i = 0; i < 16; ++i) {
;       if (!(HM & (1 << k2))) continue;
;       float v = s[k2][i];
;       if (MASKED) {
;         const int tk = key0 + 32 * k2 + crow(i, h);
;         const bool valid = (MODE == 0) ? ((tk <= tq) && (tq - tk <= maxdist)) : (tk <= tq);
;         v = valid ? v : NINF; s[k2][i] = v;
;       }
;       mx = fmaxf(mx, v);
; template <int MODE>
; DI void flash_loop(char* smem, const bf16_t* Kbase, size_t ldk, const bf16_t* Vtbase, size_t ldv, ull tiles, ull wtiles,
;                    const bf16x8 (&qf)[4], f32x16 (&o)[2], float& m, float& l, int tq, int tqmin, int tqmax, int maxdist, const float* cn_lds, ull lmask) {
;     ...
;     const bool interior = (64 * kt + 63 <= tqmin) && (MODE != 0 || (tqmax - 64 * kt <= maxdist));
;     int hm = 3;
;     if (MODE == 0) {
;       hm = 0;
;       if (64 * kt <= tqmax && 64 * kt + 31 >= tqmin - maxdist) hm |= 1;
;       if (64 * kt + 32 <= tqmax && 64 * kt + 63 >= tqmin - maxdist) hm |= 2;
;     }
;     if (MODE == 0 && hm == 1) attn_tile<MODE, true, 1>(Ks, Vs, qf, o, m, l, 64 * kt, tq, maxdist, cn_lds, sel);
;     else if (MODE == 0 && hm == 2) attn_tile<MODE, true, 2>(Ks, Vs, qf, o, m, l, 64 * kt, tq, maxdist, cn_lds, sel);
;     else if (interior) attn_tile<MODE, false>(Ks, Vs, qf, o, m, l, 64 * kt, tq, maxdist, cn_lds, sel);
;     else attn_tile<MODE, true>(Ks, Vs, qf, o, m, l, 64 * kt, tq, maxdist, cn_lds, sel);
.LBB0_959:
	ds_read_b128 v[82:85], v196 offset:18432
	ds_read_b128 v[78:81], v196 offset:18464
	ds_read_b128 v[74:77], v196 offset:18496
	ds_read_b128 v[66:69], v196 offset:18528
	ds_read_b128 v[70:73], v196 offset:23040
	s_cmp_le_u32 s33, s5
	s_cselect_b64 s[6:7], -1, 0
	s_cmp_ge_i32 s58, s30
	s_cselect_b64 s[36:37], -1, 0
	s_and_b64 s[6:7], s[6:7], s[36:37]
	s_andn2_b64 vcc, exec, s[6:7]
	s_mov_b64 s[6:7], -1
	s_cbranch_vccz .LBB0_963
	s_waitcnt lgkmcnt(4)
	v_mfma_f32_32x32x16_bf16 v[50:65], v[82:85], v[98:101], 0
	ds_read_b128 v[86:89], v196 offset:23072
	ds_read_b128 v[90:93], v196 offset:23104
	v_or_b32_e32 v0, s58, v197
	v_cmp_gt_u32_e32 vcc, v0, v157
	v_cmp_lt_i32_e64 s[6:7], v0, v147
	s_or_b64 vcc, vcc, s[6:7]
	s_waitcnt lgkmcnt(5)
	v_mfma_f32_32x32x16_bf16 v[50:65], v[78:81], v[102:105], v[50:65]
	s_waitcnt lgkmcnt(2)
	v_mfma_f32_32x32x16_bf16 v[34:49], v[70:73], v[98:101], 0
	v_mfma_f32_32x32x16_bf16 v[50:65], v[74:77], v[106:109], v[50:65]
	s_waitcnt lgkmcnt(1)
	v_mfma_f32_32x32x16_bf16 v[34:49], v[86:89], v[102:105], v[34:49]
	ds_read_b128 v[86:89], v196 offset:23136
	v_mfma_f32_32x32x16_bf16 v[50:65], v[66:69], v[110:113], v[50:65]
	s_waitcnt lgkmcnt(1)
	v_mfma_f32_32x32x16_bf16 v[34:49], v[90:93], v[106:109], v[34:49]
	s_waitcnt lgkmcnt(0)
	v_mfma_f32_32x32x16_bf16 v[34:49], v[86:89], v[110:113], v[34:49]
	s_nop 7
	v_cndmask_b32_e32 v86, v50, v204, vcc
	v_bitop3_b32 v50, s58, v197, s58 bitop3:3
	v_cmp_ge_u32_e32 vcc, v0, v157
	v_cmp_lt_i32_e64 s[6:7], v158, v50
	s_or_b64 vcc, vcc, s[6:7]
	v_cndmask_b32_e32 v87, v51, v204, vcc
	v_or_b32_e32 v51, 2, v0
	v_cmp_gt_u32_e32 vcc, v51, v157
	v_cmp_lt_i32_e64 s[6:7], v51, v147
	s_or_b64 vcc, vcc, s[6:7]
	v_or_b32_e32 v51, 3, v0
	v_cndmask_b32_e32 v88, v52, v204, vcc
	v_cmp_gt_u32_e32 vcc, v51, v157
	v_cmp_lt_i32_e64 s[6:7], v51, v147
	s_or_b64 vcc, vcc, s[6:7]
	v_or_b32_e32 v51, 8, v0
	v_cndmask_b32_e32 v89, v53, v204, vcc
	v_cmp_gt_u32_e32 vcc, v51, v157
	v_cmp_lt_i32_e64 s[6:7], v51, v147
	s_or_b64 vcc, vcc, s[6:7]
	v_or_b32_e32 v51, 9, v0
	v_cndmask_b32_e32 v90, v54, v204, vcc
	v_cmp_gt_u32_e32 vcc, v51, v157
	v_cmp_lt_i32_e64 s[6:7], v51, v147
	s_or_b64 vcc, vcc, s[6:7]
	v_or_b32_e32 v51, 10, v0
	v_cndmask_b32_e32 v194, v55, v204, vcc
	v_cmp_gt_u32_e32 vcc, v51, v157
	v_cmp_lt_i32_e64 s[6:7], v51, v147
	s_or_b64 vcc, vcc, s[6:7]
	v_or_b32_e32 v51, 11, v0
	v_cndmask_b32_e32 v193, v56, v204, vcc
	v_cmp_gt_u32_e32 vcc, v51, v157
	v_cmp_lt_i32_e64 s[6:7], v51, v147
	s_or_b64 vcc, vcc, s[6:7]
	v_or_b32_e32 v51, 16, v0
	v_cndmask_b32_e32 v195, v57, v204, vcc
	v_cmp_gt_u32_e32 vcc, v51, v157
	v_cmp_lt_i32_e64 s[6:7], v51, v147
	s_or_b64 vcc, vcc, s[6:7]
	v_or_b32_e32 v51, 17, v0
	v_cndmask_b32_e32 v190, v58, v204, vcc
	v_cmp_gt_u32_e32 vcc, v51, v157
	v_cmp_lt_i32_e64 s[6:7], v51, v147
	s_or_b64 vcc, vcc, s[6:7]
	v_or_b32_e32 v51, 18, v0
	v_cndmask_b32_e32 v192, v59, v204, vcc
	v_cmp_gt_u32_e32 vcc, v51, v157
	v_cmp_lt_i32_e64 s[6:7], v51, v147
	s_or_b64 vcc, vcc, s[6:7]
	v_or_b32_e32 v51, 19, v0
	v_cndmask_b32_e32 v191, v60, v204, vcc
	v_cmp_gt_u32_e32 vcc, v51, v157
	v_cmp_lt_i32_e64 s[6:7], v51, v147
	s_or_b64 vcc, vcc, s[6:7]
	v_or_b32_e32 v51, 24, v0
	v_cndmask_b32_e32 v189, v61, v204, vcc
	v_cmp_gt_u32_e32 vcc, v51, v157
	v_cmp_lt_i32_e64 s[6:7], v51, v147
	s_or_b64 vcc, vcc, s[6:7]
	v_or_b32_e32 v51, 25, v0
	v_cndmask_b32_e32 v188, v62, v204, vcc
	v_cmp_gt_u32_e32 vcc, v51, v157
	v_cmp_lt_i32_e64 s[6:7], v51, v147
	s_or_b64 vcc, vcc, s[6:7]
	v_or_b32_e32 v51, 26, v0
	v_cndmask_b32_e32 v187, v63, v204, vcc
	v_cmp_gt_u32_e32 vcc, v51, v157
	v_cmp_lt_i32_e64 s[6:7], v51, v147
	s_or_b64 vcc, vcc, s[6:7]
	v_or_b32_e32 v51, 27, v0
	v_cndmask_b32_e32 v186, v64, v204, vcc
	v_cmp_gt_u32_e32 vcc, v51, v157
	v_cmp_lt_i32_e64 s[6:7], v51, v147
	s_or_b64 vcc, vcc, s[6:7]
	v_or_b32_e32 v51, 32, v0
	v_cndmask_b32_e32 v184, v65, v204, vcc
	v_cmp_gt_u32_e32 vcc, v51, v157
	v_cmp_lt_i32_e64 s[6:7], v51, v147
	s_or_b64 vcc, vcc, s[6:7]
	v_cndmask_b32_e32 v180, v34, v204, vcc
	v_or_b32_e32 v34, 33, v0
	v_cmp_gt_u32_e32 vcc, v34, v157
	v_cmp_lt_i32_e64 s[6:7], v34, v147
	s_or_b64 vcc, vcc, s[6:7]
	v_cndmask_b32_e32 v164, v35, v204, vcc
	v_or_b32_e32 v35, 34, v0
	v_cmp_gt_u32_e32 vcc, v35, v157
	v_cmp_lt_i32_e64 s[6:7], v35, v147
	s_or_b64 vcc, vcc, s[6:7]
	v_or_b32_e32 v35, 35, v0
	v_cndmask_b32_e32 v161, v36, v204, vcc
	v_cmp_gt_u32_e32 vcc, v35, v157
	v_cmp_lt_i32_e64 s[6:7], v35, v147
	s_or_b64 vcc, vcc, s[6:7]
	v_or_b32_e32 v35, 40, v0
	v_cndmask_b32_e32 v97, v37, v204, vcc
	v_cmp_gt_u32_e32 vcc, v35, v157
	v_cmp_lt_i32_e64 s[6:7], v35, v147
	s_or_b64 vcc, vcc, s[6:7]
	v_or_b32_e32 v35, 41, v0
	v_cndmask_b32_e32 v92, v38, v204, vcc
	v_cmp_gt_u32_e32 vcc, v35, v157
	v_cmp_lt_i32_e64 s[6:7], v35, v147
	s_or_b64 vcc, vcc, s[6:7]
	v_or_b32_e32 v35, 42, v0
	v_cndmask_b32_e32 v91, v39, v204, vcc
	v_cmp_gt_u32_e32 vcc, v35, v157
	v_cmp_lt_i32_e64 s[6:7], v35, v147
	s_or_b64 vcc, vcc, s[6:7]
	v_or_b32_e32 v35, 43, v0
	v_cndmask_b32_e32 v93, v40, v204, vcc
	v_cmp_gt_u32_e32 vcc, v35, v157
	v_cmp_lt_i32_e64 s[6:7], v35, v147
	s_or_b64 vcc, vcc, s[6:7]
	v_or_b32_e32 v35, 48, v0
	v_cndmask_b32_e32 v94, v41, v204, vcc
	v_cmp_gt_u32_e32 vcc, v35, v157
	v_cmp_lt_i32_e64 s[6:7], v35, v147
	s_or_b64 vcc, vcc, s[6:7]
	v_or_b32_e32 v35, 49, v0
	v_max3_f32 v50, v86, s35, v87
	v_cndmask_b32_e32 v95, v42, v204, vcc
	v_cmp_gt_u32_e32 vcc, v35, v157
	v_cmp_lt_i32_e64 s[6:7], v35, v147
	v_max3_f32 v50, v50, v88, v89
	s_or_b64 vcc, vcc, s[6:7]
	v_or_b32_e32 v35, 50, v0
	v_max3_f32 v50, v50, v90, v194
	v_cndmask_b32_e32 v96, v43, v204, vcc
	v_cmp_gt_u32_e32 vcc, v35, v157
	v_cmp_lt_i32_e64 s[6:7], v35, v147
; DI int crow(int i, int h) { return (i & 3) + 8 * (i >> 2) + 4 * h; }
;     ...
;   float mx = NINF;
; #pragma unroll
;   for (int k2 = 0; k2 < 2; ++k2)
; #pragma unroll
;     for (int i = 0; i < 16; ++i) {
;       if (!(HM & (1 << k2))) continue;
;       float v = s[k2][i];
;       if (MASKED) {
;         const int tk = key0 + 32 * k2 + crow(i, h);
;         const bool valid = (MODE == 0) ? ((tk <= tq) && (tq - tk <= maxdist)) : (tk <= tq);
;         v = valid ? v : NINF; s[k2][i] = v;
;       }
;       mx = fmaxf(mx, v);
;     }
;   mx = fmaxf(mx, __shfl_xor(mx, 32));
;   if (MODE != 1) mx *= L2E;
;   if (MODE == 2) mx = lanesel ? mx : NINF;
;   const float mn = fmaxf(m, mx); const float alpha = __builtin_amdgcn_exp2f(m - mn);
;   const float neg = (MODE == 2 && !lanesel) ? NINF : -mn;
;   float ps = 0.f;
; #pragma unroll
;   for (int k2 = 0; k2 < 2; ++k2)
; #pragma unroll
;     for (int i = 0; i < 16; ++i) {
;       if (!(HM & (1 << k2))) continue;
;       const float pv = (MODE == 1) ? __builtin_amdgcn_exp2f(s[k2][i] + neg) : __builtin_amdgcn_exp2f(fmaf(s[k2][i], L2E, neg));
;       s[k2][i] = pv; ps += pv;
;     }
;   l = l * alpha + ps;
	v_max3_f32 v50, v50, v193, v195
	s_or_b64 vcc, vcc, s[6:7]
	v_or_b32_e32 v35, 51, v0
	v_max3_f32 v50, v50, v190, v192
	v_cndmask_b32_e32 v163, v44, v204, vcc
	v_cmp_gt_u32_e32 vcc, v35, v157
	v_cmp_lt_i32_e64 s[6:7], v35, v147
	v_max3_f32 v50, v50, v191, v189
	s_or_b64 vcc, vcc, s[6:7]
	v_or_b32_e32 v35, 56, v0
	v_max3_f32 v50, v50, v188, v187
	v_cndmask_b32_e32 v165, v45, v204, vcc
	v_cmp_gt_u32_e32 vcc, v35, v157
	v_cmp_lt_i32_e64 s[6:7], v35, v147
	v_max3_f32 v50, v50, v186, v184
	s_or_b64 vcc, vcc, s[6:7]
	v_or_b32_e32 v35, 57, v0
	v_max3_f32 v34, v50, v180, v164
	v_cndmask_b32_e32 v181, v46, v204, vcc
	v_cmp_gt_u32_e32 vcc, v35, v157
	v_cmp_lt_i32_e64 s[6:7], v35, v147
	v_max3_f32 v34, v34, v161, v97
	s_or_b64 vcc, vcc, s[6:7]
	v_or_b32_e32 v35, 58, v0
	v_max3_f32 v34, v34, v92, v91
	v_cndmask_b32_e32 v182, v47, v204, vcc
	v_cmp_gt_u32_e32 vcc, v35, v157
	v_cmp_lt_i32_e64 s[6:7], v35, v147
	v_max3_f32 v34, v34, v93, v94
	s_or_b64 vcc, vcc, s[6:7]
	v_or_b32_e32 v0, 59, v0
	v_max3_f32 v34, v34, v95, v96
	v_cndmask_b32_e32 v183, v48, v204, vcc
	v_cmp_gt_u32_e32 vcc, v0, v157
	v_cmp_lt_i32_e64 s[6:7], v0, v147
	v_max3_f32 v34, v34, v163, v165
	s_or_b64 vcc, vcc, s[6:7]
	v_max3_f32 v34, v34, v181, v182
	v_cndmask_b32_e32 v185, v49, v204, vcc
	v_and_b32_e32 v35, 64, v202
	v_max3_f32 v0, v34, v183, v185
	v_xor_b32_e32 v34, 32, v202
	v_add_u32_e32 v35, 64, v35
	v_cmp_lt_i32_e32 vcc, v34, v35
	s_nop 1
	v_cndmask_b32_e32 v34, v202, v34, vcc
	v_lshlrev_b32_e32 v34, 2, v34
	ds_bpermute_b32 v34, v34, v0
	s_waitcnt lgkmcnt(0)
	v_max_f32_e32 v34, v34, v34
	v_max_f32_e32 v0, v0, v34
	v_mul_f32_e32 v0, 0x3fb8aa3b, v0
	v_max_f32_e32 v34, v160, v160
	v_max_f32_e32 v159, v34, v0
	v_sub_f32_e32 v0, v160, v159
	v_exp_f32_e32 v0, v0
	v_cmp_neq_f32_e32 vcc, v159, v160
	s_cbranch_vccz .LBB0_962
	v_pk_mul_f32 v[32:33], v[32:33], v[0:1] op_sel_hi:[1,0]
	v_pk_mul_f32 v[30:31], v[30:31], v[0:1] op_sel_hi:[1,0]
	v_pk_mul_f32 v[28:29], v[28:29], v[0:1] op_sel_hi:[1,0]
	v_pk_mul_f32 v[26:27], v[26:27], v[0:1] op_sel_hi:[1,0]
	v_pk_mul_f32 v[24:25], v[24:25], v[0:1] op_sel_hi:[1,0]
	v_pk_mul_f32 v[22:23], v[22:23], v[0:1] op_sel_hi:[1,0]
	v_pk_mul_f32 v[20:21], v[20:21], v[0:1] op_sel_hi:[1,0]
	v_pk_mul_f32 v[18:19], v[18:19], v[0:1] op_sel_hi:[1,0]
	v_pk_mul_f32 v[16:17], v[16:17], v[0:1] op_sel_hi:[1,0]
	v_pk_mul_f32 v[14:15], v[14:15], v[0:1] op_sel_hi:[1,0]
	v_pk_mul_f32 v[12:13], v[12:13], v[0:1] op_sel_hi:[1,0]
	v_pk_mul_f32 v[10:11], v[10:11], v[0:1] op_sel_hi:[1,0]
	v_pk_mul_f32 v[8:9], v[8:9], v[0:1] op_sel_hi:[1,0]
	v_pk_mul_f32 v[6:7], v[6:7], v[0:1] op_sel_hi:[1,0]
	v_pk_mul_f32 v[4:5], v[4:5], v[0:1] op_sel_hi:[1,0]
	v_pk_mul_f32 v[2:3], v[2:3], v[0:1] op_sel_hi:[1,0]
.LBB0_962:
	v_fma_f32 v86, v86, s34, -v159
	v_exp_f32_e32 v86, v86
	v_fma_f32 v87, v87, s34, -v159
	v_exp_f32_e32 v87, v87
	v_fma_f32 v88, v88, s34, -v159
	v_exp_f32_e32 v88, v88
	v_fma_f32 v89, v89, s34, -v159
	v_exp_f32_e32 v89, v89
	v_fma_f32 v90, v90, s34, -v159
	v_add_f32_e32 v209, 0, v86
	v_exp_f32_e32 v90, v90
	v_fma_f32 v194, v194, s34, -v159
	v_add_f32_e32 v209, v87, v209
	v_exp_f32_e32 v194, v194
	v_fma_f32 v193, v193, s34, -v159
	v_add_f32_e32 v209, v88, v209
	v_exp_f32_e32 v193, v193
	v_fma_f32 v195, v195, s34, -v159
	v_add_f32_e32 v209, v89, v209
	v_exp_f32_e32 v195, v195
	v_fma_f32 v190, v190, s34, -v159
	v_add_f32_e32 v209, v90, v209
	v_exp_f32_e32 v190, v190
	v_fma_f32 v192, v192, s34, -v159
	v_add_f32_e32 v209, v194, v209
	v_exp_f32_e32 v192, v192
	v_fma_f32 v191, v191, s34, -v159
	v_add_f32_e32 v209, v193, v209
	v_exp_f32_e32 v191, v191
	v_fma_f32 v189, v189, s34, -v159
	v_add_f32_e32 v209, v195, v209
	v_exp_f32_e32 v189, v189
	v_fma_f32 v188, v188, s34, -v159
	v_add_f32_e32 v209, v190, v209
	v_exp_f32_e32 v188, v188
	v_fma_f32 v187, v187, s34, -v159
	v_add_f32_e32 v209, v192, v209
	v_exp_f32_e32 v187, v187
	v_fma_f32 v186, v186, s34, -v159
	v_add_f32_e32 v209, v191, v209
	v_exp_f32_e32 v186, v186
	v_fma_f32 v184, v184, s34, -v159
	v_add_f32_e32 v209, v189, v209
	v_exp_f32_e32 v184, v184
	v_fma_f32 v180, v180, s34, -v159
	v_add_f32_e32 v209, v188, v209
	v_exp_f32_e32 v180, v180
	v_fma_f32 v164, v164, s34, -v159
	v_add_f32_e32 v209, v187, v209
	v_exp_f32_e32 v164, v164
	v_fma_f32 v161, v161, s34, -v159
	v_add_f32_e32 v209, v186, v209
	v_exp_f32_e32 v210, v161
	v_add_f32_e32 v209, v184, v209
	v_add_f32_e32 v209, v180, v209
	v_add_f32_e32 v209, v164, v209
	v_fma_f32 v97, v97, s34, -v159
	v_add_f32_e32 v161, v210, v209
	v_exp_f32_e32 v209, v97
	v_fma_f32 v92, v92, s34, -v159
	v_exp_f32_e32 v211, v92
	v_fma_f32 v91, v91, s34, -v159
	v_exp_f32_e32 v212, v91
	v_add_f32_e32 v97, v209, v161
	v_add_f32_e32 v92, v211, v97
	v_cvt_pk_bf16_f32 v86, v86, v87
	v_add_f32_e32 v91, v212, v92
	v_fma_f32 v92, v93, s34, -v159
	v_exp_f32_e32 v213, v92
	v_fma_f32 v92, v94, s34, -v159
	v_exp_f32_e32 v214, v92
	v_fma_f32 v92, v95, s34, -v159
	v_exp_f32_e32 v215, v92
	v_fma_f32 v92, v96, s34, -v159
	v_exp_f32_e32 v216, v92
	v_fma_f32 v92, v163, s34, -v159
	v_add_f32_e32 v91, v213, v91
	v_exp_f32_e32 v163, v92
	v_fma_f32 v92, v165, s34, -v159
	v_add_f32_e32 v91, v214, v91
	v_exp_f32_e32 v165, v92
	v_fma_f32 v92, v181, s34, -v159
	v_add_f32_e32 v91, v215, v91
	v_exp_f32_e32 v181, v92
	v_fma_f32 v92, v182, s34, -v159
	v_add_f32_e32 v91, v216, v91
	v_exp_f32_e32 v182, v92
	v_fma_f32 v92, v183, s34, -v159
	v_add_f32_e32 v91, v163, v91
	v_exp_f32_e32 v183, v92
	v_fma_f32 v92, v185, s34, -v159
	v_add_f32_e32 v91, v165, v91
	v_exp_f32_e32 v185, v92
	v_add_f32_e32 v91, v181, v91
	v_add_f32_e32 v91, v182, v91
	v_add_f32_e32 v91, v183, v91
	v_add_f32_e32 v161, v185, v91
	v_fmac_f32_e32 v161, v162, v0
	v_add_u32_e32 v0, 0x6800, v198
	v_cvt_pk_bf16_f32 v87, v88, v89
	v_cvt_pk_bf16_f32 v88, v90, v194
	ds_read2_b64 v[90:93], v0 offset0:128 offset1:130
	ds_read2_b64 v[94:97], v0 offset0:132 offset1:134
	v_cvt_pk_bf16_f32 v89, v193, v195
	v_add_u32_e32 v193, 0x7800, v198
	s_mov_b64 s[6:7], 0
	s_waitcnt lgkmcnt(1)
; DI unsigned pack2(float a, float b) { f32x2 v = {a, b}; bf16x2_t r = __builtin_convertvector(v, bf16x2_t); return __builtin_bit_cast(unsigned, r); }
; DI f32x16 mfma32(bf16x8 a, bf16x8 b, f32x16 c) { return __builtin_amdgcn_mfma_f32_32x32x16_bf16(a, b, c, 0, 0, 0); }
; DI int crow(int i, int h) { return (i & 3) + 8 * (i >> 2) + 4 * h; }
;     ...
;   float mx = NINF;
; #pragma unroll
;   for (int k2 = 0; k2 < 2; ++k2)
; #pragma unroll
;     for (int i = 0; i < 16; ++i) {
;       if (!(HM & (1 << k2))) continue;
;       float v = s[k2][i];
;       if (MASKED) {
;         const int tk = key0 + 32 * k2 + crow(i, h);
;         const bool valid = (MODE == 0) ? ((tk <= tq) && (tq - tk <= maxdist)) : (tk <= tq);
;         v = valid ? v : NINF; s[k2][i] = v;
;       }
;       mx = fmaxf(mx, v);
;     }
;   mx = fmaxf(mx, __shfl_xor(mx, 32));
;   if (MODE != 1) mx *= L2E;
;   if (MODE == 2) mx = lanesel ? mx : NINF;
;   const float mn = fmaxf(m, mx); const float alpha = __builtin_amdgcn_exp2f(m - mn);
;   const float neg = (MODE == 2 && !lanesel) ? NINF : -mn;
;   float ps = 0.f;
; #pragma unroll
;   for (int k2 = 0; k2 < 2; ++k2)
; #pragma unroll
;     for (int i = 0; i < 16; ++i) {
;       if (!(HM & (1 << k2))) continue;
;       const float pv = (MODE == 1) ? __builtin_amdgcn_exp2f(s[k2][i] + neg) : __builtin_amdgcn_exp2f(fmaf(s[k2][i], L2E, neg));
;       s[k2][i] = pv; ps += pv;
;     }
;   l = l * alpha + ps;
;   if (__builtin_amdgcn_ballot_w64(mn != m) != 0ull) {
; #pragma unroll
;     for (int dt = 0; dt < 2; ++dt)
; #pragma unroll
;       for (int i = 0; i < 16; ++i) o[dt][i] *= alpha;
;   }
;     ...
; #pragma unroll
;   for (int st = 0; st < 4; ++st) {
;     if (!(HM & (1 << (st >> 1)))) continue;
;     const int k2 = st >> 1, b8 = 8 * (st & 1);
;     const u32x4 pw = {pack2(s[k2][b8], s[k2][b8 + 1]), pack2(s[k2][b8 + 2], s[k2][b8 + 3]), pack2(s[k2][b8 + 4], s[k2][b8 + 5]), pack2(s[k2][b8 + 6], s[k2][b8 + 7])};
;     const bf16x8 pb = __builtin_bit_cast(bf16x8, pw);
; #pragma unroll
;     for (int dt = 0; dt < 2; ++dt) {
;       const s16x4 lo = *(const s16x4*)(Vs + (32 * dt + r) * LSTR + 16 * st + 4 * h);
;       const s16x4 hi = *(const s16x4*)(Vs + (32 * dt + r) * LSTR + 16 * st + 8 + 4 * h);
;       const bf16x8 a = __builtin_shufflevector(lo, hi, 0, 1, 2, 3, 4, 5, 6, 7);
;       o[dt] = mfma32(a, pb, o[dt]);
;     }
;   }
	v_mfma_f32_32x32x16_bf16 v[34:49], v[90:93], v[86:89], v[2:17]
	ds_read2_b64 v[90:93], v193 offset0:192 offset1:194
	s_waitcnt lgkmcnt(0)
	v_mfma_f32_32x32x16_bf16 v[50:65], v[90:93], v[86:89], v[18:33]
	ds_read2_b64 v[90:93], v193 offset0:196 offset1:198
	v_cvt_pk_bf16_f32 v86, v190, v192
	v_cvt_pk_bf16_f32 v87, v191, v189
	v_cvt_pk_bf16_f32 v88, v188, v187
	v_cvt_pk_bf16_f32 v89, v186, v184
	s_waitcnt lgkmcnt(0)
	s_nop 0
	v_mfma_f32_32x32x16_bf16 v[50:65], v[90:93], v[86:89], v[50:65]
	ds_read2_b64 v[90:93], v0 offset0:136 offset1:138
	v_mfma_f32_32x32x16_bf16 v[34:49], v[94:97], v[86:89], v[34:49]
	v_cvt_pk_bf16_f32 v86, v180, v164
	v_cvt_pk_bf16_f32 v87, v210, v209
	v_cvt_pk_bf16_f32 v88, v211, v212
	v_cvt_pk_bf16_f32 v89, v213, v214
	s_waitcnt lgkmcnt(0)
	s_nop 0
	v_mfma_f32_32x32x16_bf16 v[34:49], v[90:93], v[86:89], v[34:49]
	ds_read2_b64 v[90:93], v193 offset0:200 offset1:202
	s_waitcnt lgkmcnt(0)
	v_mfma_f32_32x32x16_bf16 v[50:65], v[90:93], v[86:89], v[50:65]
	ds_read2_b64 v[90:93], v0 offset0:140 offset1:142
	v_cvt_pk_bf16_f32 v86, v215, v216
	v_cvt_pk_bf16_f32 v87, v163, v165
	v_cvt_pk_bf16_f32 v88, v181, v182
	v_cvt_pk_bf16_f32 v89, v183, v185
	s_waitcnt lgkmcnt(0)
	s_nop 0
	v_mfma_f32_32x32x16_bf16 v[2:17], v[90:93], v[86:89], v[34:49]
	ds_read2_b64 v[90:93], v193 offset0:204 offset1:206
	s_waitcnt lgkmcnt(0)
	v_mfma_f32_32x32x16_bf16 v[18:33], v[90:93], v[86:89], v[50:65]
.LBB0_963:
	s_and_b64 vcc, exec, s[6:7]
	s_cbranch_vccz .LBB0_967
	s_waitcnt lgkmcnt(4)
	v_mfma_f32_32x32x16_bf16 v[82:97], v[82:85], v[98:101], 0
	s_nop 4
	ds_read_b128 v[34:37], v196 offset:23072
	ds_read_b128 v[38:41], v196 offset:23104
	s_waitcnt lgkmcnt(5)
	v_mfma_f32_32x32x16_bf16 v[82:97], v[78:81], v[102:105], v[82:97]
	s_waitcnt lgkmcnt(4)
	v_mfma_f32_32x32x16_bf16 v[82:97], v[74:77], v[106:109], v[82:97]
	s_waitcnt lgkmcnt(3)
	v_mfma_f32_32x32x16_bf16 v[82:97], v[66:69], v[110:113], v[82:97]
	s_waitcnt lgkmcnt(2)
	v_mfma_f32_32x32x16_bf16 v[66:81], v[70:73], v[98:101], 0
	s_nop 9
	v_max3_f32 v0, v82, s35, v83
	v_max3_f32 v0, v0, v84, v85
	v_max3_f32 v0, v0, v86, v87
	v_max3_f32 v0, v0, v88, v89
	v_max3_f32 v0, v0, v90, v91
	v_max3_f32 v0, v0, v92, v93
	v_max3_f32 v0, v0, v94, v95
	s_waitcnt lgkmcnt(1)
	v_mfma_f32_32x32x16_bf16 v[66:81], v[34:37], v[102:105], v[66:81]
	ds_read_b128 v[34:37], v196 offset:23136
	v_max3_f32 v0, v0, v96, v97
	s_waitcnt lgkmcnt(1)
	v_mfma_f32_32x32x16_bf16 v[66:81], v[38:41], v[106:109], v[66:81]
	s_waitcnt lgkmcnt(0)
	v_mfma_f32_32x32x16_bf16 v[66:81], v[34:37], v[110:113], v[66:81]
	v_and_b32_e32 v35, 64, v202
	v_xor_b32_e32 v34, 32, v202
	v_add_u32_e32 v35, 64, v35
	v_cmp_lt_i32_e32 vcc, v34, v35
	s_nop 1
	v_cndmask_b32_e32 v34, v202, v34, vcc
	s_nop 4
	v_max3_f32 v0, v0, v66, v67
	v_max3_f32 v0, v0, v68, v69
	v_max3_f32 v0, v0, v70, v71
	v_max3_f32 v0, v0, v72, v73
	v_max3_f32 v0, v0, v74, v75
	v_max3_f32 v0, v0, v76, v77
	v_max3_f32 v0, v0, v78, v79
	v_max3_f32 v0, v0, v80, v81
	v_lshlrev_b32_e32 v34, 2, v34
	ds_bpermute_b32 v34, v34, v0
	s_waitcnt lgkmcnt(0)
	v_max_f32_e32 v34, v34, v34
	v_max_f32_e32 v0, v0, v34
	v_mul_f32_e32 v0, 0x3fb8aa3b, v0
	v_max_f32_e32 v34, v160, v160
	v_max_f32_e32 v159, v34, v0
	v_sub_f32_e32 v0, v160, v159
	v_exp_f32_e32 v0, v0
	v_cmp_neq_f32_e32 vcc, v159, v160
	s_cbranch_vccz .LBB0_966
	v_pk_mul_f32 v[32:33], v[32:33], v[0:1] op_sel_hi:[1,0]
	v_pk_mul_f32 v[30:31], v[30:31], v[0:1] op_sel_hi:[1,0]
	v_pk_mul_f32 v[28:29], v[28:29], v[0:1] op_sel_hi:[1,0]
	v_pk_mul_f32 v[26:27], v[26:27], v[0:1] op_sel_hi:[1,0]
	v_pk_mul_f32 v[24:25], v[24:25], v[0:1] op_sel_hi:[1,0]
	v_pk_mul_f32 v[22:23], v[22:23], v[0:1] op_sel_hi:[1,0]
	v_pk_mul_f32 v[20:21], v[20:21], v[0:1] op_sel_hi:[1,0]
	v_pk_mul_f32 v[18:19], v[18:19], v[0:1] op_sel_hi:[1,0]
	v_pk_mul_f32 v[16:17], v[16:17], v[0:1] op_sel_hi:[1,0]
	v_pk_mul_f32 v[14:15], v[14:15], v[0:1] op_sel_hi:[1,0]
	v_pk_mul_f32 v[12:13], v[12:13], v[0:1] op_sel_hi:[1,0]
	v_pk_mul_f32 v[10:11], v[10:11], v[0:1] op_sel_hi:[1,0]
	v_pk_mul_f32 v[8:9], v[8:9], v[0:1] op_sel_hi:[1,0]
	v_pk_mul_f32 v[6:7], v[6:7], v[0:1] op_sel_hi:[1,0]
	v_pk_mul_f32 v[4:5], v[4:5], v[0:1] op_sel_hi:[1,0]
	v_pk_mul_f32 v[2:3], v[2:3], v[0:1] op_sel_hi:[1,0]
; DI unsigned pack2(float a, float b) { f32x2 v = {a, b}; bf16x2_t r = __builtin_convertvector(v, bf16x2_t); return __builtin_bit_cast(unsigned, r); }
; DI f32x16 mfma32(bf16x8 a, bf16x8 b, f32x16 c) { return __builtin_amdgcn_mfma_f32_32x32x16_bf16(a, b, c, 0, 0, 0); }
;     ...
;   const float mn = fmaxf(m, mx); const float alpha = __builtin_amdgcn_exp2f(m - mn);
;   const float neg = (MODE == 2 && !lanesel) ? NINF : -mn;
;   float ps = 0.f;
; #pragma unroll
;   for (int k2 = 0; k2 < 2; ++k2)
; #pragma unroll
;     for (int i = 0; i < 16; ++i) {
;       if (!(HM & (1 << k2))) continue;
;       const float pv = (MODE == 1) ? __builtin_amdgcn_exp2f(s[k2][i] + neg) : __builtin_amdgcn_exp2f(fmaf(s[k2][i], L2E, neg));
;       s[k2][i] = pv; ps += pv;
;     }
;   l = l * alpha + ps;
;   if (__builtin_amdgcn_ballot_w64(mn != m) != 0ull) {
; #pragma unroll
;     for (int dt = 0; dt < 2; ++dt)
; #pragma unroll
;       for (int i = 0; i < 16; ++i) o[dt][i] *= alpha;
;   }
;   m = mn;
; #pragma unroll
;   for (int st = 0; st < 4; ++st) {
;     if (!(HM & (1 << (st >> 1)))) continue;
;     const int k2 = st >> 1, b8 = 8 * (st & 1);
;     const u32x4 pw = {pack2(s[k2][b8], s[k2][b8 + 1]), pack2(s[k2][b8 + 2], s[k2][b8 + 3]), pack2(s[k2][b8 + 4], s[k2][b8 + 5]), pack2(s[k2][b8 + 6], s[k2][b8 + 7])};
;     const bf16x8 pb = __builtin_bit_cast(bf16x8, pw);
; #pragma unroll
;     for (int dt = 0; dt < 2; ++dt) {
;       const s16x4 lo = *(const s16x4*)(Vs + (32 * dt + r) * LSTR + 16 * st + 4 * h);
;       const s16x4 hi = *(const s16x4*)(Vs + (32 * dt + r) * LSTR + 16 * st + 8 + 4 * h);
;       const bf16x8 a = __builtin_shufflevector(lo, hi, 0, 1, 2, 3, 4, 5, 6, 7);
;       o[dt] = mfma32(a, pb, o[dt]);
;     }
;   }
.LBB0_966:
	v_fma_f32 v82, v82, s34, -v159
	v_exp_f32_e32 v82, v82
	v_fma_f32 v83, v83, s34, -v159
	v_exp_f32_e32 v83, v83
	v_fma_f32 v84, v84, s34, -v159
	v_exp_f32_e32 v84, v84
	v_fma_f32 v85, v85, s34, -v159
	v_exp_f32_e32 v85, v85
	v_fma_f32 v86, v86, s34, -v159
	v_add_f32_e32 v161, 0, v82
	v_exp_f32_e32 v86, v86
	v_fma_f32 v87, v87, s34, -v159
	v_add_f32_e32 v161, v83, v161
	v_exp_f32_e32 v87, v87
	v_fma_f32 v88, v88, s34, -v159
	v_add_f32_e32 v161, v84, v161
	v_exp_f32_e32 v88, v88
	v_fma_f32 v89, v89, s34, -v159
	v_add_f32_e32 v161, v85, v161
	v_exp_f32_e32 v89, v89
	v_fma_f32 v90, v90, s34, -v159
	v_add_f32_e32 v161, v86, v161
	v_exp_f32_e32 v90, v90
	v_fma_f32 v91, v91, s34, -v159
	v_add_f32_e32 v161, v87, v161
	v_exp_f32_e32 v91, v91
	v_fma_f32 v92, v92, s34, -v159
	v_add_f32_e32 v161, v88, v161
	v_exp_f32_e32 v92, v92
	v_fma_f32 v93, v93, s34, -v159
	v_add_f32_e32 v161, v89, v161
	v_exp_f32_e32 v93, v93
	v_fma_f32 v94, v94, s34, -v159
	v_add_f32_e32 v161, v90, v161
	v_exp_f32_e32 v94, v94
	v_fma_f32 v95, v95, s34, -v159
	v_add_f32_e32 v161, v91, v161
	v_exp_f32_e32 v95, v95
	v_fma_f32 v96, v96, s34, -v159
	v_add_f32_e32 v161, v92, v161
	v_exp_f32_e32 v96, v96
	v_fma_f32 v97, v97, s34, -v159
	v_add_f32_e32 v161, v93, v161
	v_exp_f32_e32 v97, v97
	v_fma_f32 v66, v66, s34, -v159
	v_add_f32_e32 v161, v94, v161
	v_exp_f32_e32 v163, v66
	v_fma_f32 v67, v67, s34, -v159
	v_add_f32_e32 v161, v95, v161
	v_exp_f32_e32 v164, v67
	v_fma_f32 v67, v68, s34, -v159
	v_add_f32_e32 v161, v96, v161
	v_exp_f32_e32 v165, v67
	v_fma_f32 v67, v69, s34, -v159
	v_add_f32_e32 v161, v97, v161
	v_exp_f32_e32 v180, v67
	v_fma_f32 v67, v70, s34, -v159
	v_add_f32_e32 v66, v163, v161
	v_exp_f32_e32 v181, v67
	v_fma_f32 v67, v71, s34, -v159
	v_add_f32_e32 v66, v164, v66
	v_exp_f32_e32 v182, v67
	v_fma_f32 v67, v72, s34, -v159
	v_add_f32_e32 v66, v165, v66
	v_exp_f32_e32 v183, v67
	v_fma_f32 v67, v73, s34, -v159
	v_add_f32_e32 v66, v180, v66
	v_exp_f32_e32 v184, v67
	v_fma_f32 v67, v74, s34, -v159
	v_add_f32_e32 v66, v181, v66
	v_exp_f32_e32 v185, v67
	v_fma_f32 v67, v75, s34, -v159
	v_add_f32_e32 v66, v182, v66
	v_exp_f32_e32 v186, v67
	v_fma_f32 v67, v76, s34, -v159
	v_add_f32_e32 v66, v183, v66
	v_exp_f32_e32 v187, v67
	v_fma_f32 v67, v77, s34, -v159
	v_add_f32_e32 v66, v184, v66
	v_exp_f32_e32 v188, v67
	v_fma_f32 v67, v78, s34, -v159
	v_add_f32_e32 v66, v185, v66
	v_exp_f32_e32 v78, v67
	v_fma_f32 v67, v79, s34, -v159
	v_add_f32_e32 v66, v186, v66
	v_exp_f32_e32 v79, v67
	v_fma_f32 v67, v80, s34, -v159
	v_add_f32_e32 v66, v187, v66
	v_exp_f32_e32 v80, v67
	v_fma_f32 v67, v81, s34, -v159
	v_add_f32_e32 v66, v188, v66
	v_exp_f32_e32 v81, v67
	v_add_f32_e32 v66, v78, v66
	v_add_f32_e32 v66, v79, v66
	v_add_f32_e32 v66, v80, v66
	v_add_f32_e32 v161, v81, v66
	v_fmac_f32_e32 v161, v162, v0
	v_add_u32_e32 v0, 0x6800, v198
	ds_read2_b64 v[70:73], v0 offset0:128 offset1:130
	ds_read2_b64 v[74:77], v0 offset0:132 offset1:134
	v_cvt_pk_bf16_f32 v66, v82, v83
	v_cvt_pk_bf16_f32 v67, v84, v85
	v_cvt_pk_bf16_f32 v68, v86, v87
	v_cvt_pk_bf16_f32 v69, v88, v89
	v_add_u32_e32 v82, 0x7800, v198
	s_waitcnt lgkmcnt(1)
	v_mfma_f32_32x32x16_bf16 v[34:49], v[70:73], v[66:69], v[2:17]
	ds_read2_b64 v[70:73], v82 offset0:192 offset1:194
	s_waitcnt lgkmcnt(0)
	v_mfma_f32_32x32x16_bf16 v[50:65], v[70:73], v[66:69], v[18:33]
	ds_read2_b64 v[70:73], v82 offset0:196 offset1:198
	v_cvt_pk_bf16_f32 v66, v90, v91
	v_cvt_pk_bf16_f32 v67, v92, v93
	v_cvt_pk_bf16_f32 v68, v94, v95
	v_cvt_pk_bf16_f32 v69, v96, v97
	s_waitcnt lgkmcnt(0)
	s_nop 0
	v_mfma_f32_32x32x16_bf16 v[50:65], v[70:73], v[66:69], v[50:65]
	ds_read2_b64 v[70:73], v0 offset0:136 offset1:138
	v_mfma_f32_32x32x16_bf16 v[34:49], v[74:77], v[66:69], v[34:49]
	v_cvt_pk_bf16_f32 v66, v163, v164
	v_cvt_pk_bf16_f32 v67, v165, v180
	v_cvt_pk_bf16_f32 v68, v181, v182
	v_cvt_pk_bf16_f32 v69, v183, v184
	s_waitcnt lgkmcnt(0)
	s_nop 0
	v_mfma_f32_32x32x16_bf16 v[34:49], v[70:73], v[66:69], v[34:49]
	ds_read2_b64 v[70:73], v82 offset0:200 offset1:202
	s_waitcnt lgkmcnt(0)
	v_mfma_f32_32x32x16_bf16 v[50:65], v[70:73], v[66:69], v[50:65]
	ds_read2_b64 v[70:73], v0 offset0:140 offset1:142
	v_cvt_pk_bf16_f32 v66, v185, v186
	v_cvt_pk_bf16_f32 v67, v187, v188
	v_cvt_pk_bf16_f32 v68, v78, v79
	v_cvt_pk_bf16_f32 v69, v80, v81
	s_waitcnt lgkmcnt(0)
	s_nop 0
	v_mfma_f32_32x32x16_bf16 v[2:17], v[70:73], v[66:69], v[34:49]
	ds_read2_b64 v[70:73], v82 offset0:204 offset1:206
	s_waitcnt lgkmcnt(0)
	v_mfma_f32_32x32x16_bf16 v[18:33], v[70:73], v[66:69], v[50:65]

; DI unsigned pack2(float a, float b) { f32x2 v = {a, b}; bf16x2_t r = __builtin_convertvector(v, bf16x2_t); return __builtin_bit_cast(unsigned, r); }
; DI f32x16 mfma32(bf16x8 a, bf16x8 b, f32x16 c) { return __builtin_amdgcn_mfma_f32_32x32x16_bf16(a, b, c, 0, 0, 0); }
;     ...
;   float ps = 0.f;
; #pragma unroll
;   for (int k2 = 0; k2 < 2; ++k2)
; #pragma unroll
;     for (int i = 0; i < 16; ++i) {
;       if (!(HM & (1 << k2))) continue;
;       const float pv = (MODE == 1) ? __builtin_amdgcn_exp2f(s[k2][i] + neg) : __builtin_amdgcn_exp2f(fmaf(s[k2][i], L2E, neg));
;       s[k2][i] = pv; ps += pv;
;     }
;   l = l * alpha + ps;
;   if (__builtin_amdgcn_ballot_w64(mn != m) != 0ull) {
; #pragma unroll
;     for (int dt = 0; dt < 2; ++dt)
; #pragma unroll
;       for (int i = 0; i < 16; ++i) o[dt][i] *= alpha;
;   }
;   m = mn;
; #pragma unroll
;   for (int st = 0; st < 4; ++st) {
;     if (!(HM & (1 << (st >> 1)))) continue;
;     const int k2 = st >> 1, b8 = 8 * (st & 1);
;     const u32x4 pw = {pack2(s[k2][b8], s[k2][b8 + 1]), pack2(s[k2][b8 + 2], s[k2][b8 + 3]), pack2(s[k2][b8 + 4], s[k2][b8 + 5]), pack2(s[k2][b8 + 6], s[k2][b8 + 7])};
;     const bf16x8 pb = __builtin_bit_cast(bf16x8, pw);
; #pragma unroll
;     for (int dt = 0; dt < 2; ++dt) {
;       const s16x4 lo = *(const s16x4*)(Vs + (32 * dt + r) * LSTR + 16 * st + 4 * h);
;       const s16x4 hi = *(const s16x4*)(Vs + (32 * dt + r) * LSTR + 16 * st + 8 + 4 * h);
;       const bf16x8 a = __builtin_shufflevector(lo, hi, 0, 1, 2, 3, 4, 5, 6, 7);
;       o[dt] = mfma32(a, pb, o[dt]);
;     }
;   }
.LBB0_973:
	v_fma_f32 v34, v34, s34, -v159
	v_exp_f32_e32 v46, v34
	v_fma_f32 v34, v35, s34, -v159
	v_exp_f32_e32 v47, v34
	v_fma_f32 v34, v36, s34, -v159
	v_exp_f32_e32 v48, v34
	v_fma_f32 v34, v37, s34, -v159
	v_add_f32_e32 v35, 0, v46
	v_exp_f32_e32 v49, v34
	v_fma_f32 v34, v38, s34, -v159
	v_add_f32_e32 v35, v47, v35
	v_exp_f32_e32 v38, v34
	v_fma_f32 v34, v39, s34, -v159
	v_exp_f32_e32 v39, v34
	v_add_f32_e32 v34, v48, v35
	v_fma_f32 v35, v50, s34, -v159
	v_exp_f32_e32 v50, v35
	v_fma_f32 v35, v51, s34, -v159
	v_add_f32_e32 v34, v49, v34
	v_exp_f32_e32 v51, v35
	v_fma_f32 v35, v52, s34, -v159
	v_add_f32_e32 v34, v38, v34
	v_exp_f32_e32 v52, v35
	v_fma_f32 v35, v53, s34, -v159
	v_add_f32_e32 v34, v39, v34
	v_exp_f32_e32 v53, v35
	v_add_f32_e32 v34, v50, v34
	v_add_f32_e32 v34, v51, v34
	v_add_f32_e32 v34, v52, v34
	v_add_f32_e32 v54, v53, v34
	v_fma_f32 v34, v44, s34, -v159
	v_fma_f32 v44, v45, s34, -v159
	v_add_u32_e32 v56, 0x6800, v198
	v_exp_f32_e32 v55, v34
	ds_read2_b64 v[34:37], v56 offset0:128 offset1:130
	v_exp_f32_e32 v57, v44
	v_cvt_pk_bf16_f32 v44, v46, v47
	v_cvt_pk_bf16_f32 v46, v38, v39
	v_add_u32_e32 v38, v199, v200
	v_add_u32_e32 v38, 0x7800, v38
	v_cvt_pk_bf16_f32 v45, v48, v49
	v_cvt_pk_bf16_f32 v47, v50, v51
	ds_read2_b64 v[48:51], v38 offset0:192 offset1:194
	v_fma_f32 v39, v40, s34, -v159
	s_waitcnt lgkmcnt(1)
	v_mfma_f32_32x32x16_bf16 v[2:17], v[34:37], v[44:47], v[2:17]
	v_fma_f32 v34, v41, s34, -v159
	v_exp_f32_e32 v58, v34
	v_fma_f32 v34, v42, s34, -v159
	v_exp_f32_e32 v59, v34
	v_fma_f32 v34, v43, s34, -v159
	v_exp_f32_e32 v60, v34
	ds_read2_b64 v[34:37], v56 offset0:132 offset1:134
	s_waitcnt lgkmcnt(1)
	v_mfma_f32_32x32x16_bf16 v[18:33], v[48:51], v[44:47], v[18:33]
	v_exp_f32_e32 v46, v39
	ds_read2_b64 v[38:41], v38 offset0:196 offset1:198
	v_cvt_pk_bf16_f32 v42, v52, v53
	v_cvt_pk_bf16_f32 v43, v55, v57
	v_cvt_pk_bf16_f32 v44, v58, v59
	v_cvt_pk_bf16_f32 v45, v60, v46
	s_waitcnt lgkmcnt(0)
	s_nop 0
	v_mfma_f32_32x32x16_bf16 v[18:33], v[38:41], v[42:45], v[18:33]
	v_mfma_f32_32x32x16_bf16 v[2:17], v[34:37], v[42:45], v[2:17]
	v_add_f32_e32 v34, v55, v54
	v_add_f32_e32 v34, v57, v34
	v_add_f32_e32 v34, v58, v34
	v_add_f32_e32 v34, v59, v34
	v_add_f32_e32 v34, v60, v34
	v_add_f32_e32 v161, v46, v34
	s_nop 4
	v_fmac_f32_e32 v161, v162, v0

; DI f32x16 mfma32(bf16x8 a, bf16x8 b, f32x16 c) { return __builtin_amdgcn_mfma_f32_32x32x16_bf16(a, b, c, 0, 0, 0); }
; DI int crow(int i, int h) { return (i & 3) + 8 * (i >> 2) + 4 * h; }
;     ...
; #pragma unroll
;   for (int k2 = 0; k2 < 2; ++k2) {
;     if (!(HM & (1 << k2))) continue;
; #pragma unroll
;     for (int i = 0; i < 16; ++i) s[k2][i] = 0.f;
; #pragma unroll
;     for (int ks = 0; ks < 4; ++ks) {
;       const bf16x8 a = *(const bf16x8*)(Ks + (32 * k2 + r) * LSTR + 16 * ks + 8 * h);
;       s[k2] = mfma32(a, qf[ks], s[k2]);
;     }
;   }
;   if (MODE == 1) {
; #pragma unroll
;     for (int k2 = 0; k2 < 2; ++k2)
; #pragma unroll
;       for (int g = 0; g < 4; ++g) {
;         if (!(HM & (1 << k2))) continue;
;         const f32x4 cv = *(const f32x4*)(cn_lds + key0 + 32 * k2 + 8 * g + 4 * h);
; #pragma unroll
;         for (int e = 0; e < 4; ++e) s[k2][4 * g + e] = fmaf(s[k2][4 * g + e], L2E, cv[e]);
;       }
;   }
;   float mx = NINF;
; #pragma unroll
;   for (int k2 = 0; k2 < 2; ++k2)
; #pragma unroll
;     for (int i = 0; i < 16; ++i) {
;       if (!(HM & (1 << k2))) continue;
;       float v = s[k2][i];
;       if (MASKED) {
;         const int tk = key0 + 32 * k2 + crow(i, h);
;         const bool valid = (MODE == 0) ? ((tk <= tq) && (tq - tk <= maxdist)) : (tk <= tq);
;         v = valid ? v : NINF; s[k2][i] = v;
;       }
;       mx = fmaxf(mx, v);
;     }
;   mx = fmaxf(mx, __shfl_xor(mx, 32));
;   if (MODE != 1) mx *= L2E;
;   if (MODE == 2) mx = lanesel ? mx : NINF;
;   const float mn = fmaxf(m, mx); const float alpha = __builtin_amdgcn_exp2f(m - mn);
;   const float neg = (MODE == 2 && !lanesel) ? NINF : -mn;
;   float ps = 0.f;
; #pragma unroll
;   for (int k2 = 0; k2 < 2; ++k2)
; #pragma unroll
;     for (int i = 0; i < 16; ++i) {
;       if (!(HM & (1 << k2))) continue;
;       const float pv = (MODE == 1) ? __builtin_amdgcn_exp2f(s[k2][i] + neg) : __builtin_amdgcn_exp2f(fmaf(s[k2][i], L2E, neg));
;       s[k2][i] = pv; ps += pv;
;     }
;   l = l * alpha + ps;
;   if (__builtin_amdgcn_ballot_w64(mn != m) != 0ull) {
; #pragma unroll
;     for (int dt = 0; dt < 2; ++dt)
; #pragma unroll
;       for (int i = 0; i < 16; ++i) o[dt][i] *= alpha;
;   }
.LBB0_990:
	s_lshr_b64 s[6:7], s[4:5], s33
	s_and_b32 s58, s6, 1
	s_cmp_eq_u64 s[58:59], 0
	s_cbranch_scc1 .LBB0_1014
	s_lshl_b32 s58, s33, 6
	s_or_b32 s33, s58, 63
	s_cmp_le_u32 s58, s3
	s_cselect_b64 s[6:7], -1, 0
	s_or_b32 s36, s58, 31
	s_cmp_ge_i32 s36, s29
	s_cselect_b64 s[36:37], -1, 0
	s_and_b64 s[6:7], s[6:7], s[36:37]
	v_cndmask_b32_e64 v0, 0, 1, s[6:7]
	s_or_b32 s6, s58, 32
	s_cmp_gt_u32 s6, s3
	s_cselect_b64 s[6:7], -1, 0
	s_cmp_lt_i32 s33, s29
	s_cselect_b64 s[36:37], -1, 0
	v_readfirstlane_b32 s38, v0
	s_or_b32 s39, s38, 2
	s_or_b64 s[6:7], s[6:7], s[36:37]
	s_and_b64 s[6:7], s[6:7], exec
	s_cselect_b32 s65, s38, s39
	s_mov_b64 s[62:63], -1
	s_mov_b64 s[54:55], 0
	s_cmp_lt_i32 s65, 2
	s_mov_b64 s[6:7], 0
	s_cbranch_scc1 .LBB0_1007
	s_cmp_eq_u32 s65, 2
	s_mov_b64 s[6:7], -1
	s_cbranch_scc0 .LBB0_996
	ds_read_b128 v[34:37], v199 offset:4608
	ds_read_b128 v[50:53], v199 offset:4640
	v_or_b32_e32 v0, s58, v197
	s_waitcnt lgkmcnt(1)
	v_mfma_f32_32x32x16_bf16 v[34:49], v[34:37], v[98:101], 0
	s_waitcnt lgkmcnt(0)
	v_mfma_f32_32x32x16_bf16 v[34:49], v[50:53], v[102:105], v[34:49]
	ds_read_b128 v[50:53], v199 offset:4672
	s_waitcnt lgkmcnt(0)
	v_mfma_f32_32x32x16_bf16 v[34:49], v[50:53], v[106:109], v[34:49]
	ds_read_b128 v[50:53], v199 offset:4704
	s_waitcnt lgkmcnt(0)
	v_mfma_f32_32x32x16_bf16 v[34:49], v[50:53], v[110:113], v[34:49]
	v_or_b32_e32 v50, 32, v0
	v_cmp_gt_u32_e32 vcc, v50, v154
	v_cmp_lt_i32_e64 s[6:7], v50, v155
	s_or_b64 vcc, vcc, s[6:7]
	s_nop 7
	v_cndmask_b32_e32 v66, v34, v204, vcc
	v_bitop3_b32 v34, s58, v205, v197 bitop3:0x36
	v_cmp_ge_u32_e32 vcc, v50, v154
	v_cmp_gt_i32_e64 s[6:7], v34, v156
	s_or_b64 vcc, vcc, s[6:7]
	v_cndmask_b32_e32 v67, v35, v204, vcc
	v_or_b32_e32 v35, 34, v0
	v_cmp_gt_u32_e32 vcc, v35, v154
	v_cmp_lt_i32_e64 s[6:7], v35, v155
	s_or_b64 vcc, vcc, s[6:7]
	v_or_b32_e32 v35, 35, v0
	v_cndmask_b32_e32 v68, v36, v204, vcc
	v_cmp_gt_u32_e32 vcc, v35, v154
	v_cmp_lt_i32_e64 s[6:7], v35, v155
	s_or_b64 vcc, vcc, s[6:7]
	v_or_b32_e32 v35, 40, v0
	v_cndmask_b32_e32 v69, v37, v204, vcc
	v_cmp_gt_u32_e32 vcc, v35, v154
	v_cmp_lt_i32_e64 s[6:7], v35, v155
	s_or_b64 vcc, vcc, s[6:7]
	v_or_b32_e32 v35, 41, v0
	v_cndmask_b32_e32 v70, v38, v204, vcc
	v_cmp_gt_u32_e32 vcc, v35, v154
	v_cmp_lt_i32_e64 s[6:7], v35, v155
	s_or_b64 vcc, vcc, s[6:7]
	v_or_b32_e32 v35, 42, v0
	v_cndmask_b32_e32 v71, v39, v204, vcc
	v_cmp_gt_u32_e32 vcc, v35, v154
	v_cmp_lt_i32_e64 s[6:7], v35, v155
	s_or_b64 vcc, vcc, s[6:7]
	v_or_b32_e32 v35, 43, v0
	v_cndmask_b32_e32 v77, v40, v204, vcc
	v_cmp_gt_u32_e32 vcc, v35, v154
	v_cmp_lt_i32_e64 s[6:7], v35, v155
	s_or_b64 vcc, vcc, s[6:7]
	v_or_b32_e32 v35, 48, v0
	v_cndmask_b32_e32 v78, v41, v204, vcc
	v_cmp_gt_u32_e32 vcc, v35, v154
	v_cmp_lt_i32_e64 s[6:7], v35, v155
	s_or_b64 vcc, vcc, s[6:7]
	v_or_b32_e32 v35, 49, v0
	v_cndmask_b32_e32 v79, v42, v204, vcc
	v_cmp_gt_u32_e32 vcc, v35, v154
	v_cmp_lt_i32_e64 s[6:7], v35, v155
	s_or_b64 vcc, vcc, s[6:7]
	v_or_b32_e32 v35, 50, v0
	v_cndmask_b32_e32 v80, v43, v204, vcc
	v_cmp_gt_u32_e32 vcc, v35, v154
	v_cmp_lt_i32_e64 s[6:7], v35, v155
	s_or_b64 vcc, vcc, s[6:7]
	v_or_b32_e32 v35, 51, v0
	v_cndmask_b32_e32 v81, v44, v204, vcc
	v_cmp_gt_u32_e32 vcc, v35, v154
	v_cmp_lt_i32_e64 s[6:7], v35, v155
	s_or_b64 vcc, vcc, s[6:7]
	v_or_b32_e32 v35, 56, v0
	v_cndmask_b32_e32 v76, v45, v204, vcc
	v_cmp_gt_u32_e32 vcc, v35, v154
	v_cmp_lt_i32_e64 s[6:7], v35, v155
	s_or_b64 vcc, vcc, s[6:7]
	v_or_b32_e32 v35, 57, v0
	v_max3_f32 v34, v66, s35, v67
	v_cndmask_b32_e32 v73, v46, v204, vcc
	v_cmp_gt_u32_e32 vcc, v35, v154
	v_cmp_lt_i32_e64 s[6:7], v35, v155
	v_max3_f32 v34, v34, v68, v69
	s_or_b64 vcc, vcc, s[6:7]
	v_or_b32_e32 v35, 58, v0
	v_max3_f32 v34, v34, v70, v71
	v_cndmask_b32_e32 v74, v47, v204, vcc
	v_cmp_gt_u32_e32 vcc, v35, v154
	v_cmp_lt_i32_e64 s[6:7], v35, v155
	v_max3_f32 v34, v34, v77, v78
	s_or_b64 vcc, vcc, s[6:7]
	v_or_b32_e32 v0, 59, v0
	v_max3_f32 v34, v34, v79, v80
	v_cndmask_b32_e32 v75, v48, v204, vcc
	v_cmp_gt_u32_e32 vcc, v0, v154
	v_cmp_lt_i32_e64 s[6:7], v0, v155
	v_max3_f32 v34, v34, v81, v76
	s_or_b64 vcc, vcc, s[6:7]
	v_max3_f32 v34, v34, v73, v74
	v_cndmask_b32_e32 v72, v49, v204, vcc
	v_and_b32_e32 v35, 64, v202
	v_max3_f32 v0, v34, v75, v72
	v_xor_b32_e32 v34, 32, v202
	v_add_u32_e32 v35, 64, v35
	v_cmp_lt_i32_e32 vcc, v34, v35
	s_nop 1
	v_cndmask_b32_e32 v34, v202, v34, vcc
	v_lshlrev_b32_e32 v34, 2, v34
	ds_bpermute_b32 v34, v34, v0
	s_waitcnt lgkmcnt(0)
	v_max_f32_e32 v34, v34, v34
	v_max_f32_e32 v0, v0, v34
	v_mul_f32_e32 v0, 0x3fb8aa3b, v0
	v_max_f32_e32 v34, v157, v157
	v_max_f32_e32 v158, v34, v0
	v_sub_f32_e32 v0, v157, v158
	v_exp_f32_e32 v0, v0
	v_cmp_neq_f32_e32 vcc, v158, v157
	s_cbranch_vccz .LBB0_995
	v_pk_mul_f32 v[32:33], v[32:33], v[0:1] op_sel_hi:[1,0]
	v_pk_mul_f32 v[30:31], v[30:31], v[0:1] op_sel_hi:[1,0]
	v_pk_mul_f32 v[28:29], v[28:29], v[0:1] op_sel_hi:[1,0]
	v_pk_mul_f32 v[26:27], v[26:27], v[0:1] op_sel_hi:[1,0]
	v_pk_mul_f32 v[24:25], v[24:25], v[0:1] op_sel_hi:[1,0]
	v_pk_mul_f32 v[22:23], v[22:23], v[0:1] op_sel_hi:[1,0]
	v_pk_mul_f32 v[20:21], v[20:21], v[0:1] op_sel_hi:[1,0]
	v_pk_mul_f32 v[18:19], v[18:19], v[0:1] op_sel_hi:[1,0]
	v_pk_mul_f32 v[16:17], v[16:17], v[0:1] op_sel_hi:[1,0]
	v_pk_mul_f32 v[14:15], v[14:15], v[0:1] op_sel_hi:[1,0]
	v_pk_mul_f32 v[12:13], v[12:13], v[0:1] op_sel_hi:[1,0]
	v_pk_mul_f32 v[10:11], v[10:11], v[0:1] op_sel_hi:[1,0]
	v_pk_mul_f32 v[8:9], v[8:9], v[0:1] op_sel_hi:[1,0]
	v_pk_mul_f32 v[6:7], v[6:7], v[0:1] op_sel_hi:[1,0]
	v_pk_mul_f32 v[4:5], v[4:5], v[0:1] op_sel_hi:[1,0]
	v_pk_mul_f32 v[2:3], v[2:3], v[0:1] op_sel_hi:[1,0]

; DI f32x16 mfma32(bf16x8 a, bf16x8 b, f32x16 c) { return __builtin_amdgcn_mfma_f32_32x32x16_bf16(a, b, c, 0, 0, 0); }
;     ...
; #pragma unroll
;   for (int k2 = 0; k2 < 2; ++k2) {
;     if (!(HM & (1 << k2))) continue;
; #pragma unroll
;     for (int i = 0; i < 16; ++i) s[k2][i] = 0.f;
; #pragma unroll
;     for (int ks = 0; ks < 4; ++ks) {
;       const bf16x8 a = *(const bf16x8*)(Ks + (32 * k2 + r) * LSTR + 16 * ks + 8 * h);
;       s[k2] = mfma32(a, qf[ks], s[k2]);
;     }
;   }
;   if (MODE == 1) {
; #pragma unroll
;     for (int k2 = 0; k2 < 2; ++k2)
; #pragma unroll
;       for (int g = 0; g < 4; ++g) {
;         if (!(HM & (1 << k2))) continue;
;         const f32x4 cv = *(const f32x4*)(cn_lds + key0 + 32 * k2 + 8 * g + 4 * h);
; #pragma unroll
;         for (int e = 0; e < 4; ++e) s[k2][4 * g + e] = fmaf(s[k2][4 * g + e], L2E, cv[e]);
;       }
;   }
;   float mx = NINF;
; #pragma unroll
;   for (int k2 = 0; k2 < 2; ++k2)
; #pragma unroll
;     for (int i = 0; i < 16; ++i) {
;       if (!(HM & (1 << k2))) continue;
;       float v = s[k2][i];
;       if (MASKED) {
;         const int tk = key0 + 32 * k2 + crow(i, h);
;         const bool valid = (MODE == 0) ? ((tk <= tq) && (tq - tk <= maxdist)) : (tk <= tq);
;         v = valid ? v : NINF; s[k2][i] = v;
;       }
;       mx = fmaxf(mx, v);
; template <int MODE>
; DI void flash_loop(char* smem, const bf16_t* Kbase, size_t ldk, const bf16_t* Vtbase, size_t ldv, ull tiles, ull wtiles,
;                    const bf16x8 (&qf)[4], f32x16 (&o)[2], float& m, float& l, int tq, int tqmin, int tqmax, int maxdist, const float* cn_lds, ull lmask) {
;     ...
;     const bool interior = (64 * kt + 63 <= tqmin) && (MODE != 0 || (tqmax - 64 * kt <= maxdist));
;     int hm = 3;
;     if (MODE == 0) {
;       hm = 0;
;       if (64 * kt <= tqmax && 64 * kt + 31 >= tqmin - maxdist) hm |= 1;
;       if (64 * kt + 32 <= tqmax && 64 * kt + 63 >= tqmin - maxdist) hm |= 2;
;     }
;     if (MODE == 0 && hm == 1) attn_tile<MODE, true, 1>(Ks, Vs, qf, o, m, l, 64 * kt, tq, maxdist, cn_lds, sel);
;     else if (MODE == 0 && hm == 2) attn_tile<MODE, true, 2>(Ks, Vs, qf, o, m, l, 64 * kt, tq, maxdist, cn_lds, sel);
;     else if (interior) attn_tile<MODE, false>(Ks, Vs, qf, o, m, l, 64 * kt, tq, maxdist, cn_lds, sel);
;     else attn_tile<MODE, true>(Ks, Vs, qf, o, m, l, 64 * kt, tq, maxdist, cn_lds, sel);
.LBB0_998:
	ds_read_b128 v[82:85], v196
	ds_read_b128 v[78:81], v196 offset:32
	ds_read_b128 v[74:77], v196 offset:64
	ds_read_b128 v[66:69], v196 offset:96
	ds_read_b128 v[70:73], v196 offset:4608
	s_cmp_le_u32 s33, s28
	s_cselect_b64 s[6:7], -1, 0
	s_cmp_ge_i32 s58, s30
	s_cselect_b64 s[36:37], -1, 0
	s_and_b64 s[6:7], s[6:7], s[36:37]
	s_andn2_b64 vcc, exec, s[6:7]
	s_mov_b64 s[6:7], -1
	s_cbranch_vccz .LBB0_1002
	s_waitcnt lgkmcnt(4)
	v_mfma_f32_32x32x16_bf16 v[50:65], v[82:85], v[98:101], 0
	ds_read_b128 v[86:89], v196 offset:4640
	ds_read_b128 v[90:93], v196 offset:4672
	v_or_b32_e32 v0, s58, v197
	v_cmp_gt_u32_e32 vcc, v0, v154
	v_cmp_lt_i32_e64 s[6:7], v0, v155
	s_or_b64 vcc, vcc, s[6:7]
	s_waitcnt lgkmcnt(5)
	v_mfma_f32_32x32x16_bf16 v[50:65], v[78:81], v[102:105], v[50:65]
	s_waitcnt lgkmcnt(2)
	v_mfma_f32_32x32x16_bf16 v[34:49], v[70:73], v[98:101], 0
	v_mfma_f32_32x32x16_bf16 v[50:65], v[74:77], v[106:109], v[50:65]
	s_waitcnt lgkmcnt(1)
	v_mfma_f32_32x32x16_bf16 v[34:49], v[86:89], v[102:105], v[34:49]
	ds_read_b128 v[86:89], v196 offset:4704
	v_mfma_f32_32x32x16_bf16 v[50:65], v[66:69], v[110:113], v[50:65]
	s_waitcnt lgkmcnt(1)
	v_mfma_f32_32x32x16_bf16 v[34:49], v[90:93], v[106:109], v[34:49]
	s_waitcnt lgkmcnt(0)
	v_mfma_f32_32x32x16_bf16 v[34:49], v[86:89], v[110:113], v[34:49]
	s_nop 7
	v_cndmask_b32_e32 v86, v50, v204, vcc
	v_bitop3_b32 v50, s58, v197, s58 bitop3:3
	v_cmp_ge_u32_e32 vcc, v0, v154
	v_cmp_lt_i32_e64 s[6:7], v156, v50
	s_or_b64 vcc, vcc, s[6:7]
	v_cndmask_b32_e32 v87, v51, v204, vcc
	v_or_b32_e32 v51, 2, v0
	v_cmp_gt_u32_e32 vcc, v51, v154
	v_cmp_lt_i32_e64 s[6:7], v51, v155
	s_or_b64 vcc, vcc, s[6:7]
	v_or_b32_e32 v51, 3, v0
	v_cndmask_b32_e32 v88, v52, v204, vcc
	v_cmp_gt_u32_e32 vcc, v51, v154
	v_cmp_lt_i32_e64 s[6:7], v51, v155
	s_or_b64 vcc, vcc, s[6:7]
	v_or_b32_e32 v51, 8, v0
	v_cndmask_b32_e32 v89, v53, v204, vcc
	v_cmp_gt_u32_e32 vcc, v51, v154
	v_cmp_lt_i32_e64 s[6:7], v51, v155
	s_or_b64 vcc, vcc, s[6:7]
	v_or_b32_e32 v51, 9, v0
	v_cndmask_b32_e32 v90, v54, v204, vcc
	v_cmp_gt_u32_e32 vcc, v51, v154
	v_cmp_lt_i32_e64 s[6:7], v51, v155
	s_or_b64 vcc, vcc, s[6:7]
	v_or_b32_e32 v51, 10, v0
	v_cndmask_b32_e32 v192, v55, v204, vcc
	v_cmp_gt_u32_e32 vcc, v51, v154
	v_cmp_lt_i32_e64 s[6:7], v51, v155
	s_or_b64 vcc, vcc, s[6:7]
	v_or_b32_e32 v51, 11, v0
	v_cndmask_b32_e32 v191, v56, v204, vcc
	v_cmp_gt_u32_e32 vcc, v51, v154
	v_cmp_lt_i32_e64 s[6:7], v51, v155
	s_or_b64 vcc, vcc, s[6:7]
	v_or_b32_e32 v51, 16, v0
	v_cndmask_b32_e32 v193, v57, v204, vcc
	v_cmp_gt_u32_e32 vcc, v51, v154
	v_cmp_lt_i32_e64 s[6:7], v51, v155
	s_or_b64 vcc, vcc, s[6:7]
	v_or_b32_e32 v51, 17, v0
	v_cndmask_b32_e32 v188, v58, v204, vcc
	v_cmp_gt_u32_e32 vcc, v51, v154
	v_cmp_lt_i32_e64 s[6:7], v51, v155
	s_or_b64 vcc, vcc, s[6:7]
	v_or_b32_e32 v51, 18, v0
	v_cndmask_b32_e32 v190, v59, v204, vcc
	v_cmp_gt_u32_e32 vcc, v51, v154
	v_cmp_lt_i32_e64 s[6:7], v51, v155
	s_or_b64 vcc, vcc, s[6:7]
	v_or_b32_e32 v51, 19, v0
	v_cndmask_b32_e32 v189, v60, v204, vcc
	v_cmp_gt_u32_e32 vcc, v51, v154
	v_cmp_lt_i32_e64 s[6:7], v51, v155
	s_or_b64 vcc, vcc, s[6:7]
	v_or_b32_e32 v51, 24, v0
	v_cndmask_b32_e32 v187, v61, v204, vcc
	v_cmp_gt_u32_e32 vcc, v51, v154
	v_cmp_lt_i32_e64 s[6:7], v51, v155
	s_or_b64 vcc, vcc, s[6:7]
	v_or_b32_e32 v51, 25, v0
	v_cndmask_b32_e32 v186, v62, v204, vcc
	v_cmp_gt_u32_e32 vcc, v51, v154
	v_cmp_lt_i32_e64 s[6:7], v51, v155
	s_or_b64 vcc, vcc, s[6:7]
	v_or_b32_e32 v51, 26, v0
	v_cndmask_b32_e32 v185, v63, v204, vcc
	v_cmp_gt_u32_e32 vcc, v51, v154
	v_cmp_lt_i32_e64 s[6:7], v51, v155
	s_or_b64 vcc, vcc, s[6:7]
	v_or_b32_e32 v51, 27, v0
	v_cndmask_b32_e32 v184, v64, v204, vcc
	v_cmp_gt_u32_e32 vcc, v51, v154
	v_cmp_lt_i32_e64 s[6:7], v51, v155
	s_or_b64 vcc, vcc, s[6:7]
	v_or_b32_e32 v51, 32, v0
	v_cndmask_b32_e32 v182, v65, v204, vcc
	v_cmp_gt_u32_e32 vcc, v51, v154
	v_cmp_lt_i32_e64 s[6:7], v51, v155
	s_or_b64 vcc, vcc, s[6:7]
	v_cndmask_b32_e32 v164, v34, v204, vcc
	v_or_b32_e32 v34, 33, v0
	v_cmp_gt_u32_e32 vcc, v34, v154
	v_cmp_lt_i32_e64 s[6:7], v34, v155
	s_or_b64 vcc, vcc, s[6:7]
	v_cndmask_b32_e32 v162, v35, v204, vcc
	v_or_b32_e32 v35, 34, v0
; DI int crow(int i, int h) { return (i & 3) + 8 * (i >> 2) + 4 * h; }
;     ...
;   float mx = NINF;
; #pragma unroll
;   for (int k2 = 0; k2 < 2; ++k2)
; #pragma unroll
;     for (int i = 0; i < 16; ++i) {
;       if (!(HM & (1 << k2))) continue;
;       float v = s[k2][i];
;       if (MASKED) {
;         const int tk = key0 + 32 * k2 + crow(i, h);
;         const bool valid = (MODE == 0) ? ((tk <= tq) && (tq - tk <= maxdist)) : (tk <= tq);
;         v = valid ? v : NINF; s[k2][i] = v;
;       }
;       mx = fmaxf(mx, v);
;     }
;   mx = fmaxf(mx, __shfl_xor(mx, 32));
;   if (MODE != 1) mx *= L2E;
;   if (MODE == 2) mx = lanesel ? mx : NINF;
;   const float mn = fmaxf(m, mx); const float alpha = __builtin_amdgcn_exp2f(m - mn);
;   const float neg = (MODE == 2 && !lanesel) ? NINF : -mn;
;   float ps = 0.f;
; #pragma unroll
;   for (int k2 = 0; k2 < 2; ++k2)
; #pragma unroll
;     for (int i = 0; i < 16; ++i) {
;       if (!(HM & (1 << k2))) continue;
;       const float pv = (MODE == 1) ? __builtin_amdgcn_exp2f(s[k2][i] + neg) : __builtin_amdgcn_exp2f(fmaf(s[k2][i], L2E, neg));
;       s[k2][i] = pv; ps += pv;
;     }
;   l = l * alpha + ps;
;   if (__builtin_amdgcn_ballot_w64(mn != m) != 0ull) {
; #pragma unroll
;     for (int dt = 0; dt < 2; ++dt)
; #pragma unroll
;       for (int i = 0; i < 16; ++i) o[dt][i] *= alpha;
;   }
	v_cmp_gt_u32_e32 vcc, v35, v154
	v_cmp_lt_i32_e64 s[6:7], v35, v155
	s_or_b64 vcc, vcc, s[6:7]
	v_or_b32_e32 v35, 35, v0
	v_cndmask_b32_e32 v160, v36, v204, vcc
	v_cmp_gt_u32_e32 vcc, v35, v154
	v_cmp_lt_i32_e64 s[6:7], v35, v155
	s_or_b64 vcc, vcc, s[6:7]
	v_or_b32_e32 v35, 40, v0
	v_cndmask_b32_e32 v97, v37, v204, vcc
	v_cmp_gt_u32_e32 vcc, v35, v154
	v_cmp_lt_i32_e64 s[6:7], v35, v155
	s_or_b64 vcc, vcc, s[6:7]
	v_or_b32_e32 v35, 41, v0
	v_cndmask_b32_e32 v92, v38, v204, vcc
	v_cmp_gt_u32_e32 vcc, v35, v154
	v_cmp_lt_i32_e64 s[6:7], v35, v155
	s_or_b64 vcc, vcc, s[6:7]
	v_or_b32_e32 v35, 42, v0
	v_cndmask_b32_e32 v91, v39, v204, vcc
	v_cmp_gt_u32_e32 vcc, v35, v154
	v_cmp_lt_i32_e64 s[6:7], v35, v155
	s_or_b64 vcc, vcc, s[6:7]
	v_or_b32_e32 v35, 43, v0
	v_cndmask_b32_e32 v93, v40, v204, vcc
	v_cmp_gt_u32_e32 vcc, v35, v154
	v_cmp_lt_i32_e64 s[6:7], v35, v155
	s_or_b64 vcc, vcc, s[6:7]
	v_or_b32_e32 v35, 48, v0
	v_cndmask_b32_e32 v94, v41, v204, vcc
	v_cmp_gt_u32_e32 vcc, v35, v154
	v_cmp_lt_i32_e64 s[6:7], v35, v155
	s_or_b64 vcc, vcc, s[6:7]
	v_or_b32_e32 v35, 49, v0
	v_max3_f32 v50, v86, s35, v87
	v_cndmask_b32_e32 v95, v42, v204, vcc
	v_cmp_gt_u32_e32 vcc, v35, v154
	v_cmp_lt_i32_e64 s[6:7], v35, v155
	v_max3_f32 v50, v50, v88, v89
	s_or_b64 vcc, vcc, s[6:7]
	v_or_b32_e32 v35, 50, v0
	v_max3_f32 v50, v50, v90, v192
	v_cndmask_b32_e32 v96, v43, v204, vcc
	v_cmp_gt_u32_e32 vcc, v35, v154
	v_cmp_lt_i32_e64 s[6:7], v35, v155
	v_max3_f32 v50, v50, v191, v193
	s_or_b64 vcc, vcc, s[6:7]
	v_or_b32_e32 v35, 51, v0
	v_max3_f32 v50, v50, v188, v190
	v_cndmask_b32_e32 v161, v44, v204, vcc
	v_cmp_gt_u32_e32 vcc, v35, v154
	v_cmp_lt_i32_e64 s[6:7], v35, v155
	v_max3_f32 v50, v50, v189, v187
	s_or_b64 vcc, vcc, s[6:7]
	v_or_b32_e32 v35, 56, v0
	v_max3_f32 v50, v50, v186, v185
	v_cndmask_b32_e32 v163, v45, v204, vcc
	v_cmp_gt_u32_e32 vcc, v35, v154
	v_cmp_lt_i32_e64 s[6:7], v35, v155
	v_max3_f32 v50, v50, v184, v182
	s_or_b64 vcc, vcc, s[6:7]
	v_or_b32_e32 v35, 57, v0
	v_max3_f32 v34, v50, v164, v162
	v_cndmask_b32_e32 v165, v46, v204, vcc
	v_cmp_gt_u32_e32 vcc, v35, v154
	v_cmp_lt_i32_e64 s[6:7], v35, v155
	v_max3_f32 v34, v34, v160, v97
	s_or_b64 vcc, vcc, s[6:7]
	v_or_b32_e32 v35, 58, v0
	v_max3_f32 v34, v34, v92, v91
	v_cndmask_b32_e32 v180, v47, v204, vcc
	v_cmp_gt_u32_e32 vcc, v35, v154
	v_cmp_lt_i32_e64 s[6:7], v35, v155
	v_max3_f32 v34, v34, v93, v94
	s_or_b64 vcc, vcc, s[6:7]
	v_or_b32_e32 v0, 59, v0
	v_max3_f32 v34, v34, v95, v96
	v_cndmask_b32_e32 v181, v48, v204, vcc
	v_cmp_gt_u32_e32 vcc, v0, v154
	v_cmp_lt_i32_e64 s[6:7], v0, v155
	v_max3_f32 v34, v34, v161, v163
	s_or_b64 vcc, vcc, s[6:7]
	v_max3_f32 v34, v34, v165, v180
	v_cndmask_b32_e32 v183, v49, v204, vcc
	v_and_b32_e32 v35, 64, v202
	v_max3_f32 v0, v34, v181, v183
	v_xor_b32_e32 v34, 32, v202
	v_add_u32_e32 v35, 64, v35
	v_cmp_lt_i32_e32 vcc, v34, v35
	s_nop 1
	v_cndmask_b32_e32 v34, v202, v34, vcc
	v_lshlrev_b32_e32 v34, 2, v34
	ds_bpermute_b32 v34, v34, v0
	s_waitcnt lgkmcnt(0)
	v_max_f32_e32 v34, v34, v34
	v_max_f32_e32 v0, v0, v34
	v_mul_f32_e32 v0, 0x3fb8aa3b, v0
	v_max_f32_e32 v34, v157, v157
	v_max_f32_e32 v158, v34, v0
	v_sub_f32_e32 v0, v157, v158
	v_exp_f32_e32 v0, v0
	v_cmp_neq_f32_e32 vcc, v158, v157
	s_cbranch_vccz .LBB0_1001
	v_pk_mul_f32 v[32:33], v[32:33], v[0:1] op_sel_hi:[1,0]
	v_pk_mul_f32 v[30:31], v[30:31], v[0:1] op_sel_hi:[1,0]
	v_pk_mul_f32 v[28:29], v[28:29], v[0:1] op_sel_hi:[1,0]
	v_pk_mul_f32 v[26:27], v[26:27], v[0:1] op_sel_hi:[1,0]
	v_pk_mul_f32 v[24:25], v[24:25], v[0:1] op_sel_hi:[1,0]
	v_pk_mul_f32 v[22:23], v[22:23], v[0:1] op_sel_hi:[1,0]
	v_pk_mul_f32 v[20:21], v[20:21], v[0:1] op_sel_hi:[1,0]
	v_pk_mul_f32 v[18:19], v[18:19], v[0:1] op_sel_hi:[1,0]
	v_pk_mul_f32 v[16:17], v[16:17], v[0:1] op_sel_hi:[1,0]
	v_pk_mul_f32 v[14:15], v[14:15], v[0:1] op_sel_hi:[1,0]
	v_pk_mul_f32 v[12:13], v[12:13], v[0:1] op_sel_hi:[1,0]
	v_pk_mul_f32 v[10:11], v[10:11], v[0:1] op_sel_hi:[1,0]
	v_pk_mul_f32 v[8:9], v[8:9], v[0:1] op_sel_hi:[1,0]
	v_pk_mul_f32 v[6:7], v[6:7], v[0:1] op_sel_hi:[1,0]
	v_pk_mul_f32 v[4:5], v[4:5], v[0:1] op_sel_hi:[1,0]
	v_pk_mul_f32 v[2:3], v[2:3], v[0:1] op_sel_hi:[1,0]

; DI f32x16 mfma32(bf16x8 a, bf16x8 b, f32x16 c) { return __builtin_amdgcn_mfma_f32_32x32x16_bf16(a, b, c, 0, 0, 0); }
; DI int crow(int i, int h) { return (i & 3) + 8 * (i >> 2) + 4 * h; }
;     ...
; #pragma unroll
;   for (int k2 = 0; k2 < 2; ++k2) {
;     if (!(HM & (1 << k2))) continue;
; #pragma unroll
;     for (int i = 0; i < 16; ++i) s[k2][i] = 0.f;
; #pragma unroll
;     for (int ks = 0; ks < 4; ++ks) {
;       const bf16x8 a = *(const bf16x8*)(Ks + (32 * k2 + r) * LSTR + 16 * ks + 8 * h);
;       s[k2] = mfma32(a, qf[ks], s[k2]);
;     }
;   }
;   if (MODE == 1) {
; #pragma unroll
;     for (int k2 = 0; k2 < 2; ++k2)
; #pragma unroll
;       for (int g = 0; g < 4; ++g) {
;         if (!(HM & (1 << k2))) continue;
;         const f32x4 cv = *(const f32x4*)(cn_lds + key0 + 32 * k2 + 8 * g + 4 * h);
; #pragma unroll
;         for (int e = 0; e < 4; ++e) s[k2][4 * g + e] = fmaf(s[k2][4 * g + e], L2E, cv[e]);
;       }
;   }
;   float mx = NINF;
; #pragma unroll
;   for (int k2 = 0; k2 < 2; ++k2)
; #pragma unroll
;     for (int i = 0; i < 16; ++i) {
;       if (!(HM & (1 << k2))) continue;
;       float v = s[k2][i];
;       if (MASKED) {
;         const int tk = key0 + 32 * k2 + crow(i, h);
;         const bool valid = (MODE == 0) ? ((tk <= tq) && (tq - tk <= maxdist)) : (tk <= tq);
;         v = valid ? v : NINF; s[k2][i] = v;
;       }
;       mx = fmaxf(mx, v);
;     }
;   mx = fmaxf(mx, __shfl_xor(mx, 32));
;   if (MODE != 1) mx *= L2E;
;   if (MODE == 2) mx = lanesel ? mx : NINF;
;   const float mn = fmaxf(m, mx); const float alpha = __builtin_amdgcn_exp2f(m - mn);
;   const float neg = (MODE == 2 && !lanesel) ? NINF : -mn;
;   float ps = 0.f;
; #pragma unroll
;   for (int k2 = 0; k2 < 2; ++k2)
; #pragma unroll
;     for (int i = 0; i < 16; ++i) {
;       if (!(HM & (1 << k2))) continue;
;       const float pv = (MODE == 1) ? __builtin_amdgcn_exp2f(s[k2][i] + neg) : __builtin_amdgcn_exp2f(fmaf(s[k2][i], L2E, neg));
;       s[k2][i] = pv; ps += pv;
;     }
;   l = l * alpha + ps;
;   if (__builtin_amdgcn_ballot_w64(mn != m) != 0ull) {
; #pragma unroll
;     for (int dt = 0; dt < 2; ++dt)
; #pragma unroll
;       for (int i = 0; i < 16; ++i) o[dt][i] *= alpha;
;   }
.LBB0_1018:
	s_lshr_b64 s[6:7], s[4:5], s64
	s_and_b32 s58, s6, 1
	s_cmp_eq_u64 s[58:59], 0
	s_cbranch_scc1 .LBB0_1042
	s_lshl_b32 s58, s64, 6
	s_or_b32 s33, s58, 63
	s_cmp_le_u32 s58, s3
	s_cselect_b64 s[6:7], -1, 0
	s_or_b32 s36, s58, 31
	s_cmp_ge_i32 s36, s29
	s_cselect_b64 s[36:37], -1, 0
	s_and_b64 s[6:7], s[6:7], s[36:37]
	v_cndmask_b32_e64 v0, 0, 1, s[6:7]
	s_or_b32 s6, s58, 32
	s_cmp_gt_u32 s6, s3
	s_cselect_b64 s[6:7], -1, 0
	s_cmp_lt_i32 s33, s29
	s_cselect_b64 s[36:37], -1, 0
	v_readfirstlane_b32 s38, v0
	s_or_b32 s39, s38, 2
	s_or_b64 s[6:7], s[6:7], s[36:37]
	s_and_b64 s[6:7], s[6:7], exec
	s_cselect_b32 s64, s38, s39
	s_mov_b64 s[62:63], -1
	s_mov_b64 s[54:55], 0
	s_cmp_lt_i32 s64, 2
	s_mov_b64 s[6:7], 0
	s_cbranch_scc1 .LBB0_1035
	s_cmp_eq_u32 s64, 2
	s_mov_b64 s[6:7], -1
	s_cbranch_scc0 .LBB0_1024
	ds_read_b128 v[34:37], v199 offset:23040
	ds_read_b128 v[50:53], v199 offset:23072
	v_or_b32_e32 v0, s58, v197
	s_waitcnt lgkmcnt(1)
	v_mfma_f32_32x32x16_bf16 v[34:49], v[34:37], v[98:101], 0
	s_waitcnt lgkmcnt(0)
	v_mfma_f32_32x32x16_bf16 v[34:49], v[50:53], v[102:105], v[34:49]
	ds_read_b128 v[50:53], v199 offset:23104
	s_waitcnt lgkmcnt(0)
	v_mfma_f32_32x32x16_bf16 v[34:49], v[50:53], v[106:109], v[34:49]
	ds_read_b128 v[50:53], v199 offset:23136
	s_waitcnt lgkmcnt(0)
	v_mfma_f32_32x32x16_bf16 v[34:49], v[50:53], v[110:113], v[34:49]
	v_or_b32_e32 v50, 32, v0
	v_cmp_gt_u32_e32 vcc, v50, v154
	v_cmp_lt_i32_e64 s[6:7], v50, v155
	s_or_b64 vcc, vcc, s[6:7]
	s_nop 7
	v_cndmask_b32_e32 v66, v34, v204, vcc
	v_bitop3_b32 v34, s58, v205, v197 bitop3:0x36
	v_cmp_ge_u32_e32 vcc, v50, v154
	v_cmp_gt_i32_e64 s[6:7], v34, v156
	s_or_b64 vcc, vcc, s[6:7]
	v_cndmask_b32_e32 v67, v35, v204, vcc
	v_or_b32_e32 v35, 34, v0
	v_cmp_gt_u32_e32 vcc, v35, v154
	v_cmp_lt_i32_e64 s[6:7], v35, v155
	s_or_b64 vcc, vcc, s[6:7]
	v_or_b32_e32 v35, 35, v0
	v_cndmask_b32_e32 v68, v36, v204, vcc
	v_cmp_gt_u32_e32 vcc, v35, v154
	v_cmp_lt_i32_e64 s[6:7], v35, v155
	s_or_b64 vcc, vcc, s[6:7]
	v_or_b32_e32 v35, 40, v0
	v_cndmask_b32_e32 v69, v37, v204, vcc
	v_cmp_gt_u32_e32 vcc, v35, v154
	v_cmp_lt_i32_e64 s[6:7], v35, v155
	s_or_b64 vcc, vcc, s[6:7]
	v_or_b32_e32 v35, 41, v0
	v_cndmask_b32_e32 v70, v38, v204, vcc
	v_cmp_gt_u32_e32 vcc, v35, v154
	v_cmp_lt_i32_e64 s[6:7], v35, v155
	s_or_b64 vcc, vcc, s[6:7]
	v_or_b32_e32 v35, 42, v0
	v_cndmask_b32_e32 v71, v39, v204, vcc
	v_cmp_gt_u32_e32 vcc, v35, v154
	v_cmp_lt_i32_e64 s[6:7], v35, v155
	s_or_b64 vcc, vcc, s[6:7]
	v_or_b32_e32 v35, 43, v0
	v_cndmask_b32_e32 v76, v40, v204, vcc
	v_cmp_gt_u32_e32 vcc, v35, v154
	v_cmp_lt_i32_e64 s[6:7], v35, v155
	s_or_b64 vcc, vcc, s[6:7]
	v_or_b32_e32 v35, 48, v0
	v_cndmask_b32_e32 v77, v41, v204, vcc
	v_cmp_gt_u32_e32 vcc, v35, v154
	v_cmp_lt_i32_e64 s[6:7], v35, v155
	s_or_b64 vcc, vcc, s[6:7]
	v_or_b32_e32 v35, 49, v0
	v_cndmask_b32_e32 v78, v42, v204, vcc
	v_cmp_gt_u32_e32 vcc, v35, v154
	v_cmp_lt_i32_e64 s[6:7], v35, v155
	s_or_b64 vcc, vcc, s[6:7]
	v_or_b32_e32 v35, 50, v0
	v_cndmask_b32_e32 v79, v43, v204, vcc
	v_cmp_gt_u32_e32 vcc, v35, v154
	v_cmp_lt_i32_e64 s[6:7], v35, v155
	s_or_b64 vcc, vcc, s[6:7]
	v_or_b32_e32 v35, 51, v0
	v_cndmask_b32_e32 v80, v44, v204, vcc
	v_cmp_gt_u32_e32 vcc, v35, v154
	v_cmp_lt_i32_e64 s[6:7], v35, v155
	s_or_b64 vcc, vcc, s[6:7]
	v_or_b32_e32 v35, 56, v0
	v_cndmask_b32_e32 v81, v45, v204, vcc
	v_cmp_gt_u32_e32 vcc, v35, v154
	v_cmp_lt_i32_e64 s[6:7], v35, v155
	s_or_b64 vcc, vcc, s[6:7]
	v_or_b32_e32 v35, 57, v0
	v_max3_f32 v34, v66, s35, v67
	v_cndmask_b32_e32 v73, v46, v204, vcc
	v_cmp_gt_u32_e32 vcc, v35, v154
	v_cmp_lt_i32_e64 s[6:7], v35, v155
	v_max3_f32 v34, v34, v68, v69
	s_or_b64 vcc, vcc, s[6:7]
	v_or_b32_e32 v35, 58, v0
	v_max3_f32 v34, v34, v70, v71
	v_cndmask_b32_e32 v74, v47, v204, vcc
	v_cmp_gt_u32_e32 vcc, v35, v154
	v_cmp_lt_i32_e64 s[6:7], v35, v155
	v_max3_f32 v34, v34, v76, v77
	s_or_b64 vcc, vcc, s[6:7]
	v_or_b32_e32 v0, 59, v0
	v_max3_f32 v34, v34, v78, v79
	v_cndmask_b32_e32 v75, v48, v204, vcc
	v_cmp_gt_u32_e32 vcc, v0, v154
	v_cmp_lt_i32_e64 s[6:7], v0, v155
	v_max3_f32 v34, v34, v80, v81
	s_or_b64 vcc, vcc, s[6:7]
	v_max3_f32 v34, v34, v73, v74
	v_cndmask_b32_e32 v72, v49, v204, vcc
	v_and_b32_e32 v35, 64, v202
	v_max3_f32 v0, v34, v75, v72
	v_xor_b32_e32 v34, 32, v202
	v_add_u32_e32 v35, 64, v35
	v_cmp_lt_i32_e32 vcc, v34, v35
	s_nop 1
	v_cndmask_b32_e32 v34, v202, v34, vcc
	v_lshlrev_b32_e32 v34, 2, v34
	ds_bpermute_b32 v34, v34, v0
	s_waitcnt lgkmcnt(0)
	v_max_f32_e32 v34, v34, v34
	v_max_f32_e32 v0, v0, v34
	v_mul_f32_e32 v0, 0x3fb8aa3b, v0
	v_max_f32_e32 v34, v158, v158
	v_max_f32_e32 v157, v34, v0
	v_sub_f32_e32 v0, v158, v157
	v_exp_f32_e32 v0, v0
	v_cmp_neq_f32_e32 vcc, v157, v158
	s_cbranch_vccz .LBB0_1023
	v_pk_mul_f32 v[32:33], v[32:33], v[0:1] op_sel_hi:[1,0]
	v_pk_mul_f32 v[30:31], v[30:31], v[0:1] op_sel_hi:[1,0]
	v_pk_mul_f32 v[28:29], v[28:29], v[0:1] op_sel_hi:[1,0]
	v_pk_mul_f32 v[26:27], v[26:27], v[0:1] op_sel_hi:[1,0]
	v_pk_mul_f32 v[24:25], v[24:25], v[0:1] op_sel_hi:[1,0]
	v_pk_mul_f32 v[22:23], v[22:23], v[0:1] op_sel_hi:[1,0]
	v_pk_mul_f32 v[20:21], v[20:21], v[0:1] op_sel_hi:[1,0]
	v_pk_mul_f32 v[18:19], v[18:19], v[0:1] op_sel_hi:[1,0]
	v_pk_mul_f32 v[16:17], v[16:17], v[0:1] op_sel_hi:[1,0]
	v_pk_mul_f32 v[14:15], v[14:15], v[0:1] op_sel_hi:[1,0]
	v_pk_mul_f32 v[12:13], v[12:13], v[0:1] op_sel_hi:[1,0]
	v_pk_mul_f32 v[10:11], v[10:11], v[0:1] op_sel_hi:[1,0]
	v_pk_mul_f32 v[8:9], v[8:9], v[0:1] op_sel_hi:[1,0]
	v_pk_mul_f32 v[6:7], v[6:7], v[0:1] op_sel_hi:[1,0]
	v_pk_mul_f32 v[4:5], v[4:5], v[0:1] op_sel_hi:[1,0]
	v_pk_mul_f32 v[2:3], v[2:3], v[0:1] op_sel_hi:[1,0]

; DI f32x16 mfma32(bf16x8 a, bf16x8 b, f32x16 c) { return __builtin_amdgcn_mfma_f32_32x32x16_bf16(a, b, c, 0, 0, 0); }
;     ...
; #pragma unroll
;   for (int k2 = 0; k2 < 2; ++k2) {
;     if (!(HM & (1 << k2))) continue;
; #pragma unroll
;     for (int i = 0; i < 16; ++i) s[k2][i] = 0.f;
; #pragma unroll
;     for (int ks = 0; ks < 4; ++ks) {
;       const bf16x8 a = *(const bf16x8*)(Ks + (32 * k2 + r) * LSTR + 16 * ks + 8 * h);
;       s[k2] = mfma32(a, qf[ks], s[k2]);
;     }
;   }
;   if (MODE == 1) {
; #pragma unroll
;     for (int k2 = 0; k2 < 2; ++k2)
; #pragma unroll
;       for (int g = 0; g < 4; ++g) {
;         if (!(HM & (1 << k2))) continue;
;         const f32x4 cv = *(const f32x4*)(cn_lds + key0 + 32 * k2 + 8 * g + 4 * h);
; #pragma unroll
;         for (int e = 0; e < 4; ++e) s[k2][4 * g + e] = fmaf(s[k2][4 * g + e], L2E, cv[e]);
;       }
;   }
;   float mx = NINF;
; #pragma unroll
;   for (int k2 = 0; k2 < 2; ++k2)
; #pragma unroll
;     for (int i = 0; i < 16; ++i) {
;       if (!(HM & (1 << k2))) continue;
;       float v = s[k2][i];
;       if (MASKED) {
;         const int tk = key0 + 32 * k2 + crow(i, h);
;         const bool valid = (MODE == 0) ? ((tk <= tq) && (tq - tk <= maxdist)) : (tk <= tq);
;         v = valid ? v : NINF; s[k2][i] = v;
;       }
;       mx = fmaxf(mx, v);
; template <int MODE>
; DI void flash_loop(char* smem, const bf16_t* Kbase, size_t ldk, const bf16_t* Vtbase, size_t ldv, ull tiles, ull wtiles,
;                    const bf16x8 (&qf)[4], f32x16 (&o)[2], float& m, float& l, int tq, int tqmin, int tqmax, int maxdist, const float* cn_lds, ull lmask) {
;     ...
;     const bool interior = (64 * kt + 63 <= tqmin) && (MODE != 0 || (tqmax - 64 * kt <= maxdist));
;     int hm = 3;
;     if (MODE == 0) {
;       hm = 0;
;       if (64 * kt <= tqmax && 64 * kt + 31 >= tqmin - maxdist) hm |= 1;
;       if (64 * kt + 32 <= tqmax && 64 * kt + 63 >= tqmin - maxdist) hm |= 2;
;     }
;     if (MODE == 0 && hm == 1) attn_tile<MODE, true, 1>(Ks, Vs, qf, o, m, l, 64 * kt, tq, maxdist, cn_lds, sel);
;     else if (MODE == 0 && hm == 2) attn_tile<MODE, true, 2>(Ks, Vs, qf, o, m, l, 64 * kt, tq, maxdist, cn_lds, sel);
;     else if (interior) attn_tile<MODE, false>(Ks, Vs, qf, o, m, l, 64 * kt, tq, maxdist, cn_lds, sel);
;     else attn_tile<MODE, true>(Ks, Vs, qf, o, m, l, 64 * kt, tq, maxdist, cn_lds, sel);
.LBB0_1026:
	ds_read_b128 v[82:85], v196 offset:18432
	ds_read_b128 v[78:81], v196 offset:18464
	ds_read_b128 v[74:77], v196 offset:18496
	ds_read_b128 v[66:69], v196 offset:18528
	ds_read_b128 v[70:73], v196 offset:23040
	s_cmp_le_u32 s33, s28
	s_cselect_b64 s[6:7], -1, 0
	s_cmp_ge_i32 s58, s30
	s_cselect_b64 s[36:37], -1, 0
	s_and_b64 s[6:7], s[6:7], s[36:37]
	s_andn2_b64 vcc, exec, s[6:7]
	s_mov_b64 s[6:7], -1
	s_cbranch_vccz .LBB0_1030
	s_waitcnt lgkmcnt(4)
	v_mfma_f32_32x32x16_bf16 v[50:65], v[82:85], v[98:101], 0
	ds_read_b128 v[86:89], v196 offset:23072
	ds_read_b128 v[90:93], v196 offset:23104
	v_or_b32_e32 v0, s58, v197
	v_cmp_gt_u32_e32 vcc, v0, v154
	v_cmp_lt_i32_e64 s[6:7], v0, v155
	s_or_b64 vcc, vcc, s[6:7]
	s_waitcnt lgkmcnt(5)
	v_mfma_f32_32x32x16_bf16 v[50:65], v[78:81], v[102:105], v[50:65]
	s_waitcnt lgkmcnt(2)
	v_mfma_f32_32x32x16_bf16 v[34:49], v[70:73], v[98:101], 0
	v_mfma_f32_32x32x16_bf16 v[50:65], v[74:77], v[106:109], v[50:65]
	s_waitcnt lgkmcnt(1)
	v_mfma_f32_32x32x16_bf16 v[34:49], v[86:89], v[102:105], v[34:49]
	ds_read_b128 v[86:89], v196 offset:23136
	v_mfma_f32_32x32x16_bf16 v[50:65], v[66:69], v[110:113], v[50:65]
	s_waitcnt lgkmcnt(1)
	v_mfma_f32_32x32x16_bf16 v[34:49], v[90:93], v[106:109], v[34:49]
	s_waitcnt lgkmcnt(0)
	v_mfma_f32_32x32x16_bf16 v[34:49], v[86:89], v[110:113], v[34:49]
	s_nop 7
	v_cndmask_b32_e32 v86, v50, v204, vcc
	v_bitop3_b32 v50, s58, v197, s58 bitop3:3
	v_cmp_ge_u32_e32 vcc, v0, v154
	v_cmp_lt_i32_e64 s[6:7], v156, v50
	s_or_b64 vcc, vcc, s[6:7]
	v_cndmask_b32_e32 v87, v51, v204, vcc
	v_or_b32_e32 v51, 2, v0
	v_cmp_gt_u32_e32 vcc, v51, v154
	v_cmp_lt_i32_e64 s[6:7], v51, v155
	s_or_b64 vcc, vcc, s[6:7]
	v_or_b32_e32 v51, 3, v0
	v_cndmask_b32_e32 v88, v52, v204, vcc
	v_cmp_gt_u32_e32 vcc, v51, v154
	v_cmp_lt_i32_e64 s[6:7], v51, v155
	s_or_b64 vcc, vcc, s[6:7]
	v_or_b32_e32 v51, 8, v0
	v_cndmask_b32_e32 v89, v53, v204, vcc
	v_cmp_gt_u32_e32 vcc, v51, v154
	v_cmp_lt_i32_e64 s[6:7], v51, v155
	s_or_b64 vcc, vcc, s[6:7]
	v_or_b32_e32 v51, 9, v0
	v_cndmask_b32_e32 v90, v54, v204, vcc
	v_cmp_gt_u32_e32 vcc, v51, v154
	v_cmp_lt_i32_e64 s[6:7], v51, v155
	s_or_b64 vcc, vcc, s[6:7]
	v_or_b32_e32 v51, 10, v0
	v_cndmask_b32_e32 v192, v55, v204, vcc
	v_cmp_gt_u32_e32 vcc, v51, v154
	v_cmp_lt_i32_e64 s[6:7], v51, v155
	s_or_b64 vcc, vcc, s[6:7]
	v_or_b32_e32 v51, 11, v0
	v_cndmask_b32_e32 v191, v56, v204, vcc
	v_cmp_gt_u32_e32 vcc, v51, v154
	v_cmp_lt_i32_e64 s[6:7], v51, v155
	s_or_b64 vcc, vcc, s[6:7]
	v_or_b32_e32 v51, 16, v0
	v_cndmask_b32_e32 v193, v57, v204, vcc
	v_cmp_gt_u32_e32 vcc, v51, v154
	v_cmp_lt_i32_e64 s[6:7], v51, v155
	s_or_b64 vcc, vcc, s[6:7]
	v_or_b32_e32 v51, 17, v0
	v_cndmask_b32_e32 v188, v58, v204, vcc
	v_cmp_gt_u32_e32 vcc, v51, v154
	v_cmp_lt_i32_e64 s[6:7], v51, v155
	s_or_b64 vcc, vcc, s[6:7]
	v_or_b32_e32 v51, 18, v0
	v_cndmask_b32_e32 v190, v59, v204, vcc
	v_cmp_gt_u32_e32 vcc, v51, v154
	v_cmp_lt_i32_e64 s[6:7], v51, v155
	s_or_b64 vcc, vcc, s[6:7]
	v_or_b32_e32 v51, 19, v0
	v_cndmask_b32_e32 v189, v60, v204, vcc
	v_cmp_gt_u32_e32 vcc, v51, v154
	v_cmp_lt_i32_e64 s[6:7], v51, v155
	s_or_b64 vcc, vcc, s[6:7]
	v_or_b32_e32 v51, 24, v0
	v_cndmask_b32_e32 v187, v61, v204, vcc
	v_cmp_gt_u32_e32 vcc, v51, v154
	v_cmp_lt_i32_e64 s[6:7], v51, v155
	s_or_b64 vcc, vcc, s[6:7]
	v_or_b32_e32 v51, 25, v0
	v_cndmask_b32_e32 v186, v62, v204, vcc
	v_cmp_gt_u32_e32 vcc, v51, v154
	v_cmp_lt_i32_e64 s[6:7], v51, v155
	s_or_b64 vcc, vcc, s[6:7]
	v_or_b32_e32 v51, 26, v0
	v_cndmask_b32_e32 v185, v63, v204, vcc
	v_cmp_gt_u32_e32 vcc, v51, v154
	v_cmp_lt_i32_e64 s[6:7], v51, v155
	s_or_b64 vcc, vcc, s[6:7]
	v_or_b32_e32 v51, 27, v0
	v_cndmask_b32_e32 v184, v64, v204, vcc
	v_cmp_gt_u32_e32 vcc, v51, v154
	v_cmp_lt_i32_e64 s[6:7], v51, v155
	s_or_b64 vcc, vcc, s[6:7]
	v_or_b32_e32 v51, 32, v0
	v_cndmask_b32_e32 v182, v65, v204, vcc
	v_cmp_gt_u32_e32 vcc, v51, v154
	v_cmp_lt_i32_e64 s[6:7], v51, v155
	s_or_b64 vcc, vcc, s[6:7]
	v_cndmask_b32_e32 v164, v34, v204, vcc
	v_or_b32_e32 v34, 33, v0
	v_cmp_gt_u32_e32 vcc, v34, v154
	v_cmp_lt_i32_e64 s[6:7], v34, v155
	s_or_b64 vcc, vcc, s[6:7]
	v_cndmask_b32_e32 v162, v35, v204, vcc
	v_or_b32_e32 v35, 34, v0
; DI int crow(int i, int h) { return (i & 3) + 8 * (i >> 2) + 4 * h; }
;     ...
;   float mx = NINF;
; #pragma unroll
;   for (int k2 = 0; k2 < 2; ++k2)
; #pragma unroll
;     for (int i = 0; i < 16; ++i) {
;       if (!(HM & (1 << k2))) continue;
;       float v = s[k2][i];
;       if (MASKED) {
;         const int tk = key0 + 32 * k2 + crow(i, h);
;         const bool valid = (MODE == 0) ? ((tk <= tq) && (tq - tk <= maxdist)) : (tk <= tq);
;         v = valid ? v : NINF; s[k2][i] = v;
;       }
;       mx = fmaxf(mx, v);
;     }
;   mx = fmaxf(mx, __shfl_xor(mx, 32));
;   if (MODE != 1) mx *= L2E;
;   if (MODE == 2) mx = lanesel ? mx : NINF;
;   const float mn = fmaxf(m, mx); const float alpha = __builtin_amdgcn_exp2f(m - mn);
;   const float neg = (MODE == 2 && !lanesel) ? NINF : -mn;
;   float ps = 0.f;
; #pragma unroll
;   for (int k2 = 0; k2 < 2; ++k2)
; #pragma unroll
;     for (int i = 0; i < 16; ++i) {
;       if (!(HM & (1 << k2))) continue;
;       const float pv = (MODE == 1) ? __builtin_amdgcn_exp2f(s[k2][i] + neg) : __builtin_amdgcn_exp2f(fmaf(s[k2][i], L2E, neg));
;       s[k2][i] = pv; ps += pv;
;     }
;   l = l * alpha + ps;
;   if (__builtin_amdgcn_ballot_w64(mn != m) != 0ull) {
; #pragma unroll
;     for (int dt = 0; dt < 2; ++dt)
; #pragma unroll
;       for (int i = 0; i < 16; ++i) o[dt][i] *= alpha;
;   }
	v_cmp_gt_u32_e32 vcc, v35, v154
	v_cmp_lt_i32_e64 s[6:7], v35, v155
	s_or_b64 vcc, vcc, s[6:7]
	v_or_b32_e32 v35, 35, v0
	v_cndmask_b32_e32 v159, v36, v204, vcc
	v_cmp_gt_u32_e32 vcc, v35, v154
	v_cmp_lt_i32_e64 s[6:7], v35, v155
	s_or_b64 vcc, vcc, s[6:7]
	v_or_b32_e32 v35, 40, v0
	v_cndmask_b32_e32 v97, v37, v204, vcc
	v_cmp_gt_u32_e32 vcc, v35, v154
	v_cmp_lt_i32_e64 s[6:7], v35, v155
	s_or_b64 vcc, vcc, s[6:7]
	v_or_b32_e32 v35, 41, v0
	v_cndmask_b32_e32 v92, v38, v204, vcc
	v_cmp_gt_u32_e32 vcc, v35, v154
	v_cmp_lt_i32_e64 s[6:7], v35, v155
	s_or_b64 vcc, vcc, s[6:7]
	v_or_b32_e32 v35, 42, v0
	v_cndmask_b32_e32 v91, v39, v204, vcc
	v_cmp_gt_u32_e32 vcc, v35, v154
	v_cmp_lt_i32_e64 s[6:7], v35, v155
	s_or_b64 vcc, vcc, s[6:7]
	v_or_b32_e32 v35, 43, v0
	v_cndmask_b32_e32 v93, v40, v204, vcc
	v_cmp_gt_u32_e32 vcc, v35, v154
	v_cmp_lt_i32_e64 s[6:7], v35, v155
	s_or_b64 vcc, vcc, s[6:7]
	v_or_b32_e32 v35, 48, v0
	v_cndmask_b32_e32 v94, v41, v204, vcc
	v_cmp_gt_u32_e32 vcc, v35, v154
	v_cmp_lt_i32_e64 s[6:7], v35, v155
	s_or_b64 vcc, vcc, s[6:7]
	v_or_b32_e32 v35, 49, v0
	v_max3_f32 v50, v86, s35, v87
	v_cndmask_b32_e32 v95, v42, v204, vcc
	v_cmp_gt_u32_e32 vcc, v35, v154
	v_cmp_lt_i32_e64 s[6:7], v35, v155
	v_max3_f32 v50, v50, v88, v89
	s_or_b64 vcc, vcc, s[6:7]
	v_or_b32_e32 v35, 50, v0
	v_max3_f32 v50, v50, v90, v192
	v_cndmask_b32_e32 v96, v43, v204, vcc
	v_cmp_gt_u32_e32 vcc, v35, v154
	v_cmp_lt_i32_e64 s[6:7], v35, v155
	v_max3_f32 v50, v50, v191, v193
	s_or_b64 vcc, vcc, s[6:7]
	v_or_b32_e32 v35, 51, v0
	v_max3_f32 v50, v50, v188, v190
	v_cndmask_b32_e32 v161, v44, v204, vcc
	v_cmp_gt_u32_e32 vcc, v35, v154
	v_cmp_lt_i32_e64 s[6:7], v35, v155
	v_max3_f32 v50, v50, v189, v187
	s_or_b64 vcc, vcc, s[6:7]
	v_or_b32_e32 v35, 56, v0
	v_max3_f32 v50, v50, v186, v185
	v_cndmask_b32_e32 v163, v45, v204, vcc
	v_cmp_gt_u32_e32 vcc, v35, v154
	v_cmp_lt_i32_e64 s[6:7], v35, v155
	v_max3_f32 v50, v50, v184, v182
	s_or_b64 vcc, vcc, s[6:7]
	v_or_b32_e32 v35, 57, v0
	v_max3_f32 v34, v50, v164, v162
	v_cndmask_b32_e32 v165, v46, v204, vcc
	v_cmp_gt_u32_e32 vcc, v35, v154
	v_cmp_lt_i32_e64 s[6:7], v35, v155
	v_max3_f32 v34, v34, v159, v97
	s_or_b64 vcc, vcc, s[6:7]
	v_or_b32_e32 v35, 58, v0
	v_max3_f32 v34, v34, v92, v91
	v_cndmask_b32_e32 v180, v47, v204, vcc
	v_cmp_gt_u32_e32 vcc, v35, v154
	v_cmp_lt_i32_e64 s[6:7], v35, v155
	v_max3_f32 v34, v34, v93, v94
	s_or_b64 vcc, vcc, s[6:7]
	v_or_b32_e32 v0, 59, v0
	v_max3_f32 v34, v34, v95, v96
	v_cndmask_b32_e32 v181, v48, v204, vcc
	v_cmp_gt_u32_e32 vcc, v0, v154
	v_cmp_lt_i32_e64 s[6:7], v0, v155
	v_max3_f32 v34, v34, v161, v163
	s_or_b64 vcc, vcc, s[6:7]
	v_max3_f32 v34, v34, v165, v180
	v_cndmask_b32_e32 v183, v49, v204, vcc
	v_and_b32_e32 v35, 64, v202
	v_max3_f32 v0, v34, v181, v183
	v_xor_b32_e32 v34, 32, v202
	v_add_u32_e32 v35, 64, v35
	v_cmp_lt_i32_e32 vcc, v34, v35
	s_nop 1
	v_cndmask_b32_e32 v34, v202, v34, vcc
	v_lshlrev_b32_e32 v34, 2, v34
	ds_bpermute_b32 v34, v34, v0
	s_waitcnt lgkmcnt(0)
	v_max_f32_e32 v34, v34, v34
	v_max_f32_e32 v0, v0, v34
	v_mul_f32_e32 v0, 0x3fb8aa3b, v0
	v_max_f32_e32 v34, v158, v158
	v_max_f32_e32 v157, v34, v0
	v_sub_f32_e32 v0, v158, v157
	v_exp_f32_e32 v0, v0
	v_cmp_neq_f32_e32 vcc, v157, v158
	s_cbranch_vccz .LBB0_1029
	v_pk_mul_f32 v[32:33], v[32:33], v[0:1] op_sel_hi:[1,0]
	v_pk_mul_f32 v[30:31], v[30:31], v[0:1] op_sel_hi:[1,0]
	v_pk_mul_f32 v[28:29], v[28:29], v[0:1] op_sel_hi:[1,0]
	v_pk_mul_f32 v[26:27], v[26:27], v[0:1] op_sel_hi:[1,0]
	v_pk_mul_f32 v[24:25], v[24:25], v[0:1] op_sel_hi:[1,0]
	v_pk_mul_f32 v[22:23], v[22:23], v[0:1] op_sel_hi:[1,0]
	v_pk_mul_f32 v[20:21], v[20:21], v[0:1] op_sel_hi:[1,0]
	v_pk_mul_f32 v[18:19], v[18:19], v[0:1] op_sel_hi:[1,0]
	v_pk_mul_f32 v[16:17], v[16:17], v[0:1] op_sel_hi:[1,0]
	v_pk_mul_f32 v[14:15], v[14:15], v[0:1] op_sel_hi:[1,0]
	v_pk_mul_f32 v[12:13], v[12:13], v[0:1] op_sel_hi:[1,0]
	v_pk_mul_f32 v[10:11], v[10:11], v[0:1] op_sel_hi:[1,0]
	v_pk_mul_f32 v[8:9], v[8:9], v[0:1] op_sel_hi:[1,0]
	v_pk_mul_f32 v[6:7], v[6:7], v[0:1] op_sel_hi:[1,0]
	v_pk_mul_f32 v[4:5], v[4:5], v[0:1] op_sel_hi:[1,0]
	v_pk_mul_f32 v[2:3], v[2:3], v[0:1] op_sel_hi:[1,0]
